# stack of the individually neutral edits on k17: in-place scan state, helper wait sunk to consumer, DPP l2norm chains, no mid-segment setprio dip
# speedup vs baseline: 1.0121x; 1.0121x over previous
; #define PG8_STAGE(bufoff, gbase, voff) do { _Pragma("unroll") for (int _i = 0; _i < 2; ++_i) \
;         __builtin_amdgcn_global_load_lds((const unsigned*)((const char*)(gbase) + (voff)[_i]), (LAS unsigned*)(lds + (bufoff) + ldsw + _i * 8192), 16, 0, 0); } while (0)
; #define PG8_LDA(dst, b, h) do { _Pragma("unroll") for (int m = 0; m < 4; ++m) _Pragma("unroll") for (int k = 0; k < 2; ++k) dst[m][k] = *(const LAS bf16x8*)(lds + PG8_SA(b, h) + aoff + m * 2048 + k * 1024); } while (0)
; #define PG8_LDB(dst, b, h) do { _Pragma("unroll") for (int n = 0; n < 2; ++n) _Pragma("unroll") for (int k = 0; k < 2; ++k) dst[n][k] = *(const LAS bf16x8*)(lds + PG8_SB(b, h) + boff + n * 2048 + k * 1024); } while (0)
; #define PG8_MMA(ai, bj, At, Bt) do { __builtin_amdgcn_s_setprio(1); _Pragma("unroll") for (int m = 0; m < 4; ++m) _Pragma("unroll") for (int n = 0; n < 2; ++n) _Pragma("unroll") for (int k = 0; k < 2; ++k) \
;         acc[ai][bj][m][n] = __builtin_amdgcn_mfma_f32_16x16x32_bf16(Bt[n][k], At[m][k], acc[ai][bj][m][n], 0, 0, 0); __builtin_amdgcn_s_setprio(0); } while (0)
; #define PG8_WAIT_V(n) asm volatile("s_waitcnt vmcnt(" #n ")" ::: "memory")
; #define PG8_WAIT_L(n) asm volatile("s_waitcnt lgkmcnt(" #n ")" ::: "memory")
; #define PG8_BAR __builtin_amdgcn_s_barrier()
; #define PG8_SCHED __builtin_amdgcn_sched_barrier(0)
; template <class Epi, class Sched, bool ALIGN_EPI>
; DI void gemm_phase(LAS unsigned char* lds, const Gemm g, const Sched& S, const Epi& E) {
;     ...
;         for (int t = 0; t < nt; t += 2) {
;             const bool last = (t == nt - 2);
;             const char* a1 = cA + (size_t)(t + 1) * kstep;
;             const char* a2 = last ? nA : cA + (size_t)(t + 2) * kstep; const char* b2 = last ? nB : cB + (size_t)(t + 2) * kstep;
;             const char* a3 = a2 + kstep; const char* b3 = b2 + kstep;
;             PG8_LDB(B0, 0, 0); PG8_LDB(B1, 0, 1); PG8_SCHED; PG8_LDA(At, 0, 0); PG8_STAGE(PG8_SA(1, 1), a1 + hstepA, voffA);
;             PG8_WAIT_V(8); PG8_WAIT_L(0); PG8_BAR; PG8_MMA(0, 0, At, B0); PG8_MMA(0, 1, At, B1); PG8_BAR; PG8_SCHED;
;             PG8_LDA(At, 0, 1); PG8_STAGE(PG8_SB(0, 0), b2, voffB); PG8_STAGE(PG8_SB(0, 1), b2 + hstepB, voffB); PG8_STAGE(PG8_SA(0, 0), a2, voffA);
;             PG8_WAIT_V(8); PG8_WAIT_L(0); PG8_BAR; PG8_MMA(1, 0, At, B0); PG8_MMA(1, 1, At, B1); PG8_BAR; PG8_SCHED;
.LBB0_98:
	ds_read_b128 v[156:159], v149
	ds_read_b128 v[160:163], v149 offset:1024
	ds_read_b128 v[164:167], v149 offset:2048
	ds_read_b128 v[168:171], v149 offset:3072
	ds_read_b128 v[172:175], v150
	ds_read_b128 v[176:179], v150 offset:1024
	ds_read_b128 v[180:183], v150 offset:2048
	ds_read_b128 v[184:187], v150 offset:3072
	s_add_u32 s24, s22, 0xfffc0080
	s_addc_u32 s25, s23, -1
	s_cmp_eq_u32 s56, 12
	s_cselect_b32 s27, s15, s25
	s_cselect_b32 s26, s52, s24
	s_cselect_b32 s25, s13, s55
	s_cselect_b32 s24, s53, s54
	v_lshl_add_u64 v[146:147], s[22:23], 0, v[138:139]
	s_add_i32 m0, s21, 0xc000
	ds_read_b128 v[188:191], v151
	ds_read_b128 v[192:195], v151 offset:1024
	ds_read_b128 v[196:199], v151 offset:2048
	ds_read_b128 v[204:207], v151 offset:3072
	ds_read_b128 v[208:211], v151 offset:4096
	ds_read_b128 v[212:215], v151 offset:5120
	ds_read_b128 v[216:219], v151 offset:6144
	ds_read_b128 v[220:223], v151 offset:7168
	global_load_lds_dwordx4 v[146:147], off
	v_lshl_add_u64 v[146:147], s[22:23], 0, v[140:141]
	s_add_i32 m0, s21, 0xe000
	s_nop 0
	global_load_lds_dwordx4 v[146:147], off
	s_waitcnt vmcnt(8)
	s_waitcnt lgkmcnt(0)
	s_barrier
	s_setprio 1
	s_waitcnt lgkmcnt(0)
	v_mfma_f32_16x16x32_bf16 v[126:129], v[156:159], v[188:191], v[126:129]
	v_mfma_f32_16x16x32_bf16 v[122:125], v[164:167], v[188:191], v[122:125]
	v_mfma_f32_16x16x32_bf16 v[110:113], v[156:159], v[196:199], v[110:113]
	v_mfma_f32_16x16x32_bf16 v[106:109], v[164:167], v[196:199], v[106:109]
	v_mfma_f32_16x16x32_bf16 v[94:97], v[156:159], v[208:211], v[94:97]
	v_mfma_f32_16x16x32_bf16 v[90:93], v[164:167], v[208:211], v[90:93]
	v_mfma_f32_16x16x32_bf16 v[78:81], v[156:159], v[216:219], v[78:81]
	v_mfma_f32_16x16x32_bf16 v[74:77], v[164:167], v[216:219], v[74:77]
	v_mfma_f32_16x16x32_bf16 v[126:129], v[160:163], v[192:195], v[126:129]
	v_mfma_f32_16x16x32_bf16 v[122:125], v[168:171], v[192:195], v[122:125]
	v_mfma_f32_16x16x32_bf16 v[110:113], v[160:163], v[204:207], v[110:113]
	v_mfma_f32_16x16x32_bf16 v[106:109], v[168:171], v[204:207], v[106:109]
	v_mfma_f32_16x16x32_bf16 v[94:97], v[160:163], v[212:215], v[94:97]
	v_mfma_f32_16x16x32_bf16 v[90:93], v[168:171], v[212:215], v[90:93]
	v_mfma_f32_16x16x32_bf16 v[78:81], v[160:163], v[220:223], v[78:81]
	v_mfma_f32_16x16x32_bf16 v[74:77], v[168:171], v[220:223], v[74:77]
	v_mfma_f32_16x16x32_bf16 v[118:121], v[172:175], v[188:191], v[118:121]
	v_mfma_f32_16x16x32_bf16 v[114:117], v[180:183], v[188:191], v[114:117]
	v_mfma_f32_16x16x32_bf16 v[102:105], v[172:175], v[196:199], v[102:105]
	v_mfma_f32_16x16x32_bf16 v[98:101], v[180:183], v[196:199], v[98:101]
	v_mfma_f32_16x16x32_bf16 v[86:89], v[172:175], v[208:211], v[86:89]
	v_mfma_f32_16x16x32_bf16 v[82:85], v[180:183], v[208:211], v[82:85]
	v_mfma_f32_16x16x32_bf16 v[70:73], v[172:175], v[216:219], v[70:73]
	v_mfma_f32_16x16x32_bf16 v[66:69], v[180:183], v[216:219], v[66:69]
	v_mfma_f32_16x16x32_bf16 v[118:121], v[176:179], v[192:195], v[118:121]
	v_mfma_f32_16x16x32_bf16 v[114:117], v[184:187], v[192:195], v[114:117]
	v_mfma_f32_16x16x32_bf16 v[102:105], v[176:179], v[204:207], v[102:105]
	v_mfma_f32_16x16x32_bf16 v[98:101], v[184:187], v[204:207], v[98:101]
	v_mfma_f32_16x16x32_bf16 v[86:89], v[176:179], v[212:215], v[86:89]
	v_mfma_f32_16x16x32_bf16 v[82:85], v[184:187], v[212:215], v[82:85]
	v_mfma_f32_16x16x32_bf16 v[70:73], v[176:179], v[220:223], v[70:73]
	v_mfma_f32_16x16x32_bf16 v[66:69], v[184:187], v[220:223], v[66:69]
	s_setprio 0
	s_barrier
	s_add_i32 s57, s80, s68
	v_lshl_add_u64 v[146:147], s[24:25], 0, v[134:135]
	s_mov_b32 m0, s57
	ds_read_b128 v[188:191], v151 offset:16384
	ds_read_b128 v[192:195], v151 offset:17408
	ds_read_b128 v[196:199], v151 offset:18432
	ds_read_b128 v[204:207], v151 offset:19456
	ds_read_b128 v[208:211], v151 offset:20480
	ds_read_b128 v[212:215], v151 offset:21504
	ds_read_b128 v[216:219], v151 offset:22528
	ds_read_b128 v[220:223], v151 offset:23552
	global_load_lds_dwordx4 v[146:147], off
	s_add_i32 m0, s57, 0x2000
	s_add_u32 s58, s24, 0x40000
	v_lshl_add_u64 v[200:201], s[24:25], 0, v[130:131]
	s_addc_u32 s59, s25, 0
	s_add_i32 s57, s81, s68
	global_load_lds_dwordx4 v[200:201], off
	v_lshl_add_u64 v[224:225], s[58:59], 0, v[134:135]
	s_mov_b32 m0, s57
	v_lshl_add_u64 v[226:227], s[26:27], 0, v[132:133]
	global_load_lds_dwordx4 v[224:225], off
	v_lshl_add_u64 v[224:225], s[58:59], 0, v[130:131]
	s_add_i32 m0, s57, 0x2000
	s_nop 0
	global_load_lds_dwordx4 v[224:225], off
	v_lshl_add_u64 v[224:225], s[26:27], 0, v[136:137]
	s_mov_b32 m0, s21
	s_nop 0
	global_load_lds_dwordx4 v[224:225], off
	s_mov_b32 m0, s72
	s_nop 0
	global_load_lds_dwordx4 v[226:227], off
	s_waitcnt vmcnt(8)
	s_waitcnt lgkmcnt(0)
	s_barrier
; #define PG8_STAGE(bufoff, gbase, voff) do { _Pragma("unroll") for (int _i = 0; _i < 2; ++_i) \
;         __builtin_amdgcn_global_load_lds((const unsigned*)((const char*)(gbase) + (voff)[_i]), (LAS unsigned*)(lds + (bufoff) + ldsw + _i * 8192), 16, 0, 0); } while (0)
; #define PG8_LDA(dst, b, h) do { _Pragma("unroll") for (int m = 0; m < 4; ++m) _Pragma("unroll") for (int k = 0; k < 2; ++k) dst[m][k] = *(const LAS bf16x8*)(lds + PG8_SA(b, h) + aoff + m * 2048 + k * 1024); } while (0)
; #define PG8_LDB(dst, b, h) do { _Pragma("unroll") for (int n = 0; n < 2; ++n) _Pragma("unroll") for (int k = 0; k < 2; ++k) dst[n][k] = *(const LAS bf16x8*)(lds + PG8_SB(b, h) + boff + n * 2048 + k * 1024); } while (0)
; #define PG8_MMA(ai, bj, At, Bt) do { __builtin_amdgcn_s_setprio(1); _Pragma("unroll") for (int m = 0; m < 4; ++m) _Pragma("unroll") for (int n = 0; n < 2; ++n) _Pragma("unroll") for (int k = 0; k < 2; ++k) \
;         acc[ai][bj][m][n] = __builtin_amdgcn_mfma_f32_16x16x32_bf16(Bt[n][k], At[m][k], acc[ai][bj][m][n], 0, 0, 0); __builtin_amdgcn_s_setprio(0); } while (0)
; #define PG8_WAIT_V(n) asm volatile("s_waitcnt vmcnt(" #n ")" ::: "memory")
; #define PG8_WAIT_L(n) asm volatile("s_waitcnt lgkmcnt(" #n ")" ::: "memory")
; #define PG8_BAR __builtin_amdgcn_s_barrier()
; #define PG8_SCHED __builtin_amdgcn_sched_barrier(0)
; template <class Epi, class Sched, bool ALIGN_EPI>
; DI void gemm_phase(LAS unsigned char* lds, const Gemm g, const Sched& S, const Epi& E) {
;     ...
;             PG8_WAIT_V(8); PG8_WAIT_L(0); PG8_BAR; PG8_MMA(1, 0, At, B0); PG8_MMA(1, 1, At, B1); PG8_BAR; PG8_SCHED;
;             PG8_LDB(B0, 1, 0); PG8_LDB(B1, 1, 1); PG8_SCHED; PG8_LDA(At, 1, 0); PG8_STAGE(PG8_SA(0, 1), a2 + hstepA, voffA);
;             PG8_WAIT_V(8); PG8_WAIT_L(0); PG8_BAR; PG8_MMA(0, 0, At, B0); PG8_MMA(0, 1, At, B1); PG8_BAR; PG8_SCHED;
;             PG8_LDA(At, 1, 1); PG8_STAGE(PG8_SB(1, 0), b3, voffB); PG8_STAGE(PG8_SB(1, 1), b3 + hstepB, voffB); PG8_STAGE(PG8_SA(1, 0), a3, voffA);
	s_setprio 1
	s_waitcnt lgkmcnt(0)
	v_mfma_f32_16x16x32_bf16 v[62:65], v[156:159], v[188:191], v[62:65]
	v_mfma_f32_16x16x32_bf16 v[58:61], v[164:167], v[188:191], v[58:61]
	v_mfma_f32_16x16x32_bf16 v[46:49], v[156:159], v[196:199], v[46:49]
	v_mfma_f32_16x16x32_bf16 v[42:45], v[164:167], v[196:199], v[42:45]
	v_mfma_f32_16x16x32_bf16 v[30:33], v[156:159], v[208:211], v[30:33]
	v_mfma_f32_16x16x32_bf16 v[26:29], v[164:167], v[208:211], v[26:29]
	v_mfma_f32_16x16x32_bf16 v[14:17], v[156:159], v[216:219], v[14:17]
	v_mfma_f32_16x16x32_bf16 v[10:13], v[164:167], v[216:219], v[10:13]
	v_mfma_f32_16x16x32_bf16 v[62:65], v[160:163], v[192:195], v[62:65]
	v_mfma_f32_16x16x32_bf16 v[58:61], v[168:171], v[192:195], v[58:61]
	v_mfma_f32_16x16x32_bf16 v[46:49], v[160:163], v[204:207], v[46:49]
	v_mfma_f32_16x16x32_bf16 v[42:45], v[168:171], v[204:207], v[42:45]
	v_mfma_f32_16x16x32_bf16 v[30:33], v[160:163], v[212:215], v[30:33]
	v_mfma_f32_16x16x32_bf16 v[26:29], v[168:171], v[212:215], v[26:29]
	v_mfma_f32_16x16x32_bf16 v[14:17], v[160:163], v[220:223], v[14:17]
	v_mfma_f32_16x16x32_bf16 v[10:13], v[168:171], v[220:223], v[10:13]
	v_mfma_f32_16x16x32_bf16 v[54:57], v[172:175], v[188:191], v[54:57]
	v_mfma_f32_16x16x32_bf16 v[50:53], v[180:183], v[188:191], v[50:53]
	v_mfma_f32_16x16x32_bf16 v[38:41], v[172:175], v[196:199], v[38:41]
	v_mfma_f32_16x16x32_bf16 v[34:37], v[180:183], v[196:199], v[34:37]
	v_mfma_f32_16x16x32_bf16 v[22:25], v[172:175], v[208:211], v[22:25]
	v_mfma_f32_16x16x32_bf16 v[18:21], v[180:183], v[208:211], v[18:21]
	v_mfma_f32_16x16x32_bf16 v[6:9], v[172:175], v[216:219], v[6:9]
	v_mfma_f32_16x16x32_bf16 v[2:5], v[180:183], v[216:219], v[2:5]
	v_mfma_f32_16x16x32_bf16 v[54:57], v[176:179], v[192:195], v[54:57]
	v_mfma_f32_16x16x32_bf16 v[50:53], v[184:187], v[192:195], v[50:53]
	v_mfma_f32_16x16x32_bf16 v[38:41], v[176:179], v[204:207], v[38:41]
	v_mfma_f32_16x16x32_bf16 v[34:37], v[184:187], v[204:207], v[34:37]
	v_mfma_f32_16x16x32_bf16 v[22:25], v[176:179], v[212:215], v[22:25]
	v_mfma_f32_16x16x32_bf16 v[18:21], v[184:187], v[212:215], v[18:21]
	v_mfma_f32_16x16x32_bf16 v[6:9], v[176:179], v[220:223], v[6:9]
	v_mfma_f32_16x16x32_bf16 v[2:5], v[184:187], v[220:223], v[2:5]
	s_setprio 0
	s_barrier
	ds_read_b128 v[156:159], v153
	ds_read_b128 v[160:163], v153 offset:1024
	ds_read_b128 v[164:167], v153 offset:2048
	ds_read_b128 v[168:171], v153 offset:3072
	ds_read_b128 v[172:175], v154
	ds_read_b128 v[176:179], v154 offset:1024
	ds_read_b128 v[180:183], v154 offset:2048
	ds_read_b128 v[184:187], v154 offset:3072
	s_add_u32 s26, s26, 0x40000
	s_addc_u32 s27, s27, 0
	s_mov_b32 m0, s73
	v_lshl_add_u64 v[228:229], s[26:27], 0, v[136:137]
	ds_read_b128 v[188:191], v151 offset:32768
	ds_read_b128 v[192:195], v151 offset:33792
	ds_read_b128 v[196:199], v151 offset:34816
	ds_read_b128 v[204:207], v151 offset:35840
	ds_read_b128 v[208:211], v151 offset:36864
	ds_read_b128 v[212:215], v151 offset:37888
	ds_read_b128 v[216:219], v151 offset:38912
	ds_read_b128 v[220:223], v151 offset:39936
	global_load_lds_dwordx4 v[228:229], off
	v_lshl_add_u64 v[228:229], s[26:27], 0, v[132:133]
	s_mov_b32 m0, s74
	s_nop 0
	global_load_lds_dwordx4 v[228:229], off
	s_waitcnt vmcnt(8)
	s_waitcnt lgkmcnt(0)
	s_barrier
	s_setprio 1
	s_waitcnt lgkmcnt(0)
	v_mfma_f32_16x16x32_bf16 v[126:129], v[156:159], v[188:191], v[126:129]
	v_mfma_f32_16x16x32_bf16 v[122:125], v[164:167], v[188:191], v[122:125]
	v_mfma_f32_16x16x32_bf16 v[110:113], v[156:159], v[196:199], v[110:113]
	v_mfma_f32_16x16x32_bf16 v[106:109], v[164:167], v[196:199], v[106:109]
	v_mfma_f32_16x16x32_bf16 v[94:97], v[156:159], v[208:211], v[94:97]
	v_mfma_f32_16x16x32_bf16 v[90:93], v[164:167], v[208:211], v[90:93]
	v_mfma_f32_16x16x32_bf16 v[78:81], v[156:159], v[216:219], v[78:81]
	v_mfma_f32_16x16x32_bf16 v[74:77], v[164:167], v[216:219], v[74:77]
	v_mfma_f32_16x16x32_bf16 v[126:129], v[160:163], v[192:195], v[126:129]
	v_mfma_f32_16x16x32_bf16 v[122:125], v[168:171], v[192:195], v[122:125]
	v_mfma_f32_16x16x32_bf16 v[110:113], v[160:163], v[204:207], v[110:113]
	v_mfma_f32_16x16x32_bf16 v[106:109], v[168:171], v[204:207], v[106:109]
	v_mfma_f32_16x16x32_bf16 v[94:97], v[160:163], v[212:215], v[94:97]
	v_mfma_f32_16x16x32_bf16 v[90:93], v[168:171], v[212:215], v[90:93]
	v_mfma_f32_16x16x32_bf16 v[78:81], v[160:163], v[220:223], v[78:81]
	v_mfma_f32_16x16x32_bf16 v[74:77], v[168:171], v[220:223], v[74:77]
	v_mfma_f32_16x16x32_bf16 v[118:121], v[172:175], v[188:191], v[118:121]
	v_mfma_f32_16x16x32_bf16 v[114:117], v[180:183], v[188:191], v[114:117]
	v_mfma_f32_16x16x32_bf16 v[102:105], v[172:175], v[196:199], v[102:105]
	v_mfma_f32_16x16x32_bf16 v[98:101], v[180:183], v[196:199], v[98:101]
	v_mfma_f32_16x16x32_bf16 v[86:89], v[172:175], v[208:211], v[86:89]
	v_mfma_f32_16x16x32_bf16 v[82:85], v[180:183], v[208:211], v[82:85]
	v_mfma_f32_16x16x32_bf16 v[70:73], v[172:175], v[216:219], v[70:73]
	v_mfma_f32_16x16x32_bf16 v[66:69], v[180:183], v[216:219], v[66:69]
	v_mfma_f32_16x16x32_bf16 v[118:121], v[176:179], v[192:195], v[118:121]
	v_mfma_f32_16x16x32_bf16 v[114:117], v[184:187], v[192:195], v[114:117]
	v_mfma_f32_16x16x32_bf16 v[102:105], v[176:179], v[204:207], v[102:105]
	v_mfma_f32_16x16x32_bf16 v[98:101], v[184:187], v[204:207], v[98:101]
	v_mfma_f32_16x16x32_bf16 v[86:89], v[176:179], v[212:215], v[86:89]
	v_mfma_f32_16x16x32_bf16 v[82:85], v[184:187], v[212:215], v[82:85]
	v_mfma_f32_16x16x32_bf16 v[70:73], v[176:179], v[220:223], v[70:73]
	v_mfma_f32_16x16x32_bf16 v[66:69], v[184:187], v[220:223], v[66:69]
	s_setprio 0
	s_barrier
; #define PG8_STAGE(bufoff, gbase, voff) do { _Pragma("unroll") for (int _i = 0; _i < 2; ++_i) \
;         __builtin_amdgcn_global_load_lds((const unsigned*)((const char*)(gbase) + (voff)[_i]), (LAS unsigned*)(lds + (bufoff) + ldsw + _i * 8192), 16, 0, 0); } while (0)
; #define PG8_LDA(dst, b, h) do { _Pragma("unroll") for (int m = 0; m < 4; ++m) _Pragma("unroll") for (int k = 0; k < 2; ++k) dst[m][k] = *(const LAS bf16x8*)(lds + PG8_SA(b, h) + aoff + m * 2048 + k * 1024); } while (0)
; #define PG8_MMA(ai, bj, At, Bt) do { __builtin_amdgcn_s_setprio(1); _Pragma("unroll") for (int m = 0; m < 4; ++m) _Pragma("unroll") for (int n = 0; n < 2; ++n) _Pragma("unroll") for (int k = 0; k < 2; ++k) \
;         acc[ai][bj][m][n] = __builtin_amdgcn_mfma_f32_16x16x32_bf16(Bt[n][k], At[m][k], acc[ai][bj][m][n], 0, 0, 0); __builtin_amdgcn_s_setprio(0); } while (0)
; #define PG8_WAIT_V(n) asm volatile("s_waitcnt vmcnt(" #n ")" ::: "memory")
; #define PG8_WAIT_L(n) asm volatile("s_waitcnt lgkmcnt(" #n ")" ::: "memory")
; #define PG8_BAR __builtin_amdgcn_s_barrier()
; #define PG8_SCHED __builtin_amdgcn_sched_barrier(0)
; template <class Epi, class Sched, bool ALIGN_EPI>
; DI void gemm_phase(LAS unsigned char* lds, const Gemm g, const Sched& S, const Epi& E) {
;     ...
;             PG8_LDA(At, 1, 1); PG8_STAGE(PG8_SB(1, 0), b3, voffB); PG8_STAGE(PG8_SB(1, 1), b3 + hstepB, voffB); PG8_STAGE(PG8_SA(1, 0), a3, voffA);
;             PG8_WAIT_V(8); PG8_WAIT_L(0); PG8_BAR; PG8_MMA(1, 0, At, B0); PG8_MMA(1, 1, At, B1); PG8_BAR; PG8_SCHED;
;         }
	s_add_i32 s26, s83, s68
	v_lshl_add_u64 v[146:147], v[146:147], 0, s[8:9]
	s_mov_b32 m0, s26
	ds_read_b128 v[188:191], v151 offset:49152
	ds_read_b128 v[192:195], v151 offset:50176
	ds_read_b128 v[196:199], v151 offset:51200
	ds_read_b128 v[204:207], v151 offset:52224
	ds_read_b128 v[208:211], v151 offset:53248
	ds_read_b128 v[212:215], v151 offset:54272
	ds_read_b128 v[216:219], v151 offset:55296
	ds_read_b128 v[220:223], v151 offset:56320
	global_load_lds_dwordx4 v[146:147], off
	s_add_i32 m0, s26, 0x2000
	s_add_u32 s24, s24, 0x40080
	v_lshl_add_u64 v[146:147], v[200:201], 0, s[8:9]
	s_addc_u32 s25, s25, 0
	s_add_i32 s26, s84, s68
	global_load_lds_dwordx4 v[146:147], off
	v_lshl_add_u64 v[146:147], s[24:25], 0, v[134:135]
	s_mov_b32 m0, s26
	s_nop 0
	global_load_lds_dwordx4 v[146:147], off
	v_lshl_add_u64 v[146:147], s[24:25], 0, v[130:131]
	s_add_i32 m0, s26, 0x2000
	s_nop 0
	global_load_lds_dwordx4 v[146:147], off
	v_lshl_add_u64 v[146:147], v[224:225], 0, s[8:9]
	s_mov_b32 m0, s76
	s_nop 0
	global_load_lds_dwordx4 v[146:147], off
	v_lshl_add_u64 v[146:147], v[226:227], 0, s[8:9]
	s_mov_b32 m0, s77
	s_nop 0
	global_load_lds_dwordx4 v[146:147], off
	s_waitcnt vmcnt(8)
	s_waitcnt lgkmcnt(0)
	s_barrier
	s_setprio 1
	s_waitcnt lgkmcnt(0)
	v_mfma_f32_16x16x32_bf16 v[62:65], v[156:159], v[188:191], v[62:65]
	v_mfma_f32_16x16x32_bf16 v[58:61], v[164:167], v[188:191], v[58:61]
	v_mfma_f32_16x16x32_bf16 v[46:49], v[156:159], v[196:199], v[46:49]
	v_mfma_f32_16x16x32_bf16 v[42:45], v[164:167], v[196:199], v[42:45]
	v_mfma_f32_16x16x32_bf16 v[30:33], v[156:159], v[208:211], v[30:33]
	v_mfma_f32_16x16x32_bf16 v[26:29], v[164:167], v[208:211], v[26:29]
	v_mfma_f32_16x16x32_bf16 v[14:17], v[156:159], v[216:219], v[14:17]
	v_mfma_f32_16x16x32_bf16 v[10:13], v[164:167], v[216:219], v[10:13]
	v_mfma_f32_16x16x32_bf16 v[62:65], v[160:163], v[192:195], v[62:65]
	v_mfma_f32_16x16x32_bf16 v[58:61], v[168:171], v[192:195], v[58:61]
	v_mfma_f32_16x16x32_bf16 v[46:49], v[160:163], v[204:207], v[46:49]
	v_mfma_f32_16x16x32_bf16 v[42:45], v[168:171], v[204:207], v[42:45]
	v_mfma_f32_16x16x32_bf16 v[30:33], v[160:163], v[212:215], v[30:33]
	v_mfma_f32_16x16x32_bf16 v[26:29], v[168:171], v[212:215], v[26:29]
	v_mfma_f32_16x16x32_bf16 v[14:17], v[160:163], v[220:223], v[14:17]
	v_mfma_f32_16x16x32_bf16 v[10:13], v[168:171], v[220:223], v[10:13]
	v_mfma_f32_16x16x32_bf16 v[54:57], v[172:175], v[188:191], v[54:57]
	v_mfma_f32_16x16x32_bf16 v[50:53], v[180:183], v[188:191], v[50:53]
	v_mfma_f32_16x16x32_bf16 v[38:41], v[172:175], v[196:199], v[38:41]
	v_mfma_f32_16x16x32_bf16 v[34:37], v[180:183], v[196:199], v[34:37]
	v_mfma_f32_16x16x32_bf16 v[22:25], v[172:175], v[208:211], v[22:25]
	v_mfma_f32_16x16x32_bf16 v[18:21], v[180:183], v[208:211], v[18:21]
	v_mfma_f32_16x16x32_bf16 v[6:9], v[172:175], v[216:219], v[6:9]
	v_mfma_f32_16x16x32_bf16 v[2:5], v[180:183], v[216:219], v[2:5]
	v_mfma_f32_16x16x32_bf16 v[54:57], v[176:179], v[192:195], v[54:57]
	v_mfma_f32_16x16x32_bf16 v[50:53], v[184:187], v[192:195], v[50:53]
	v_mfma_f32_16x16x32_bf16 v[38:41], v[176:179], v[204:207], v[38:41]
	v_mfma_f32_16x16x32_bf16 v[34:37], v[184:187], v[204:207], v[34:37]
	v_mfma_f32_16x16x32_bf16 v[22:25], v[176:179], v[212:215], v[22:25]
	v_mfma_f32_16x16x32_bf16 v[18:21], v[184:187], v[212:215], v[18:21]
	v_mfma_f32_16x16x32_bf16 v[6:9], v[176:179], v[220:223], v[6:9]
	v_mfma_f32_16x16x32_bf16 v[2:5], v[184:187], v[220:223], v[2:5]
	s_setprio 0
	s_barrier
	s_add_i32 s56, s56, 2
	s_add_u32 s22, s22, 0x100
	s_addc_u32 s23, s23, 0
	s_add_u32 s54, s54, 0x100
	s_addc_u32 s55, s55, 0
	s_cmp_gt_u32 s56, 13
	s_cbranch_scc0 .LBB0_98
	s_and_b64 vcc, exec, s[10:11]
	s_cbranch_vccz .LBB0_101
	s_barrier

; #define PG8_STAGE(bufoff, gbase, voff) do { _Pragma("unroll") for (int _i = 0; _i < 2; ++_i) \
;         __builtin_amdgcn_global_load_lds((const unsigned*)((const char*)(gbase) + (voff)[_i]), (LAS unsigned*)(lds + (bufoff) + ldsw + _i * 8192), 16, 0, 0); } while (0)
; #define PG8_LDA(dst, b, h) do { _Pragma("unroll") for (int m = 0; m < 4; ++m) _Pragma("unroll") for (int k = 0; k < 2; ++k) dst[m][k] = *(const LAS bf16x8*)(lds + PG8_SA(b, h) + aoff + m * 2048 + k * 1024); } while (0)
; #define PG8_LDB(dst, b, h) do { _Pragma("unroll") for (int n = 0; n < 2; ++n) _Pragma("unroll") for (int k = 0; k < 2; ++k) dst[n][k] = *(const LAS bf16x8*)(lds + PG8_SB(b, h) + boff + n * 2048 + k * 1024); } while (0)
; #define PG8_MMA(ai, bj, At, Bt) do { __builtin_amdgcn_s_setprio(1); _Pragma("unroll") for (int m = 0; m < 4; ++m) _Pragma("unroll") for (int n = 0; n < 2; ++n) _Pragma("unroll") for (int k = 0; k < 2; ++k) \
;         acc[ai][bj][m][n] = __builtin_amdgcn_mfma_f32_16x16x32_bf16(Bt[n][k], At[m][k], acc[ai][bj][m][n], 0, 0, 0); __builtin_amdgcn_s_setprio(0); } while (0)
; #define PG8_WAIT_V(n) asm volatile("s_waitcnt vmcnt(" #n ")" ::: "memory")
; #define PG8_WAIT_L(n) asm volatile("s_waitcnt lgkmcnt(" #n ")" ::: "memory")
; #define PG8_BAR __builtin_amdgcn_s_barrier()
; #define PG8_SCHED __builtin_amdgcn_sched_barrier(0)
; template <class Epi, class Sched, bool ALIGN_EPI>
; DI void gemm_phase(LAS unsigned char* lds, const Gemm g, const Sched& S, const Epi& E) {
;     ...
;             const char* a1 = cA + (size_t)(t + 1) * kstep;
;             const char* a2 = last ? nA : cA + (size_t)(t + 2) * kstep; const char* b2 = last ? nB : cB + (size_t)(t + 2) * kstep;
;             const char* a3 = a2 + kstep; const char* b3 = b2 + kstep;
;             PG8_LDB(B0, 0, 0); PG8_LDB(B1, 0, 1); PG8_SCHED; PG8_LDA(At, 0, 0); PG8_STAGE(PG8_SA(1, 1), a1 + hstepA, voffA);
;             PG8_WAIT_V(8); PG8_WAIT_L(0); PG8_BAR; PG8_MMA(0, 0, At, B0); PG8_MMA(0, 1, At, B1); PG8_BAR; PG8_SCHED;
;             PG8_LDA(At, 0, 1); PG8_STAGE(PG8_SB(0, 0), b2, voffB); PG8_STAGE(PG8_SB(0, 1), b2 + hstepB, voffB); PG8_STAGE(PG8_SA(0, 0), a2, voffA);
;             PG8_WAIT_V(8); PG8_WAIT_L(0); PG8_BAR; PG8_MMA(1, 0, At, B0); PG8_MMA(1, 1, At, B1); PG8_BAR; PG8_SCHED;
.LBB0_211:
	v_add_u32_e32 v147, s74, v1
	ds_read_b128 v[148:151], v147
	ds_read_b128 v[154:157], v147 offset:1024
	ds_read_b128 v[158:161], v147 offset:2048
	ds_read_b128 v[162:165], v147 offset:3072
	v_add_u32_e32 v147, s75, v1
	s_add_u32 s16, s8, s14
	ds_read_b128 v[166:169], v147
	ds_read_b128 v[170:173], v147 offset:1024
	ds_read_b128 v[174:177], v147 offset:2048
	ds_read_b128 v[178:181], v147 offset:3072
	s_addc_u32 s17, s9, s15
	s_add_u32 s16, s16, 0x100
	s_addc_u32 s17, s17, 0
	s_add_u32 s55, s52, s14
	s_addc_u32 s56, s53, s15
	s_cmpk_eq_i32 s14, 0x1500
	s_cselect_b32 s19, s13, s17
	s_cselect_b32 s18, s12, s16
	s_cselect_b32 s17, s1, s56
	s_cselect_b32 s16, s0, s55
	v_lshl_add_u64 v[216:217], v[142:143], 0, s[14:15]
	s_add_i32 m0, s41, 0xc000
	ds_read_b128 v[182:185], v146
	ds_read_b128 v[186:189], v146 offset:1024
	ds_read_b128 v[190:193], v146 offset:2048
	ds_read_b128 v[194:197], v146 offset:3072
	ds_read_b128 v[198:201], v146 offset:4096
	ds_read_b128 v[204:207], v146 offset:5120
	ds_read_b128 v[208:211], v146 offset:6144
	ds_read_b128 v[212:215], v146 offset:7168
	global_load_lds_dwordx4 v[216:217], off
	v_lshl_add_u64 v[216:217], v[144:145], 0, s[14:15]
	s_add_i32 m0, s41, 0xe000
	s_nop 0
	global_load_lds_dwordx4 v[216:217], off
	s_waitcnt vmcnt(8)
	s_waitcnt lgkmcnt(0)
	s_barrier
	s_setprio 1
	s_waitcnt lgkmcnt(0)
	v_mfma_f32_16x16x32_bf16 v[126:129], v[148:151], v[182:185], v[126:129]
	v_mfma_f32_16x16x32_bf16 v[122:125], v[158:161], v[182:185], v[122:125]
	v_mfma_f32_16x16x32_bf16 v[114:117], v[148:151], v[190:193], v[114:117]
	v_mfma_f32_16x16x32_bf16 v[110:113], v[158:161], v[190:193], v[110:113]
	v_mfma_f32_16x16x32_bf16 v[98:101], v[148:151], v[198:201], v[98:101]
	v_mfma_f32_16x16x32_bf16 v[94:97], v[158:161], v[198:201], v[94:97]
	v_mfma_f32_16x16x32_bf16 v[82:85], v[148:151], v[208:211], v[82:85]
	v_mfma_f32_16x16x32_bf16 v[78:81], v[158:161], v[208:211], v[78:81]
	v_mfma_f32_16x16x32_bf16 v[126:129], v[154:157], v[186:189], v[126:129]
	v_mfma_f32_16x16x32_bf16 v[122:125], v[162:165], v[186:189], v[122:125]
	v_mfma_f32_16x16x32_bf16 v[114:117], v[154:157], v[194:197], v[114:117]
	v_mfma_f32_16x16x32_bf16 v[110:113], v[162:165], v[194:197], v[110:113]
	v_mfma_f32_16x16x32_bf16 v[98:101], v[154:157], v[204:207], v[98:101]
	v_mfma_f32_16x16x32_bf16 v[94:97], v[162:165], v[204:207], v[94:97]
	v_mfma_f32_16x16x32_bf16 v[82:85], v[154:157], v[212:215], v[82:85]
	v_mfma_f32_16x16x32_bf16 v[78:81], v[162:165], v[212:215], v[78:81]
	v_mfma_f32_16x16x32_bf16 v[118:121], v[166:169], v[182:185], v[118:121]
	v_mfma_f32_16x16x32_bf16 v[106:109], v[174:177], v[182:185], v[106:109]
	v_mfma_f32_16x16x32_bf16 v[102:105], v[166:169], v[190:193], v[102:105]
	v_mfma_f32_16x16x32_bf16 v[90:93], v[174:177], v[190:193], v[90:93]
	v_mfma_f32_16x16x32_bf16 v[86:89], v[166:169], v[198:201], v[86:89]
	v_mfma_f32_16x16x32_bf16 v[74:77], v[174:177], v[198:201], v[74:77]
	v_mfma_f32_16x16x32_bf16 v[70:73], v[166:169], v[208:211], v[70:73]
	v_mfma_f32_16x16x32_bf16 v[66:69], v[174:177], v[208:211], v[66:69]
	v_mfma_f32_16x16x32_bf16 v[118:121], v[170:173], v[186:189], v[118:121]
	v_mfma_f32_16x16x32_bf16 v[106:109], v[178:181], v[186:189], v[106:109]
	v_mfma_f32_16x16x32_bf16 v[102:105], v[170:173], v[194:197], v[102:105]
	v_mfma_f32_16x16x32_bf16 v[90:93], v[178:181], v[194:197], v[90:93]
	v_mfma_f32_16x16x32_bf16 v[86:89], v[170:173], v[204:207], v[86:89]
	v_mfma_f32_16x16x32_bf16 v[74:77], v[178:181], v[204:207], v[74:77]
	v_mfma_f32_16x16x32_bf16 v[70:73], v[170:173], v[212:215], v[70:73]
	v_mfma_f32_16x16x32_bf16 v[66:69], v[178:181], v[212:215], v[66:69]
	s_setprio 0
	s_barrier
	s_add_i32 s55, s74, s40
	v_lshl_add_u64 v[216:217], s[16:17], 0, v[130:131]
	s_mov_b32 m0, s55
	ds_read_b128 v[182:185], v146 offset:16384
	ds_read_b128 v[186:189], v146 offset:17408
	ds_read_b128 v[190:193], v146 offset:18432
	ds_read_b128 v[194:197], v146 offset:19456
	ds_read_b128 v[198:201], v146 offset:20480
	ds_read_b128 v[204:207], v146 offset:21504
	ds_read_b128 v[208:211], v146 offset:22528
	ds_read_b128 v[212:215], v146 offset:23552
	global_load_lds_dwordx4 v[216:217], off
	s_add_i32 m0, s55, 0x2000
	s_add_u32 s56, s16, 0xb0000
	v_lshl_add_u64 v[218:219], s[16:17], 0, v[132:133]
	s_addc_u32 s57, s17, 0
	s_add_i32 s55, s75, s40
	global_load_lds_dwordx4 v[218:219], off
	v_lshl_add_u64 v[220:221], s[56:57], 0, v[130:131]
	s_mov_b32 m0, s55
	v_lshl_add_u64 v[222:223], s[18:19], 0, v[132:133]
	global_load_lds_dwordx4 v[220:221], off
	v_lshl_add_u64 v[220:221], s[56:57], 0, v[132:133]
	s_add_i32 m0, s55, 0x2000
	s_nop 0
	global_load_lds_dwordx4 v[220:221], off
	v_lshl_add_u64 v[220:221], s[18:19], 0, v[130:131]
	s_mov_b32 m0, s41
	s_nop 0
	global_load_lds_dwordx4 v[220:221], off
	s_mov_b32 m0, s68
	s_nop 0
	global_load_lds_dwordx4 v[222:223], off
	s_waitcnt vmcnt(8)
	s_waitcnt lgkmcnt(0)
	s_barrier
; #define PG8_STAGE(bufoff, gbase, voff) do { _Pragma("unroll") for (int _i = 0; _i < 2; ++_i) \
;         __builtin_amdgcn_global_load_lds((const unsigned*)((const char*)(gbase) + (voff)[_i]), (LAS unsigned*)(lds + (bufoff) + ldsw + _i * 8192), 16, 0, 0); } while (0)
; #define PG8_LDA(dst, b, h) do { _Pragma("unroll") for (int m = 0; m < 4; ++m) _Pragma("unroll") for (int k = 0; k < 2; ++k) dst[m][k] = *(const LAS bf16x8*)(lds + PG8_SA(b, h) + aoff + m * 2048 + k * 1024); } while (0)
; #define PG8_LDB(dst, b, h) do { _Pragma("unroll") for (int n = 0; n < 2; ++n) _Pragma("unroll") for (int k = 0; k < 2; ++k) dst[n][k] = *(const LAS bf16x8*)(lds + PG8_SB(b, h) + boff + n * 2048 + k * 1024); } while (0)
; #define PG8_MMA(ai, bj, At, Bt) do { __builtin_amdgcn_s_setprio(1); _Pragma("unroll") for (int m = 0; m < 4; ++m) _Pragma("unroll") for (int n = 0; n < 2; ++n) _Pragma("unroll") for (int k = 0; k < 2; ++k) \
;         acc[ai][bj][m][n] = __builtin_amdgcn_mfma_f32_16x16x32_bf16(Bt[n][k], At[m][k], acc[ai][bj][m][n], 0, 0, 0); __builtin_amdgcn_s_setprio(0); } while (0)
; #define PG8_WAIT_V(n) asm volatile("s_waitcnt vmcnt(" #n ")" ::: "memory")
; #define PG8_WAIT_L(n) asm volatile("s_waitcnt lgkmcnt(" #n ")" ::: "memory")
; #define PG8_BAR __builtin_amdgcn_s_barrier()
; #define PG8_SCHED __builtin_amdgcn_sched_barrier(0)
; template <class Epi, class Sched, bool ALIGN_EPI>
; DI void gemm_phase(LAS unsigned char* lds, const Gemm g, const Sched& S, const Epi& E) {
;     ...
;             PG8_WAIT_V(8); PG8_WAIT_L(0); PG8_BAR; PG8_MMA(1, 0, At, B0); PG8_MMA(1, 1, At, B1); PG8_BAR; PG8_SCHED;
;             PG8_LDB(B0, 1, 0); PG8_LDB(B1, 1, 1); PG8_SCHED; PG8_LDA(At, 1, 0); PG8_STAGE(PG8_SA(0, 1), a2 + hstepA, voffA);
;             PG8_WAIT_V(8); PG8_WAIT_L(0); PG8_BAR; PG8_MMA(0, 0, At, B0); PG8_MMA(0, 1, At, B1); PG8_BAR; PG8_SCHED;
;             PG8_LDA(At, 1, 1); PG8_STAGE(PG8_SB(1, 0), b3, voffB); PG8_STAGE(PG8_SB(1, 1), b3 + hstepB, voffB); PG8_STAGE(PG8_SA(1, 0), a3, voffA);
	s_setprio 1
	s_waitcnt lgkmcnt(0)
	v_mfma_f32_16x16x32_bf16 v[62:65], v[148:151], v[182:185], v[62:65]
	v_mfma_f32_16x16x32_bf16 v[58:61], v[158:161], v[182:185], v[58:61]
	v_mfma_f32_16x16x32_bf16 v[46:49], v[148:151], v[190:193], v[46:49]
	v_mfma_f32_16x16x32_bf16 v[42:45], v[158:161], v[190:193], v[42:45]
	v_mfma_f32_16x16x32_bf16 v[30:33], v[148:151], v[198:201], v[30:33]
	v_mfma_f32_16x16x32_bf16 v[26:29], v[158:161], v[198:201], v[26:29]
	v_mfma_f32_16x16x32_bf16 v[14:17], v[148:151], v[208:211], v[14:17]
	v_mfma_f32_16x16x32_bf16 v[10:13], v[158:161], v[208:211], v[10:13]
	v_mfma_f32_16x16x32_bf16 v[62:65], v[154:157], v[186:189], v[62:65]
	v_mfma_f32_16x16x32_bf16 v[58:61], v[162:165], v[186:189], v[58:61]
	v_mfma_f32_16x16x32_bf16 v[46:49], v[154:157], v[194:197], v[46:49]
	v_mfma_f32_16x16x32_bf16 v[42:45], v[162:165], v[194:197], v[42:45]
	v_mfma_f32_16x16x32_bf16 v[30:33], v[154:157], v[204:207], v[30:33]
	v_mfma_f32_16x16x32_bf16 v[26:29], v[162:165], v[204:207], v[26:29]
	v_mfma_f32_16x16x32_bf16 v[14:17], v[154:157], v[212:215], v[14:17]
	v_mfma_f32_16x16x32_bf16 v[10:13], v[162:165], v[212:215], v[10:13]
	v_mfma_f32_16x16x32_bf16 v[54:57], v[166:169], v[182:185], v[54:57]
	v_mfma_f32_16x16x32_bf16 v[50:53], v[174:177], v[182:185], v[50:53]
	v_mfma_f32_16x16x32_bf16 v[38:41], v[166:169], v[190:193], v[38:41]
	v_mfma_f32_16x16x32_bf16 v[34:37], v[174:177], v[190:193], v[34:37]
	v_mfma_f32_16x16x32_bf16 v[22:25], v[166:169], v[198:201], v[22:25]
	v_mfma_f32_16x16x32_bf16 v[18:21], v[174:177], v[198:201], v[18:21]
	v_mfma_f32_16x16x32_bf16 v[6:9], v[166:169], v[208:211], v[6:9]
	v_mfma_f32_16x16x32_bf16 v[2:5], v[174:177], v[208:211], v[2:5]
	v_mfma_f32_16x16x32_bf16 v[54:57], v[170:173], v[186:189], v[54:57]
	v_mfma_f32_16x16x32_bf16 v[50:53], v[178:181], v[186:189], v[50:53]
	v_mfma_f32_16x16x32_bf16 v[38:41], v[170:173], v[194:197], v[38:41]
	v_mfma_f32_16x16x32_bf16 v[34:37], v[178:181], v[194:197], v[34:37]
	v_mfma_f32_16x16x32_bf16 v[22:25], v[170:173], v[204:207], v[22:25]
	v_mfma_f32_16x16x32_bf16 v[18:21], v[178:181], v[204:207], v[18:21]
	v_mfma_f32_16x16x32_bf16 v[6:9], v[170:173], v[212:215], v[6:9]
	v_mfma_f32_16x16x32_bf16 v[2:5], v[178:181], v[212:215], v[2:5]
	s_setprio 0
	s_barrier
	v_add_u32_e32 v147, s76, v1
	ds_read_b128 v[148:151], v147
	ds_read_b128 v[154:157], v147 offset:1024
	ds_read_b128 v[158:161], v147 offset:2048
	ds_read_b128 v[162:165], v147 offset:3072
	v_add_u32_e32 v147, s78, v1
	ds_read_b128 v[166:169], v147
	ds_read_b128 v[170:173], v147 offset:1024
	ds_read_b128 v[174:177], v147 offset:2048
	ds_read_b128 v[178:181], v147 offset:3072
	s_add_u32 s18, s18, 0xb0000
	s_addc_u32 s19, s19, 0
	s_mov_b32 m0, s69
	v_lshl_add_u64 v[224:225], s[18:19], 0, v[130:131]
	ds_read_b128 v[182:185], v146 offset:32768
	ds_read_b128 v[186:189], v146 offset:33792
	ds_read_b128 v[190:193], v146 offset:34816
	ds_read_b128 v[194:197], v146 offset:35840
	ds_read_b128 v[198:201], v146 offset:36864
	ds_read_b128 v[204:207], v146 offset:37888
	ds_read_b128 v[208:211], v146 offset:38912
	ds_read_b128 v[212:215], v146 offset:39936
	global_load_lds_dwordx4 v[224:225], off
	v_lshl_add_u64 v[224:225], s[18:19], 0, v[132:133]
	s_mov_b32 m0, s71
	s_nop 0
	global_load_lds_dwordx4 v[224:225], off
	s_waitcnt vmcnt(8)
	s_waitcnt lgkmcnt(0)
	s_barrier
	s_setprio 1
	s_waitcnt lgkmcnt(0)
	v_mfma_f32_16x16x32_bf16 v[126:129], v[148:151], v[182:185], v[126:129]
	v_mfma_f32_16x16x32_bf16 v[122:125], v[158:161], v[182:185], v[122:125]
	v_mfma_f32_16x16x32_bf16 v[114:117], v[148:151], v[190:193], v[114:117]
	v_mfma_f32_16x16x32_bf16 v[110:113], v[158:161], v[190:193], v[110:113]
	v_mfma_f32_16x16x32_bf16 v[98:101], v[148:151], v[198:201], v[98:101]
	v_mfma_f32_16x16x32_bf16 v[94:97], v[158:161], v[198:201], v[94:97]
	v_mfma_f32_16x16x32_bf16 v[82:85], v[148:151], v[208:211], v[82:85]
	v_mfma_f32_16x16x32_bf16 v[78:81], v[158:161], v[208:211], v[78:81]
	v_mfma_f32_16x16x32_bf16 v[126:129], v[154:157], v[186:189], v[126:129]
	v_mfma_f32_16x16x32_bf16 v[122:125], v[162:165], v[186:189], v[122:125]
	v_mfma_f32_16x16x32_bf16 v[114:117], v[154:157], v[194:197], v[114:117]
	v_mfma_f32_16x16x32_bf16 v[110:113], v[162:165], v[194:197], v[110:113]
	v_mfma_f32_16x16x32_bf16 v[98:101], v[154:157], v[204:207], v[98:101]
	v_mfma_f32_16x16x32_bf16 v[94:97], v[162:165], v[204:207], v[94:97]
	v_mfma_f32_16x16x32_bf16 v[82:85], v[154:157], v[212:215], v[82:85]
	v_mfma_f32_16x16x32_bf16 v[78:81], v[162:165], v[212:215], v[78:81]
	v_mfma_f32_16x16x32_bf16 v[118:121], v[166:169], v[182:185], v[118:121]
	v_mfma_f32_16x16x32_bf16 v[106:109], v[174:177], v[182:185], v[106:109]
	v_mfma_f32_16x16x32_bf16 v[102:105], v[166:169], v[190:193], v[102:105]
	v_mfma_f32_16x16x32_bf16 v[90:93], v[174:177], v[190:193], v[90:93]
	v_mfma_f32_16x16x32_bf16 v[86:89], v[166:169], v[198:201], v[86:89]
	v_mfma_f32_16x16x32_bf16 v[74:77], v[174:177], v[198:201], v[74:77]
	v_mfma_f32_16x16x32_bf16 v[70:73], v[166:169], v[208:211], v[70:73]
	v_mfma_f32_16x16x32_bf16 v[66:69], v[174:177], v[208:211], v[66:69]
	v_mfma_f32_16x16x32_bf16 v[118:121], v[170:173], v[186:189], v[118:121]
	v_mfma_f32_16x16x32_bf16 v[106:109], v[178:181], v[186:189], v[106:109]
	v_mfma_f32_16x16x32_bf16 v[102:105], v[170:173], v[194:197], v[102:105]
	v_mfma_f32_16x16x32_bf16 v[90:93], v[178:181], v[194:197], v[90:93]
	v_mfma_f32_16x16x32_bf16 v[86:89], v[170:173], v[204:207], v[86:89]
	v_mfma_f32_16x16x32_bf16 v[74:77], v[178:181], v[204:207], v[74:77]
	v_mfma_f32_16x16x32_bf16 v[70:73], v[170:173], v[212:215], v[70:73]
	v_mfma_f32_16x16x32_bf16 v[66:69], v[178:181], v[212:215], v[66:69]
	s_setprio 0
	s_barrier
; #define PG8_STAGE(bufoff, gbase, voff) do { _Pragma("unroll") for (int _i = 0; _i < 2; ++_i) \
;         __builtin_amdgcn_global_load_lds((const unsigned*)((const char*)(gbase) + (voff)[_i]), (LAS unsigned*)(lds + (bufoff) + ldsw + _i * 8192), 16, 0, 0); } while (0)
; #define PG8_LDA(dst, b, h) do { _Pragma("unroll") for (int m = 0; m < 4; ++m) _Pragma("unroll") for (int k = 0; k < 2; ++k) dst[m][k] = *(const LAS bf16x8*)(lds + PG8_SA(b, h) + aoff + m * 2048 + k * 1024); } while (0)
; #define PG8_MMA(ai, bj, At, Bt) do { __builtin_amdgcn_s_setprio(1); _Pragma("unroll") for (int m = 0; m < 4; ++m) _Pragma("unroll") for (int n = 0; n < 2; ++n) _Pragma("unroll") for (int k = 0; k < 2; ++k) \
;         acc[ai][bj][m][n] = __builtin_amdgcn_mfma_f32_16x16x32_bf16(Bt[n][k], At[m][k], acc[ai][bj][m][n], 0, 0, 0); __builtin_amdgcn_s_setprio(0); } while (0)
; #define PG8_WAIT_V(n) asm volatile("s_waitcnt vmcnt(" #n ")" ::: "memory")
; #define PG8_WAIT_L(n) asm volatile("s_waitcnt lgkmcnt(" #n ")" ::: "memory")
; #define PG8_BAR __builtin_amdgcn_s_barrier()
; #define PG8_SCHED __builtin_amdgcn_sched_barrier(0)
; template <class Epi, class Sched, bool ALIGN_EPI>
; DI void gemm_phase(LAS unsigned char* lds, const Gemm g, const Sched& S, const Epi& E) {
;     ...
;             PG8_LDA(At, 1, 1); PG8_STAGE(PG8_SB(1, 0), b3, voffB); PG8_STAGE(PG8_SB(1, 1), b3 + hstepB, voffB); PG8_STAGE(PG8_SA(1, 0), a3, voffA);
;             PG8_WAIT_V(8); PG8_WAIT_L(0); PG8_BAR; PG8_MMA(1, 0, At, B0); PG8_MMA(1, 1, At, B1); PG8_BAR; PG8_SCHED;
;         }
;         if constexpr (ALIGN_EPI) { if (wr == 0) PG8_BAR; }
;         if constexpr (!Epi::AFTER_DRAIN) E(acc, cur, wr, wc, fr, fq);
;         if (!has_next) break;
; #pragma unroll
;         for (int a = 0; a < 2; ++a)
; #pragma unroll
;             for (int b = 0; b < 2; ++b)
; #pragma unroll
;                 for (int m = 0; m < 4; ++m)
; #pragma unroll
;                     for (int n = 0; n < 2; ++n) acc[a][b][m][n] = (f32x4){0.f, 0.f, 0.f, 0.f};
	s_add_i32 s18, s76, s40
	v_lshl_add_u64 v[216:217], v[216:217], 0, s[10:11]
	s_mov_b32 m0, s18
	ds_read_b128 v[182:185], v146 offset:49152
	ds_read_b128 v[186:189], v146 offset:50176
	ds_read_b128 v[190:193], v146 offset:51200
	ds_read_b128 v[194:197], v146 offset:52224
	ds_read_b128 v[198:201], v146 offset:53248
	ds_read_b128 v[204:207], v146 offset:54272
	ds_read_b128 v[208:211], v146 offset:55296
	ds_read_b128 v[212:215], v146 offset:56320
	global_load_lds_dwordx4 v[216:217], off
	s_add_i32 m0, s18, 0x2000
	s_add_u32 s16, s16, 0xb0080
	v_lshl_add_u64 v[216:217], v[218:219], 0, s[10:11]
	s_addc_u32 s17, s17, 0
	s_add_i32 s18, s78, s40
	global_load_lds_dwordx4 v[216:217], off
	v_lshl_add_u64 v[216:217], s[16:17], 0, v[130:131]
	s_mov_b32 m0, s18
	s_nop 0
	global_load_lds_dwordx4 v[216:217], off
	v_lshl_add_u64 v[216:217], s[16:17], 0, v[132:133]
	s_add_i32 m0, s18, 0x2000
	s_nop 0
	global_load_lds_dwordx4 v[216:217], off
	v_lshl_add_u64 v[216:217], v[220:221], 0, s[10:11]
	s_mov_b32 m0, s72
	s_nop 0
	global_load_lds_dwordx4 v[216:217], off
	v_lshl_add_u64 v[216:217], v[222:223], 0, s[10:11]
	s_mov_b32 m0, s73
	s_nop 0
	global_load_lds_dwordx4 v[216:217], off
	s_waitcnt vmcnt(8)
	s_waitcnt lgkmcnt(0)
	s_barrier
	s_setprio 1
	s_waitcnt lgkmcnt(0)
	v_mfma_f32_16x16x32_bf16 v[62:65], v[148:151], v[182:185], v[62:65]
	v_mfma_f32_16x16x32_bf16 v[58:61], v[158:161], v[182:185], v[58:61]
	v_mfma_f32_16x16x32_bf16 v[46:49], v[148:151], v[190:193], v[46:49]
	v_mfma_f32_16x16x32_bf16 v[42:45], v[158:161], v[190:193], v[42:45]
	v_mfma_f32_16x16x32_bf16 v[30:33], v[148:151], v[198:201], v[30:33]
	v_mfma_f32_16x16x32_bf16 v[26:29], v[158:161], v[198:201], v[26:29]
	v_mfma_f32_16x16x32_bf16 v[14:17], v[148:151], v[208:211], v[14:17]
	v_mfma_f32_16x16x32_bf16 v[10:13], v[158:161], v[208:211], v[10:13]
	v_mfma_f32_16x16x32_bf16 v[62:65], v[154:157], v[186:189], v[62:65]
	v_mfma_f32_16x16x32_bf16 v[58:61], v[162:165], v[186:189], v[58:61]
	v_mfma_f32_16x16x32_bf16 v[46:49], v[154:157], v[194:197], v[46:49]
	v_mfma_f32_16x16x32_bf16 v[42:45], v[162:165], v[194:197], v[42:45]
	v_mfma_f32_16x16x32_bf16 v[30:33], v[154:157], v[204:207], v[30:33]
	v_mfma_f32_16x16x32_bf16 v[26:29], v[162:165], v[204:207], v[26:29]
	v_mfma_f32_16x16x32_bf16 v[14:17], v[154:157], v[212:215], v[14:17]
	v_mfma_f32_16x16x32_bf16 v[10:13], v[162:165], v[212:215], v[10:13]
	v_mfma_f32_16x16x32_bf16 v[54:57], v[166:169], v[182:185], v[54:57]
	v_mfma_f32_16x16x32_bf16 v[50:53], v[174:177], v[182:185], v[50:53]
	v_mfma_f32_16x16x32_bf16 v[38:41], v[166:169], v[190:193], v[38:41]
	v_mfma_f32_16x16x32_bf16 v[34:37], v[174:177], v[190:193], v[34:37]
	v_mfma_f32_16x16x32_bf16 v[22:25], v[166:169], v[198:201], v[22:25]
	v_mfma_f32_16x16x32_bf16 v[18:21], v[174:177], v[198:201], v[18:21]
	v_mfma_f32_16x16x32_bf16 v[6:9], v[166:169], v[208:211], v[6:9]
	v_mfma_f32_16x16x32_bf16 v[2:5], v[174:177], v[208:211], v[2:5]
	v_mfma_f32_16x16x32_bf16 v[54:57], v[170:173], v[186:189], v[54:57]
	v_mfma_f32_16x16x32_bf16 v[50:53], v[178:181], v[186:189], v[50:53]
	v_mfma_f32_16x16x32_bf16 v[38:41], v[170:173], v[194:197], v[38:41]
	v_mfma_f32_16x16x32_bf16 v[34:37], v[178:181], v[194:197], v[34:37]
	v_mfma_f32_16x16x32_bf16 v[22:25], v[170:173], v[204:207], v[22:25]
	v_mfma_f32_16x16x32_bf16 v[18:21], v[178:181], v[204:207], v[18:21]
	v_mfma_f32_16x16x32_bf16 v[6:9], v[170:173], v[212:215], v[6:9]
	v_mfma_f32_16x16x32_bf16 v[2:5], v[178:181], v[212:215], v[2:5]
	s_setprio 0
	s_barrier
	s_add_i32 s54, s54, 2
	s_add_u32 s14, s14, 0x100
	s_addc_u32 s15, s15, 0
	s_cmp_gt_u32 s54, 41
	s_cbranch_scc0 .LBB0_211
	s_add_u32 s14, s52, 0xffffff00
	s_addc_u32 s15, s53, -1
	s_and_b64 vcc, exec, s[6:7]
	s_cbranch_vccnz .LBB0_214
	v_mov_b32_e32 v2, 0
	s_mov_b32 s2, s79
	s_mov_b32 s22, s80
	s_mov_b64 s[8:9], s[12:13]
	s_mov_b32 s77, s33
	v_mov_b32_e32 v3, v2
	v_mov_b32_e32 v4, v2
	v_mov_b32_e32 v5, v2
	v_mov_b32_e32 v6, v2
	v_mov_b32_e32 v7, v2
	v_mov_b32_e32 v8, v2
	v_mov_b32_e32 v9, v2
	v_mov_b32_e32 v18, v2
	v_mov_b32_e32 v19, v2
	v_mov_b32_e32 v20, v2
	v_mov_b32_e32 v21, v2
	v_mov_b32_e32 v22, v2
	v_mov_b32_e32 v23, v2
	v_mov_b32_e32 v24, v2
	v_mov_b32_e32 v25, v2
	v_mov_b32_e32 v34, v2
	v_mov_b32_e32 v35, v2
	v_mov_b32_e32 v36, v2
	v_mov_b32_e32 v37, v2
	v_mov_b32_e32 v38, v2
	v_mov_b32_e32 v39, v2
	v_mov_b32_e32 v40, v2
	v_mov_b32_e32 v41, v2
	v_mov_b32_e32 v50, v2
	v_mov_b32_e32 v51, v2
	v_mov_b32_e32 v52, v2
	v_mov_b32_e32 v53, v2
	v_mov_b32_e32 v54, v2
	v_mov_b32_e32 v55, v2
	v_mov_b32_e32 v56, v2
	v_mov_b32_e32 v57, v2
	v_mov_b32_e32 v10, v2
	v_mov_b32_e32 v11, v2
	v_mov_b32_e32 v12, v2
	v_mov_b32_e32 v13, v2
	v_mov_b32_e32 v14, v2
	v_mov_b32_e32 v15, v2
	v_mov_b32_e32 v16, v2
	v_mov_b32_e32 v17, v2
	v_mov_b32_e32 v26, v2
	v_mov_b32_e32 v27, v2
	v_mov_b32_e32 v28, v2
	v_mov_b32_e32 v29, v2
	v_mov_b32_e32 v30, v2
	v_mov_b32_e32 v31, v2
	v_mov_b32_e32 v32, v2
	v_mov_b32_e32 v33, v2
	v_mov_b32_e32 v42, v2
	v_mov_b32_e32 v43, v2
	v_mov_b32_e32 v44, v2
	v_mov_b32_e32 v45, v2
	v_mov_b32_e32 v46, v2
	v_mov_b32_e32 v47, v2
	v_mov_b32_e32 v48, v2
	v_mov_b32_e32 v49, v2
	v_mov_b32_e32 v58, v2
	v_mov_b32_e32 v59, v2
	v_mov_b32_e32 v60, v2
	v_mov_b32_e32 v61, v2
	v_mov_b32_e32 v62, v2
	v_mov_b32_e32 v63, v2
	v_mov_b32_e32 v64, v2
	v_mov_b32_e32 v65, v2
	v_mov_b32_e32 v66, v2
	v_mov_b32_e32 v67, v2
	v_mov_b32_e32 v68, v2
	v_mov_b32_e32 v69, v2
	v_mov_b32_e32 v70, v2
	v_mov_b32_e32 v71, v2
	v_mov_b32_e32 v72, v2
	v_mov_b32_e32 v73, v2
	v_mov_b32_e32 v74, v2
	v_mov_b32_e32 v75, v2
	v_mov_b32_e32 v76, v2
	v_mov_b32_e32 v77, v2
	v_mov_b32_e32 v86, v2
	v_mov_b32_e32 v87, v2
	v_mov_b32_e32 v88, v2
	v_mov_b32_e32 v89, v2
	v_mov_b32_e32 v90, v2
	v_mov_b32_e32 v91, v2
	v_mov_b32_e32 v92, v2
	v_mov_b32_e32 v93, v2
	v_mov_b32_e32 v102, v2
	v_mov_b32_e32 v103, v2
	v_mov_b32_e32 v104, v2
	v_mov_b32_e32 v105, v2
	v_mov_b32_e32 v106, v2
	v_mov_b32_e32 v107, v2
	v_mov_b32_e32 v108, v2
	v_mov_b32_e32 v109, v2
	v_mov_b32_e32 v118, v2
	v_mov_b32_e32 v119, v2
	v_mov_b32_e32 v120, v2
	v_mov_b32_e32 v121, v2
	v_mov_b32_e32 v78, v2
	v_mov_b32_e32 v79, v2
	v_mov_b32_e32 v80, v2
	v_mov_b32_e32 v81, v2
	v_mov_b32_e32 v82, v2
	v_mov_b32_e32 v83, v2
	v_mov_b32_e32 v84, v2
	v_mov_b32_e32 v85, v2
	v_mov_b32_e32 v94, v2
	v_mov_b32_e32 v95, v2
	v_mov_b32_e32 v96, v2
	v_mov_b32_e32 v97, v2
	v_mov_b32_e32 v98, v2
	v_mov_b32_e32 v99, v2
	v_mov_b32_e32 v100, v2
	v_mov_b32_e32 v101, v2
	v_mov_b32_e32 v110, v2
	v_mov_b32_e32 v111, v2
	v_mov_b32_e32 v112, v2
	v_mov_b32_e32 v113, v2
	v_mov_b32_e32 v114, v2
	v_mov_b32_e32 v115, v2
	v_mov_b32_e32 v116, v2
	v_mov_b32_e32 v117, v2
	v_mov_b32_e32 v122, v2
	v_mov_b32_e32 v123, v2
	v_mov_b32_e32 v124, v2
	v_mov_b32_e32 v125, v2
	v_mov_b32_e32 v126, v2
	v_mov_b32_e32 v127, v2
	v_mov_b32_e32 v128, v2
	v_mov_b32_e32 v129, v2
	s_andn2_b64 vcc, exec, s[4:5]
	s_cbranch_vccnz .LBB0_215
	s_branch .LBB0_216

; #define PG8_STAGE(bufoff, gbase, voff) do { _Pragma("unroll") for (int _i = 0; _i < 2; ++_i) \
;         __builtin_amdgcn_global_load_lds((const unsigned*)((const char*)(gbase) + (voff)[_i]), (LAS unsigned*)(lds + (bufoff) + ldsw + _i * 8192), 16, 0, 0); } while (0)
; #define PG8_LDA(dst, b, h) do { _Pragma("unroll") for (int m = 0; m < 4; ++m) _Pragma("unroll") for (int k = 0; k < 2; ++k) dst[m][k] = *(const LAS bf16x8*)(lds + PG8_SA(b, h) + aoff + m * 2048 + k * 1024); } while (0)
; #define PG8_LDB(dst, b, h) do { _Pragma("unroll") for (int n = 0; n < 2; ++n) _Pragma("unroll") for (int k = 0; k < 2; ++k) dst[n][k] = *(const LAS bf16x8*)(lds + PG8_SB(b, h) + boff + n * 2048 + k * 1024); } while (0)
; #define PG8_MMA(ai, bj, At, Bt) do { __builtin_amdgcn_s_setprio(1); _Pragma("unroll") for (int m = 0; m < 4; ++m) _Pragma("unroll") for (int n = 0; n < 2; ++n) _Pragma("unroll") for (int k = 0; k < 2; ++k) \
;         acc[ai][bj][m][n] = __builtin_amdgcn_mfma_f32_16x16x32_bf16(Bt[n][k], At[m][k], acc[ai][bj][m][n], 0, 0, 0); __builtin_amdgcn_s_setprio(0); } while (0)
; #define PG8_WAIT_V(n) asm volatile("s_waitcnt vmcnt(" #n ")" ::: "memory")
; #define PG8_WAIT_L(n) asm volatile("s_waitcnt lgkmcnt(" #n ")" ::: "memory")
; #define PG8_BAR __builtin_amdgcn_s_barrier()
; #define PG8_SCHED __builtin_amdgcn_sched_barrier(0)
; template <class Epi, class Sched, bool ALIGN_EPI>
; DI void gemm_phase(LAS unsigned char* lds, const Gemm g, const Sched& S, const Epi& E) {
;     ...
;             const char* a1 = cA + (size_t)(t + 1) * kstep;
;             const char* a2 = last ? nA : cA + (size_t)(t + 2) * kstep; const char* b2 = last ? nB : cB + (size_t)(t + 2) * kstep;
;             const char* a3 = a2 + kstep; const char* b3 = b2 + kstep;
;             PG8_LDB(B0, 0, 0); PG8_LDB(B1, 0, 1); PG8_SCHED; PG8_LDA(At, 0, 0); PG8_STAGE(PG8_SA(1, 1), a1 + hstepA, voffA);
;             PG8_WAIT_V(8); PG8_WAIT_L(0); PG8_BAR; PG8_MMA(0, 0, At, B0); PG8_MMA(0, 1, At, B1); PG8_BAR; PG8_SCHED;
;             PG8_LDA(At, 0, 1); PG8_STAGE(PG8_SB(0, 0), b2, voffB); PG8_STAGE(PG8_SB(0, 1), b2 + hstepB, voffB); PG8_STAGE(PG8_SA(0, 0), a2, voffA);
;             PG8_WAIT_V(8); PG8_WAIT_L(0); PG8_BAR; PG8_MMA(1, 0, At, B0); PG8_MMA(1, 1, At, B1); PG8_BAR; PG8_SCHED;
.LBB0_316:
	ds_read_b128 v[154:157], v147
	ds_read_b128 v[158:161], v147 offset:1024
	ds_read_b128 v[162:165], v147 offset:2048
	ds_read_b128 v[166:169], v147 offset:3072
	ds_read_b128 v[170:173], v148
	ds_read_b128 v[174:177], v148 offset:1024
	ds_read_b128 v[178:181], v148 offset:2048
	ds_read_b128 v[182:185], v148 offset:3072
	s_add_u32 s24, s22, 0xfffc0080
	s_addc_u32 s25, s23, -1
	s_cmp_eq_u32 s56, 12
	s_cselect_b32 s27, s17, s25
	s_cselect_b32 s26, s52, s24
	s_cselect_b32 s25, s15, s55
	s_cselect_b32 s24, s53, s54
	v_lshl_add_u64 v[220:221], s[22:23], 0, v[138:139]
	s_add_i32 m0, s13, 0xc000
	ds_read_b128 v[186:189], v149
	ds_read_b128 v[190:193], v149 offset:1024
	ds_read_b128 v[194:197], v149 offset:2048
	ds_read_b128 v[198:201], v149 offset:3072
	ds_read_b128 v[204:207], v149 offset:4096
	ds_read_b128 v[208:211], v149 offset:5120
	ds_read_b128 v[212:215], v149 offset:6144
	ds_read_b128 v[216:219], v149 offset:7168
	global_load_lds_dwordx4 v[220:221], off
	v_lshl_add_u64 v[220:221], s[22:23], 0, v[140:141]
	s_add_i32 m0, s13, 0xe000
	s_nop 0
	global_load_lds_dwordx4 v[220:221], off
	s_waitcnt vmcnt(8)
	s_waitcnt lgkmcnt(0)
	s_barrier
	s_setprio 1
	s_waitcnt lgkmcnt(0)
	v_mfma_f32_16x16x32_bf16 v[126:129], v[154:157], v[186:189], v[126:129]
	v_mfma_f32_16x16x32_bf16 v[122:125], v[162:165], v[186:189], v[122:125]
	v_mfma_f32_16x16x32_bf16 v[118:121], v[154:157], v[194:197], v[118:121]
	v_mfma_f32_16x16x32_bf16 v[114:117], v[162:165], v[194:197], v[114:117]
	v_mfma_f32_16x16x32_bf16 v[102:105], v[154:157], v[204:207], v[102:105]
	v_mfma_f32_16x16x32_bf16 v[98:101], v[162:165], v[204:207], v[98:101]
	v_mfma_f32_16x16x32_bf16 v[86:89], v[154:157], v[212:215], v[86:89]
	v_mfma_f32_16x16x32_bf16 v[82:85], v[162:165], v[212:215], v[82:85]
	v_mfma_f32_16x16x32_bf16 v[126:129], v[158:161], v[190:193], v[126:129]
	v_mfma_f32_16x16x32_bf16 v[122:125], v[166:169], v[190:193], v[122:125]
	v_mfma_f32_16x16x32_bf16 v[118:121], v[158:161], v[198:201], v[118:121]
	v_mfma_f32_16x16x32_bf16 v[114:117], v[166:169], v[198:201], v[114:117]
	v_mfma_f32_16x16x32_bf16 v[102:105], v[158:161], v[208:211], v[102:105]
	v_mfma_f32_16x16x32_bf16 v[98:101], v[166:169], v[208:211], v[98:101]
	v_mfma_f32_16x16x32_bf16 v[86:89], v[158:161], v[216:219], v[86:89]
	v_mfma_f32_16x16x32_bf16 v[82:85], v[166:169], v[216:219], v[82:85]
	v_mfma_f32_16x16x32_bf16 v[110:113], v[170:173], v[186:189], v[110:113]
	v_mfma_f32_16x16x32_bf16 v[106:109], v[178:181], v[186:189], v[106:109]
	v_mfma_f32_16x16x32_bf16 v[94:97], v[170:173], v[194:197], v[94:97]
	v_mfma_f32_16x16x32_bf16 v[90:93], v[178:181], v[194:197], v[90:93]
	v_mfma_f32_16x16x32_bf16 v[78:81], v[170:173], v[204:207], v[78:81]
	v_mfma_f32_16x16x32_bf16 v[74:77], v[178:181], v[204:207], v[74:77]
	v_mfma_f32_16x16x32_bf16 v[70:73], v[170:173], v[212:215], v[70:73]
	v_mfma_f32_16x16x32_bf16 v[66:69], v[178:181], v[212:215], v[66:69]
	v_mfma_f32_16x16x32_bf16 v[110:113], v[174:177], v[190:193], v[110:113]
	v_mfma_f32_16x16x32_bf16 v[106:109], v[182:185], v[190:193], v[106:109]
	v_mfma_f32_16x16x32_bf16 v[94:97], v[174:177], v[198:201], v[94:97]
	v_mfma_f32_16x16x32_bf16 v[90:93], v[182:185], v[198:201], v[90:93]
	v_mfma_f32_16x16x32_bf16 v[78:81], v[174:177], v[208:211], v[78:81]
	v_mfma_f32_16x16x32_bf16 v[74:77], v[182:185], v[208:211], v[74:77]
	v_mfma_f32_16x16x32_bf16 v[70:73], v[174:177], v[216:219], v[70:73]
	v_mfma_f32_16x16x32_bf16 v[66:69], v[182:185], v[216:219], v[66:69]
	s_setprio 0
	s_barrier
	s_add_i32 s57, s78, s40
	v_lshl_add_u64 v[220:221], s[24:25], 0, v[134:135]
	s_mov_b32 m0, s57
	ds_read_b128 v[186:189], v149 offset:16384
	ds_read_b128 v[190:193], v149 offset:17408
	ds_read_b128 v[194:197], v149 offset:18432
	ds_read_b128 v[198:201], v149 offset:19456
	ds_read_b128 v[204:207], v149 offset:20480
	ds_read_b128 v[208:211], v149 offset:21504
	ds_read_b128 v[212:215], v149 offset:22528
	ds_read_b128 v[216:219], v149 offset:23552
	global_load_lds_dwordx4 v[220:221], off
	s_add_i32 m0, s57, 0x2000
	s_add_u32 s58, s24, 0x40000
	v_lshl_add_u64 v[222:223], s[24:25], 0, v[130:131]
	s_addc_u32 s59, s25, 0
	s_add_i32 s57, s79, s40
	global_load_lds_dwordx4 v[222:223], off
	v_lshl_add_u64 v[224:225], s[58:59], 0, v[134:135]
	s_mov_b32 m0, s57
	v_lshl_add_u64 v[226:227], s[26:27], 0, v[132:133]
	global_load_lds_dwordx4 v[224:225], off
	v_lshl_add_u64 v[224:225], s[58:59], 0, v[130:131]
	s_add_i32 m0, s57, 0x2000
	s_nop 0
	global_load_lds_dwordx4 v[224:225], off
	v_lshl_add_u64 v[224:225], s[26:27], 0, v[136:137]
	s_mov_b32 m0, s13
	s_nop 0
	global_load_lds_dwordx4 v[224:225], off
	s_mov_b32 m0, s69
	s_nop 0
	global_load_lds_dwordx4 v[226:227], off
	s_waitcnt vmcnt(8)
	s_waitcnt lgkmcnt(0)
	s_barrier
; #define PG8_STAGE(bufoff, gbase, voff) do { _Pragma("unroll") for (int _i = 0; _i < 2; ++_i) \
;         __builtin_amdgcn_global_load_lds((const unsigned*)((const char*)(gbase) + (voff)[_i]), (LAS unsigned*)(lds + (bufoff) + ldsw + _i * 8192), 16, 0, 0); } while (0)
; #define PG8_LDA(dst, b, h) do { _Pragma("unroll") for (int m = 0; m < 4; ++m) _Pragma("unroll") for (int k = 0; k < 2; ++k) dst[m][k] = *(const LAS bf16x8*)(lds + PG8_SA(b, h) + aoff + m * 2048 + k * 1024); } while (0)
; #define PG8_LDB(dst, b, h) do { _Pragma("unroll") for (int n = 0; n < 2; ++n) _Pragma("unroll") for (int k = 0; k < 2; ++k) dst[n][k] = *(const LAS bf16x8*)(lds + PG8_SB(b, h) + boff + n * 2048 + k * 1024); } while (0)
; #define PG8_MMA(ai, bj, At, Bt) do { __builtin_amdgcn_s_setprio(1); _Pragma("unroll") for (int m = 0; m < 4; ++m) _Pragma("unroll") for (int n = 0; n < 2; ++n) _Pragma("unroll") for (int k = 0; k < 2; ++k) \
;         acc[ai][bj][m][n] = __builtin_amdgcn_mfma_f32_16x16x32_bf16(Bt[n][k], At[m][k], acc[ai][bj][m][n], 0, 0, 0); __builtin_amdgcn_s_setprio(0); } while (0)
; #define PG8_WAIT_V(n) asm volatile("s_waitcnt vmcnt(" #n ")" ::: "memory")
; #define PG8_WAIT_L(n) asm volatile("s_waitcnt lgkmcnt(" #n ")" ::: "memory")
; #define PG8_BAR __builtin_amdgcn_s_barrier()
; #define PG8_SCHED __builtin_amdgcn_sched_barrier(0)
; template <class Epi, class Sched, bool ALIGN_EPI>
; DI void gemm_phase(LAS unsigned char* lds, const Gemm g, const Sched& S, const Epi& E) {
;     ...
;             PG8_WAIT_V(8); PG8_WAIT_L(0); PG8_BAR; PG8_MMA(1, 0, At, B0); PG8_MMA(1, 1, At, B1); PG8_BAR; PG8_SCHED;
;             PG8_LDB(B0, 1, 0); PG8_LDB(B1, 1, 1); PG8_SCHED; PG8_LDA(At, 1, 0); PG8_STAGE(PG8_SA(0, 1), a2 + hstepA, voffA);
;             PG8_WAIT_V(8); PG8_WAIT_L(0); PG8_BAR; PG8_MMA(0, 0, At, B0); PG8_MMA(0, 1, At, B1); PG8_BAR; PG8_SCHED;
;             PG8_LDA(At, 1, 1); PG8_STAGE(PG8_SB(1, 0), b3, voffB); PG8_STAGE(PG8_SB(1, 1), b3 + hstepB, voffB); PG8_STAGE(PG8_SA(1, 0), a3, voffA);
	s_setprio 1
	s_waitcnt lgkmcnt(0)
	v_mfma_f32_16x16x32_bf16 v[62:65], v[154:157], v[186:189], v[62:65]
	v_mfma_f32_16x16x32_bf16 v[58:61], v[162:165], v[186:189], v[58:61]
	v_mfma_f32_16x16x32_bf16 v[54:57], v[154:157], v[194:197], v[54:57]
	v_mfma_f32_16x16x32_bf16 v[50:53], v[162:165], v[194:197], v[50:53]
	v_mfma_f32_16x16x32_bf16 v[38:41], v[154:157], v[204:207], v[38:41]
	v_mfma_f32_16x16x32_bf16 v[34:37], v[162:165], v[204:207], v[34:37]
	v_mfma_f32_16x16x32_bf16 v[22:25], v[154:157], v[212:215], v[22:25]
	v_mfma_f32_16x16x32_bf16 v[18:21], v[162:165], v[212:215], v[18:21]
	v_mfma_f32_16x16x32_bf16 v[62:65], v[158:161], v[190:193], v[62:65]
	v_mfma_f32_16x16x32_bf16 v[58:61], v[166:169], v[190:193], v[58:61]
	v_mfma_f32_16x16x32_bf16 v[54:57], v[158:161], v[198:201], v[54:57]
	v_mfma_f32_16x16x32_bf16 v[50:53], v[166:169], v[198:201], v[50:53]
	v_mfma_f32_16x16x32_bf16 v[38:41], v[158:161], v[208:211], v[38:41]
	v_mfma_f32_16x16x32_bf16 v[34:37], v[166:169], v[208:211], v[34:37]
	v_mfma_f32_16x16x32_bf16 v[22:25], v[158:161], v[216:219], v[22:25]
	v_mfma_f32_16x16x32_bf16 v[18:21], v[166:169], v[216:219], v[18:21]
	v_mfma_f32_16x16x32_bf16 v[46:49], v[170:173], v[186:189], v[46:49]
	v_mfma_f32_16x16x32_bf16 v[42:45], v[178:181], v[186:189], v[42:45]
	v_mfma_f32_16x16x32_bf16 v[30:33], v[170:173], v[194:197], v[30:33]
	v_mfma_f32_16x16x32_bf16 v[26:29], v[178:181], v[194:197], v[26:29]
	v_mfma_f32_16x16x32_bf16 v[14:17], v[170:173], v[204:207], v[14:17]
	v_mfma_f32_16x16x32_bf16 v[10:13], v[178:181], v[204:207], v[10:13]
	v_mfma_f32_16x16x32_bf16 v[6:9], v[170:173], v[212:215], v[6:9]
	v_mfma_f32_16x16x32_bf16 v[2:5], v[178:181], v[212:215], v[2:5]
	v_mfma_f32_16x16x32_bf16 v[46:49], v[174:177], v[190:193], v[46:49]
	v_mfma_f32_16x16x32_bf16 v[42:45], v[182:185], v[190:193], v[42:45]
	v_mfma_f32_16x16x32_bf16 v[30:33], v[174:177], v[198:201], v[30:33]
	v_mfma_f32_16x16x32_bf16 v[26:29], v[182:185], v[198:201], v[26:29]
	v_mfma_f32_16x16x32_bf16 v[14:17], v[174:177], v[208:211], v[14:17]
	v_mfma_f32_16x16x32_bf16 v[10:13], v[182:185], v[208:211], v[10:13]
	v_mfma_f32_16x16x32_bf16 v[6:9], v[174:177], v[216:219], v[6:9]
	v_mfma_f32_16x16x32_bf16 v[2:5], v[182:185], v[216:219], v[2:5]
	s_setprio 0
	s_barrier
	ds_read_b128 v[154:157], v150
	ds_read_b128 v[158:161], v150 offset:1024
	ds_read_b128 v[162:165], v150 offset:2048
	ds_read_b128 v[166:169], v150 offset:3072
	ds_read_b128 v[170:173], v151
	ds_read_b128 v[174:177], v151 offset:1024
	ds_read_b128 v[178:181], v151 offset:2048
	ds_read_b128 v[182:185], v151 offset:3072
	s_add_u32 s26, s26, 0x40000
	s_addc_u32 s27, s27, 0
	s_mov_b32 m0, s71
	v_lshl_add_u64 v[228:229], s[26:27], 0, v[136:137]
	ds_read_b128 v[186:189], v149 offset:32768
	ds_read_b128 v[190:193], v149 offset:33792
	ds_read_b128 v[194:197], v149 offset:34816
	ds_read_b128 v[198:201], v149 offset:35840
	ds_read_b128 v[204:207], v149 offset:36864
	ds_read_b128 v[208:211], v149 offset:37888
	ds_read_b128 v[212:215], v149 offset:38912
	ds_read_b128 v[216:219], v149 offset:39936
	global_load_lds_dwordx4 v[228:229], off
	v_lshl_add_u64 v[228:229], s[26:27], 0, v[132:133]
	s_mov_b32 m0, s72
	s_nop 0
	global_load_lds_dwordx4 v[228:229], off
	s_waitcnt vmcnt(8)
	s_waitcnt lgkmcnt(0)
	s_barrier
	s_setprio 1
	s_waitcnt lgkmcnt(0)
	v_mfma_f32_16x16x32_bf16 v[126:129], v[154:157], v[186:189], v[126:129]
	v_mfma_f32_16x16x32_bf16 v[122:125], v[162:165], v[186:189], v[122:125]
	v_mfma_f32_16x16x32_bf16 v[118:121], v[154:157], v[194:197], v[118:121]
	v_mfma_f32_16x16x32_bf16 v[114:117], v[162:165], v[194:197], v[114:117]
	v_mfma_f32_16x16x32_bf16 v[102:105], v[154:157], v[204:207], v[102:105]
	v_mfma_f32_16x16x32_bf16 v[98:101], v[162:165], v[204:207], v[98:101]
	v_mfma_f32_16x16x32_bf16 v[86:89], v[154:157], v[212:215], v[86:89]
	v_mfma_f32_16x16x32_bf16 v[82:85], v[162:165], v[212:215], v[82:85]
	v_mfma_f32_16x16x32_bf16 v[126:129], v[158:161], v[190:193], v[126:129]
	v_mfma_f32_16x16x32_bf16 v[122:125], v[166:169], v[190:193], v[122:125]
	v_mfma_f32_16x16x32_bf16 v[118:121], v[158:161], v[198:201], v[118:121]
	v_mfma_f32_16x16x32_bf16 v[114:117], v[166:169], v[198:201], v[114:117]
	v_mfma_f32_16x16x32_bf16 v[102:105], v[158:161], v[208:211], v[102:105]
	v_mfma_f32_16x16x32_bf16 v[98:101], v[166:169], v[208:211], v[98:101]
	v_mfma_f32_16x16x32_bf16 v[86:89], v[158:161], v[216:219], v[86:89]
	v_mfma_f32_16x16x32_bf16 v[82:85], v[166:169], v[216:219], v[82:85]
	v_mfma_f32_16x16x32_bf16 v[110:113], v[170:173], v[186:189], v[110:113]
	v_mfma_f32_16x16x32_bf16 v[106:109], v[178:181], v[186:189], v[106:109]
	v_mfma_f32_16x16x32_bf16 v[94:97], v[170:173], v[194:197], v[94:97]
	v_mfma_f32_16x16x32_bf16 v[90:93], v[178:181], v[194:197], v[90:93]
	v_mfma_f32_16x16x32_bf16 v[78:81], v[170:173], v[204:207], v[78:81]
	v_mfma_f32_16x16x32_bf16 v[74:77], v[178:181], v[204:207], v[74:77]
	v_mfma_f32_16x16x32_bf16 v[70:73], v[170:173], v[212:215], v[70:73]
	v_mfma_f32_16x16x32_bf16 v[66:69], v[178:181], v[212:215], v[66:69]
	v_mfma_f32_16x16x32_bf16 v[110:113], v[174:177], v[190:193], v[110:113]
	v_mfma_f32_16x16x32_bf16 v[106:109], v[182:185], v[190:193], v[106:109]
	v_mfma_f32_16x16x32_bf16 v[94:97], v[174:177], v[198:201], v[94:97]
	v_mfma_f32_16x16x32_bf16 v[90:93], v[182:185], v[198:201], v[90:93]
	v_mfma_f32_16x16x32_bf16 v[78:81], v[174:177], v[208:211], v[78:81]
	v_mfma_f32_16x16x32_bf16 v[74:77], v[182:185], v[208:211], v[74:77]
	v_mfma_f32_16x16x32_bf16 v[70:73], v[174:177], v[216:219], v[70:73]
	v_mfma_f32_16x16x32_bf16 v[66:69], v[182:185], v[216:219], v[66:69]
	s_setprio 0
	s_barrier
; #define PG8_STAGE(bufoff, gbase, voff) do { _Pragma("unroll") for (int _i = 0; _i < 2; ++_i) \
;         __builtin_amdgcn_global_load_lds((const unsigned*)((const char*)(gbase) + (voff)[_i]), (LAS unsigned*)(lds + (bufoff) + ldsw + _i * 8192), 16, 0, 0); } while (0)
; #define PG8_LDA(dst, b, h) do { _Pragma("unroll") for (int m = 0; m < 4; ++m) _Pragma("unroll") for (int k = 0; k < 2; ++k) dst[m][k] = *(const LAS bf16x8*)(lds + PG8_SA(b, h) + aoff + m * 2048 + k * 1024); } while (0)
; #define PG8_MMA(ai, bj, At, Bt) do { __builtin_amdgcn_s_setprio(1); _Pragma("unroll") for (int m = 0; m < 4; ++m) _Pragma("unroll") for (int n = 0; n < 2; ++n) _Pragma("unroll") for (int k = 0; k < 2; ++k) \
;         acc[ai][bj][m][n] = __builtin_amdgcn_mfma_f32_16x16x32_bf16(Bt[n][k], At[m][k], acc[ai][bj][m][n], 0, 0, 0); __builtin_amdgcn_s_setprio(0); } while (0)
; #define PG8_WAIT_V(n) asm volatile("s_waitcnt vmcnt(" #n ")" ::: "memory")
; #define PG8_WAIT_L(n) asm volatile("s_waitcnt lgkmcnt(" #n ")" ::: "memory")
; #define PG8_BAR __builtin_amdgcn_s_barrier()
; #define PG8_SCHED __builtin_amdgcn_sched_barrier(0)
; template <class Epi, class Sched, bool ALIGN_EPI>
; DI void gemm_phase(LAS unsigned char* lds, const Gemm g, const Sched& S, const Epi& E) {
;     ...
;             PG8_LDA(At, 1, 1); PG8_STAGE(PG8_SB(1, 0), b3, voffB); PG8_STAGE(PG8_SB(1, 1), b3 + hstepB, voffB); PG8_STAGE(PG8_SA(1, 0), a3, voffA);
;             PG8_WAIT_V(8); PG8_WAIT_L(0); PG8_BAR; PG8_MMA(1, 0, At, B0); PG8_MMA(1, 1, At, B1); PG8_BAR; PG8_SCHED;
;         }
;         if constexpr (ALIGN_EPI) { if (wr == 0) PG8_BAR; }
	s_add_i32 s26, s81, s40
	v_lshl_add_u64 v[220:221], v[220:221], 0, s[8:9]
	s_mov_b32 m0, s26
	ds_read_b128 v[186:189], v149 offset:49152
	ds_read_b128 v[190:193], v149 offset:50176
	ds_read_b128 v[194:197], v149 offset:51200
	ds_read_b128 v[198:201], v149 offset:52224
	ds_read_b128 v[204:207], v149 offset:53248
	ds_read_b128 v[208:211], v149 offset:54272
	ds_read_b128 v[212:215], v149 offset:55296
	ds_read_b128 v[216:219], v149 offset:56320
	global_load_lds_dwordx4 v[220:221], off
	s_add_i32 m0, s26, 0x2000
	s_add_u32 s24, s24, 0x40080
	v_lshl_add_u64 v[220:221], v[222:223], 0, s[8:9]
	s_addc_u32 s25, s25, 0
	s_add_i32 s26, s82, s40
	global_load_lds_dwordx4 v[220:221], off
	v_lshl_add_u64 v[220:221], s[24:25], 0, v[134:135]
	s_mov_b32 m0, s26
	s_nop 0
	global_load_lds_dwordx4 v[220:221], off
	v_lshl_add_u64 v[220:221], s[24:25], 0, v[130:131]
	s_add_i32 m0, s26, 0x2000
	s_nop 0
	global_load_lds_dwordx4 v[220:221], off
	v_lshl_add_u64 v[220:221], v[224:225], 0, s[8:9]
	s_mov_b32 m0, s74
	s_nop 0
	global_load_lds_dwordx4 v[220:221], off
	v_lshl_add_u64 v[220:221], v[226:227], 0, s[8:9]
	s_mov_b32 m0, s75
	s_nop 0
	global_load_lds_dwordx4 v[220:221], off
	s_waitcnt vmcnt(8)
	s_waitcnt lgkmcnt(0)
	s_barrier
	s_setprio 1
	s_waitcnt lgkmcnt(0)
	v_mfma_f32_16x16x32_bf16 v[62:65], v[154:157], v[186:189], v[62:65]
	v_mfma_f32_16x16x32_bf16 v[58:61], v[162:165], v[186:189], v[58:61]
	v_mfma_f32_16x16x32_bf16 v[54:57], v[154:157], v[194:197], v[54:57]
	v_mfma_f32_16x16x32_bf16 v[50:53], v[162:165], v[194:197], v[50:53]
	v_mfma_f32_16x16x32_bf16 v[38:41], v[154:157], v[204:207], v[38:41]
	v_mfma_f32_16x16x32_bf16 v[34:37], v[162:165], v[204:207], v[34:37]
	v_mfma_f32_16x16x32_bf16 v[22:25], v[154:157], v[212:215], v[22:25]
	v_mfma_f32_16x16x32_bf16 v[18:21], v[162:165], v[212:215], v[18:21]
	v_mfma_f32_16x16x32_bf16 v[62:65], v[158:161], v[190:193], v[62:65]
	v_mfma_f32_16x16x32_bf16 v[58:61], v[166:169], v[190:193], v[58:61]
	v_mfma_f32_16x16x32_bf16 v[54:57], v[158:161], v[198:201], v[54:57]
	v_mfma_f32_16x16x32_bf16 v[50:53], v[166:169], v[198:201], v[50:53]
	v_mfma_f32_16x16x32_bf16 v[38:41], v[158:161], v[208:211], v[38:41]
	v_mfma_f32_16x16x32_bf16 v[34:37], v[166:169], v[208:211], v[34:37]
	v_mfma_f32_16x16x32_bf16 v[22:25], v[158:161], v[216:219], v[22:25]
	v_mfma_f32_16x16x32_bf16 v[18:21], v[166:169], v[216:219], v[18:21]
	v_mfma_f32_16x16x32_bf16 v[46:49], v[170:173], v[186:189], v[46:49]
	v_mfma_f32_16x16x32_bf16 v[42:45], v[178:181], v[186:189], v[42:45]
	v_mfma_f32_16x16x32_bf16 v[30:33], v[170:173], v[194:197], v[30:33]
	v_mfma_f32_16x16x32_bf16 v[26:29], v[178:181], v[194:197], v[26:29]
	v_mfma_f32_16x16x32_bf16 v[14:17], v[170:173], v[204:207], v[14:17]
	v_mfma_f32_16x16x32_bf16 v[10:13], v[178:181], v[204:207], v[10:13]
	v_mfma_f32_16x16x32_bf16 v[6:9], v[170:173], v[212:215], v[6:9]
	v_mfma_f32_16x16x32_bf16 v[2:5], v[178:181], v[212:215], v[2:5]
	v_mfma_f32_16x16x32_bf16 v[46:49], v[174:177], v[190:193], v[46:49]
	v_mfma_f32_16x16x32_bf16 v[42:45], v[182:185], v[190:193], v[42:45]
	v_mfma_f32_16x16x32_bf16 v[30:33], v[174:177], v[198:201], v[30:33]
	v_mfma_f32_16x16x32_bf16 v[26:29], v[182:185], v[198:201], v[26:29]
	v_mfma_f32_16x16x32_bf16 v[14:17], v[174:177], v[208:211], v[14:17]
	v_mfma_f32_16x16x32_bf16 v[10:13], v[182:185], v[208:211], v[10:13]
	v_mfma_f32_16x16x32_bf16 v[6:9], v[174:177], v[216:219], v[6:9]
	v_mfma_f32_16x16x32_bf16 v[2:5], v[182:185], v[216:219], v[2:5]
	s_setprio 0
	s_barrier
	s_add_i32 s56, s56, 2
	s_add_u32 s22, s22, 0x100
	s_addc_u32 s23, s23, 0
	s_add_u32 s54, s54, 0x100
	s_addc_u32 s55, s55, 0
	s_cmp_gt_u32 s56, 13
	s_cbranch_scc0 .LBB0_316
	s_and_b64 vcc, exec, s[10:11]
	s_cbranch_vccz .LBB0_319
	s_barrier

; #define LAS __attribute__((address_space(3)))
; #define LBAR() do { asm volatile("s_waitcnt lgkmcnt(0)" ::: "memory"); __builtin_amdgcn_s_barrier(); asm volatile("" ::: "memory"); } while (0)
; #define GDMA(chunk) do { if ((chunk) < 64) { const unsigned char* g_ = src + (size_t)(chunk) * GSLOT + (size_t)(lw * 64 + lane) * 16; LAS unsigned char* d_ = c.lds + ((chunk) % 3) * GSLOT + lw * 1024; \
;         _Pragma("unroll") for (int p = 0; p < 10; ++p) __builtin_amdgcn_global_load_lds((const unsigned*)(g_ + p * 4096), (LAS unsigned*)(d_ + p * 4096), 16, 0, 0); } } while (0)
; DI void gdn_step(const Ctx& c, const int n, const int vt, const LAS unsigned char* lds0, f32x16& S0, f32x16& S1, const float gl, bf16_t* proj, const int b, const int h) {
;     const int lane = c.lane, hi = lane >> 5;
;     const LAS unsigned char* sl = lds0 + (n % 3) * GSLOT;
; DI void gdn_scan(const Ctx& c, int bh, const unsigned char* gbase, const float* GL, bf16_t* proj, const float* normw) {
;     ...
;         for (int n = 0; n < 64; ++n) {
;             if (wid >= 2) { if (n + 2 < 64 && n > 0) asm volatile("s_waitcnt vmcnt(10)" ::: "memory"); else asm volatile("s_waitcnt vmcnt(0)" ::: "memory"); }
;             LBAR();
;             if (wid >= 2) { if (n > 0) GDMA(n + 2); }
;             else gdn_step(c, n, wid, sl_base, S0, S1, glds[n], proj, b, h);
.LBB0_871:
	s_add_u32 s28, s28, 0xa000
	s_addc_u32 s29, s29, 0
	s_add_i32 s12, s12, 4
	s_nop 4
	s_nop 0
	s_cmp_eq_u32 s28, 0x280000
	s_mov_b32 s52, s33
	s_cbranch_scc1 .LBB0_882

; #define LAS __attribute__((address_space(3)))
; DI float bflo(unsigned w) { return __uint_as_float(w << 16); }
; DI float bfhi(unsigned w) { return __uint_as_float(w & 0xffff0000u); }
; #define GLOAD4(dst, mat, mt) do { _Pragma("unroll") for (int ks_ = 0; ks_ < 4; ++ks_) dst[ks_] = GFRAG(mat, mt, ks_); } while (0)
; #define SCHEDB() __builtin_amdgcn_sched_barrier(0)
; #define MMA8(acc0, acc1, f0, f1, bop) do { _Pragma("unroll") for (int ks_ = 0; ks_ < 4; ++ks_) { acc0 = MFMA32(f0[ks_], bop[ks_], acc0); acc1 = MFMA32(f1[ks_], bop[ks_], acc1); } } while (0)
; DI void gdn_step(const Ctx& c, const int n, const int vt, const LAS unsigned char* lds0, f32x16& S0, f32x16& S1, const float gl, bf16_t* proj, const int b, const int h) {
;     ...
;     const LAS unsigned char* sl = lds0 + (n % 3) * GSLOT;
;     bf16x8 sb[4]; sb[0] = pack8(S0, 0); sb[1] = pack8(S0, 1); sb[2] = pack8(S1, 0); sb[3] = pack8(S1, 1);
;     f32x16 vn[2], o[2];
; #pragma unroll
;     for (int ct = 0; ct < 2; ++ct) { const u32x4 u0 = *(const LAS u32x4*)(sl + 4 * 8192 + ((ct * 2 + vt) * 64 + lane) * 32), u1 = *(const LAS u32x4*)(sl + 4 * 8192 + ((ct * 2 + vt) * 64 + lane) * 32 + 16);
;         vn[ct][0] = bflo(u0.x); vn[ct][1] = bfhi(u0.x); vn[ct][2] = bflo(u0.y); vn[ct][3] = bfhi(u0.y); vn[ct][4] = bflo(u0.z); vn[ct][5] = bfhi(u0.z); vn[ct][6] = bflo(u0.w); vn[ct][7] = bfhi(u0.w);
;         vn[ct][8] = bflo(u1.x); vn[ct][9] = bfhi(u1.x); vn[ct][10] = bflo(u1.y); vn[ct][11] = bfhi(u1.y); vn[ct][12] = bflo(u1.z); vn[ct][13] = bfhi(u1.z); vn[ct][14] = bflo(u1.w); vn[ct][15] = bfhi(u1.w);
; #pragma unroll
;         for (int r = 0; r < 16; ++r) o[ct][r] = 0.f; }
;     ...
;     bf16x8 fa[4], fb[4], fc[4], fd[4];
;     GLOAD4(fa, 0, 0); GLOAD4(fb, 0, 1); GLOAD4(fc, 1, 0); GLOAD4(fd, 1, 1); SCHEDB();
;     MMA8(vn[0], vn[1], fa, fb, sb); SCHEDB();
;     GLOAD4(fa, 3, 0); GLOAD4(fb, 3, 1); SCHEDB();
;     MMA8(o[0], o[1], fc, fd, sb); SCHEDB();
;     GLOAD4(fc, 2, 0); GLOAD4(fd, 2, 1); SCHEDB();
;     bf16x8 vb[4]; vb[0] = pack8(vn[0], 0); vb[1] = pack8(vn[0], 1); vb[2] = pack8(vn[1], 0); vb[3] = pack8(vn[1], 1);
; #pragma unroll
;     for (int r = 0; r < 16; ++r) { S0[r] *= gl; S1[r] *= gl; }
;     SCHEDB();
;     MMA8(S0, S1, fa, fb, vb);
.LBB0_877:
	s_waitcnt lgkmcnt(0)
	s_barrier
	s_add_i32 s33, s52, 1
	s_mov_b64 s[36:37], -1
	s_and_b64 vcc, exec, s[18:19]
	s_cbranch_vccz .LBB0_879
	s_mul_i32 s36, s33, 0xab
	s_bfe_u32 s36, s36, 0x70009
	s_mul_i32 s36, s36, 3
	s_sub_i32 s36, s33, s36
	s_and_b32 s36, s36, 0xff
	s_mul_i32 s36, s36, 0xa000
	s_addk_i32 s36, 0x100
	v_mov_b32_e32 v3, s12
	s_add_i32 s37, s36, s43
	ds_read_b32 v8, v3
	v_add_u32_e32 v3, s37, v128
	ds_read_b128 v[50:53], v3 offset:32768
	ds_read_b128 v[54:57], v3 offset:32784
	v_cvt_pk_bf16_f32 v4, v18, v19
	v_cvt_pk_bf16_f32 v5, v20, v21
	v_cvt_pk_bf16_f32 v6, v22, v23
	s_waitcnt lgkmcnt(0)
	v_lshlrev_b32_e32 v66, 16, v50
	v_and_b32_e32 v67, 0xffff0000, v50
	v_lshlrev_b32_e32 v68, 16, v51
	v_and_b32_e32 v69, 0xffff0000, v51
	v_lshlrev_b32_e32 v70, 16, v52
	v_and_b32_e32 v71, 0xffff0000, v52
	v_lshlrev_b32_e32 v72, 16, v53
	v_and_b32_e32 v73, 0xffff0000, v53
	v_lshlrev_b32_e32 v74, 16, v54
	v_and_b32_e32 v75, 0xffff0000, v54
	v_lshlrev_b32_e32 v76, 16, v55
	v_and_b32_e32 v77, 0xffff0000, v55
	v_lshlrev_b32_e32 v78, 16, v56
	v_and_b32_e32 v79, 0xffff0000, v56
	v_lshlrev_b32_e32 v80, 16, v57
	v_and_b32_e32 v81, 0xffff0000, v57
	ds_read_b128 v[50:53], v3 offset:36864
	ds_read_b128 v[54:57], v3 offset:36880
	v_add_u32_e32 v3, s36, v129
	v_cvt_pk_bf16_f32 v7, v24, v25
	v_cvt_pk_bf16_f32 v10, v26, v27
	s_waitcnt lgkmcnt(0)
	v_lshlrev_b32_e32 v82, 16, v50
	v_and_b32_e32 v83, 0xffff0000, v50
	v_lshlrev_b32_e32 v84, 16, v51
	v_and_b32_e32 v85, 0xffff0000, v51
	v_lshlrev_b32_e32 v86, 16, v52
	v_and_b32_e32 v87, 0xffff0000, v52
	v_lshlrev_b32_e32 v88, 16, v53
	v_and_b32_e32 v89, 0xffff0000, v53
	v_lshlrev_b32_e32 v90, 16, v54
	v_and_b32_e32 v91, 0xffff0000, v54
	v_lshlrev_b32_e32 v92, 16, v55
	v_and_b32_e32 v93, 0xffff0000, v55
	v_lshlrev_b32_e32 v94, 16, v56
	v_and_b32_e32 v95, 0xffff0000, v56
	v_lshlrev_b32_e32 v96, 16, v57
	v_and_b32_e32 v97, 0xffff0000, v57
	ds_read_b128 v[50:53], v3
	ds_read_b128 v[54:57], v3 offset:1024
	ds_read_b128 v[58:61], v3 offset:2048
	ds_read_b128 v[62:65], v3 offset:3072
	ds_read_b128 v[98:101], v3 offset:4096
	ds_read_b128 v[102:105], v3 offset:5120
	ds_read_b128 v[106:109], v3 offset:6144
	ds_read_b128 v[140:143], v3 offset:7168
	ds_read_b128 v[110:113], v3 offset:8192
	ds_read_b128 v[144:147], v3 offset:9216
	ds_read_b128 v[148:151], v3 offset:10240
	ds_read_b128 v[154:157], v3 offset:11264
	ds_read_b128 v[158:161], v3 offset:12288
	ds_read_b128 v[162:165], v3 offset:13312
	ds_read_b128 v[166:169], v3 offset:14336
	ds_read_b128 v[170:173], v3 offset:15360
	v_cvt_pk_bf16_f32 v11, v28, v29
	v_cvt_pk_bf16_f32 v12, v30, v31
	v_cvt_pk_bf16_f32 v13, v32, v33
	v_cvt_pk_bf16_f32 v14, v34, v35
	v_cvt_pk_bf16_f32 v15, v36, v37
	v_cvt_pk_bf16_f32 v16, v38, v39
	v_cvt_pk_bf16_f32 v17, v40, v41
	v_cvt_pk_bf16_f32 v136, v42, v43
	v_cvt_pk_bf16_f32 v137, v44, v45
	v_cvt_pk_bf16_f32 v138, v46, v47
	v_cvt_pk_bf16_f32 v139, v48, v49
	s_waitcnt lgkmcnt(0)
	v_mfma_f32_32x32x16_bf16 v[66:81], v[50:53], v[4:7], v[66:81]
	ds_read_b128 v[174:177], v3 offset:24576
	ds_read_b128 v[178:181], v3 offset:25600
	ds_read_b128 v[182:185], v3 offset:26624
	ds_read_b128 v[186:189], v3 offset:27648
	ds_read_b128 v[190:193], v3 offset:28672
	ds_read_b128 v[194:197], v3 offset:29696
	ds_read_b128 v[198:201], v3 offset:30720
	ds_read_b128 v[204:207], v3 offset:31744
	v_mfma_f32_32x32x16_bf16 v[66:81], v[54:57], v[10:13], v[66:81]
	v_mfma_f32_32x32x16_bf16 v[82:97], v[98:101], v[4:7], v[82:97]
	v_mfma_f32_32x32x16_bf16 v[66:81], v[58:61], v[14:17], v[66:81]
	v_mfma_f32_32x32x16_bf16 v[82:97], v[102:105], v[10:13], v[82:97]
	v_mfma_f32_32x32x16_bf16 v[66:81], v[62:65], v[136:139], v[66:81]
	v_mfma_f32_32x32x16_bf16 v[82:97], v[106:109], v[14:17], v[82:97]
	v_mfma_f32_32x32x16_bf16 v[98:113], v[110:113], v[4:7], 0
	v_mfma_f32_32x32x16_bf16 v[50:65], v[158:161], v[4:7], 0
	v_mfma_f32_32x32x16_bf16 v[98:113], v[144:147], v[10:13], v[98:113]
	v_mfma_f32_32x32x16_bf16 v[50:65], v[162:165], v[10:13], v[50:65]
	v_mfma_f32_32x32x16_bf16 v[98:113], v[148:151], v[14:17], v[98:113]
	v_mfma_f32_32x32x16_bf16 v[50:65], v[166:169], v[14:17], v[50:65]
	v_mfma_f32_32x32x16_bf16 v[98:113], v[154:157], v[136:139], v[98:113]
	v_mfma_f32_32x32x16_bf16 v[50:65], v[170:173], v[136:139], v[50:65]
	ds_read_b128 v[4:7], v3 offset:16384
	ds_read_b128 v[10:13], v3 offset:17408
	ds_read_b128 v[14:17], v3 offset:18432
	ds_read_b128 v[144:147], v3 offset:19456
	ds_read_b128 v[148:151], v3 offset:20480
	ds_read_b128 v[154:157], v3 offset:21504
	ds_read_b128 v[158:161], v3 offset:22528
	ds_read_b128 v[162:165], v3 offset:23552
	v_mfma_f32_32x32x16_bf16 v[82:97], v[140:143], v[136:139], v[82:97]
	v_cvt_pk_bf16_f32 v136, v66, v67
	v_cvt_pk_bf16_f32 v137, v68, v69
	v_cvt_pk_bf16_f32 v138, v70, v71
	v_cvt_pk_bf16_f32 v139, v72, v73
	v_cvt_pk_bf16_f32 v140, v74, v75
	v_cvt_pk_bf16_f32 v141, v76, v77
	v_cvt_pk_bf16_f32 v142, v78, v79
	v_cvt_pk_bf16_f32 v143, v80, v81
	s_nop 3
	v_cvt_pk_bf16_f32 v166, v82, v83
	v_cvt_pk_bf16_f32 v167, v84, v85
	v_cvt_pk_bf16_f32 v168, v86, v87
	v_cvt_pk_bf16_f32 v169, v88, v89
	v_cvt_pk_bf16_f32 v170, v90, v91
	v_cvt_pk_bf16_f32 v171, v92, v93
	v_cvt_pk_bf16_f32 v172, v94, v95
	v_cvt_pk_bf16_f32 v173, v96, v97
	v_pk_mul_f32 v[32:33], v[32:33], v[8:9] op_sel_hi:[1,0]
	v_pk_mul_f32 v[30:31], v[30:31], v[8:9] op_sel_hi:[1,0]
	v_pk_mul_f32 v[28:29], v[28:29], v[8:9] op_sel_hi:[1,0]
	v_pk_mul_f32 v[26:27], v[26:27], v[8:9] op_sel_hi:[1,0]
	v_pk_mul_f32 v[24:25], v[24:25], v[8:9] op_sel_hi:[1,0]
	v_pk_mul_f32 v[22:23], v[22:23], v[8:9] op_sel_hi:[1,0]
	v_pk_mul_f32 v[20:21], v[20:21], v[8:9] op_sel_hi:[1,0]
	v_pk_mul_f32 v[18:19], v[18:19], v[8:9] op_sel_hi:[1,0]
	v_pk_mul_f32 v[48:49], v[48:49], v[8:9] op_sel_hi:[1,0]
	v_pk_mul_f32 v[46:47], v[46:47], v[8:9] op_sel_hi:[1,0]
	v_pk_mul_f32 v[44:45], v[44:45], v[8:9] op_sel_hi:[1,0]
	v_pk_mul_f32 v[42:43], v[42:43], v[8:9] op_sel_hi:[1,0]
	v_pk_mul_f32 v[40:41], v[40:41], v[8:9] op_sel_hi:[1,0]
	v_pk_mul_f32 v[38:39], v[38:39], v[8:9] op_sel_hi:[1,0]
	v_pk_mul_f32 v[36:37], v[36:37], v[8:9] op_sel_hi:[1,0]
	v_pk_mul_f32 v[34:35], v[34:35], v[8:9] op_sel_hi:[1,0]
	s_waitcnt lgkmcnt(0)
; #define LAS __attribute__((address_space(3)))
; DI bf16_t f2bf(float f) { return (bf16_t)(pk2(f, 0.f) & 0xffffu); }
; DI int crow(int r, int hi) { return (r & 3) + 8 * (r >> 2) + 4 * hi; }
; #define MMA8(acc0, acc1, f0, f1, bop) do { _Pragma("unroll") for (int ks_ = 0; ks_ < 4; ++ks_) { acc0 = MFMA32(f0[ks_], bop[ks_], acc0); acc1 = MFMA32(f1[ks_], bop[ks_], acc1); } } while (0)
; DI void gdn_step(const Ctx& c, const int n, const int vt, const LAS unsigned char* lds0, f32x16& S0, f32x16& S1, const float gl, bf16_t* proj, const int b, const int h) {
;     ...
;     MMA8(S0, S1, fa, fb, vb);
;     MMA8(o[0], o[1], fc, fd, vb);
;     ...
;     LAS bf16_t* ot = (LAS bf16_t*)(lds0 + OT_OFF + (n & 1) * 9216) + crow(0, hi) * 72 + 32 * vt + (lane & 31);
; #pragma unroll
;     for (int ct = 0; ct < 2; ++ct)
; #pragma unroll
;         for (int r = 0; r < 16; ++r) ot[(32 * ct + (r & 3) + 8 * (r >> 2)) * 72] = f2bf(o[ct][r]);
	v_mfma_f32_32x32x16_bf16 v[98:113], v[4:7], v[136:139], v[98:113]
	s_bitcmp1_b32 s33, 0
	s_cselect_b32 s36, 0x2400, 0
	v_add_u32_e32 v3, s36, v130
	s_mov_b64 s[36:37], 0
	v_mfma_f32_32x32x16_bf16 v[98:113], v[10:13], v[140:143], v[98:113]
	v_mfma_f32_32x32x16_bf16 v[98:113], v[14:17], v[166:169], v[98:113]
	v_mfma_f32_32x32x16_bf16 v[50:65], v[148:151], v[136:139], v[50:65]
	v_mfma_f32_32x32x16_bf16 v[98:113], v[144:147], v[170:173], v[98:113]
	v_mfma_f32_32x32x16_bf16 v[50:65], v[154:157], v[140:143], v[50:65]
	s_nop 10
	v_cvt_pk_bf16_f32 v4, v98, s0
	ds_write_b16 v3, v4
	v_cvt_pk_bf16_f32 v4, v99, s0
	ds_write_b16 v3, v4 offset:144
	v_cvt_pk_bf16_f32 v4, v100, s0
	ds_write_b16 v3, v4 offset:288
	v_cvt_pk_bf16_f32 v4, v101, s0
	v_mfma_f32_32x32x16_bf16 v[50:65], v[158:161], v[166:169], v[50:65]
	ds_write_b16 v3, v4 offset:432
	v_cvt_pk_bf16_f32 v4, v102, s0
	ds_write_b16 v3, v4 offset:1152
	v_cvt_pk_bf16_f32 v4, v103, s0
	ds_write_b16 v3, v4 offset:1296
	v_cvt_pk_bf16_f32 v4, v104, s0
	ds_write_b16 v3, v4 offset:1440
	v_cvt_pk_bf16_f32 v4, v105, s0
	v_mfma_f32_32x32x16_bf16 v[18:33], v[174:177], v[136:139], v[18:33]
	ds_write_b16 v3, v4 offset:1584
	v_cvt_pk_bf16_f32 v4, v106, s0
	ds_write_b16 v3, v4 offset:2304
	v_cvt_pk_bf16_f32 v4, v107, s0
	ds_write_b16 v3, v4 offset:2448
	v_cvt_pk_bf16_f32 v4, v108, s0
	ds_write_b16 v3, v4 offset:2592
	v_mfma_f32_32x32x16_bf16 v[34:49], v[190:193], v[136:139], v[34:49]
	v_cvt_pk_bf16_f32 v4, v109, s0
	ds_write_b16 v3, v4 offset:2736
	v_cvt_pk_bf16_f32 v4, v110, s0
	ds_write_b16 v3, v4 offset:3456
	v_cvt_pk_bf16_f32 v4, v111, s0
	ds_write_b16 v3, v4 offset:3600
	v_cvt_pk_bf16_f32 v4, v112, s0
	v_mfma_f32_32x32x16_bf16 v[50:65], v[162:165], v[170:173], v[50:65]
	ds_write_b16 v3, v4 offset:3744
	v_cvt_pk_bf16_f32 v4, v113, s0
	ds_write_b16 v3, v4 offset:3888
	v_mfma_f32_32x32x16_bf16 v[18:33], v[178:181], v[140:143], v[18:33]
	s_nop 7
	v_cvt_pk_bf16_f32 v4, v50, s0
	ds_write_b16 v3, v4 offset:4608
	v_cvt_pk_bf16_f32 v4, v51, s0
	ds_write_b16 v3, v4 offset:4752
	v_cvt_pk_bf16_f32 v4, v52, s0
	ds_write_b16 v3, v4 offset:4896
	v_cvt_pk_bf16_f32 v4, v53, s0
	v_mfma_f32_32x32x16_bf16 v[34:49], v[194:197], v[140:143], v[34:49]
	ds_write_b16 v3, v4 offset:5040
	v_cvt_pk_bf16_f32 v4, v54, s0
	ds_write_b16 v3, v4 offset:5760
	v_cvt_pk_bf16_f32 v4, v55, s0
	ds_write_b16 v3, v4 offset:5904
	v_cvt_pk_bf16_f32 v4, v56, s0
	ds_write_b16 v3, v4 offset:6048
	v_cvt_pk_bf16_f32 v4, v57, s0
	v_mfma_f32_32x32x16_bf16 v[18:33], v[182:185], v[166:169], v[18:33]
	ds_write_b16 v3, v4 offset:6192
	v_cvt_pk_bf16_f32 v4, v58, s0
	ds_write_b16 v3, v4 offset:6912
	v_cvt_pk_bf16_f32 v4, v59, s0
	ds_write_b16 v3, v4 offset:7056
	v_cvt_pk_bf16_f32 v4, v60, s0
	ds_write_b16 v3, v4 offset:7200
	v_mfma_f32_32x32x16_bf16 v[34:49], v[198:201], v[166:169], v[34:49]
	v_cvt_pk_bf16_f32 v4, v61, s0
	ds_write_b16 v3, v4 offset:7344
	v_cvt_pk_bf16_f32 v4, v62, s0
	ds_write_b16 v3, v4 offset:8064
	v_cvt_pk_bf16_f32 v4, v63, s0
	ds_write_b16 v3, v4 offset:8208
	v_cvt_pk_bf16_f32 v4, v64, s0
	ds_write_b16 v3, v4 offset:8352
	v_cvt_pk_bf16_f32 v4, v65, s0
	v_mfma_f32_32x32x16_bf16 v[18:33], v[186:189], v[170:173], v[18:33]
	ds_write_b16 v3, v4 offset:8496
	v_mfma_f32_32x32x16_bf16 v[34:49], v[204:207], v[170:173], v[34:49]

; #define LBAR() do { asm volatile("s_waitcnt lgkmcnt(0)" ::: "memory"); __builtin_amdgcn_s_barrier(); asm volatile("" ::: "memory"); } while (0)
; #define GZLOAD(ZR, chunk) do { const bf16_t* zp_ = proj + (size_t)(b * SEQ + (chunk) * 64 + lane) * NINP + C_GZ + h * 64 + 32 * hc; \
;         _Pragma("unroll") for (int k = 0; k < 4; ++k) ZR[k] = *(const u32x4*)(zp_ + 8 * k); } while (0)
; DI void gdn_scan(const Ctx& c, int bh, const unsigned char* gbase, const float* GL, bf16_t* proj, const float* normw) {
;     ...
;     if (wid >= 6) {
;         const int hc = wid - 6;
;         u32x4 zA[4], zB[4];
;         GZLOAD(zA, 0);
;         for (int n = 0; n < 64; n += 2) {
;             LBAR(); if (n > 0) GHELP(n - 1, zB); GZLOAD(zB, n + 1);
;             LBAR(); GHELP(n, zA); { const int nx = n + 2 < 64 ? n + 2 : 63; GZLOAD(zA, nx); }
.LBB0_885:
	v_mov_b64_e32 v[18:19], s[8:9]
	v_mad_i64_i32 v[32:33], s[52:53], v16, s73, v[18:19]
	global_load_dwordx4 v[16:19], v[32:33], off offset:3120
	global_load_dwordx4 v[24:27], v[32:33], off offset:3104
	global_load_dwordx4 v[28:31], v[32:33], off offset:3088
	s_nop 0
	global_load_dwordx4 v[32:35], v[32:33], off offset:3072
	s_waitcnt lgkmcnt(0)
	s_barrier
	s_cmp_eq_u32 s29, 0
	s_mov_b32 s33, 0
	s_cbranch_scc1 .Lnwl_init_0
	v_add_u32_e32 v40, 0x20600, v135
	ds_read_b128 v[66:69], v40
	ds_read_b128 v[52:55], v40 offset:16
	ds_read_b128 v[44:47], v40 offset:32
	ds_read_b128 v[36:39], v40 offset:48
	ds_read_b128 v[70:73], v40 offset:64
	ds_read_b128 v[56:59], v40 offset:80
	ds_read_b128 v[48:51], v40 offset:96
	ds_read_b128 v[40:43], v40 offset:112
	s_waitcnt lgkmcnt(0)
	v_and_b32_e32 v75, 0xffff0000, v52
	v_and_b32_e32 v74, 0xffff0000, v66
	v_lshlrev_b32_e32 v61, 16, v52
	v_lshlrev_b32_e32 v60, 16, v66
	v_pk_mul_f32 v[74:75], v[74:75], v[74:75]
	v_and_b32_e32 v77, 0xffff0000, v36
	v_pk_fma_f32 v[60:61], v[60:61], v[60:61], v[74:75]
	v_lshlrev_b32_e32 v75, 16, v53
	v_lshlrev_b32_e32 v74, 16, v67
	v_pk_fma_f32 v[60:61], v[74:75], v[74:75], v[60:61]
	v_and_b32_e32 v75, 0xffff0000, v53
	v_and_b32_e32 v74, 0xffff0000, v67
	v_pk_fma_f32 v[60:61], v[74:75], v[74:75], v[60:61]
	v_lshlrev_b32_e32 v75, 16, v54
	v_lshlrev_b32_e32 v74, 16, v68
	v_pk_fma_f32 v[60:61], v[74:75], v[74:75], v[60:61]
	v_and_b32_e32 v75, 0xffff0000, v54
	v_and_b32_e32 v74, 0xffff0000, v68
	v_pk_fma_f32 v[60:61], v[74:75], v[74:75], v[60:61]
	v_lshlrev_b32_e32 v75, 16, v55
	v_lshlrev_b32_e32 v74, 16, v69
	v_pk_fma_f32 v[60:61], v[74:75], v[74:75], v[60:61]
	v_and_b32_e32 v75, 0xffff0000, v55
	v_and_b32_e32 v74, 0xffff0000, v69
	v_and_b32_e32 v76, 0xffff0000, v44
	v_pk_fma_f32 v[60:61], v[74:75], v[74:75], v[60:61]
	v_lshlrev_b32_e32 v75, 16, v36
	v_lshlrev_b32_e32 v74, 16, v44
	v_pk_mul_f32 v[76:77], v[76:77], v[76:77]
	v_and_b32_e32 v79, 0xffff0000, v56
	v_pk_fma_f32 v[74:75], v[74:75], v[74:75], v[76:77]
	v_lshlrev_b32_e32 v77, 16, v37
	v_lshlrev_b32_e32 v76, 16, v45
	v_pk_fma_f32 v[74:75], v[76:77], v[76:77], v[74:75]
	v_and_b32_e32 v77, 0xffff0000, v37
	v_and_b32_e32 v76, 0xffff0000, v45
	v_pk_fma_f32 v[74:75], v[76:77], v[76:77], v[74:75]
	v_lshlrev_b32_e32 v77, 16, v38
	v_lshlrev_b32_e32 v76, 16, v46
	v_pk_fma_f32 v[74:75], v[76:77], v[76:77], v[74:75]
	v_and_b32_e32 v77, 0xffff0000, v38
	v_and_b32_e32 v76, 0xffff0000, v46
	v_pk_fma_f32 v[74:75], v[76:77], v[76:77], v[74:75]
	v_lshlrev_b32_e32 v77, 16, v39
	v_lshlrev_b32_e32 v76, 16, v47
	v_pk_fma_f32 v[74:75], v[76:77], v[76:77], v[74:75]
	v_and_b32_e32 v77, 0xffff0000, v39
	v_and_b32_e32 v76, 0xffff0000, v47
	v_and_b32_e32 v78, 0xffff0000, v70
	v_pk_fma_f32 v[74:75], v[76:77], v[76:77], v[74:75]
	v_lshlrev_b32_e32 v77, 16, v56
	v_lshlrev_b32_e32 v76, 16, v70
	v_pk_mul_f32 v[78:79], v[78:79], v[78:79]
	v_and_b32_e32 v81, 0xffff0000, v40
	v_pk_fma_f32 v[76:77], v[76:77], v[76:77], v[78:79]
	v_lshlrev_b32_e32 v79, 16, v57
	v_lshlrev_b32_e32 v78, 16, v71
	v_pk_fma_f32 v[76:77], v[78:79], v[78:79], v[76:77]
	v_and_b32_e32 v79, 0xffff0000, v57
	v_and_b32_e32 v78, 0xffff0000, v71
	v_pk_fma_f32 v[76:77], v[78:79], v[78:79], v[76:77]
	v_lshlrev_b32_e32 v79, 16, v58
	v_lshlrev_b32_e32 v78, 16, v72
	v_pk_fma_f32 v[76:77], v[78:79], v[78:79], v[76:77]
	v_and_b32_e32 v79, 0xffff0000, v58
	v_and_b32_e32 v78, 0xffff0000, v72
	v_pk_fma_f32 v[76:77], v[78:79], v[78:79], v[76:77]
	v_lshlrev_b32_e32 v79, 16, v59
	v_lshlrev_b32_e32 v78, 16, v73
	v_pk_fma_f32 v[76:77], v[78:79], v[78:79], v[76:77]
	v_and_b32_e32 v79, 0xffff0000, v59
	v_and_b32_e32 v78, 0xffff0000, v73
	v_and_b32_e32 v80, 0xffff0000, v48
	v_pk_fma_f32 v[76:77], v[78:79], v[78:79], v[76:77]
	v_lshlrev_b32_e32 v79, 16, v40
	v_lshlrev_b32_e32 v78, 16, v48
	v_pk_mul_f32 v[80:81], v[80:81], v[80:81]
	v_add_f32_e32 v60, v60, v61
	v_pk_fma_f32 v[78:79], v[78:79], v[78:79], v[80:81]
	v_lshlrev_b32_e32 v81, 16, v41
	v_lshlrev_b32_e32 v80, 16, v49
	v_pk_fma_f32 v[78:79], v[80:81], v[80:81], v[78:79]
	v_and_b32_e32 v81, 0xffff0000, v41
	v_and_b32_e32 v80, 0xffff0000, v49
	v_pk_fma_f32 v[78:79], v[80:81], v[80:81], v[78:79]
	v_lshlrev_b32_e32 v81, 16, v42
	v_lshlrev_b32_e32 v80, 16, v50
	v_pk_fma_f32 v[78:79], v[80:81], v[80:81], v[78:79]
	v_and_b32_e32 v81, 0xffff0000, v42
	v_and_b32_e32 v80, 0xffff0000, v50
	v_add_f32_e32 v60, v60, v74
	v_pk_fma_f32 v[78:79], v[80:81], v[80:81], v[78:79]
	v_lshlrev_b32_e32 v81, 16, v43
	v_lshlrev_b32_e32 v80, 16, v51
	v_add_f32_e32 v60, v60, v75
	v_pk_fma_f32 v[78:79], v[80:81], v[80:81], v[78:79]
	v_and_b32_e32 v81, 0xffff0000, v43
	v_and_b32_e32 v80, 0xffff0000, v51
	v_add_f32_e32 v60, v60, v76
	v_pk_fma_f32 v[78:79], v[80:81], v[80:81], v[78:79]
	v_add_f32_e32 v60, v60, v77
	v_add_f32_e32 v60, v60, v78
	v_add_f32_e32 v60, v60, v79
	v_fmamk_f32 v60, v60, 0x3c800000, v134
	v_rsq_f32_e32 v62, v60
	v_add_u32_e32 v65, s29, v3
	v_mov_b64_e32 v[60:61], s[8:9]
	v_cndmask_b32_e64 v72, v72, v68, s[6:7]
	s_waitcnt vmcnt(8)
	v_lshlrev_b32_e32 v68, 16, v20
	v_mad_i64_i32 v[60:61], s[52:53], v65, s73, v[60:61]
	v_cndmask_b32_e64 v65, v73, v69, s[6:7]
	v_and_b32_e32 v69, 0xffff0000, v20
	v_mul_f32_e32 v20, 0xbfb8aa3b, v68
	v_cndmask_b32_e64 v73, v71, v67, s[6:7]
	v_exp_f32_e32 v20, v20
	v_mul_f32_e32 v67, 0xbfb8aa3b, v69
	v_exp_f32_e32 v67, v67
	v_mov_b32_e32 v90, s68
	v_add_f32_e32 v20, 1.0, v20
	v_cndmask_b32_e64 v71, v70, v66, s[6:7]
	v_rcp_f32_e32 v66, v20
	v_add_f32_e32 v20, 1.0, v67
	v_rcp_f32_e32 v67, v20
	v_lshlrev_b32_e32 v70, 16, v71
	v_and_b32_e32 v71, 0xffff0000, v71
	v_pk_mul_f32 v[66:67], v[66:67], v[68:69]
	v_lshlrev_b32_e32 v68, 16, v21
	s_waitcnt lgkmcnt(0)
	v_pk_mul_f32 v[74:75], v[208:209], v[62:63] op_sel_hi:[1,0]
	v_and_b32_e32 v69, 0xffff0000, v21
	v_mul_f32_e32 v20, 0xbfb8aa3b, v68
	v_pk_mul_f32 v[70:71], v[74:75], v[70:71]
	v_exp_f32_e32 v21, v20
	v_mul_f32_e32 v20, 0xbfb8aa3b, v69
	v_pk_mul_f32 v[66:67], v[66:67], v[70:71]
	v_exp_f32_e32 v70, v20
	v_add_f32_e32 v21, 1.0, v21
	v_cvt_pk_bf16_f32 v20, v66, v67
	v_rcp_f32_e32 v66, v21
	v_add_f32_e32 v21, 1.0, v70
	v_rcp_f32_e32 v67, v21
	v_pk_mul_f32 v[76:77], v[210:211], v[62:63] op_sel_hi:[1,0]
	v_lshlrev_b32_e32 v70, 16, v73
	v_and_b32_e32 v71, 0xffff0000, v73
	v_pk_mul_f32 v[66:67], v[66:67], v[68:69]
	v_lshlrev_b32_e32 v68, 16, v22
	v_and_b32_e32 v69, 0xffff0000, v22
	v_mul_f32_e32 v21, 0xbfb8aa3b, v68
	v_pk_mul_f32 v[70:71], v[76:77], v[70:71]
	v_exp_f32_e32 v22, v21
	v_mul_f32_e32 v21, 0xbfb8aa3b, v69
	v_pk_mul_f32 v[66:67], v[66:67], v[70:71]
	v_exp_f32_e32 v70, v21
	v_add_f32_e32 v22, 1.0, v22
	v_cvt_pk_bf16_f32 v21, v66, v67
	v_rcp_f32_e32 v66, v22
	v_add_f32_e32 v22, 1.0, v70
	v_rcp_f32_e32 v67, v22
	v_pk_mul_f32 v[78:79], v[212:213], v[62:63] op_sel_hi:[1,0]
	v_lshlrev_b32_e32 v70, 16, v72
	v_and_b32_e32 v71, 0xffff0000, v72
	v_pk_mul_f32 v[66:67], v[66:67], v[68:69]
	v_lshlrev_b32_e32 v68, 16, v23
	v_and_b32_e32 v69, 0xffff0000, v23
	v_mul_f32_e32 v22, 0xbfb8aa3b, v68
	v_pk_mul_f32 v[70:71], v[78:79], v[70:71]
	v_exp_f32_e32 v23, v22
	v_mul_f32_e32 v22, 0xbfb8aa3b, v69
	v_pk_mul_f32 v[66:67], v[66:67], v[70:71]
	v_exp_f32_e32 v70, v22
	v_cndmask_b32_e64 v58, v58, v54, s[6:7]
	v_lshlrev_b32_e32 v54, 16, v12
	v_add_f32_e32 v23, 1.0, v23
	v_cndmask_b32_e64 v59, v59, v55, s[6:7]
	v_and_b32_e32 v55, 0xffff0000, v12
	v_mul_f32_e32 v12, 0xbfb8aa3b, v54
	v_cvt_pk_bf16_f32 v22, v66, v67
	v_rcp_f32_e32 v66, v23
	v_add_f32_e32 v23, 1.0, v70
	v_lshlrev_b32_e32 v70, 16, v65
	v_and_b32_e32 v71, 0xffff0000, v65
	v_cndmask_b32_e64 v65, v57, v53, s[6:7]
	v_exp_f32_e32 v12, v12
	v_mul_f32_e32 v53, 0xbfb8aa3b, v55
	v_exp_f32_e32 v53, v53
	v_rcp_f32_e32 v67, v23
	v_add_f32_e32 v12, 1.0, v12
	v_pk_mul_f32 v[80:81], v[214:215], v[62:63] op_sel_hi:[1,0]
	v_cndmask_b32_e64 v57, v56, v52, s[6:7]
	v_rcp_f32_e32 v52, v12
	v_add_f32_e32 v12, 1.0, v53
	v_pk_mul_f32 v[70:71], v[80:81], v[70:71]
	v_pk_mul_f32 v[66:67], v[66:67], v[68:69]
	v_rcp_f32_e32 v53, v12
	v_pk_mul_f32 v[66:67], v[66:67], v[70:71]
	v_lshlrev_b32_e32 v56, 16, v57
	v_cvt_pk_bf16_f32 v23, v66, v67
	global_store_dwordx4 v[60:61], v[20:23], off
	v_and_b32_e32 v57, 0xffff0000, v57
	v_pk_mul_f32 v[52:53], v[52:53], v[54:55]
	v_pk_mul_f32 v[22:23], v[216:217], v[62:63] op_sel_hi:[1,0]
	v_pk_mul_f32 v[20:21], v[218:219], v[62:63] op_sel_hi:[1,0]
	v_pk_mul_f32 v[22:23], v[22:23], v[56:57]
	v_and_b32_e32 v55, 0xffff0000, v65
	v_pk_mul_f32 v[22:23], v[52:53], v[22:23]
	v_lshlrev_b32_e32 v52, 16, v13
	v_and_b32_e32 v53, 0xffff0000, v13
	v_mul_f32_e32 v12, 0xbfb8aa3b, v52
	v_exp_f32_e32 v13, v12
	v_mul_f32_e32 v12, 0xbfb8aa3b, v53
	v_exp_f32_e32 v54, v12
	v_cvt_pk_bf16_f32 v12, v22, v23
	v_add_f32_e32 v13, 1.0, v13
	v_rcp_f32_e32 v22, v13
	v_add_f32_e32 v13, 1.0, v54
	v_rcp_f32_e32 v23, v13
	v_lshlrev_b32_e32 v54, 16, v65
	v_pk_mul_f32 v[20:21], v[20:21], v[54:55]
	v_pk_mul_f32 v[68:69], v[220:221], v[62:63] op_sel_hi:[1,0]
	v_pk_mul_f32 v[22:23], v[22:23], v[52:53]
	v_and_b32_e32 v53, 0xffff0000, v58
	v_pk_mul_f32 v[20:21], v[22:23], v[20:21]
	v_lshlrev_b32_e32 v22, 16, v14
	v_and_b32_e32 v23, 0xffff0000, v14
	v_mul_f32_e32 v13, 0xbfb8aa3b, v22
	v_exp_f32_e32 v14, v13
	v_mul_f32_e32 v13, 0xbfb8aa3b, v23
	v_exp_f32_e32 v52, v13
	v_cvt_pk_bf16_f32 v13, v20, v21
	v_add_f32_e32 v14, 1.0, v14
	v_rcp_f32_e32 v20, v14
	v_add_f32_e32 v14, 1.0, v52
	v_rcp_f32_e32 v21, v14
	v_lshlrev_b32_e32 v52, 16, v58
	v_pk_mul_f32 v[52:53], v[68:69], v[52:53]
	v_pk_mul_f32 v[66:67], v[222:223], v[62:63] op_sel_hi:[1,0]
	v_pk_mul_f32 v[20:21], v[20:21], v[22:23]
	v_lshlrev_b32_e32 v22, 16, v15
	v_and_b32_e32 v23, 0xffff0000, v15
	v_mul_f32_e32 v14, 0xbfb8aa3b, v22
	v_exp_f32_e32 v15, v14
	v_mul_f32_e32 v14, 0xbfb8aa3b, v23
	v_pk_mul_f32 v[20:21], v[20:21], v[52:53]
	v_exp_f32_e32 v52, v14
	v_add_f32_e32 v15, 1.0, v15
	v_cvt_pk_bf16_f32 v14, v20, v21
	v_rcp_f32_e32 v20, v15
	v_add_f32_e32 v15, 1.0, v52
	v_rcp_f32_e32 v21, v15
	v_lshlrev_b32_e32 v52, 16, v59
	v_and_b32_e32 v53, 0xffff0000, v59
	v_pk_mul_f32 v[52:53], v[66:67], v[52:53]
	v_pk_mul_f32 v[54:55], v[20:21], v[22:23]
	v_pk_mul_f32 v[56:57], v[54:55], v[52:53]
	v_cndmask_b32_e64 v50, v50, v46, s[6:7]
	v_lshlrev_b32_e32 v46, 16, v8
	v_cvt_pk_bf16_f32 v15, v56, v57
	v_cndmask_b32_e64 v51, v51, v47, s[6:7]
	v_and_b32_e32 v47, 0xffff0000, v8
	v_mul_f32_e32 v8, 0xbfb8aa3b, v46
	global_store_dwordx4 v[60:61], v[12:15], off offset:16
	v_exp_f32_e32 v8, v8
	v_cndmask_b32_e64 v41, v41, v37, s[6:7]
	s_waitcnt lgkmcnt(0)
; #define LBAR() do { asm volatile("s_waitcnt lgkmcnt(0)" ::: "memory"); __builtin_amdgcn_s_barrier(); asm volatile("" ::: "memory"); } while (0)
; #define GZLOAD(ZR, chunk) do { const bf16_t* zp_ = proj + (size_t)(b * SEQ + (chunk) * 64 + lane) * NINP + C_GZ + h * 64 + 32 * hc; \
;         _Pragma("unroll") for (int k = 0; k < 4; ++k) ZR[k] = *(const u32x4*)(zp_ + 8 * k); } while (0)
; DI void gdn_scan(const Ctx& c, int bh, const unsigned char* gbase, const float* GL, bf16_t* proj, const float* normw) {
;     ...
;     if (wid >= 6) {
;         const int hc = wid - 6;
;         u32x4 zA[4], zB[4];
;         GZLOAD(zA, 0);
;         for (int n = 0; n < 64; n += 2) {
;             LBAR(); if (n > 0) GHELP(n - 1, zB); GZLOAD(zB, n + 1);
;             LBAR(); GHELP(n, zA); { const int nx = n + 2 < 64 ? n + 2 : 63; GZLOAD(zA, nx); }
	v_pk_mul_f32 v[12:13], v[226:227], v[62:63] op_sel_hi:[1,0]
	v_pk_mul_f32 v[22:23], v[228:229], v[62:63] op_sel_hi:[1,0]
	v_cndmask_b32_e64 v52, v49, v45, s[6:7]
	v_mul_f32_e32 v45, 0xbfb8aa3b, v47
	v_exp_f32_e32 v45, v45
	v_add_f32_e32 v8, 1.0, v8
	v_cndmask_b32_e64 v49, v48, v44, s[6:7]
	v_rcp_f32_e32 v44, v8
	v_add_f32_e32 v8, 1.0, v45
	v_rcp_f32_e32 v45, v8
	v_pk_mul_f32 v[14:15], v[224:225], v[62:63] op_sel_hi:[1,0]
	v_lshlrev_b32_e32 v48, 16, v49
	v_and_b32_e32 v49, 0xffff0000, v49
	v_pk_mul_f32 v[14:15], v[14:15], v[48:49]
	v_pk_mul_f32 v[44:45], v[44:45], v[46:47]
	v_and_b32_e32 v47, 0xffff0000, v52
	v_pk_mul_f32 v[14:15], v[44:45], v[14:15]
	v_lshlrev_b32_e32 v44, 16, v9
	v_and_b32_e32 v45, 0xffff0000, v9
	v_mul_f32_e32 v8, 0xbfb8aa3b, v44
	v_exp_f32_e32 v9, v8
	v_mul_f32_e32 v8, 0xbfb8aa3b, v45
	v_exp_f32_e32 v46, v8
	v_cvt_pk_bf16_f32 v8, v14, v15
	v_add_f32_e32 v9, 1.0, v9
	v_rcp_f32_e32 v14, v9
	v_add_f32_e32 v9, 1.0, v46
	v_rcp_f32_e32 v15, v9
	v_lshlrev_b32_e32 v46, 16, v52
	v_pk_mul_f32 v[12:13], v[12:13], v[46:47]
	v_pk_mul_f32 v[20:21], v[230:231], v[62:63] op_sel_hi:[1,0]
	v_pk_mul_f32 v[14:15], v[14:15], v[44:45]
	v_and_b32_e32 v45, 0xffff0000, v50
	v_pk_mul_f32 v[12:13], v[14:15], v[12:13]
	v_lshlrev_b32_e32 v14, 16, v10
	v_and_b32_e32 v15, 0xffff0000, v10
	v_mul_f32_e32 v9, 0xbfb8aa3b, v14
	v_exp_f32_e32 v10, v9
	v_mul_f32_e32 v9, 0xbfb8aa3b, v15
	v_exp_f32_e32 v44, v9
	v_cvt_pk_bf16_f32 v9, v12, v13
	v_add_f32_e32 v10, 1.0, v10
	v_rcp_f32_e32 v12, v10
	v_add_f32_e32 v10, 1.0, v44
	v_rcp_f32_e32 v13, v10
	v_lshlrev_b32_e32 v44, 16, v50
	v_pk_mul_f32 v[22:23], v[22:23], v[44:45]
	v_cndmask_b32_e64 v37, v40, v36, s[6:7]
	v_pk_mul_f32 v[12:13], v[12:13], v[14:15]
	v_lshlrev_b32_e32 v14, 16, v11
	v_and_b32_e32 v15, 0xffff0000, v11
	v_mul_f32_e32 v10, 0xbfb8aa3b, v14
	v_exp_f32_e32 v11, v10
	v_mul_f32_e32 v10, 0xbfb8aa3b, v15
	v_pk_mul_f32 v[12:13], v[12:13], v[22:23]
	v_exp_f32_e32 v22, v10
	v_add_f32_e32 v11, 1.0, v11
	v_cvt_pk_bf16_f32 v10, v12, v13
	v_rcp_f32_e32 v12, v11
	v_add_f32_e32 v11, 1.0, v22
	v_rcp_f32_e32 v13, v11
	v_lshlrev_b32_e32 v22, 16, v51
	v_and_b32_e32 v23, 0xffff0000, v51
	v_pk_mul_f32 v[20:21], v[20:21], v[22:23]
	v_pk_mul_f32 v[22:23], v[12:13], v[14:15]
	v_pk_mul_f32 v[44:45], v[22:23], v[20:21]
	v_cvt_pk_bf16_f32 v11, v44, v45
	global_store_dwordx4 v[60:61], v[8:11], off offset:32
	v_lshlrev_b32_e32 v36, 16, v37
	v_and_b32_e32 v37, 0xffff0000, v37
	s_waitcnt lgkmcnt(0)
	v_pk_mul_f32 v[8:9], v[234:235], v[62:63] op_sel_hi:[1,0]
	v_pk_mul_f32 v[14:15], v[236:237], v[62:63] op_sel_hi:[1,0]
	v_lshlrev_b32_e32 v20, 16, v4
	v_and_b32_e32 v21, 0xffff0000, v4
	v_mul_f32_e32 v4, 0xbfb8aa3b, v20
	v_pk_mul_f32 v[10:11], v[232:233], v[62:63] op_sel_hi:[1,0]
	v_pk_mul_f32 v[12:13], v[238:239], v[62:63] op_sel_hi:[1,0]
	v_exp_f32_e32 v4, v4
	v_mul_f32_e32 v22, 0xbfb8aa3b, v21
	v_exp_f32_e32 v23, v22
	v_pk_mul_f32 v[10:11], v[10:11], v[36:37]
	v_add_f32_e32 v4, 1.0, v4
	v_rcp_f32_e32 v22, v4
	v_add_f32_e32 v4, 1.0, v23
	v_rcp_f32_e32 v23, v4
	v_cndmask_b32_e64 v38, v42, v38, s[6:7]
	v_cndmask_b32_e64 v39, v43, v39, s[6:7]
	s_mov_b32 s33, s29
	v_pk_mul_f32 v[20:21], v[22:23], v[20:21]
	v_and_b32_e32 v23, 0xffff0000, v41
	v_pk_mul_f32 v[10:11], v[20:21], v[10:11]
	v_lshlrev_b32_e32 v20, 16, v5
	v_and_b32_e32 v21, 0xffff0000, v5
	v_mul_f32_e32 v4, 0xbfb8aa3b, v20
	v_exp_f32_e32 v5, v4
	v_mul_f32_e32 v4, 0xbfb8aa3b, v21
	v_exp_f32_e32 v22, v4
	v_cvt_pk_bf16_f32 v4, v10, v11
	v_add_f32_e32 v5, 1.0, v5
	v_rcp_f32_e32 v10, v5
	v_add_f32_e32 v5, 1.0, v22
	v_rcp_f32_e32 v11, v5
	v_lshlrev_b32_e32 v22, 16, v41
	v_pk_mul_f32 v[8:9], v[8:9], v[22:23]
	v_pk_mul_f32 v[10:11], v[10:11], v[20:21]
	s_nop 0
	v_pk_mul_f32 v[8:9], v[10:11], v[8:9]
	v_lshlrev_b32_e32 v10, 16, v6
	v_and_b32_e32 v11, 0xffff0000, v6
	v_mul_f32_e32 v5, 0xbfb8aa3b, v10
	v_exp_f32_e32 v6, v5
	v_mul_f32_e32 v5, 0xbfb8aa3b, v11
	v_exp_f32_e32 v20, v5
	v_cvt_pk_bf16_f32 v5, v8, v9
	v_add_f32_e32 v6, 1.0, v6
	v_rcp_f32_e32 v8, v6
	v_add_f32_e32 v6, 1.0, v20
	v_rcp_f32_e32 v9, v6
	v_lshlrev_b32_e32 v20, 16, v38
	v_and_b32_e32 v21, 0xffff0000, v38
	v_pk_mul_f32 v[14:15], v[14:15], v[20:21]
	v_pk_mul_f32 v[8:9], v[8:9], v[10:11]
	v_lshlrev_b32_e32 v10, 16, v7
	v_and_b32_e32 v11, 0xffff0000, v7
	v_mul_f32_e32 v6, 0xbfb8aa3b, v10
	v_exp_f32_e32 v7, v6
	v_mul_f32_e32 v6, 0xbfb8aa3b, v11
	v_pk_mul_f32 v[8:9], v[8:9], v[14:15]
	v_exp_f32_e32 v14, v6
	v_add_f32_e32 v7, 1.0, v7
	v_cvt_pk_bf16_f32 v6, v8, v9
	v_rcp_f32_e32 v8, v7
	v_add_f32_e32 v7, 1.0, v14
	v_rcp_f32_e32 v9, v7
	v_lshlrev_b32_e32 v14, 16, v39
	v_and_b32_e32 v15, 0xffff0000, v39
	v_pk_mul_f32 v[12:13], v[12:13], v[14:15]
	v_pk_mul_f32 v[8:9], v[8:9], v[10:11]
	s_nop 0
	v_pk_mul_f32 v[8:9], v[8:9], v[12:13]
	s_nop 0
	v_cvt_pk_bf16_f32 v7, v8, v9
	global_store_dwordx4 v[60:61], v[4:7], off offset:48
	s_branch .LBB0_884

; #define PG8_STAGE(bufoff, gbase, voff) do { _Pragma("unroll") for (int _i = 0; _i < 2; ++_i) \
;         __builtin_amdgcn_global_load_lds((const unsigned*)((const char*)(gbase) + (voff)[_i]), (LAS unsigned*)(lds + (bufoff) + ldsw + _i * 8192), 16, 0, 0); } while (0)
; #define PG8_LDA(dst, b, h) do { _Pragma("unroll") for (int m = 0; m < 4; ++m) _Pragma("unroll") for (int k = 0; k < 2; ++k) dst[m][k] = *(const LAS bf16x8*)(lds + PG8_SA(b, h) + aoff + m * 2048 + k * 1024); } while (0)
; #define PG8_LDB(dst, b, h) do { _Pragma("unroll") for (int n = 0; n < 2; ++n) _Pragma("unroll") for (int k = 0; k < 2; ++k) dst[n][k] = *(const LAS bf16x8*)(lds + PG8_SB(b, h) + boff + n * 2048 + k * 1024); } while (0)
; #define PG8_MMA(ai, bj, At, Bt) do { __builtin_amdgcn_s_setprio(1); _Pragma("unroll") for (int m = 0; m < 4; ++m) _Pragma("unroll") for (int n = 0; n < 2; ++n) _Pragma("unroll") for (int k = 0; k < 2; ++k) \
;         acc[ai][bj][m][n] = __builtin_amdgcn_mfma_f32_16x16x32_bf16(Bt[n][k], At[m][k], acc[ai][bj][m][n], 0, 0, 0); __builtin_amdgcn_s_setprio(0); } while (0)
; #define PG8_WAIT_V(n) asm volatile("s_waitcnt vmcnt(" #n ")" ::: "memory")
; #define PG8_WAIT_L(n) asm volatile("s_waitcnt lgkmcnt(" #n ")" ::: "memory")
; #define PG8_BAR __builtin_amdgcn_s_barrier()
; #define PG8_SCHED __builtin_amdgcn_sched_barrier(0)
; template <class Epi, class Sched, bool ALIGN_EPI>
; DI void gemm_phase(LAS unsigned char* lds, const Gemm g, const Sched& S, const Epi& E) {
;     ...
;             PG8_LDB(B0, 0, 0); PG8_LDB(B1, 0, 1); PG8_SCHED; PG8_LDA(At, 0, 0); PG8_STAGE(PG8_SA(1, 1), a1 + hstepA, voffA);
;             PG8_WAIT_V(8); PG8_WAIT_L(0); PG8_BAR; PG8_MMA(0, 0, At, B0); PG8_MMA(0, 1, At, B1); PG8_BAR; PG8_SCHED;
;             PG8_LDA(At, 0, 1); PG8_STAGE(PG8_SB(0, 0), b2, voffB); PG8_STAGE(PG8_SB(0, 1), b2 + hstepB, voffB); PG8_STAGE(PG8_SA(0, 0), a2, voffA);
;             PG8_WAIT_V(8); PG8_WAIT_L(0); PG8_BAR; PG8_MMA(1, 0, At, B0); PG8_MMA(1, 1, At, B1); PG8_BAR; PG8_SCHED;
.LBB0_1004:
	v_add_u32_e32 v151, s72, v1
	ds_read_b128 v[154:157], v151
	ds_read_b128 v[158:161], v151 offset:1024
	ds_read_b128 v[162:165], v151 offset:2048
	ds_read_b128 v[166:169], v151 offset:3072
	v_add_u32_e32 v151, s73, v1
	s_add_u32 s20, s10, s0
	ds_read_b128 v[170:173], v151
	ds_read_b128 v[174:177], v151 offset:1024
	ds_read_b128 v[178:181], v151 offset:2048
	ds_read_b128 v[182:185], v151 offset:3072
	s_addc_u32 s21, s11, s1
	s_add_u32 s20, s20, 0x100
	s_addc_u32 s21, s21, 0
	s_add_u32 s56, s52, s0
	s_addc_u32 s57, s53, s1
	s_cmpk_eq_i32 s0, 0x700
	s_cselect_b32 s23, s19, s21
	s_cselect_b32 s22, s18, s20
	s_cselect_b32 s21, s15, s57
	s_cselect_b32 s20, s54, s56
	v_lshl_add_u64 v[220:221], v[146:147], 0, s[0:1]
	s_add_i32 m0, s42, 0xc000
	ds_read_b128 v[186:189], v150
	ds_read_b128 v[190:193], v150 offset:1024
	ds_read_b128 v[194:197], v150 offset:2048
	ds_read_b128 v[198:201], v150 offset:3072
	ds_read_b128 v[204:207], v150 offset:4096
	ds_read_b128 v[208:211], v150 offset:5120
	ds_read_b128 v[212:215], v150 offset:6144
	ds_read_b128 v[216:219], v150 offset:7168
	global_load_lds_dwordx4 v[220:221], off
	v_lshl_add_u64 v[220:221], v[148:149], 0, s[0:1]
	s_add_i32 m0, s42, 0xe000
	s_nop 0
	global_load_lds_dwordx4 v[220:221], off
	s_waitcnt vmcnt(8)
	s_waitcnt lgkmcnt(0)
	s_barrier
	s_setprio 1
	s_waitcnt lgkmcnt(0)
	v_mfma_f32_16x16x32_bf16 v[126:129], v[154:157], v[186:189], v[126:129]
	v_mfma_f32_16x16x32_bf16 v[122:125], v[162:165], v[186:189], v[122:125]
	v_mfma_f32_16x16x32_bf16 v[114:117], v[154:157], v[194:197], v[114:117]
	v_mfma_f32_16x16x32_bf16 v[106:109], v[162:165], v[194:197], v[106:109]
	v_mfma_f32_16x16x32_bf16 v[98:101], v[154:157], v[204:207], v[98:101]
	v_mfma_f32_16x16x32_bf16 v[90:93], v[162:165], v[204:207], v[90:93]
	v_mfma_f32_16x16x32_bf16 v[82:85], v[154:157], v[212:215], v[82:85]
	v_mfma_f32_16x16x32_bf16 v[74:77], v[162:165], v[212:215], v[74:77]
	v_mfma_f32_16x16x32_bf16 v[126:129], v[158:161], v[190:193], v[126:129]
	v_mfma_f32_16x16x32_bf16 v[122:125], v[166:169], v[190:193], v[122:125]
	v_mfma_f32_16x16x32_bf16 v[114:117], v[158:161], v[198:201], v[114:117]
	v_mfma_f32_16x16x32_bf16 v[106:109], v[166:169], v[198:201], v[106:109]
	v_mfma_f32_16x16x32_bf16 v[98:101], v[158:161], v[208:211], v[98:101]
	v_mfma_f32_16x16x32_bf16 v[90:93], v[166:169], v[208:211], v[90:93]
	v_mfma_f32_16x16x32_bf16 v[82:85], v[158:161], v[216:219], v[82:85]
	v_mfma_f32_16x16x32_bf16 v[74:77], v[166:169], v[216:219], v[74:77]
	v_mfma_f32_16x16x32_bf16 v[118:121], v[170:173], v[186:189], v[118:121]
	v_mfma_f32_16x16x32_bf16 v[110:113], v[178:181], v[186:189], v[110:113]
	v_mfma_f32_16x16x32_bf16 v[102:105], v[170:173], v[194:197], v[102:105]
	v_mfma_f32_16x16x32_bf16 v[94:97], v[178:181], v[194:197], v[94:97]
	v_mfma_f32_16x16x32_bf16 v[86:89], v[170:173], v[204:207], v[86:89]
	v_mfma_f32_16x16x32_bf16 v[78:81], v[178:181], v[204:207], v[78:81]
	v_mfma_f32_16x16x32_bf16 v[70:73], v[170:173], v[212:215], v[70:73]
	v_mfma_f32_16x16x32_bf16 v[66:69], v[178:181], v[212:215], v[66:69]
	v_mfma_f32_16x16x32_bf16 v[118:121], v[174:177], v[190:193], v[118:121]
	v_mfma_f32_16x16x32_bf16 v[110:113], v[182:185], v[190:193], v[110:113]
	v_mfma_f32_16x16x32_bf16 v[102:105], v[174:177], v[198:201], v[102:105]
	v_mfma_f32_16x16x32_bf16 v[94:97], v[182:185], v[198:201], v[94:97]
	v_mfma_f32_16x16x32_bf16 v[86:89], v[174:177], v[208:211], v[86:89]
	v_mfma_f32_16x16x32_bf16 v[78:81], v[182:185], v[208:211], v[78:81]
	v_mfma_f32_16x16x32_bf16 v[70:73], v[174:177], v[216:219], v[70:73]
	v_mfma_f32_16x16x32_bf16 v[66:69], v[182:185], v[216:219], v[66:69]
	s_setprio 0
	s_barrier
	s_add_i32 s56, s72, s41
	v_lshl_add_u64 v[220:221], s[20:21], 0, v[132:133]
	s_mov_b32 m0, s56
	ds_read_b128 v[186:189], v150 offset:16384
	ds_read_b128 v[190:193], v150 offset:17408
	ds_read_b128 v[194:197], v150 offset:18432
	ds_read_b128 v[198:201], v150 offset:19456
	ds_read_b128 v[204:207], v150 offset:20480
	ds_read_b128 v[208:211], v150 offset:21504
	ds_read_b128 v[212:215], v150 offset:22528
	ds_read_b128 v[216:219], v150 offset:23552
	global_load_lds_dwordx4 v[220:221], off
	s_add_i32 m0, s56, 0x2000
	s_add_u32 s56, s20, 0x40000
	v_lshl_add_u64 v[222:223], s[20:21], 0, v[136:137]
	s_addc_u32 s57, s21, 0
	s_add_i32 s58, s73, s41
	global_load_lds_dwordx4 v[222:223], off
	v_lshl_add_u64 v[224:225], s[56:57], 0, v[132:133]
	s_mov_b32 m0, s58
	v_lshl_add_u64 v[226:227], s[22:23], 0, v[134:135]
	global_load_lds_dwordx4 v[224:225], off
	v_lshl_add_u64 v[224:225], s[56:57], 0, v[136:137]
	s_add_i32 m0, s58, 0x2000
	s_nop 0
	global_load_lds_dwordx4 v[224:225], off
	v_lshl_add_u64 v[224:225], s[22:23], 0, v[130:131]
	s_mov_b32 m0, s42
	s_nop 0
	global_load_lds_dwordx4 v[224:225], off
	s_mov_b32 m0, s43
	s_nop 0
	global_load_lds_dwordx4 v[226:227], off
	s_waitcnt vmcnt(8)
	s_waitcnt lgkmcnt(0)
	s_barrier
; #define PG8_STAGE(bufoff, gbase, voff) do { _Pragma("unroll") for (int _i = 0; _i < 2; ++_i) \
;         __builtin_amdgcn_global_load_lds((const unsigned*)((const char*)(gbase) + (voff)[_i]), (LAS unsigned*)(lds + (bufoff) + ldsw + _i * 8192), 16, 0, 0); } while (0)
; #define PG8_LDA(dst, b, h) do { _Pragma("unroll") for (int m = 0; m < 4; ++m) _Pragma("unroll") for (int k = 0; k < 2; ++k) dst[m][k] = *(const LAS bf16x8*)(lds + PG8_SA(b, h) + aoff + m * 2048 + k * 1024); } while (0)
; #define PG8_LDB(dst, b, h) do { _Pragma("unroll") for (int n = 0; n < 2; ++n) _Pragma("unroll") for (int k = 0; k < 2; ++k) dst[n][k] = *(const LAS bf16x8*)(lds + PG8_SB(b, h) + boff + n * 2048 + k * 1024); } while (0)
; #define PG8_MMA(ai, bj, At, Bt) do { __builtin_amdgcn_s_setprio(1); _Pragma("unroll") for (int m = 0; m < 4; ++m) _Pragma("unroll") for (int n = 0; n < 2; ++n) _Pragma("unroll") for (int k = 0; k < 2; ++k) \
;         acc[ai][bj][m][n] = __builtin_amdgcn_mfma_f32_16x16x32_bf16(Bt[n][k], At[m][k], acc[ai][bj][m][n], 0, 0, 0); __builtin_amdgcn_s_setprio(0); } while (0)
; #define PG8_WAIT_V(n) asm volatile("s_waitcnt vmcnt(" #n ")" ::: "memory")
; #define PG8_WAIT_L(n) asm volatile("s_waitcnt lgkmcnt(" #n ")" ::: "memory")
; #define PG8_BAR __builtin_amdgcn_s_barrier()
; #define PG8_SCHED __builtin_amdgcn_sched_barrier(0)
; template <class Epi, class Sched, bool ALIGN_EPI>
; DI void gemm_phase(LAS unsigned char* lds, const Gemm g, const Sched& S, const Epi& E) {
;     ...
;             PG8_WAIT_V(8); PG8_WAIT_L(0); PG8_BAR; PG8_MMA(1, 0, At, B0); PG8_MMA(1, 1, At, B1); PG8_BAR; PG8_SCHED;
;             PG8_LDB(B0, 1, 0); PG8_LDB(B1, 1, 1); PG8_SCHED; PG8_LDA(At, 1, 0); PG8_STAGE(PG8_SA(0, 1), a2 + hstepA, voffA);
;             PG8_WAIT_V(8); PG8_WAIT_L(0); PG8_BAR; PG8_MMA(0, 0, At, B0); PG8_MMA(0, 1, At, B1); PG8_BAR; PG8_SCHED;
	s_setprio 1
	s_waitcnt lgkmcnt(0)
	v_mfma_f32_16x16x32_bf16 v[62:65], v[154:157], v[186:189], v[62:65]
	v_mfma_f32_16x16x32_bf16 v[58:61], v[162:165], v[186:189], v[58:61]
	v_mfma_f32_16x16x32_bf16 v[46:49], v[154:157], v[194:197], v[46:49]
	v_mfma_f32_16x16x32_bf16 v[42:45], v[162:165], v[194:197], v[42:45]
	v_mfma_f32_16x16x32_bf16 v[30:33], v[154:157], v[204:207], v[30:33]
	v_mfma_f32_16x16x32_bf16 v[26:29], v[162:165], v[204:207], v[26:29]
	v_mfma_f32_16x16x32_bf16 v[14:17], v[154:157], v[212:215], v[14:17]
	v_mfma_f32_16x16x32_bf16 v[10:13], v[162:165], v[212:215], v[10:13]
	v_mfma_f32_16x16x32_bf16 v[62:65], v[158:161], v[190:193], v[62:65]
	v_mfma_f32_16x16x32_bf16 v[58:61], v[166:169], v[190:193], v[58:61]
	v_mfma_f32_16x16x32_bf16 v[46:49], v[158:161], v[198:201], v[46:49]
	v_mfma_f32_16x16x32_bf16 v[42:45], v[166:169], v[198:201], v[42:45]
	v_mfma_f32_16x16x32_bf16 v[30:33], v[158:161], v[208:211], v[30:33]
	v_mfma_f32_16x16x32_bf16 v[26:29], v[166:169], v[208:211], v[26:29]
	v_mfma_f32_16x16x32_bf16 v[14:17], v[158:161], v[216:219], v[14:17]
	v_mfma_f32_16x16x32_bf16 v[10:13], v[166:169], v[216:219], v[10:13]
	v_mfma_f32_16x16x32_bf16 v[54:57], v[170:173], v[186:189], v[54:57]
	v_mfma_f32_16x16x32_bf16 v[50:53], v[178:181], v[186:189], v[50:53]
	v_mfma_f32_16x16x32_bf16 v[38:41], v[170:173], v[194:197], v[38:41]
	v_mfma_f32_16x16x32_bf16 v[34:37], v[178:181], v[194:197], v[34:37]
	v_mfma_f32_16x16x32_bf16 v[22:25], v[170:173], v[204:207], v[22:25]
	v_mfma_f32_16x16x32_bf16 v[18:21], v[178:181], v[204:207], v[18:21]
	v_mfma_f32_16x16x32_bf16 v[6:9], v[170:173], v[212:215], v[6:9]
	v_mfma_f32_16x16x32_bf16 v[2:5], v[178:181], v[212:215], v[2:5]
	v_mfma_f32_16x16x32_bf16 v[54:57], v[174:177], v[190:193], v[54:57]
	v_mfma_f32_16x16x32_bf16 v[50:53], v[182:185], v[190:193], v[50:53]
	v_mfma_f32_16x16x32_bf16 v[38:41], v[174:177], v[198:201], v[38:41]
	v_mfma_f32_16x16x32_bf16 v[34:37], v[182:185], v[198:201], v[34:37]
	v_mfma_f32_16x16x32_bf16 v[22:25], v[174:177], v[208:211], v[22:25]
	v_mfma_f32_16x16x32_bf16 v[18:21], v[182:185], v[208:211], v[18:21]
	v_mfma_f32_16x16x32_bf16 v[6:9], v[174:177], v[216:219], v[6:9]
	v_mfma_f32_16x16x32_bf16 v[2:5], v[182:185], v[216:219], v[2:5]
	s_setprio 0
	s_barrier
	v_add_u32_e32 v151, s74, v1
	ds_read_b128 v[154:157], v151
	ds_read_b128 v[158:161], v151 offset:1024
	ds_read_b128 v[162:165], v151 offset:2048
	ds_read_b128 v[166:169], v151 offset:3072
	v_add_u32_e32 v151, s76, v1
	ds_read_b128 v[170:173], v151
	ds_read_b128 v[174:177], v151 offset:1024
	ds_read_b128 v[178:181], v151 offset:2048
	ds_read_b128 v[182:185], v151 offset:3072
	s_add_u32 s22, s22, 0xd0000
	s_addc_u32 s23, s23, 0
	s_mov_b32 m0, s44
	v_lshl_add_u64 v[228:229], s[22:23], 0, v[130:131]
	ds_read_b128 v[186:189], v150 offset:32768
	ds_read_b128 v[190:193], v150 offset:33792
	ds_read_b128 v[194:197], v150 offset:34816
	ds_read_b128 v[198:201], v150 offset:35840
	ds_read_b128 v[204:207], v150 offset:36864
	ds_read_b128 v[208:211], v150 offset:37888
	ds_read_b128 v[212:215], v150 offset:38912
	ds_read_b128 v[216:219], v150 offset:39936
	global_load_lds_dwordx4 v[228:229], off
	v_lshl_add_u64 v[228:229], s[22:23], 0, v[134:135]
	s_mov_b32 m0, s45
	s_nop 0
	global_load_lds_dwordx4 v[228:229], off
	s_waitcnt vmcnt(8)
	s_waitcnt lgkmcnt(0)
	s_barrier
	s_setprio 1
	s_waitcnt lgkmcnt(0)
	v_mfma_f32_16x16x32_bf16 v[126:129], v[154:157], v[186:189], v[126:129]
	v_mfma_f32_16x16x32_bf16 v[122:125], v[162:165], v[186:189], v[122:125]
	v_mfma_f32_16x16x32_bf16 v[114:117], v[154:157], v[194:197], v[114:117]
	v_mfma_f32_16x16x32_bf16 v[106:109], v[162:165], v[194:197], v[106:109]
	v_mfma_f32_16x16x32_bf16 v[98:101], v[154:157], v[204:207], v[98:101]
	v_mfma_f32_16x16x32_bf16 v[90:93], v[162:165], v[204:207], v[90:93]
	v_mfma_f32_16x16x32_bf16 v[82:85], v[154:157], v[212:215], v[82:85]
	v_mfma_f32_16x16x32_bf16 v[74:77], v[162:165], v[212:215], v[74:77]
	v_mfma_f32_16x16x32_bf16 v[126:129], v[158:161], v[190:193], v[126:129]
	v_mfma_f32_16x16x32_bf16 v[122:125], v[166:169], v[190:193], v[122:125]
	v_mfma_f32_16x16x32_bf16 v[114:117], v[158:161], v[198:201], v[114:117]
	v_mfma_f32_16x16x32_bf16 v[106:109], v[166:169], v[198:201], v[106:109]
	v_mfma_f32_16x16x32_bf16 v[98:101], v[158:161], v[208:211], v[98:101]
	v_mfma_f32_16x16x32_bf16 v[90:93], v[166:169], v[208:211], v[90:93]
	v_mfma_f32_16x16x32_bf16 v[82:85], v[158:161], v[216:219], v[82:85]
	v_mfma_f32_16x16x32_bf16 v[74:77], v[166:169], v[216:219], v[74:77]
	v_mfma_f32_16x16x32_bf16 v[118:121], v[170:173], v[186:189], v[118:121]
	v_mfma_f32_16x16x32_bf16 v[110:113], v[178:181], v[186:189], v[110:113]
	v_mfma_f32_16x16x32_bf16 v[102:105], v[170:173], v[194:197], v[102:105]
	v_mfma_f32_16x16x32_bf16 v[94:97], v[178:181], v[194:197], v[94:97]
	v_mfma_f32_16x16x32_bf16 v[86:89], v[170:173], v[204:207], v[86:89]
	v_mfma_f32_16x16x32_bf16 v[78:81], v[178:181], v[204:207], v[78:81]
	v_mfma_f32_16x16x32_bf16 v[70:73], v[170:173], v[212:215], v[70:73]
	v_mfma_f32_16x16x32_bf16 v[66:69], v[178:181], v[212:215], v[66:69]
	v_mfma_f32_16x16x32_bf16 v[118:121], v[174:177], v[190:193], v[118:121]
	v_mfma_f32_16x16x32_bf16 v[110:113], v[182:185], v[190:193], v[110:113]
	v_mfma_f32_16x16x32_bf16 v[102:105], v[174:177], v[198:201], v[102:105]
	v_mfma_f32_16x16x32_bf16 v[94:97], v[182:185], v[198:201], v[94:97]
	v_mfma_f32_16x16x32_bf16 v[86:89], v[174:177], v[208:211], v[86:89]
	v_mfma_f32_16x16x32_bf16 v[78:81], v[182:185], v[208:211], v[78:81]
	v_mfma_f32_16x16x32_bf16 v[70:73], v[174:177], v[216:219], v[70:73]
	v_mfma_f32_16x16x32_bf16 v[66:69], v[182:185], v[216:219], v[66:69]
	s_setprio 0
	s_barrier
; #define PG8_STAGE(bufoff, gbase, voff) do { _Pragma("unroll") for (int _i = 0; _i < 2; ++_i) \
;         __builtin_amdgcn_global_load_lds((const unsigned*)((const char*)(gbase) + (voff)[_i]), (LAS unsigned*)(lds + (bufoff) + ldsw + _i * 8192), 16, 0, 0); } while (0)
; #define PG8_LDA(dst, b, h) do { _Pragma("unroll") for (int m = 0; m < 4; ++m) _Pragma("unroll") for (int k = 0; k < 2; ++k) dst[m][k] = *(const LAS bf16x8*)(lds + PG8_SA(b, h) + aoff + m * 2048 + k * 1024); } while (0)
; #define PG8_MMA(ai, bj, At, Bt) do { __builtin_amdgcn_s_setprio(1); _Pragma("unroll") for (int m = 0; m < 4; ++m) _Pragma("unroll") for (int n = 0; n < 2; ++n) _Pragma("unroll") for (int k = 0; k < 2; ++k) \
;         acc[ai][bj][m][n] = __builtin_amdgcn_mfma_f32_16x16x32_bf16(Bt[n][k], At[m][k], acc[ai][bj][m][n], 0, 0, 0); __builtin_amdgcn_s_setprio(0); } while (0)
; #define PG8_WAIT_V(n) asm volatile("s_waitcnt vmcnt(" #n ")" ::: "memory")
; #define PG8_WAIT_L(n) asm volatile("s_waitcnt lgkmcnt(" #n ")" ::: "memory")
; #define PG8_BAR __builtin_amdgcn_s_barrier()
; #define PG8_SCHED __builtin_amdgcn_sched_barrier(0)
; template <class Epi, class Sched, bool ALIGN_EPI>
; DI void gemm_phase(LAS unsigned char* lds, const Gemm g, const Sched& S, const Epi& E) {
;     ...
;             PG8_LDA(At, 1, 1); PG8_STAGE(PG8_SB(1, 0), b3, voffB); PG8_STAGE(PG8_SB(1, 1), b3 + hstepB, voffB); PG8_STAGE(PG8_SA(1, 0), a3, voffA);
;             PG8_WAIT_V(8); PG8_WAIT_L(0); PG8_BAR; PG8_MMA(1, 0, At, B0); PG8_MMA(1, 1, At, B1); PG8_BAR; PG8_SCHED;
;         }
;         if constexpr (ALIGN_EPI) { if (wr == 0) PG8_BAR; }
;         if constexpr (!Epi::AFTER_DRAIN) E(acc, cur, wr, wc, fr, fq);
;         if (!has_next) break;
; #pragma unroll
;         for (int a = 0; a < 2; ++a)
; #pragma unroll
;             for (int b = 0; b < 2; ++b)
; #pragma unroll
;                 for (int m = 0; m < 4; ++m)
; #pragma unroll
;                     for (int n = 0; n < 2; ++n) acc[a][b][m][n] = (f32x4){0.f, 0.f, 0.f, 0.f};
;         cur = nxt; cA = nA; cB = nB; ++ui;
	s_add_i32 s22, s74, s41
	v_lshl_add_u64 v[220:221], v[220:221], 0, s[12:13]
	s_mov_b32 m0, s22
	ds_read_b128 v[186:189], v150 offset:49152
	ds_read_b128 v[190:193], v150 offset:50176
	ds_read_b128 v[194:197], v150 offset:51200
	ds_read_b128 v[198:201], v150 offset:52224
	ds_read_b128 v[204:207], v150 offset:53248
	ds_read_b128 v[208:211], v150 offset:54272
	ds_read_b128 v[212:215], v150 offset:55296
	ds_read_b128 v[216:219], v150 offset:56320
	global_load_lds_dwordx4 v[220:221], off
	s_add_i32 m0, s22, 0x2000
	s_add_u32 s20, s20, 0x40080
	v_lshl_add_u64 v[220:221], v[222:223], 0, s[12:13]
	s_addc_u32 s21, s21, 0
	s_add_i32 s22, s76, s41
	global_load_lds_dwordx4 v[220:221], off
	v_lshl_add_u64 v[220:221], s[20:21], 0, v[132:133]
	s_mov_b32 m0, s22
	s_nop 0
	global_load_lds_dwordx4 v[220:221], off
	v_lshl_add_u64 v[220:221], s[20:21], 0, v[136:137]
	s_add_i32 m0, s22, 0x2000
	s_nop 0
	global_load_lds_dwordx4 v[220:221], off
	v_lshl_add_u64 v[220:221], v[224:225], 0, s[12:13]
	s_mov_b32 m0, s68
	s_nop 0
	global_load_lds_dwordx4 v[220:221], off
	v_lshl_add_u64 v[220:221], v[226:227], 0, s[12:13]
	s_mov_b32 m0, s69
	s_nop 0
	global_load_lds_dwordx4 v[220:221], off
	s_waitcnt vmcnt(8)
	s_waitcnt lgkmcnt(0)
	s_barrier
	s_setprio 1
	s_waitcnt lgkmcnt(0)
	v_mfma_f32_16x16x32_bf16 v[62:65], v[154:157], v[186:189], v[62:65]
	v_mfma_f32_16x16x32_bf16 v[58:61], v[162:165], v[186:189], v[58:61]
	v_mfma_f32_16x16x32_bf16 v[46:49], v[154:157], v[194:197], v[46:49]
	v_mfma_f32_16x16x32_bf16 v[42:45], v[162:165], v[194:197], v[42:45]
	v_mfma_f32_16x16x32_bf16 v[30:33], v[154:157], v[204:207], v[30:33]
	v_mfma_f32_16x16x32_bf16 v[26:29], v[162:165], v[204:207], v[26:29]
	v_mfma_f32_16x16x32_bf16 v[14:17], v[154:157], v[212:215], v[14:17]
	v_mfma_f32_16x16x32_bf16 v[10:13], v[162:165], v[212:215], v[10:13]
	v_mfma_f32_16x16x32_bf16 v[62:65], v[158:161], v[190:193], v[62:65]
	v_mfma_f32_16x16x32_bf16 v[58:61], v[166:169], v[190:193], v[58:61]
	v_mfma_f32_16x16x32_bf16 v[46:49], v[158:161], v[198:201], v[46:49]
	v_mfma_f32_16x16x32_bf16 v[42:45], v[166:169], v[198:201], v[42:45]
	v_mfma_f32_16x16x32_bf16 v[30:33], v[158:161], v[208:211], v[30:33]
	v_mfma_f32_16x16x32_bf16 v[26:29], v[166:169], v[208:211], v[26:29]
	v_mfma_f32_16x16x32_bf16 v[14:17], v[158:161], v[216:219], v[14:17]
	v_mfma_f32_16x16x32_bf16 v[10:13], v[166:169], v[216:219], v[10:13]
	v_mfma_f32_16x16x32_bf16 v[54:57], v[170:173], v[186:189], v[54:57]
	v_mfma_f32_16x16x32_bf16 v[50:53], v[178:181], v[186:189], v[50:53]
	v_mfma_f32_16x16x32_bf16 v[38:41], v[170:173], v[194:197], v[38:41]
	v_mfma_f32_16x16x32_bf16 v[34:37], v[178:181], v[194:197], v[34:37]
	v_mfma_f32_16x16x32_bf16 v[22:25], v[170:173], v[204:207], v[22:25]
	v_mfma_f32_16x16x32_bf16 v[18:21], v[178:181], v[204:207], v[18:21]
	v_mfma_f32_16x16x32_bf16 v[6:9], v[170:173], v[212:215], v[6:9]
	v_mfma_f32_16x16x32_bf16 v[2:5], v[178:181], v[212:215], v[2:5]
	v_mfma_f32_16x16x32_bf16 v[54:57], v[174:177], v[190:193], v[54:57]
	v_mfma_f32_16x16x32_bf16 v[50:53], v[182:185], v[190:193], v[50:53]
	v_mfma_f32_16x16x32_bf16 v[38:41], v[174:177], v[198:201], v[38:41]
	v_mfma_f32_16x16x32_bf16 v[34:37], v[182:185], v[198:201], v[34:37]
	v_mfma_f32_16x16x32_bf16 v[22:25], v[174:177], v[208:211], v[22:25]
	v_mfma_f32_16x16x32_bf16 v[18:21], v[182:185], v[208:211], v[18:21]
	v_mfma_f32_16x16x32_bf16 v[6:9], v[174:177], v[216:219], v[6:9]
	v_mfma_f32_16x16x32_bf16 v[2:5], v[182:185], v[216:219], v[2:5]
	s_setprio 0
	s_barrier
	s_add_i32 s55, s55, 2
	s_add_u32 s0, s0, 0x100
	s_addc_u32 s1, s1, 0
	s_cmp_gt_u32 s55, 13
	s_cbranch_scc0 .LBB0_1004
	s_add_u32 s0, s52, 0xffffff00
	s_addc_u32 s1, s53, -1
	s_and_b64 vcc, exec, s[6:7]
	s_cbranch_vccnz .LBB0_1007
	v_mov_b32_e32 v2, 0
	s_mov_b32 s8, s14
	s_mov_b32 s26, s77
	s_mov_b64 s[10:11], s[18:19]
	s_mov_b32 s75, s33
	v_mov_b32_e32 v3, v2
	v_mov_b32_e32 v4, v2
	v_mov_b32_e32 v5, v2
	v_mov_b32_e32 v6, v2
	v_mov_b32_e32 v7, v2
	v_mov_b32_e32 v8, v2
	v_mov_b32_e32 v9, v2
	v_mov_b32_e32 v18, v2
	v_mov_b32_e32 v19, v2
	v_mov_b32_e32 v20, v2
	v_mov_b32_e32 v21, v2
	v_mov_b32_e32 v22, v2
	v_mov_b32_e32 v23, v2
	v_mov_b32_e32 v24, v2
	v_mov_b32_e32 v25, v2
	v_mov_b32_e32 v34, v2
	v_mov_b32_e32 v35, v2
	v_mov_b32_e32 v36, v2
	v_mov_b32_e32 v37, v2
	v_mov_b32_e32 v38, v2
	v_mov_b32_e32 v39, v2
	v_mov_b32_e32 v40, v2
	v_mov_b32_e32 v41, v2
	v_mov_b32_e32 v50, v2
	v_mov_b32_e32 v51, v2
	v_mov_b32_e32 v52, v2
	v_mov_b32_e32 v53, v2
	v_mov_b32_e32 v54, v2
	v_mov_b32_e32 v55, v2
	v_mov_b32_e32 v56, v2
	v_mov_b32_e32 v57, v2
	v_mov_b32_e32 v10, v2
	v_mov_b32_e32 v11, v2
	v_mov_b32_e32 v12, v2
	v_mov_b32_e32 v13, v2
	v_mov_b32_e32 v14, v2
	v_mov_b32_e32 v15, v2
	v_mov_b32_e32 v16, v2
	v_mov_b32_e32 v17, v2
	v_mov_b32_e32 v26, v2
	v_mov_b32_e32 v27, v2
	v_mov_b32_e32 v28, v2
	v_mov_b32_e32 v29, v2
	v_mov_b32_e32 v30, v2
	v_mov_b32_e32 v31, v2
	v_mov_b32_e32 v32, v2
	v_mov_b32_e32 v33, v2
	v_mov_b32_e32 v42, v2
	v_mov_b32_e32 v43, v2
	v_mov_b32_e32 v44, v2
	v_mov_b32_e32 v45, v2
	v_mov_b32_e32 v46, v2
	v_mov_b32_e32 v47, v2
	v_mov_b32_e32 v48, v2
	v_mov_b32_e32 v49, v2
	v_mov_b32_e32 v58, v2
	v_mov_b32_e32 v59, v2
	v_mov_b32_e32 v60, v2
	v_mov_b32_e32 v61, v2
	v_mov_b32_e32 v62, v2
	v_mov_b32_e32 v63, v2
	v_mov_b32_e32 v64, v2
	v_mov_b32_e32 v65, v2
	v_mov_b32_e32 v66, v2
	v_mov_b32_e32 v67, v2
	v_mov_b32_e32 v68, v2
	v_mov_b32_e32 v69, v2
	v_mov_b32_e32 v70, v2
	v_mov_b32_e32 v71, v2
	v_mov_b32_e32 v72, v2
	v_mov_b32_e32 v73, v2
	v_mov_b32_e32 v78, v2
	v_mov_b32_e32 v79, v2
	v_mov_b32_e32 v80, v2
	v_mov_b32_e32 v81, v2
	v_mov_b32_e32 v86, v2
	v_mov_b32_e32 v87, v2
	v_mov_b32_e32 v88, v2
	v_mov_b32_e32 v89, v2
	v_mov_b32_e32 v94, v2
	v_mov_b32_e32 v95, v2
	v_mov_b32_e32 v96, v2
	v_mov_b32_e32 v97, v2
	v_mov_b32_e32 v102, v2
	v_mov_b32_e32 v103, v2
	v_mov_b32_e32 v104, v2
	v_mov_b32_e32 v105, v2
	v_mov_b32_e32 v110, v2
	v_mov_b32_e32 v111, v2
	v_mov_b32_e32 v112, v2
	v_mov_b32_e32 v113, v2
	v_mov_b32_e32 v118, v2
	v_mov_b32_e32 v119, v2
	v_mov_b32_e32 v120, v2
	v_mov_b32_e32 v121, v2
	v_mov_b32_e32 v74, v2
	v_mov_b32_e32 v75, v2
	v_mov_b32_e32 v76, v2
	v_mov_b32_e32 v77, v2
	v_mov_b32_e32 v82, v2
	v_mov_b32_e32 v83, v2
	v_mov_b32_e32 v84, v2
	v_mov_b32_e32 v85, v2
	v_mov_b32_e32 v90, v2
	v_mov_b32_e32 v91, v2
	v_mov_b32_e32 v92, v2
	v_mov_b32_e32 v93, v2
	v_mov_b32_e32 v98, v2
	v_mov_b32_e32 v99, v2
	v_mov_b32_e32 v100, v2
	v_mov_b32_e32 v101, v2
	v_mov_b32_e32 v106, v2
	v_mov_b32_e32 v107, v2
	v_mov_b32_e32 v108, v2
	v_mov_b32_e32 v109, v2
	v_mov_b32_e32 v114, v2
	v_mov_b32_e32 v115, v2
	v_mov_b32_e32 v116, v2
	v_mov_b32_e32 v117, v2
	v_mov_b32_e32 v122, v2
	v_mov_b32_e32 v123, v2
	v_mov_b32_e32 v124, v2
	v_mov_b32_e32 v125, v2
	v_mov_b32_e32 v126, v2
	v_mov_b32_e32 v127, v2
	v_mov_b32_e32 v128, v2
	v_mov_b32_e32 v129, v2
	s_andn2_b64 vcc, exec, s[4:5]
	s_cbranch_vccnz .LBB0_1008
	s_branch .LBB0_1009

; #define PG8_STAGE(bufoff, gbase, voff) do { _Pragma("unroll") for (int _i = 0; _i < 2; ++_i) \
;         __builtin_amdgcn_global_load_lds((const unsigned*)((const char*)(gbase) + (voff)[_i]), (LAS unsigned*)(lds + (bufoff) + ldsw + _i * 8192), 16, 0, 0); } while (0)
; #define PG8_LDA(dst, b, h) do { _Pragma("unroll") for (int m = 0; m < 4; ++m) _Pragma("unroll") for (int k = 0; k < 2; ++k) dst[m][k] = *(const LAS bf16x8*)(lds + PG8_SA(b, h) + aoff + m * 2048 + k * 1024); } while (0)
; #define PG8_LDB(dst, b, h) do { _Pragma("unroll") for (int n = 0; n < 2; ++n) _Pragma("unroll") for (int k = 0; k < 2; ++k) dst[n][k] = *(const LAS bf16x8*)(lds + PG8_SB(b, h) + boff + n * 2048 + k * 1024); } while (0)
; #define PG8_MMA(ai, bj, At, Bt) do { __builtin_amdgcn_s_setprio(1); _Pragma("unroll") for (int m = 0; m < 4; ++m) _Pragma("unroll") for (int n = 0; n < 2; ++n) _Pragma("unroll") for (int k = 0; k < 2; ++k) \
;         acc[ai][bj][m][n] = __builtin_amdgcn_mfma_f32_16x16x32_bf16(Bt[n][k], At[m][k], acc[ai][bj][m][n], 0, 0, 0); __builtin_amdgcn_s_setprio(0); } while (0)
; #define PG8_WAIT_V(n) asm volatile("s_waitcnt vmcnt(" #n ")" ::: "memory")
; #define PG8_WAIT_L(n) asm volatile("s_waitcnt lgkmcnt(" #n ")" ::: "memory")
; #define PG8_BAR __builtin_amdgcn_s_barrier()
; #define PG8_SCHED __builtin_amdgcn_sched_barrier(0)
; template <class Epi, class Sched, bool ALIGN_EPI>
; DI void gemm_phase(LAS unsigned char* lds, const Gemm g, const Sched& S, const Epi& E) {
;     ...
;             PG8_LDB(B0, 0, 0); PG8_LDB(B1, 0, 1); PG8_SCHED; PG8_LDA(At, 0, 0); PG8_STAGE(PG8_SA(1, 1), a1 + hstepA, voffA);
;             PG8_WAIT_V(8); PG8_WAIT_L(0); PG8_BAR; PG8_MMA(0, 0, At, B0); PG8_MMA(0, 1, At, B1); PG8_BAR; PG8_SCHED;
;             PG8_LDA(At, 0, 1); PG8_STAGE(PG8_SB(0, 0), b2, voffB); PG8_STAGE(PG8_SB(0, 1), b2 + hstepB, voffB); PG8_STAGE(PG8_SA(0, 0), a2, voffA);
;             PG8_WAIT_V(8); PG8_WAIT_L(0); PG8_BAR; PG8_MMA(1, 0, At, B0); PG8_MMA(1, 1, At, B1); PG8_BAR; PG8_SCHED;
.LBB0_1113:
	ds_read_b128 v[164:167], v159
	ds_read_b128 v[168:171], v159 offset:1024
	ds_read_b128 v[172:175], v159 offset:2048
	ds_read_b128 v[176:179], v159 offset:3072
	ds_read_b128 v[180:183], v160
	ds_read_b128 v[184:187], v160 offset:1024
	ds_read_b128 v[188:191], v160 offset:2048
	ds_read_b128 v[192:195], v160 offset:3072
	s_add_u32 s24, s22, 0xfffc0080
	s_addc_u32 s25, s23, -1
	s_cmp_eq_u32 s56, 12
	s_cselect_b32 s27, s15, s25
	s_cselect_b32 s26, s52, s24
	s_cselect_b32 s25, s13, s55
	s_cselect_b32 s24, s53, s54
	v_lshl_add_u64 v[146:147], s[22:23], 0, v[138:139]
	s_add_i32 m0, s21, 0xc000
	ds_read_b128 v[196:199], v161
	ds_read_b128 v[204:207], v161 offset:1024
	ds_read_b128 v[208:211], v161 offset:2048
	ds_read_b128 v[212:215], v161 offset:3072
	ds_read_b128 v[216:219], v161 offset:4096
	ds_read_b128 v[220:223], v161 offset:5120
	ds_read_b128 v[224:227], v161 offset:6144
	ds_read_b128 v[228:231], v161 offset:7168
	global_load_lds_dwordx4 v[146:147], off
	v_lshl_add_u64 v[146:147], s[22:23], 0, v[140:141]
	s_add_i32 m0, s21, 0xe000
	s_nop 0
	global_load_lds_dwordx4 v[146:147], off
	s_waitcnt vmcnt(8)
	s_waitcnt lgkmcnt(0)
	s_barrier
	s_setprio 1
	s_waitcnt lgkmcnt(0)
	v_mfma_f32_16x16x32_bf16 v[126:129], v[164:167], v[196:199], v[126:129]
	v_mfma_f32_16x16x32_bf16 v[122:125], v[172:175], v[196:199], v[122:125]
	v_mfma_f32_16x16x32_bf16 v[110:113], v[164:167], v[208:211], v[110:113]
	v_mfma_f32_16x16x32_bf16 v[106:109], v[172:175], v[208:211], v[106:109]
	v_mfma_f32_16x16x32_bf16 v[94:97], v[164:167], v[216:219], v[94:97]
	v_mfma_f32_16x16x32_bf16 v[90:93], v[172:175], v[216:219], v[90:93]
	v_mfma_f32_16x16x32_bf16 v[78:81], v[164:167], v[224:227], v[78:81]
	v_mfma_f32_16x16x32_bf16 v[74:77], v[172:175], v[224:227], v[74:77]
	v_mfma_f32_16x16x32_bf16 v[126:129], v[168:171], v[204:207], v[126:129]
	v_mfma_f32_16x16x32_bf16 v[122:125], v[176:179], v[204:207], v[122:125]
	v_mfma_f32_16x16x32_bf16 v[110:113], v[168:171], v[212:215], v[110:113]
	v_mfma_f32_16x16x32_bf16 v[106:109], v[176:179], v[212:215], v[106:109]
	v_mfma_f32_16x16x32_bf16 v[94:97], v[168:171], v[220:223], v[94:97]
	v_mfma_f32_16x16x32_bf16 v[90:93], v[176:179], v[220:223], v[90:93]
	v_mfma_f32_16x16x32_bf16 v[78:81], v[168:171], v[228:231], v[78:81]
	v_mfma_f32_16x16x32_bf16 v[74:77], v[176:179], v[228:231], v[74:77]
	v_mfma_f32_16x16x32_bf16 v[118:121], v[180:183], v[196:199], v[118:121]
	v_mfma_f32_16x16x32_bf16 v[114:117], v[188:191], v[196:199], v[114:117]
	v_mfma_f32_16x16x32_bf16 v[102:105], v[180:183], v[208:211], v[102:105]
	v_mfma_f32_16x16x32_bf16 v[98:101], v[188:191], v[208:211], v[98:101]
	v_mfma_f32_16x16x32_bf16 v[86:89], v[180:183], v[216:219], v[86:89]
	v_mfma_f32_16x16x32_bf16 v[82:85], v[188:191], v[216:219], v[82:85]
	v_mfma_f32_16x16x32_bf16 v[70:73], v[180:183], v[224:227], v[70:73]
	v_mfma_f32_16x16x32_bf16 v[66:69], v[188:191], v[224:227], v[66:69]
	v_mfma_f32_16x16x32_bf16 v[118:121], v[184:187], v[204:207], v[118:121]
	v_mfma_f32_16x16x32_bf16 v[114:117], v[192:195], v[204:207], v[114:117]
	v_mfma_f32_16x16x32_bf16 v[102:105], v[184:187], v[212:215], v[102:105]
	v_mfma_f32_16x16x32_bf16 v[98:101], v[192:195], v[212:215], v[98:101]
	v_mfma_f32_16x16x32_bf16 v[86:89], v[184:187], v[220:223], v[86:89]
	v_mfma_f32_16x16x32_bf16 v[82:85], v[192:195], v[220:223], v[82:85]
	v_mfma_f32_16x16x32_bf16 v[70:73], v[184:187], v[228:231], v[70:73]
	v_mfma_f32_16x16x32_bf16 v[66:69], v[192:195], v[228:231], v[66:69]
	s_setprio 0
	s_barrier
	s_add_i32 s57, s74, s40
	v_lshl_add_u64 v[146:147], s[24:25], 0, v[134:135]
	s_mov_b32 m0, s57
	ds_read_b128 v[196:199], v161 offset:16384
	ds_read_b128 v[204:207], v161 offset:17408
	ds_read_b128 v[208:211], v161 offset:18432
	ds_read_b128 v[212:215], v161 offset:19456
	ds_read_b128 v[216:219], v161 offset:20480
	ds_read_b128 v[220:223], v161 offset:21504
	ds_read_b128 v[224:227], v161 offset:22528
	ds_read_b128 v[228:231], v161 offset:23552
	global_load_lds_dwordx4 v[146:147], off
	s_add_i32 m0, s57, 0x2000
	s_add_u32 s58, s24, 0x40000
	v_lshl_add_u64 v[200:201], s[24:25], 0, v[130:131]
	s_addc_u32 s59, s25, 0
	s_add_i32 s57, s75, s40
	global_load_lds_dwordx4 v[200:201], off
	v_lshl_add_u64 v[232:233], s[58:59], 0, v[134:135]
	s_mov_b32 m0, s57
	v_lshl_add_u64 v[234:235], s[26:27], 0, v[132:133]
	global_load_lds_dwordx4 v[232:233], off
	v_lshl_add_u64 v[232:233], s[58:59], 0, v[130:131]
	s_add_i32 m0, s57, 0x2000
	s_nop 0
	global_load_lds_dwordx4 v[232:233], off
	v_lshl_add_u64 v[232:233], s[26:27], 0, v[136:137]
	s_mov_b32 m0, s21
	s_nop 0
	global_load_lds_dwordx4 v[232:233], off
	s_mov_b32 m0, s43
	s_nop 0
	global_load_lds_dwordx4 v[234:235], off
	s_waitcnt vmcnt(8)
	s_waitcnt lgkmcnt(0)
	s_barrier
; #define PG8_STAGE(bufoff, gbase, voff) do { _Pragma("unroll") for (int _i = 0; _i < 2; ++_i) \
;         __builtin_amdgcn_global_load_lds((const unsigned*)((const char*)(gbase) + (voff)[_i]), (LAS unsigned*)(lds + (bufoff) + ldsw + _i * 8192), 16, 0, 0); } while (0)
; #define PG8_LDA(dst, b, h) do { _Pragma("unroll") for (int m = 0; m < 4; ++m) _Pragma("unroll") for (int k = 0; k < 2; ++k) dst[m][k] = *(const LAS bf16x8*)(lds + PG8_SA(b, h) + aoff + m * 2048 + k * 1024); } while (0)
; #define PG8_LDB(dst, b, h) do { _Pragma("unroll") for (int n = 0; n < 2; ++n) _Pragma("unroll") for (int k = 0; k < 2; ++k) dst[n][k] = *(const LAS bf16x8*)(lds + PG8_SB(b, h) + boff + n * 2048 + k * 1024); } while (0)
; #define PG8_MMA(ai, bj, At, Bt) do { __builtin_amdgcn_s_setprio(1); _Pragma("unroll") for (int m = 0; m < 4; ++m) _Pragma("unroll") for (int n = 0; n < 2; ++n) _Pragma("unroll") for (int k = 0; k < 2; ++k) \
;         acc[ai][bj][m][n] = __builtin_amdgcn_mfma_f32_16x16x32_bf16(Bt[n][k], At[m][k], acc[ai][bj][m][n], 0, 0, 0); __builtin_amdgcn_s_setprio(0); } while (0)
; #define PG8_WAIT_V(n) asm volatile("s_waitcnt vmcnt(" #n ")" ::: "memory")
; #define PG8_WAIT_L(n) asm volatile("s_waitcnt lgkmcnt(" #n ")" ::: "memory")
; #define PG8_BAR __builtin_amdgcn_s_barrier()
; #define PG8_SCHED __builtin_amdgcn_sched_barrier(0)
; template <class Epi, class Sched, bool ALIGN_EPI>
; DI void gemm_phase(LAS unsigned char* lds, const Gemm g, const Sched& S, const Epi& E) {
;     ...
;             PG8_WAIT_V(8); PG8_WAIT_L(0); PG8_BAR; PG8_MMA(1, 0, At, B0); PG8_MMA(1, 1, At, B1); PG8_BAR; PG8_SCHED;
;             PG8_LDB(B0, 1, 0); PG8_LDB(B1, 1, 1); PG8_SCHED; PG8_LDA(At, 1, 0); PG8_STAGE(PG8_SA(0, 1), a2 + hstepA, voffA);
;             PG8_WAIT_V(8); PG8_WAIT_L(0); PG8_BAR; PG8_MMA(0, 0, At, B0); PG8_MMA(0, 1, At, B1); PG8_BAR; PG8_SCHED;
	s_setprio 1
	s_waitcnt lgkmcnt(0)
	v_mfma_f32_16x16x32_bf16 v[62:65], v[164:167], v[196:199], v[62:65]
	v_mfma_f32_16x16x32_bf16 v[58:61], v[172:175], v[196:199], v[58:61]
	v_mfma_f32_16x16x32_bf16 v[46:49], v[164:167], v[208:211], v[46:49]
	v_mfma_f32_16x16x32_bf16 v[42:45], v[172:175], v[208:211], v[42:45]
	v_mfma_f32_16x16x32_bf16 v[30:33], v[164:167], v[216:219], v[30:33]
	v_mfma_f32_16x16x32_bf16 v[26:29], v[172:175], v[216:219], v[26:29]
	v_mfma_f32_16x16x32_bf16 v[14:17], v[164:167], v[224:227], v[14:17]
	v_mfma_f32_16x16x32_bf16 v[10:13], v[172:175], v[224:227], v[10:13]
	v_mfma_f32_16x16x32_bf16 v[62:65], v[168:171], v[204:207], v[62:65]
	v_mfma_f32_16x16x32_bf16 v[58:61], v[176:179], v[204:207], v[58:61]
	v_mfma_f32_16x16x32_bf16 v[46:49], v[168:171], v[212:215], v[46:49]
	v_mfma_f32_16x16x32_bf16 v[42:45], v[176:179], v[212:215], v[42:45]
	v_mfma_f32_16x16x32_bf16 v[30:33], v[168:171], v[220:223], v[30:33]
	v_mfma_f32_16x16x32_bf16 v[26:29], v[176:179], v[220:223], v[26:29]
	v_mfma_f32_16x16x32_bf16 v[14:17], v[168:171], v[228:231], v[14:17]
	v_mfma_f32_16x16x32_bf16 v[10:13], v[176:179], v[228:231], v[10:13]
	v_mfma_f32_16x16x32_bf16 v[54:57], v[180:183], v[196:199], v[54:57]
	v_mfma_f32_16x16x32_bf16 v[50:53], v[188:191], v[196:199], v[50:53]
	v_mfma_f32_16x16x32_bf16 v[38:41], v[180:183], v[208:211], v[38:41]
	v_mfma_f32_16x16x32_bf16 v[34:37], v[188:191], v[208:211], v[34:37]
	v_mfma_f32_16x16x32_bf16 v[22:25], v[180:183], v[216:219], v[22:25]
	v_mfma_f32_16x16x32_bf16 v[18:21], v[188:191], v[216:219], v[18:21]
	v_mfma_f32_16x16x32_bf16 v[6:9], v[180:183], v[224:227], v[6:9]
	v_mfma_f32_16x16x32_bf16 v[2:5], v[188:191], v[224:227], v[2:5]
	v_mfma_f32_16x16x32_bf16 v[54:57], v[184:187], v[204:207], v[54:57]
	v_mfma_f32_16x16x32_bf16 v[50:53], v[192:195], v[204:207], v[50:53]
	v_mfma_f32_16x16x32_bf16 v[38:41], v[184:187], v[212:215], v[38:41]
	v_mfma_f32_16x16x32_bf16 v[34:37], v[192:195], v[212:215], v[34:37]
	v_mfma_f32_16x16x32_bf16 v[22:25], v[184:187], v[220:223], v[22:25]
	v_mfma_f32_16x16x32_bf16 v[18:21], v[192:195], v[220:223], v[18:21]
	v_mfma_f32_16x16x32_bf16 v[6:9], v[184:187], v[228:231], v[6:9]
	v_mfma_f32_16x16x32_bf16 v[2:5], v[192:195], v[228:231], v[2:5]
	s_setprio 0
	s_barrier
	ds_read_b128 v[164:167], v162
	ds_read_b128 v[168:171], v162 offset:1024
	ds_read_b128 v[172:175], v162 offset:2048
	ds_read_b128 v[176:179], v162 offset:3072
	ds_read_b128 v[180:183], v163
	ds_read_b128 v[184:187], v163 offset:1024
	ds_read_b128 v[188:191], v163 offset:2048
	ds_read_b128 v[192:195], v163 offset:3072
	s_add_u32 s26, s26, 0x40000
	s_addc_u32 s27, s27, 0
	s_mov_b32 m0, s44
	v_lshl_add_u64 v[236:237], s[26:27], 0, v[136:137]
	ds_read_b128 v[196:199], v161 offset:32768
	ds_read_b128 v[204:207], v161 offset:33792
	ds_read_b128 v[208:211], v161 offset:34816
	ds_read_b128 v[212:215], v161 offset:35840
	ds_read_b128 v[216:219], v161 offset:36864
	ds_read_b128 v[220:223], v161 offset:37888
	ds_read_b128 v[224:227], v161 offset:38912
	ds_read_b128 v[228:231], v161 offset:39936
	global_load_lds_dwordx4 v[236:237], off
	v_lshl_add_u64 v[236:237], s[26:27], 0, v[132:133]
	s_mov_b32 m0, s45
	s_nop 0
	global_load_lds_dwordx4 v[236:237], off
	s_waitcnt vmcnt(8)
	s_waitcnt lgkmcnt(0)
	s_barrier
	s_setprio 1
	s_waitcnt lgkmcnt(0)
	v_mfma_f32_16x16x32_bf16 v[126:129], v[164:167], v[196:199], v[126:129]
	v_mfma_f32_16x16x32_bf16 v[122:125], v[172:175], v[196:199], v[122:125]
	v_mfma_f32_16x16x32_bf16 v[110:113], v[164:167], v[208:211], v[110:113]
	v_mfma_f32_16x16x32_bf16 v[106:109], v[172:175], v[208:211], v[106:109]
	v_mfma_f32_16x16x32_bf16 v[94:97], v[164:167], v[216:219], v[94:97]
	v_mfma_f32_16x16x32_bf16 v[90:93], v[172:175], v[216:219], v[90:93]
	v_mfma_f32_16x16x32_bf16 v[78:81], v[164:167], v[224:227], v[78:81]
	v_mfma_f32_16x16x32_bf16 v[74:77], v[172:175], v[224:227], v[74:77]
	v_mfma_f32_16x16x32_bf16 v[126:129], v[168:171], v[204:207], v[126:129]
	v_mfma_f32_16x16x32_bf16 v[122:125], v[176:179], v[204:207], v[122:125]
	v_mfma_f32_16x16x32_bf16 v[110:113], v[168:171], v[212:215], v[110:113]
	v_mfma_f32_16x16x32_bf16 v[106:109], v[176:179], v[212:215], v[106:109]
	v_mfma_f32_16x16x32_bf16 v[94:97], v[168:171], v[220:223], v[94:97]
	v_mfma_f32_16x16x32_bf16 v[90:93], v[176:179], v[220:223], v[90:93]
	v_mfma_f32_16x16x32_bf16 v[78:81], v[168:171], v[228:231], v[78:81]
	v_mfma_f32_16x16x32_bf16 v[74:77], v[176:179], v[228:231], v[74:77]
	v_mfma_f32_16x16x32_bf16 v[118:121], v[180:183], v[196:199], v[118:121]
	v_mfma_f32_16x16x32_bf16 v[114:117], v[188:191], v[196:199], v[114:117]
	v_mfma_f32_16x16x32_bf16 v[102:105], v[180:183], v[208:211], v[102:105]
	v_mfma_f32_16x16x32_bf16 v[98:101], v[188:191], v[208:211], v[98:101]
	v_mfma_f32_16x16x32_bf16 v[86:89], v[180:183], v[216:219], v[86:89]
	v_mfma_f32_16x16x32_bf16 v[82:85], v[188:191], v[216:219], v[82:85]
	v_mfma_f32_16x16x32_bf16 v[70:73], v[180:183], v[224:227], v[70:73]
	v_mfma_f32_16x16x32_bf16 v[66:69], v[188:191], v[224:227], v[66:69]
	v_mfma_f32_16x16x32_bf16 v[118:121], v[184:187], v[204:207], v[118:121]
	v_mfma_f32_16x16x32_bf16 v[114:117], v[192:195], v[204:207], v[114:117]
	v_mfma_f32_16x16x32_bf16 v[102:105], v[184:187], v[212:215], v[102:105]
	v_mfma_f32_16x16x32_bf16 v[98:101], v[192:195], v[212:215], v[98:101]
	v_mfma_f32_16x16x32_bf16 v[86:89], v[184:187], v[220:223], v[86:89]
	v_mfma_f32_16x16x32_bf16 v[82:85], v[192:195], v[220:223], v[82:85]
	v_mfma_f32_16x16x32_bf16 v[70:73], v[184:187], v[228:231], v[70:73]
	v_mfma_f32_16x16x32_bf16 v[66:69], v[192:195], v[228:231], v[66:69]
	s_setprio 0
	s_barrier
; #define PG8_STAGE(bufoff, gbase, voff) do { _Pragma("unroll") for (int _i = 0; _i < 2; ++_i) \
;         __builtin_amdgcn_global_load_lds((const unsigned*)((const char*)(gbase) + (voff)[_i]), (LAS unsigned*)(lds + (bufoff) + ldsw + _i * 8192), 16, 0, 0); } while (0)
; #define PG8_LDA(dst, b, h) do { _Pragma("unroll") for (int m = 0; m < 4; ++m) _Pragma("unroll") for (int k = 0; k < 2; ++k) dst[m][k] = *(const LAS bf16x8*)(lds + PG8_SA(b, h) + aoff + m * 2048 + k * 1024); } while (0)
; #define PG8_MMA(ai, bj, At, Bt) do { __builtin_amdgcn_s_setprio(1); _Pragma("unroll") for (int m = 0; m < 4; ++m) _Pragma("unroll") for (int n = 0; n < 2; ++n) _Pragma("unroll") for (int k = 0; k < 2; ++k) \
;         acc[ai][bj][m][n] = __builtin_amdgcn_mfma_f32_16x16x32_bf16(Bt[n][k], At[m][k], acc[ai][bj][m][n], 0, 0, 0); __builtin_amdgcn_s_setprio(0); } while (0)
; #define PG8_WAIT_V(n) asm volatile("s_waitcnt vmcnt(" #n ")" ::: "memory")
; #define PG8_WAIT_L(n) asm volatile("s_waitcnt lgkmcnt(" #n ")" ::: "memory")
; #define PG8_BAR __builtin_amdgcn_s_barrier()
; #define PG8_SCHED __builtin_amdgcn_sched_barrier(0)
; template <class Epi, class Sched, bool ALIGN_EPI>
; DI void gemm_phase(LAS unsigned char* lds, const Gemm g, const Sched& S, const Epi& E) {
;     ...
;             PG8_LDA(At, 1, 1); PG8_STAGE(PG8_SB(1, 0), b3, voffB); PG8_STAGE(PG8_SB(1, 1), b3 + hstepB, voffB); PG8_STAGE(PG8_SA(1, 0), a3, voffA);
;             PG8_WAIT_V(8); PG8_WAIT_L(0); PG8_BAR; PG8_MMA(1, 0, At, B0); PG8_MMA(1, 1, At, B1); PG8_BAR; PG8_SCHED;
;         }
;         if constexpr (ALIGN_EPI) { if (wr == 0) PG8_BAR; }
	s_add_i32 s26, s77, s40
	v_lshl_add_u64 v[146:147], v[146:147], 0, s[8:9]
	s_mov_b32 m0, s26
	ds_read_b128 v[196:199], v161 offset:49152
	ds_read_b128 v[204:207], v161 offset:50176
	ds_read_b128 v[208:211], v161 offset:51200
	ds_read_b128 v[212:215], v161 offset:52224
	ds_read_b128 v[216:219], v161 offset:53248
	ds_read_b128 v[220:223], v161 offset:54272
	ds_read_b128 v[224:227], v161 offset:55296
	ds_read_b128 v[228:231], v161 offset:56320
	global_load_lds_dwordx4 v[146:147], off
	s_add_i32 m0, s26, 0x2000
	s_add_u32 s24, s24, 0x40080
	v_lshl_add_u64 v[146:147], v[200:201], 0, s[8:9]
	s_addc_u32 s25, s25, 0
	s_add_i32 s26, s78, s40
	global_load_lds_dwordx4 v[146:147], off
	v_lshl_add_u64 v[146:147], s[24:25], 0, v[134:135]
	s_mov_b32 m0, s26
	s_nop 0
	global_load_lds_dwordx4 v[146:147], off
	v_lshl_add_u64 v[146:147], s[24:25], 0, v[130:131]
	s_add_i32 m0, s26, 0x2000
	s_nop 0
	global_load_lds_dwordx4 v[146:147], off
	v_lshl_add_u64 v[146:147], v[232:233], 0, s[8:9]
	s_mov_b32 m0, s69
	s_nop 0
	global_load_lds_dwordx4 v[146:147], off
	v_lshl_add_u64 v[146:147], v[234:235], 0, s[8:9]
	s_mov_b32 m0, s71
	s_nop 0
	global_load_lds_dwordx4 v[146:147], off
	s_waitcnt vmcnt(8)
	s_waitcnt lgkmcnt(0)
	s_barrier
	s_setprio 1
	s_waitcnt lgkmcnt(0)
	v_mfma_f32_16x16x32_bf16 v[62:65], v[164:167], v[196:199], v[62:65]
	v_mfma_f32_16x16x32_bf16 v[58:61], v[172:175], v[196:199], v[58:61]
	v_mfma_f32_16x16x32_bf16 v[46:49], v[164:167], v[208:211], v[46:49]
	v_mfma_f32_16x16x32_bf16 v[42:45], v[172:175], v[208:211], v[42:45]
	v_mfma_f32_16x16x32_bf16 v[30:33], v[164:167], v[216:219], v[30:33]
	v_mfma_f32_16x16x32_bf16 v[26:29], v[172:175], v[216:219], v[26:29]
	v_mfma_f32_16x16x32_bf16 v[14:17], v[164:167], v[224:227], v[14:17]
	v_mfma_f32_16x16x32_bf16 v[10:13], v[172:175], v[224:227], v[10:13]
	v_mfma_f32_16x16x32_bf16 v[62:65], v[168:171], v[204:207], v[62:65]
	v_mfma_f32_16x16x32_bf16 v[58:61], v[176:179], v[204:207], v[58:61]
	v_mfma_f32_16x16x32_bf16 v[46:49], v[168:171], v[212:215], v[46:49]
	v_mfma_f32_16x16x32_bf16 v[42:45], v[176:179], v[212:215], v[42:45]
	v_mfma_f32_16x16x32_bf16 v[30:33], v[168:171], v[220:223], v[30:33]
	v_mfma_f32_16x16x32_bf16 v[26:29], v[176:179], v[220:223], v[26:29]
	v_mfma_f32_16x16x32_bf16 v[14:17], v[168:171], v[228:231], v[14:17]
	v_mfma_f32_16x16x32_bf16 v[10:13], v[176:179], v[228:231], v[10:13]
	v_mfma_f32_16x16x32_bf16 v[54:57], v[180:183], v[196:199], v[54:57]
	v_mfma_f32_16x16x32_bf16 v[50:53], v[188:191], v[196:199], v[50:53]
	v_mfma_f32_16x16x32_bf16 v[38:41], v[180:183], v[208:211], v[38:41]
	v_mfma_f32_16x16x32_bf16 v[34:37], v[188:191], v[208:211], v[34:37]
	v_mfma_f32_16x16x32_bf16 v[22:25], v[180:183], v[216:219], v[22:25]
	v_mfma_f32_16x16x32_bf16 v[18:21], v[188:191], v[216:219], v[18:21]
	v_mfma_f32_16x16x32_bf16 v[6:9], v[180:183], v[224:227], v[6:9]
	v_mfma_f32_16x16x32_bf16 v[2:5], v[188:191], v[224:227], v[2:5]
	v_mfma_f32_16x16x32_bf16 v[54:57], v[184:187], v[204:207], v[54:57]
	v_mfma_f32_16x16x32_bf16 v[50:53], v[192:195], v[204:207], v[50:53]
	v_mfma_f32_16x16x32_bf16 v[38:41], v[184:187], v[212:215], v[38:41]
	v_mfma_f32_16x16x32_bf16 v[34:37], v[192:195], v[212:215], v[34:37]
	v_mfma_f32_16x16x32_bf16 v[22:25], v[184:187], v[220:223], v[22:25]
	v_mfma_f32_16x16x32_bf16 v[18:21], v[192:195], v[220:223], v[18:21]
	v_mfma_f32_16x16x32_bf16 v[6:9], v[184:187], v[228:231], v[6:9]
	v_mfma_f32_16x16x32_bf16 v[2:5], v[192:195], v[228:231], v[2:5]
	s_setprio 0
	s_barrier
	s_add_i32 s56, s56, 2
	s_add_u32 s22, s22, 0x100
	s_addc_u32 s23, s23, 0
	s_add_u32 s54, s54, 0x100
	s_addc_u32 s55, s55, 0
	s_cmp_gt_u32 s56, 13
	s_cbranch_scc0 .LBB0_1113
	s_and_b64 vcc, exec, s[10:11]
	s_cbranch_vccz .LBB0_1116
	s_barrier

; #define PG8_STAGE(bufoff, gbase, voff) do { _Pragma("unroll") for (int _i = 0; _i < 2; ++_i) \
;         __builtin_amdgcn_global_load_lds((const unsigned*)((const char*)(gbase) + (voff)[_i]), (LAS unsigned*)(lds + (bufoff) + ldsw + _i * 8192), 16, 0, 0); } while (0)
; #define PG8_LDA(dst, b, h) do { _Pragma("unroll") for (int m = 0; m < 4; ++m) _Pragma("unroll") for (int k = 0; k < 2; ++k) dst[m][k] = *(const LAS bf16x8*)(lds + PG8_SA(b, h) + aoff + m * 2048 + k * 1024); } while (0)
; #define PG8_LDB(dst, b, h) do { _Pragma("unroll") for (int n = 0; n < 2; ++n) _Pragma("unroll") for (int k = 0; k < 2; ++k) dst[n][k] = *(const LAS bf16x8*)(lds + PG8_SB(b, h) + boff + n * 2048 + k * 1024); } while (0)
; #define PG8_MMA(ai, bj, At, Bt) do { __builtin_amdgcn_s_setprio(1); _Pragma("unroll") for (int m = 0; m < 4; ++m) _Pragma("unroll") for (int n = 0; n < 2; ++n) _Pragma("unroll") for (int k = 0; k < 2; ++k) \
;         acc[ai][bj][m][n] = __builtin_amdgcn_mfma_f32_16x16x32_bf16(Bt[n][k], At[m][k], acc[ai][bj][m][n], 0, 0, 0); __builtin_amdgcn_s_setprio(0); } while (0)
; #define PG8_WAIT_V(n) asm volatile("s_waitcnt vmcnt(" #n ")" ::: "memory")
; #define PG8_BAR __builtin_amdgcn_s_barrier()
; template <class Epi, class Sched, bool ALIGN_EPI>
; DI void gemm_phase(LAS unsigned char* lds, const Gemm g, const Sched& S, const Epi& E) {
;     ...
;         const char* nA = has_next ? (const char*)g.A + (size_t)nxt.pm * tstepA : cA; const char* nB = has_next ? (const char*)g.Bt + (size_t)nxt.pn * tstepB : cB;
;         for (int t = 0; t < nt; t += 2) {
;             const bool last = (t == nt - 2);
;             const char* a1 = cA + (size_t)(t + 1) * kstep;
;             const char* a2 = last ? nA : cA + (size_t)(t + 2) * kstep; const char* b2 = last ? nB : cB + (size_t)(t + 2) * kstep;
;             const char* a3 = a2 + kstep; const char* b3 = b2 + kstep;
;             PG8_LDB(B0, 0, 0); PG8_LDB(B1, 0, 1); PG8_SCHED; PG8_LDA(At, 0, 0); PG8_STAGE(PG8_SA(1, 1), a1 + hstepA, voffA);
;             PG8_WAIT_V(8); PG8_WAIT_L(0); PG8_BAR; PG8_MMA(0, 0, At, B0); PG8_MMA(0, 1, At, B1); PG8_BAR; PG8_SCHED;
;             PG8_LDA(At, 0, 1); PG8_STAGE(PG8_SB(0, 0), b2, voffB); PG8_STAGE(PG8_SB(0, 1), b2 + hstepB, voffB); PG8_STAGE(PG8_SA(0, 0), a2, voffA);
;             PG8_WAIT_V(8); PG8_WAIT_L(0); PG8_BAR; PG8_MMA(1, 0, At, B0); PG8_MMA(1, 1, At, B1); PG8_BAR; PG8_SCHED;
.LBB0_1140:
	s_add_u32 s37, s16, s36
	s_addc_u32 s44, s17, 0
	s_add_u32 s42, s37, 0x100
	s_addc_u32 s43, s44, 0
	s_and_b64 s[40:41], s[28:29], exec
	s_cselect_b32 s41, s21, s43
	s_cselect_b32 s40, s52, s42
	s_add_u32 s36, s14, s36
	s_addc_u32 s42, s15, 0
	s_add_u32 s36, s36, 0x100
	s_addc_u32 s42, s42, 0
	s_and_b64 s[28:29], s[28:29], exec
	s_cselect_b32 s43, s19, s42
	s_cselect_b32 s42, s53, s36
	s_add_u32 s68, s37, 0x10080
	ds_read_b128 v[158:161], v144
	ds_read_b128 v[162:165], v144 offset:1024
	ds_read_b128 v[166:169], v144 offset:2048
	ds_read_b128 v[170:173], v144 offset:3072
	ds_read_b128 v[174:177], v145
	ds_read_b128 v[178:181], v145 offset:1024
	ds_read_b128 v[182:185], v145 offset:2048
	ds_read_b128 v[186:189], v145 offset:3072
	s_addc_u32 s69, s44, 0
	s_add_i32 s61, s85, s76
	s_add_i32 m0, s13, 0xc000
	s_add_i32 s62, s13, 0xe000
	s_add_i32 s58, s61, 0x2000
	s_add_u32 s44, s42, 0x10000
	s_addc_u32 s45, s43, 0
	s_add_i32 s60, s95, s76
	s_add_i32 s59, s60, 0x2000
	s_add_u32 s36, s40, 0x10000
	s_addc_u32 s37, s41, 0
	s_add_i32 s57, s96, s76
	s_add_i32 s55, s57, 0x2000
	s_add_u32 s28, s42, 0x10080
	s_addc_u32 s29, s43, 0
	s_add_i32 s56, s97, s76
	s_add_i32 s54, s56, 0x2000
	v_lshl_add_u64 v[224:225], s[68:69], 0, v[130:131]
	ds_read_b128 v[190:193], v146
	ds_read_b128 v[194:197], v146 offset:1024
	ds_read_b128 v[198:201], v146 offset:2048
	ds_read_b128 v[204:207], v146 offset:3072
	ds_read_b128 v[208:211], v146 offset:4096
	ds_read_b128 v[212:215], v146 offset:5120
	ds_read_b128 v[216:219], v146 offset:6144
	ds_read_b128 v[220:223], v146 offset:7168
	global_load_lds_dwordx4 v[224:225], off
	v_lshl_add_u64 v[224:225], s[68:69], 0, v[134:135]
	s_mov_b32 m0, s62
	s_nop 0
	global_load_lds_dwordx4 v[224:225], off
	s_waitcnt vmcnt(8)
	s_waitcnt lgkmcnt(0)
	s_barrier
	s_setprio 1
	s_waitcnt lgkmcnt(0)
	v_mfma_f32_16x16x32_bf16 v[126:129], v[158:161], v[190:193], v[126:129]
	v_mfma_f32_16x16x32_bf16 v[122:125], v[166:169], v[190:193], v[122:125]
	v_mfma_f32_16x16x32_bf16 v[118:121], v[158:161], v[198:201], v[118:121]
	v_mfma_f32_16x16x32_bf16 v[114:117], v[166:169], v[198:201], v[114:117]
	v_mfma_f32_16x16x32_bf16 v[102:105], v[158:161], v[208:211], v[102:105]
	v_mfma_f32_16x16x32_bf16 v[98:101], v[166:169], v[208:211], v[98:101]
	v_mfma_f32_16x16x32_bf16 v[86:89], v[158:161], v[216:219], v[86:89]
	v_mfma_f32_16x16x32_bf16 v[82:85], v[166:169], v[216:219], v[82:85]
	v_mfma_f32_16x16x32_bf16 v[126:129], v[162:165], v[194:197], v[126:129]
	v_mfma_f32_16x16x32_bf16 v[122:125], v[170:173], v[194:197], v[122:125]
	v_mfma_f32_16x16x32_bf16 v[118:121], v[162:165], v[204:207], v[118:121]
	v_mfma_f32_16x16x32_bf16 v[114:117], v[170:173], v[204:207], v[114:117]
	v_mfma_f32_16x16x32_bf16 v[102:105], v[162:165], v[212:215], v[102:105]
	v_mfma_f32_16x16x32_bf16 v[98:101], v[170:173], v[212:215], v[98:101]
	v_mfma_f32_16x16x32_bf16 v[86:89], v[162:165], v[220:223], v[86:89]
	v_mfma_f32_16x16x32_bf16 v[82:85], v[170:173], v[220:223], v[82:85]
	v_mfma_f32_16x16x32_bf16 v[110:113], v[174:177], v[190:193], v[110:113]
	v_mfma_f32_16x16x32_bf16 v[106:109], v[182:185], v[190:193], v[106:109]
	v_mfma_f32_16x16x32_bf16 v[94:97], v[174:177], v[198:201], v[94:97]
	v_mfma_f32_16x16x32_bf16 v[90:93], v[182:185], v[198:201], v[90:93]
	v_mfma_f32_16x16x32_bf16 v[78:81], v[174:177], v[208:211], v[78:81]
	v_mfma_f32_16x16x32_bf16 v[74:77], v[182:185], v[208:211], v[74:77]
	v_mfma_f32_16x16x32_bf16 v[70:73], v[174:177], v[216:219], v[70:73]
	v_mfma_f32_16x16x32_bf16 v[66:69], v[182:185], v[216:219], v[66:69]
	v_mfma_f32_16x16x32_bf16 v[110:113], v[178:181], v[194:197], v[110:113]
	v_mfma_f32_16x16x32_bf16 v[106:109], v[186:189], v[194:197], v[106:109]
	v_mfma_f32_16x16x32_bf16 v[94:97], v[178:181], v[204:207], v[94:97]
	v_mfma_f32_16x16x32_bf16 v[90:93], v[186:189], v[204:207], v[90:93]
	v_mfma_f32_16x16x32_bf16 v[78:81], v[178:181], v[212:215], v[78:81]
	v_mfma_f32_16x16x32_bf16 v[74:77], v[186:189], v[212:215], v[74:77]
	v_mfma_f32_16x16x32_bf16 v[70:73], v[178:181], v[220:223], v[70:73]
	v_mfma_f32_16x16x32_bf16 v[66:69], v[186:189], v[220:223], v[66:69]
	s_setprio 0
	s_barrier
	s_mov_b32 m0, s61
	v_lshl_add_u64 v[224:225], s[42:43], 0, v[132:133]
	ds_read_b128 v[190:193], v146 offset:16384
	ds_read_b128 v[194:197], v146 offset:17408
	ds_read_b128 v[198:201], v146 offset:18432
	ds_read_b128 v[204:207], v146 offset:19456
	ds_read_b128 v[208:211], v146 offset:20480
	ds_read_b128 v[212:215], v146 offset:21504
	ds_read_b128 v[216:219], v146 offset:22528
	ds_read_b128 v[220:223], v146 offset:23552
	global_load_lds_dwordx4 v[224:225], off
	v_lshl_add_u64 v[226:227], s[42:43], 0, v[136:137]
	s_mov_b32 m0, s58
	v_lshl_add_u64 v[228:229], s[44:45], 0, v[132:133]
	global_load_lds_dwordx4 v[226:227], off
	s_mov_b32 m0, s60
	v_lshl_add_u64 v[230:231], s[40:41], 0, v[134:135]
	global_load_lds_dwordx4 v[228:229], off
	v_lshl_add_u64 v[228:229], s[44:45], 0, v[136:137]
	s_mov_b32 m0, s59
	s_nop 0
	global_load_lds_dwordx4 v[228:229], off
	v_lshl_add_u64 v[228:229], s[40:41], 0, v[130:131]
	s_mov_b32 m0, s13
	s_nop 0
	global_load_lds_dwordx4 v[228:229], off
	s_mov_b32 m0, s77
	s_nop 0
	global_load_lds_dwordx4 v[230:231], off
	s_waitcnt vmcnt(8)
	s_waitcnt lgkmcnt(0)
	s_barrier
; #define PG8_STAGE(bufoff, gbase, voff) do { _Pragma("unroll") for (int _i = 0; _i < 2; ++_i) \
;         __builtin_amdgcn_global_load_lds((const unsigned*)((const char*)(gbase) + (voff)[_i]), (LAS unsigned*)(lds + (bufoff) + ldsw + _i * 8192), 16, 0, 0); } while (0)
; #define PG8_LDA(dst, b, h) do { _Pragma("unroll") for (int m = 0; m < 4; ++m) _Pragma("unroll") for (int k = 0; k < 2; ++k) dst[m][k] = *(const LAS bf16x8*)(lds + PG8_SA(b, h) + aoff + m * 2048 + k * 1024); } while (0)
; #define PG8_LDB(dst, b, h) do { _Pragma("unroll") for (int n = 0; n < 2; ++n) _Pragma("unroll") for (int k = 0; k < 2; ++k) dst[n][k] = *(const LAS bf16x8*)(lds + PG8_SB(b, h) + boff + n * 2048 + k * 1024); } while (0)
; #define PG8_MMA(ai, bj, At, Bt) do { __builtin_amdgcn_s_setprio(1); _Pragma("unroll") for (int m = 0; m < 4; ++m) _Pragma("unroll") for (int n = 0; n < 2; ++n) _Pragma("unroll") for (int k = 0; k < 2; ++k) \
;         acc[ai][bj][m][n] = __builtin_amdgcn_mfma_f32_16x16x32_bf16(Bt[n][k], At[m][k], acc[ai][bj][m][n], 0, 0, 0); __builtin_amdgcn_s_setprio(0); } while (0)
; #define PG8_WAIT_V(n) asm volatile("s_waitcnt vmcnt(" #n ")" ::: "memory")
; #define PG8_WAIT_L(n) asm volatile("s_waitcnt lgkmcnt(" #n ")" ::: "memory")
; #define PG8_BAR __builtin_amdgcn_s_barrier()
; #define PG8_SCHED __builtin_amdgcn_sched_barrier(0)
; template <class Epi, class Sched, bool ALIGN_EPI>
; DI void gemm_phase(LAS unsigned char* lds, const Gemm g, const Sched& S, const Epi& E) {
;     ...
;             PG8_WAIT_V(8); PG8_WAIT_L(0); PG8_BAR; PG8_MMA(1, 0, At, B0); PG8_MMA(1, 1, At, B1); PG8_BAR; PG8_SCHED;
;             PG8_LDB(B0, 1, 0); PG8_LDB(B1, 1, 1); PG8_SCHED; PG8_LDA(At, 1, 0); PG8_STAGE(PG8_SA(0, 1), a2 + hstepA, voffA);
;             PG8_WAIT_V(8); PG8_WAIT_L(0); PG8_BAR; PG8_MMA(0, 0, At, B0); PG8_MMA(0, 1, At, B1); PG8_BAR; PG8_SCHED;
	s_setprio 1
	s_waitcnt lgkmcnt(0)
	v_mfma_f32_16x16x32_bf16 v[62:65], v[158:161], v[190:193], v[62:65]
	v_mfma_f32_16x16x32_bf16 v[58:61], v[166:169], v[190:193], v[58:61]
	v_mfma_f32_16x16x32_bf16 v[54:57], v[158:161], v[198:201], v[54:57]
	v_mfma_f32_16x16x32_bf16 v[50:53], v[166:169], v[198:201], v[50:53]
	v_mfma_f32_16x16x32_bf16 v[38:41], v[158:161], v[208:211], v[38:41]
	v_mfma_f32_16x16x32_bf16 v[34:37], v[166:169], v[208:211], v[34:37]
	v_mfma_f32_16x16x32_bf16 v[22:25], v[158:161], v[216:219], v[22:25]
	v_mfma_f32_16x16x32_bf16 v[18:21], v[166:169], v[216:219], v[18:21]
	v_mfma_f32_16x16x32_bf16 v[62:65], v[162:165], v[194:197], v[62:65]
	v_mfma_f32_16x16x32_bf16 v[58:61], v[170:173], v[194:197], v[58:61]
	v_mfma_f32_16x16x32_bf16 v[54:57], v[162:165], v[204:207], v[54:57]
	v_mfma_f32_16x16x32_bf16 v[50:53], v[170:173], v[204:207], v[50:53]
	v_mfma_f32_16x16x32_bf16 v[38:41], v[162:165], v[212:215], v[38:41]
	v_mfma_f32_16x16x32_bf16 v[34:37], v[170:173], v[212:215], v[34:37]
	v_mfma_f32_16x16x32_bf16 v[22:25], v[162:165], v[220:223], v[22:25]
	v_mfma_f32_16x16x32_bf16 v[18:21], v[170:173], v[220:223], v[18:21]
	v_mfma_f32_16x16x32_bf16 v[46:49], v[174:177], v[190:193], v[46:49]
	v_mfma_f32_16x16x32_bf16 v[42:45], v[182:185], v[190:193], v[42:45]
	v_mfma_f32_16x16x32_bf16 v[30:33], v[174:177], v[198:201], v[30:33]
	v_mfma_f32_16x16x32_bf16 v[26:29], v[182:185], v[198:201], v[26:29]
	v_mfma_f32_16x16x32_bf16 v[14:17], v[174:177], v[208:211], v[14:17]
	v_mfma_f32_16x16x32_bf16 v[10:13], v[182:185], v[208:211], v[10:13]
	v_mfma_f32_16x16x32_bf16 v[6:9], v[174:177], v[216:219], v[6:9]
	v_mfma_f32_16x16x32_bf16 v[2:5], v[182:185], v[216:219], v[2:5]
	v_mfma_f32_16x16x32_bf16 v[46:49], v[178:181], v[194:197], v[46:49]
	v_mfma_f32_16x16x32_bf16 v[42:45], v[186:189], v[194:197], v[42:45]
	v_mfma_f32_16x16x32_bf16 v[30:33], v[178:181], v[204:207], v[30:33]
	v_mfma_f32_16x16x32_bf16 v[26:29], v[186:189], v[204:207], v[26:29]
	v_mfma_f32_16x16x32_bf16 v[14:17], v[178:181], v[212:215], v[14:17]
	v_mfma_f32_16x16x32_bf16 v[10:13], v[186:189], v[212:215], v[10:13]
	v_mfma_f32_16x16x32_bf16 v[6:9], v[178:181], v[220:223], v[6:9]
	v_mfma_f32_16x16x32_bf16 v[2:5], v[186:189], v[220:223], v[2:5]
	s_setprio 0
	s_barrier
	ds_read_b128 v[158:161], v147
	ds_read_b128 v[162:165], v147 offset:1024
	ds_read_b128 v[166:169], v147 offset:2048
	ds_read_b128 v[170:173], v147 offset:3072
	ds_read_b128 v[174:177], v157
	ds_read_b128 v[178:181], v157 offset:1024
	ds_read_b128 v[182:185], v157 offset:2048
	ds_read_b128 v[186:189], v157 offset:3072
	s_mov_b32 m0, s78
	v_lshl_add_u64 v[232:233], s[36:37], 0, v[130:131]
	ds_read_b128 v[190:193], v146 offset:32768
	ds_read_b128 v[194:197], v146 offset:33792
	ds_read_b128 v[198:201], v146 offset:34816
	ds_read_b128 v[204:207], v146 offset:35840
	ds_read_b128 v[208:211], v146 offset:36864
	ds_read_b128 v[212:215], v146 offset:37888
	ds_read_b128 v[216:219], v146 offset:38912
	ds_read_b128 v[220:223], v146 offset:39936
	global_load_lds_dwordx4 v[232:233], off
	v_lshl_add_u64 v[232:233], s[36:37], 0, v[134:135]
	s_mov_b32 m0, s79
	s_nop 0
	global_load_lds_dwordx4 v[232:233], off
	s_waitcnt vmcnt(8)
	s_waitcnt lgkmcnt(0)
	s_barrier
	s_setprio 1
	s_waitcnt lgkmcnt(0)
	v_mfma_f32_16x16x32_bf16 v[126:129], v[158:161], v[190:193], v[126:129]
	v_mfma_f32_16x16x32_bf16 v[122:125], v[166:169], v[190:193], v[122:125]
	v_mfma_f32_16x16x32_bf16 v[118:121], v[158:161], v[198:201], v[118:121]
	v_mfma_f32_16x16x32_bf16 v[114:117], v[166:169], v[198:201], v[114:117]
	v_mfma_f32_16x16x32_bf16 v[102:105], v[158:161], v[208:211], v[102:105]
	v_mfma_f32_16x16x32_bf16 v[98:101], v[166:169], v[208:211], v[98:101]
	v_mfma_f32_16x16x32_bf16 v[86:89], v[158:161], v[216:219], v[86:89]
	v_mfma_f32_16x16x32_bf16 v[82:85], v[166:169], v[216:219], v[82:85]
	v_mfma_f32_16x16x32_bf16 v[126:129], v[162:165], v[194:197], v[126:129]
	v_mfma_f32_16x16x32_bf16 v[122:125], v[170:173], v[194:197], v[122:125]
	v_mfma_f32_16x16x32_bf16 v[118:121], v[162:165], v[204:207], v[118:121]
	v_mfma_f32_16x16x32_bf16 v[114:117], v[170:173], v[204:207], v[114:117]
	v_mfma_f32_16x16x32_bf16 v[102:105], v[162:165], v[212:215], v[102:105]
	v_mfma_f32_16x16x32_bf16 v[98:101], v[170:173], v[212:215], v[98:101]
	v_mfma_f32_16x16x32_bf16 v[86:89], v[162:165], v[220:223], v[86:89]
	v_mfma_f32_16x16x32_bf16 v[82:85], v[170:173], v[220:223], v[82:85]
	v_mfma_f32_16x16x32_bf16 v[110:113], v[174:177], v[190:193], v[110:113]
	v_mfma_f32_16x16x32_bf16 v[106:109], v[182:185], v[190:193], v[106:109]
	v_mfma_f32_16x16x32_bf16 v[94:97], v[174:177], v[198:201], v[94:97]
	v_mfma_f32_16x16x32_bf16 v[90:93], v[182:185], v[198:201], v[90:93]
	v_mfma_f32_16x16x32_bf16 v[78:81], v[174:177], v[208:211], v[78:81]
	v_mfma_f32_16x16x32_bf16 v[74:77], v[182:185], v[208:211], v[74:77]
	v_mfma_f32_16x16x32_bf16 v[70:73], v[174:177], v[216:219], v[70:73]
	v_mfma_f32_16x16x32_bf16 v[66:69], v[182:185], v[216:219], v[66:69]
	v_mfma_f32_16x16x32_bf16 v[110:113], v[178:181], v[194:197], v[110:113]
	v_mfma_f32_16x16x32_bf16 v[106:109], v[186:189], v[194:197], v[106:109]
	v_mfma_f32_16x16x32_bf16 v[94:97], v[178:181], v[204:207], v[94:97]
	v_mfma_f32_16x16x32_bf16 v[90:93], v[186:189], v[204:207], v[90:93]
	v_mfma_f32_16x16x32_bf16 v[78:81], v[178:181], v[212:215], v[78:81]
	v_mfma_f32_16x16x32_bf16 v[74:77], v[186:189], v[212:215], v[74:77]
	v_mfma_f32_16x16x32_bf16 v[70:73], v[178:181], v[220:223], v[70:73]
	v_mfma_f32_16x16x32_bf16 v[66:69], v[186:189], v[220:223], v[66:69]
	s_setprio 0
	s_barrier
; #define PG8_STAGE(bufoff, gbase, voff) do { _Pragma("unroll") for (int _i = 0; _i < 2; ++_i) \
;         __builtin_amdgcn_global_load_lds((const unsigned*)((const char*)(gbase) + (voff)[_i]), (LAS unsigned*)(lds + (bufoff) + ldsw + _i * 8192), 16, 0, 0); } while (0)
; #define PG8_LDA(dst, b, h) do { _Pragma("unroll") for (int m = 0; m < 4; ++m) _Pragma("unroll") for (int k = 0; k < 2; ++k) dst[m][k] = *(const LAS bf16x8*)(lds + PG8_SA(b, h) + aoff + m * 2048 + k * 1024); } while (0)
; #define PG8_MMA(ai, bj, At, Bt) do { __builtin_amdgcn_s_setprio(1); _Pragma("unroll") for (int m = 0; m < 4; ++m) _Pragma("unroll") for (int n = 0; n < 2; ++n) _Pragma("unroll") for (int k = 0; k < 2; ++k) \
;         acc[ai][bj][m][n] = __builtin_amdgcn_mfma_f32_16x16x32_bf16(Bt[n][k], At[m][k], acc[ai][bj][m][n], 0, 0, 0); __builtin_amdgcn_s_setprio(0); } while (0)
; #define PG8_WAIT_V(n) asm volatile("s_waitcnt vmcnt(" #n ")" ::: "memory")
; #define PG8_WAIT_L(n) asm volatile("s_waitcnt lgkmcnt(" #n ")" ::: "memory")
; #define PG8_BAR __builtin_amdgcn_s_barrier()
; #define PG8_SCHED __builtin_amdgcn_sched_barrier(0)
; template <class Epi, class Sched, bool ALIGN_EPI>
; DI void gemm_phase(LAS unsigned char* lds, const Gemm g, const Sched& S, const Epi& E) {
;     ...
;             PG8_LDA(At, 1, 1); PG8_STAGE(PG8_SB(1, 0), b3, voffB); PG8_STAGE(PG8_SB(1, 1), b3 + hstepB, voffB); PG8_STAGE(PG8_SA(1, 0), a3, voffA);
;             PG8_WAIT_V(8); PG8_WAIT_L(0); PG8_BAR; PG8_MMA(1, 0, At, B0); PG8_MMA(1, 1, At, B1); PG8_BAR; PG8_SCHED;
;         }
;         if constexpr (ALIGN_EPI) { if (wr == 0) PG8_BAR; }
	s_mov_b32 m0, s57
	v_lshl_add_u64 v[224:225], v[224:225], 0, s[8:9]
	ds_read_b128 v[190:193], v146 offset:49152
	ds_read_b128 v[194:197], v146 offset:50176
	ds_read_b128 v[198:201], v146 offset:51200
	ds_read_b128 v[204:207], v146 offset:52224
	ds_read_b128 v[208:211], v146 offset:53248
	ds_read_b128 v[212:215], v146 offset:54272
	ds_read_b128 v[216:219], v146 offset:55296
	ds_read_b128 v[220:223], v146 offset:56320
	global_load_lds_dwordx4 v[224:225], off
	v_lshl_add_u64 v[224:225], v[226:227], 0, s[8:9]
	s_mov_b32 m0, s55
	s_nop 0
	global_load_lds_dwordx4 v[224:225], off
	v_lshl_add_u64 v[224:225], s[28:29], 0, v[132:133]
	s_mov_b32 m0, s56
	s_nop 0
	global_load_lds_dwordx4 v[224:225], off
	v_lshl_add_u64 v[224:225], s[28:29], 0, v[136:137]
	s_mov_b32 m0, s54
	s_nop 0
	global_load_lds_dwordx4 v[224:225], off
	v_lshl_add_u64 v[224:225], v[228:229], 0, s[8:9]
	s_mov_b32 m0, s80
	s_nop 0
	global_load_lds_dwordx4 v[224:225], off
	v_lshl_add_u64 v[224:225], v[230:231], 0, s[8:9]
	s_mov_b32 m0, s81
	s_nop 0
	global_load_lds_dwordx4 v[224:225], off
	s_waitcnt vmcnt(8)
	s_waitcnt lgkmcnt(0)
	s_barrier
	s_setprio 1
	s_waitcnt lgkmcnt(0)
	v_mfma_f32_16x16x32_bf16 v[62:65], v[158:161], v[190:193], v[62:65]
	v_mfma_f32_16x16x32_bf16 v[58:61], v[166:169], v[190:193], v[58:61]
	v_mfma_f32_16x16x32_bf16 v[54:57], v[158:161], v[198:201], v[54:57]
	v_mfma_f32_16x16x32_bf16 v[50:53], v[166:169], v[198:201], v[50:53]
	v_mfma_f32_16x16x32_bf16 v[38:41], v[158:161], v[208:211], v[38:41]
	v_mfma_f32_16x16x32_bf16 v[34:37], v[166:169], v[208:211], v[34:37]
	v_mfma_f32_16x16x32_bf16 v[22:25], v[158:161], v[216:219], v[22:25]
	v_mfma_f32_16x16x32_bf16 v[18:21], v[166:169], v[216:219], v[18:21]
	v_mfma_f32_16x16x32_bf16 v[62:65], v[162:165], v[194:197], v[62:65]
	v_mfma_f32_16x16x32_bf16 v[58:61], v[170:173], v[194:197], v[58:61]
	v_mfma_f32_16x16x32_bf16 v[54:57], v[162:165], v[204:207], v[54:57]
	v_mfma_f32_16x16x32_bf16 v[50:53], v[170:173], v[204:207], v[50:53]
	v_mfma_f32_16x16x32_bf16 v[38:41], v[162:165], v[212:215], v[38:41]
	v_mfma_f32_16x16x32_bf16 v[34:37], v[170:173], v[212:215], v[34:37]
	v_mfma_f32_16x16x32_bf16 v[22:25], v[162:165], v[220:223], v[22:25]
	v_mfma_f32_16x16x32_bf16 v[18:21], v[170:173], v[220:223], v[18:21]
	v_mfma_f32_16x16x32_bf16 v[46:49], v[174:177], v[190:193], v[46:49]
	v_mfma_f32_16x16x32_bf16 v[42:45], v[182:185], v[190:193], v[42:45]
	v_mfma_f32_16x16x32_bf16 v[30:33], v[174:177], v[198:201], v[30:33]
	v_mfma_f32_16x16x32_bf16 v[26:29], v[182:185], v[198:201], v[26:29]
	v_mfma_f32_16x16x32_bf16 v[14:17], v[174:177], v[208:211], v[14:17]
	v_mfma_f32_16x16x32_bf16 v[10:13], v[182:185], v[208:211], v[10:13]
	v_mfma_f32_16x16x32_bf16 v[6:9], v[174:177], v[216:219], v[6:9]
	v_mfma_f32_16x16x32_bf16 v[2:5], v[182:185], v[216:219], v[2:5]
	v_mfma_f32_16x16x32_bf16 v[46:49], v[178:181], v[194:197], v[46:49]
	v_mfma_f32_16x16x32_bf16 v[42:45], v[186:189], v[194:197], v[42:45]
	v_mfma_f32_16x16x32_bf16 v[30:33], v[178:181], v[204:207], v[30:33]
	v_mfma_f32_16x16x32_bf16 v[26:29], v[186:189], v[204:207], v[26:29]
	v_mfma_f32_16x16x32_bf16 v[14:17], v[178:181], v[212:215], v[14:17]
	v_mfma_f32_16x16x32_bf16 v[10:13], v[186:189], v[212:215], v[10:13]
	v_mfma_f32_16x16x32_bf16 v[6:9], v[178:181], v[220:223], v[6:9]
	v_mfma_f32_16x16x32_bf16 v[2:5], v[186:189], v[220:223], v[2:5]
	s_setprio 0
	s_barrier
	s_movk_i32 s36, 0x100
	s_andn2_b64 vcc, exec, s[26:27]
	s_mov_b64 s[28:29], -1
	s_mov_b64 s[26:27], 0
	s_cbranch_vccz .LBB0_1140
	s_and_b64 vcc, exec, s[10:11]
	s_cbranch_vccz .LBB0_1143
	s_barrier

; #define PG8_STAGE(bufoff, gbase, voff) do { _Pragma("unroll") for (int _i = 0; _i < 2; ++_i) \
;         __builtin_amdgcn_global_load_lds((const unsigned*)((const char*)(gbase) + (voff)[_i]), (LAS unsigned*)(lds + (bufoff) + ldsw + _i * 8192), 16, 0, 0); } while (0)
; #define PG8_LDA(dst, b, h) do { _Pragma("unroll") for (int m = 0; m < 4; ++m) _Pragma("unroll") for (int k = 0; k < 2; ++k) dst[m][k] = *(const LAS bf16x8*)(lds + PG8_SA(b, h) + aoff + m * 2048 + k * 1024); } while (0)
; #define PG8_LDB(dst, b, h) do { _Pragma("unroll") for (int n = 0; n < 2; ++n) _Pragma("unroll") for (int k = 0; k < 2; ++k) dst[n][k] = *(const LAS bf16x8*)(lds + PG8_SB(b, h) + boff + n * 2048 + k * 1024); } while (0)
; #define PG8_MMA(ai, bj, At, Bt) do { __builtin_amdgcn_s_setprio(1); _Pragma("unroll") for (int m = 0; m < 4; ++m) _Pragma("unroll") for (int n = 0; n < 2; ++n) _Pragma("unroll") for (int k = 0; k < 2; ++k) \
;         acc[ai][bj][m][n] = __builtin_amdgcn_mfma_f32_16x16x32_bf16(Bt[n][k], At[m][k], acc[ai][bj][m][n], 0, 0, 0); __builtin_amdgcn_s_setprio(0); } while (0)
; #define PG8_WAIT_V(n) asm volatile("s_waitcnt vmcnt(" #n ")" ::: "memory")
; #define PG8_BAR __builtin_amdgcn_s_barrier()
; template <class Epi, class Sched, bool ALIGN_EPI>
; DI void gemm_phase(LAS unsigned char* lds, const Gemm g, const Sched& S, const Epi& E) {
;     ...
;         const char* nA = has_next ? (const char*)g.A + (size_t)nxt.pm * tstepA : cA; const char* nB = has_next ? (const char*)g.Bt + (size_t)nxt.pn * tstepB : cB;
;         for (int t = 0; t < nt; t += 2) {
;             const bool last = (t == nt - 2);
;             const char* a1 = cA + (size_t)(t + 1) * kstep;
;             const char* a2 = last ? nA : cA + (size_t)(t + 2) * kstep; const char* b2 = last ? nB : cB + (size_t)(t + 2) * kstep;
;             const char* a3 = a2 + kstep; const char* b3 = b2 + kstep;
;             PG8_LDB(B0, 0, 0); PG8_LDB(B1, 0, 1); PG8_SCHED; PG8_LDA(At, 0, 0); PG8_STAGE(PG8_SA(1, 1), a1 + hstepA, voffA);
;             PG8_WAIT_V(8); PG8_WAIT_L(0); PG8_BAR; PG8_MMA(0, 0, At, B0); PG8_MMA(0, 1, At, B1); PG8_BAR; PG8_SCHED;
;             PG8_LDA(At, 0, 1); PG8_STAGE(PG8_SB(0, 0), b2, voffB); PG8_STAGE(PG8_SB(0, 1), b2 + hstepB, voffB); PG8_STAGE(PG8_SA(0, 0), a2, voffA);
;             PG8_WAIT_V(8); PG8_WAIT_L(0); PG8_BAR; PG8_MMA(1, 0, At, B0); PG8_MMA(1, 1, At, B1); PG8_BAR; PG8_SCHED;
.LBB0_1156:
	s_add_u32 s27, s18, s26
	s_addc_u32 s40, s19, 0
	s_add_u32 s36, s27, 0x100
	s_addc_u32 s37, s40, 0
	s_and_b64 s[28:29], s[24:25], exec
	s_cselect_b32 s29, s52, s37
	s_cselect_b32 s28, s53, s36
	s_add_u32 s26, s20, s26
	s_addc_u32 s36, s21, 0
	s_add_u32 s26, s26, 0x100
	s_addc_u32 s36, s36, 0
	s_and_b64 s[24:25], s[24:25], exec
	s_cselect_b32 s37, s54, s36
	s_cselect_b32 s36, s55, s26
	s_add_u32 s42, s27, 0x10080
	ds_read_b128 v[148:151], v143
	ds_read_b128 v[154:157], v143 offset:1024
	ds_read_b128 v[158:161], v143 offset:2048
	ds_read_b128 v[162:165], v143 offset:3072
	ds_read_b128 v[166:169], v144
	ds_read_b128 v[170:173], v144 offset:1024
	ds_read_b128 v[174:177], v144 offset:2048
	ds_read_b128 v[178:181], v144 offset:3072
	s_addc_u32 s43, s40, 0
	s_add_i32 s63, s81, s72
	s_add_i32 m0, s73, 0xc000
	s_add_i32 s64, s73, 0xe000
	s_add_i32 s60, s63, 0x2000
	s_add_u32 s40, s36, 0x10000
	s_addc_u32 s41, s37, 0
	s_add_i32 s62, s82, s72
	s_add_i32 s61, s62, 0x2000
	s_add_u32 s26, s28, 0x10000
	s_addc_u32 s27, s29, 0
	s_add_i32 s59, s83, s72
	s_add_i32 s57, s59, 0x2000
	s_add_u32 s24, s36, 0x10080
	s_addc_u32 s25, s37, 0
	s_add_i32 s58, s84, s72
	s_add_i32 s56, s58, 0x2000
	v_lshl_add_u64 v[216:217], s[42:43], 0, v[136:137]
	ds_read_b128 v[182:185], v145
	ds_read_b128 v[186:189], v145 offset:1024
	ds_read_b128 v[190:193], v145 offset:2048
	ds_read_b128 v[194:197], v145 offset:3072
	ds_read_b128 v[198:201], v145 offset:4096
	ds_read_b128 v[204:207], v145 offset:5120
	ds_read_b128 v[208:211], v145 offset:6144
	ds_read_b128 v[212:215], v145 offset:7168
	global_load_lds_dwordx4 v[216:217], off
	v_lshl_add_u64 v[216:217], s[42:43], 0, v[132:133]
	s_mov_b32 m0, s64
	s_nop 0
	global_load_lds_dwordx4 v[216:217], off
	s_waitcnt vmcnt(8)
	s_waitcnt lgkmcnt(0)
	s_barrier
	s_setprio 1
	s_waitcnt lgkmcnt(0)
	v_mfma_f32_16x16x32_bf16 v[126:129], v[148:151], v[182:185], v[126:129]
	v_mfma_f32_16x16x32_bf16 v[122:125], v[158:161], v[182:185], v[122:125]
	v_mfma_f32_16x16x32_bf16 v[118:121], v[148:151], v[190:193], v[118:121]
	v_mfma_f32_16x16x32_bf16 v[114:117], v[158:161], v[190:193], v[114:117]
	v_mfma_f32_16x16x32_bf16 v[102:105], v[148:151], v[198:201], v[102:105]
	v_mfma_f32_16x16x32_bf16 v[98:101], v[158:161], v[198:201], v[98:101]
	v_mfma_f32_16x16x32_bf16 v[86:89], v[148:151], v[208:211], v[86:89]
	v_mfma_f32_16x16x32_bf16 v[82:85], v[158:161], v[208:211], v[82:85]
	v_mfma_f32_16x16x32_bf16 v[126:129], v[154:157], v[186:189], v[126:129]
	v_mfma_f32_16x16x32_bf16 v[122:125], v[162:165], v[186:189], v[122:125]
	v_mfma_f32_16x16x32_bf16 v[118:121], v[154:157], v[194:197], v[118:121]
	v_mfma_f32_16x16x32_bf16 v[114:117], v[162:165], v[194:197], v[114:117]
	v_mfma_f32_16x16x32_bf16 v[102:105], v[154:157], v[204:207], v[102:105]
	v_mfma_f32_16x16x32_bf16 v[98:101], v[162:165], v[204:207], v[98:101]
	v_mfma_f32_16x16x32_bf16 v[86:89], v[154:157], v[212:215], v[86:89]
	v_mfma_f32_16x16x32_bf16 v[82:85], v[162:165], v[212:215], v[82:85]
	v_mfma_f32_16x16x32_bf16 v[110:113], v[166:169], v[182:185], v[110:113]
	v_mfma_f32_16x16x32_bf16 v[106:109], v[174:177], v[182:185], v[106:109]
	v_mfma_f32_16x16x32_bf16 v[94:97], v[166:169], v[190:193], v[94:97]
	v_mfma_f32_16x16x32_bf16 v[90:93], v[174:177], v[190:193], v[90:93]
	v_mfma_f32_16x16x32_bf16 v[78:81], v[166:169], v[198:201], v[78:81]
	v_mfma_f32_16x16x32_bf16 v[74:77], v[174:177], v[198:201], v[74:77]
	v_mfma_f32_16x16x32_bf16 v[70:73], v[166:169], v[208:211], v[70:73]
	v_mfma_f32_16x16x32_bf16 v[66:69], v[174:177], v[208:211], v[66:69]
	v_mfma_f32_16x16x32_bf16 v[110:113], v[170:173], v[186:189], v[110:113]
	v_mfma_f32_16x16x32_bf16 v[106:109], v[178:181], v[186:189], v[106:109]
	v_mfma_f32_16x16x32_bf16 v[94:97], v[170:173], v[194:197], v[94:97]
	v_mfma_f32_16x16x32_bf16 v[90:93], v[178:181], v[194:197], v[90:93]
	v_mfma_f32_16x16x32_bf16 v[78:81], v[170:173], v[204:207], v[78:81]
	v_mfma_f32_16x16x32_bf16 v[74:77], v[178:181], v[204:207], v[74:77]
	v_mfma_f32_16x16x32_bf16 v[70:73], v[170:173], v[212:215], v[70:73]
	v_mfma_f32_16x16x32_bf16 v[66:69], v[178:181], v[212:215], v[66:69]
	s_setprio 0
	s_barrier
	s_mov_b32 m0, s63
	v_lshl_add_u64 v[216:217], s[36:37], 0, v[134:135]
	ds_read_b128 v[182:185], v145 offset:16384
	ds_read_b128 v[186:189], v145 offset:17408
	ds_read_b128 v[190:193], v145 offset:18432
	ds_read_b128 v[194:197], v145 offset:19456
	ds_read_b128 v[198:201], v145 offset:20480
	ds_read_b128 v[204:207], v145 offset:21504
	ds_read_b128 v[208:211], v145 offset:22528
	ds_read_b128 v[212:215], v145 offset:23552
	global_load_lds_dwordx4 v[216:217], off
	v_lshl_add_u64 v[218:219], s[36:37], 0, v[130:131]
	s_mov_b32 m0, s60
	v_lshl_add_u64 v[220:221], s[40:41], 0, v[134:135]
	global_load_lds_dwordx4 v[218:219], off
	s_mov_b32 m0, s62
	v_lshl_add_u64 v[222:223], s[28:29], 0, v[132:133]
	global_load_lds_dwordx4 v[220:221], off
	v_lshl_add_u64 v[220:221], s[40:41], 0, v[130:131]
	s_mov_b32 m0, s61
	s_nop 0
	global_load_lds_dwordx4 v[220:221], off
	v_lshl_add_u64 v[220:221], s[28:29], 0, v[136:137]
	s_mov_b32 m0, s73
	s_nop 0
	global_load_lds_dwordx4 v[220:221], off
	s_mov_b32 m0, s75
	s_nop 0
	global_load_lds_dwordx4 v[222:223], off
	s_waitcnt vmcnt(8)
	s_waitcnt lgkmcnt(0)
	s_barrier
; #define PG8_STAGE(bufoff, gbase, voff) do { _Pragma("unroll") for (int _i = 0; _i < 2; ++_i) \
;         __builtin_amdgcn_global_load_lds((const unsigned*)((const char*)(gbase) + (voff)[_i]), (LAS unsigned*)(lds + (bufoff) + ldsw + _i * 8192), 16, 0, 0); } while (0)
; #define PG8_LDA(dst, b, h) do { _Pragma("unroll") for (int m = 0; m < 4; ++m) _Pragma("unroll") for (int k = 0; k < 2; ++k) dst[m][k] = *(const LAS bf16x8*)(lds + PG8_SA(b, h) + aoff + m * 2048 + k * 1024); } while (0)
; #define PG8_LDB(dst, b, h) do { _Pragma("unroll") for (int n = 0; n < 2; ++n) _Pragma("unroll") for (int k = 0; k < 2; ++k) dst[n][k] = *(const LAS bf16x8*)(lds + PG8_SB(b, h) + boff + n * 2048 + k * 1024); } while (0)
; #define PG8_MMA(ai, bj, At, Bt) do { __builtin_amdgcn_s_setprio(1); _Pragma("unroll") for (int m = 0; m < 4; ++m) _Pragma("unroll") for (int n = 0; n < 2; ++n) _Pragma("unroll") for (int k = 0; k < 2; ++k) \
;         acc[ai][bj][m][n] = __builtin_amdgcn_mfma_f32_16x16x32_bf16(Bt[n][k], At[m][k], acc[ai][bj][m][n], 0, 0, 0); __builtin_amdgcn_s_setprio(0); } while (0)
; #define PG8_WAIT_V(n) asm volatile("s_waitcnt vmcnt(" #n ")" ::: "memory")
; #define PG8_WAIT_L(n) asm volatile("s_waitcnt lgkmcnt(" #n ")" ::: "memory")
; #define PG8_BAR __builtin_amdgcn_s_barrier()
; #define PG8_SCHED __builtin_amdgcn_sched_barrier(0)
; template <class Epi, class Sched, bool ALIGN_EPI>
; DI void gemm_phase(LAS unsigned char* lds, const Gemm g, const Sched& S, const Epi& E) {
;     ...
;             PG8_WAIT_V(8); PG8_WAIT_L(0); PG8_BAR; PG8_MMA(1, 0, At, B0); PG8_MMA(1, 1, At, B1); PG8_BAR; PG8_SCHED;
;             PG8_LDB(B0, 1, 0); PG8_LDB(B1, 1, 1); PG8_SCHED; PG8_LDA(At, 1, 0); PG8_STAGE(PG8_SA(0, 1), a2 + hstepA, voffA);
;             PG8_WAIT_V(8); PG8_WAIT_L(0); PG8_BAR; PG8_MMA(0, 0, At, B0); PG8_MMA(0, 1, At, B1); PG8_BAR; PG8_SCHED;
	s_setprio 1
	s_waitcnt lgkmcnt(0)
	v_mfma_f32_16x16x32_bf16 v[62:65], v[148:151], v[182:185], v[62:65]
	v_mfma_f32_16x16x32_bf16 v[58:61], v[158:161], v[182:185], v[58:61]
	v_mfma_f32_16x16x32_bf16 v[54:57], v[148:151], v[190:193], v[54:57]
	v_mfma_f32_16x16x32_bf16 v[50:53], v[158:161], v[190:193], v[50:53]
	v_mfma_f32_16x16x32_bf16 v[38:41], v[148:151], v[198:201], v[38:41]
	v_mfma_f32_16x16x32_bf16 v[34:37], v[158:161], v[198:201], v[34:37]
	v_mfma_f32_16x16x32_bf16 v[22:25], v[148:151], v[208:211], v[22:25]
	v_mfma_f32_16x16x32_bf16 v[18:21], v[158:161], v[208:211], v[18:21]
	v_mfma_f32_16x16x32_bf16 v[62:65], v[154:157], v[186:189], v[62:65]
	v_mfma_f32_16x16x32_bf16 v[58:61], v[162:165], v[186:189], v[58:61]
	v_mfma_f32_16x16x32_bf16 v[54:57], v[154:157], v[194:197], v[54:57]
	v_mfma_f32_16x16x32_bf16 v[50:53], v[162:165], v[194:197], v[50:53]
	v_mfma_f32_16x16x32_bf16 v[38:41], v[154:157], v[204:207], v[38:41]
	v_mfma_f32_16x16x32_bf16 v[34:37], v[162:165], v[204:207], v[34:37]
	v_mfma_f32_16x16x32_bf16 v[22:25], v[154:157], v[212:215], v[22:25]
	v_mfma_f32_16x16x32_bf16 v[18:21], v[162:165], v[212:215], v[18:21]
	v_mfma_f32_16x16x32_bf16 v[46:49], v[166:169], v[182:185], v[46:49]
	v_mfma_f32_16x16x32_bf16 v[42:45], v[174:177], v[182:185], v[42:45]
	v_mfma_f32_16x16x32_bf16 v[30:33], v[166:169], v[190:193], v[30:33]
	v_mfma_f32_16x16x32_bf16 v[26:29], v[174:177], v[190:193], v[26:29]
	v_mfma_f32_16x16x32_bf16 v[14:17], v[166:169], v[198:201], v[14:17]
	v_mfma_f32_16x16x32_bf16 v[10:13], v[174:177], v[198:201], v[10:13]
	v_mfma_f32_16x16x32_bf16 v[6:9], v[166:169], v[208:211], v[6:9]
	v_mfma_f32_16x16x32_bf16 v[2:5], v[174:177], v[208:211], v[2:5]
	v_mfma_f32_16x16x32_bf16 v[46:49], v[170:173], v[186:189], v[46:49]
	v_mfma_f32_16x16x32_bf16 v[42:45], v[178:181], v[186:189], v[42:45]
	v_mfma_f32_16x16x32_bf16 v[30:33], v[170:173], v[194:197], v[30:33]
	v_mfma_f32_16x16x32_bf16 v[26:29], v[178:181], v[194:197], v[26:29]
	v_mfma_f32_16x16x32_bf16 v[14:17], v[170:173], v[204:207], v[14:17]
	v_mfma_f32_16x16x32_bf16 v[10:13], v[178:181], v[204:207], v[10:13]
	v_mfma_f32_16x16x32_bf16 v[6:9], v[170:173], v[212:215], v[6:9]
	v_mfma_f32_16x16x32_bf16 v[2:5], v[178:181], v[212:215], v[2:5]
	s_setprio 0
	s_barrier
	ds_read_b128 v[148:151], v146
	ds_read_b128 v[154:157], v146 offset:1024
	ds_read_b128 v[158:161], v146 offset:2048
	ds_read_b128 v[162:165], v146 offset:3072
	ds_read_b128 v[166:169], v147
	ds_read_b128 v[170:173], v147 offset:1024
	ds_read_b128 v[174:177], v147 offset:2048
	ds_read_b128 v[178:181], v147 offset:3072
	s_mov_b32 m0, s76
	v_lshl_add_u64 v[224:225], s[26:27], 0, v[136:137]
	ds_read_b128 v[182:185], v145 offset:32768
	ds_read_b128 v[186:189], v145 offset:33792
	ds_read_b128 v[190:193], v145 offset:34816
	ds_read_b128 v[194:197], v145 offset:35840
	ds_read_b128 v[198:201], v145 offset:36864
	ds_read_b128 v[204:207], v145 offset:37888
	ds_read_b128 v[208:211], v145 offset:38912
	ds_read_b128 v[212:215], v145 offset:39936
	global_load_lds_dwordx4 v[224:225], off
	v_lshl_add_u64 v[224:225], s[26:27], 0, v[132:133]
	s_mov_b32 m0, s77
	s_nop 0
	global_load_lds_dwordx4 v[224:225], off
	s_waitcnt vmcnt(8)
	s_waitcnt lgkmcnt(0)
	s_barrier
	s_setprio 1
	s_waitcnt lgkmcnt(0)
	v_mfma_f32_16x16x32_bf16 v[126:129], v[148:151], v[182:185], v[126:129]
	v_mfma_f32_16x16x32_bf16 v[122:125], v[158:161], v[182:185], v[122:125]
	v_mfma_f32_16x16x32_bf16 v[118:121], v[148:151], v[190:193], v[118:121]
	v_mfma_f32_16x16x32_bf16 v[114:117], v[158:161], v[190:193], v[114:117]
	v_mfma_f32_16x16x32_bf16 v[102:105], v[148:151], v[198:201], v[102:105]
	v_mfma_f32_16x16x32_bf16 v[98:101], v[158:161], v[198:201], v[98:101]
	v_mfma_f32_16x16x32_bf16 v[86:89], v[148:151], v[208:211], v[86:89]
	v_mfma_f32_16x16x32_bf16 v[82:85], v[158:161], v[208:211], v[82:85]
	v_mfma_f32_16x16x32_bf16 v[126:129], v[154:157], v[186:189], v[126:129]
	v_mfma_f32_16x16x32_bf16 v[122:125], v[162:165], v[186:189], v[122:125]
	v_mfma_f32_16x16x32_bf16 v[118:121], v[154:157], v[194:197], v[118:121]
	v_mfma_f32_16x16x32_bf16 v[114:117], v[162:165], v[194:197], v[114:117]
	v_mfma_f32_16x16x32_bf16 v[102:105], v[154:157], v[204:207], v[102:105]
	v_mfma_f32_16x16x32_bf16 v[98:101], v[162:165], v[204:207], v[98:101]
	v_mfma_f32_16x16x32_bf16 v[86:89], v[154:157], v[212:215], v[86:89]
	v_mfma_f32_16x16x32_bf16 v[82:85], v[162:165], v[212:215], v[82:85]
	v_mfma_f32_16x16x32_bf16 v[110:113], v[166:169], v[182:185], v[110:113]
	v_mfma_f32_16x16x32_bf16 v[106:109], v[174:177], v[182:185], v[106:109]
	v_mfma_f32_16x16x32_bf16 v[94:97], v[166:169], v[190:193], v[94:97]
	v_mfma_f32_16x16x32_bf16 v[90:93], v[174:177], v[190:193], v[90:93]
	v_mfma_f32_16x16x32_bf16 v[78:81], v[166:169], v[198:201], v[78:81]
	v_mfma_f32_16x16x32_bf16 v[74:77], v[174:177], v[198:201], v[74:77]
	v_mfma_f32_16x16x32_bf16 v[70:73], v[166:169], v[208:211], v[70:73]
	v_mfma_f32_16x16x32_bf16 v[66:69], v[174:177], v[208:211], v[66:69]
	v_mfma_f32_16x16x32_bf16 v[110:113], v[170:173], v[186:189], v[110:113]
	v_mfma_f32_16x16x32_bf16 v[106:109], v[178:181], v[186:189], v[106:109]
	v_mfma_f32_16x16x32_bf16 v[94:97], v[170:173], v[194:197], v[94:97]
	v_mfma_f32_16x16x32_bf16 v[90:93], v[178:181], v[194:197], v[90:93]
	v_mfma_f32_16x16x32_bf16 v[78:81], v[170:173], v[204:207], v[78:81]
	v_mfma_f32_16x16x32_bf16 v[74:77], v[178:181], v[204:207], v[74:77]
	v_mfma_f32_16x16x32_bf16 v[70:73], v[170:173], v[212:215], v[70:73]
	v_mfma_f32_16x16x32_bf16 v[66:69], v[178:181], v[212:215], v[66:69]
	s_setprio 0
	s_barrier
; #define PG8_STAGE(bufoff, gbase, voff) do { _Pragma("unroll") for (int _i = 0; _i < 2; ++_i) \
;         __builtin_amdgcn_global_load_lds((const unsigned*)((const char*)(gbase) + (voff)[_i]), (LAS unsigned*)(lds + (bufoff) + ldsw + _i * 8192), 16, 0, 0); } while (0)
; #define PG8_LDA(dst, b, h) do { _Pragma("unroll") for (int m = 0; m < 4; ++m) _Pragma("unroll") for (int k = 0; k < 2; ++k) dst[m][k] = *(const LAS bf16x8*)(lds + PG8_SA(b, h) + aoff + m * 2048 + k * 1024); } while (0)
; #define PG8_MMA(ai, bj, At, Bt) do { __builtin_amdgcn_s_setprio(1); _Pragma("unroll") for (int m = 0; m < 4; ++m) _Pragma("unroll") for (int n = 0; n < 2; ++n) _Pragma("unroll") for (int k = 0; k < 2; ++k) \
;         acc[ai][bj][m][n] = __builtin_amdgcn_mfma_f32_16x16x32_bf16(Bt[n][k], At[m][k], acc[ai][bj][m][n], 0, 0, 0); __builtin_amdgcn_s_setprio(0); } while (0)
; #define PG8_WAIT_V(n) asm volatile("s_waitcnt vmcnt(" #n ")" ::: "memory")
; #define PG8_WAIT_L(n) asm volatile("s_waitcnt lgkmcnt(" #n ")" ::: "memory")
; #define PG8_BAR __builtin_amdgcn_s_barrier()
; #define PG8_SCHED __builtin_amdgcn_sched_barrier(0)
; template <class Epi, class Sched, bool ALIGN_EPI>
; DI void gemm_phase(LAS unsigned char* lds, const Gemm g, const Sched& S, const Epi& E) {
;     ...
;             PG8_LDA(At, 1, 1); PG8_STAGE(PG8_SB(1, 0), b3, voffB); PG8_STAGE(PG8_SB(1, 1), b3 + hstepB, voffB); PG8_STAGE(PG8_SA(1, 0), a3, voffA);
;             PG8_WAIT_V(8); PG8_WAIT_L(0); PG8_BAR; PG8_MMA(1, 0, At, B0); PG8_MMA(1, 1, At, B1); PG8_BAR; PG8_SCHED;
;         }
;         if constexpr (ALIGN_EPI) { if (wr == 0) PG8_BAR; }
	s_mov_b32 m0, s59
	v_lshl_add_u64 v[216:217], v[216:217], 0, s[14:15]
	ds_read_b128 v[182:185], v145 offset:49152
	ds_read_b128 v[186:189], v145 offset:50176
	ds_read_b128 v[190:193], v145 offset:51200
	ds_read_b128 v[194:197], v145 offset:52224
	ds_read_b128 v[198:201], v145 offset:53248
	ds_read_b128 v[204:207], v145 offset:54272
	ds_read_b128 v[208:211], v145 offset:55296
	ds_read_b128 v[212:215], v145 offset:56320
	global_load_lds_dwordx4 v[216:217], off
	v_lshl_add_u64 v[216:217], v[218:219], 0, s[14:15]
	s_mov_b32 m0, s57
	s_nop 0
	global_load_lds_dwordx4 v[216:217], off
	v_lshl_add_u64 v[216:217], s[24:25], 0, v[134:135]
	s_mov_b32 m0, s58
	s_nop 0
	global_load_lds_dwordx4 v[216:217], off
	v_lshl_add_u64 v[216:217], s[24:25], 0, v[130:131]
	s_mov_b32 m0, s56
	s_nop 0
	global_load_lds_dwordx4 v[216:217], off
	v_lshl_add_u64 v[216:217], v[220:221], 0, s[14:15]
	s_mov_b32 m0, s79
	s_nop 0
	global_load_lds_dwordx4 v[216:217], off
	v_lshl_add_u64 v[216:217], v[222:223], 0, s[14:15]
	s_mov_b32 m0, s80
	s_nop 0
	global_load_lds_dwordx4 v[216:217], off
	s_waitcnt vmcnt(8)
	s_waitcnt lgkmcnt(0)
	s_barrier
	s_setprio 1
	s_waitcnt lgkmcnt(0)
	v_mfma_f32_16x16x32_bf16 v[62:65], v[148:151], v[182:185], v[62:65]
	v_mfma_f32_16x16x32_bf16 v[58:61], v[158:161], v[182:185], v[58:61]
	v_mfma_f32_16x16x32_bf16 v[54:57], v[148:151], v[190:193], v[54:57]
	v_mfma_f32_16x16x32_bf16 v[50:53], v[158:161], v[190:193], v[50:53]
	v_mfma_f32_16x16x32_bf16 v[38:41], v[148:151], v[198:201], v[38:41]
	v_mfma_f32_16x16x32_bf16 v[34:37], v[158:161], v[198:201], v[34:37]
	v_mfma_f32_16x16x32_bf16 v[22:25], v[148:151], v[208:211], v[22:25]
	v_mfma_f32_16x16x32_bf16 v[18:21], v[158:161], v[208:211], v[18:21]
	v_mfma_f32_16x16x32_bf16 v[62:65], v[154:157], v[186:189], v[62:65]
	v_mfma_f32_16x16x32_bf16 v[58:61], v[162:165], v[186:189], v[58:61]
	v_mfma_f32_16x16x32_bf16 v[54:57], v[154:157], v[194:197], v[54:57]
	v_mfma_f32_16x16x32_bf16 v[50:53], v[162:165], v[194:197], v[50:53]
	v_mfma_f32_16x16x32_bf16 v[38:41], v[154:157], v[204:207], v[38:41]
	v_mfma_f32_16x16x32_bf16 v[34:37], v[162:165], v[204:207], v[34:37]
	v_mfma_f32_16x16x32_bf16 v[22:25], v[154:157], v[212:215], v[22:25]
	v_mfma_f32_16x16x32_bf16 v[18:21], v[162:165], v[212:215], v[18:21]
	v_mfma_f32_16x16x32_bf16 v[46:49], v[166:169], v[182:185], v[46:49]
	v_mfma_f32_16x16x32_bf16 v[42:45], v[174:177], v[182:185], v[42:45]
	v_mfma_f32_16x16x32_bf16 v[30:33], v[166:169], v[190:193], v[30:33]
	v_mfma_f32_16x16x32_bf16 v[26:29], v[174:177], v[190:193], v[26:29]
	v_mfma_f32_16x16x32_bf16 v[14:17], v[166:169], v[198:201], v[14:17]
	v_mfma_f32_16x16x32_bf16 v[10:13], v[174:177], v[198:201], v[10:13]
	v_mfma_f32_16x16x32_bf16 v[6:9], v[166:169], v[208:211], v[6:9]
	v_mfma_f32_16x16x32_bf16 v[2:5], v[174:177], v[208:211], v[2:5]
	v_mfma_f32_16x16x32_bf16 v[46:49], v[170:173], v[186:189], v[46:49]
	v_mfma_f32_16x16x32_bf16 v[42:45], v[178:181], v[186:189], v[42:45]
	v_mfma_f32_16x16x32_bf16 v[30:33], v[170:173], v[194:197], v[30:33]
	v_mfma_f32_16x16x32_bf16 v[26:29], v[178:181], v[194:197], v[26:29]
	v_mfma_f32_16x16x32_bf16 v[14:17], v[170:173], v[204:207], v[14:17]
	v_mfma_f32_16x16x32_bf16 v[10:13], v[178:181], v[204:207], v[10:13]
	v_mfma_f32_16x16x32_bf16 v[6:9], v[170:173], v[212:215], v[6:9]
	v_mfma_f32_16x16x32_bf16 v[2:5], v[178:181], v[212:215], v[2:5]
	s_setprio 0
	s_barrier
	s_movk_i32 s26, 0x100
	s_andn2_b64 vcc, exec, s[22:23]
	s_mov_b64 s[24:25], -1
	s_mov_b64 s[22:23], 0
	s_cbranch_vccz .LBB0_1156
	s_and_b64 vcc, exec, s[16:17]
	s_cbranch_vccz .LBB0_1159
	s_barrier

; #define PG8_STAGE(bufoff, gbase, voff) do { _Pragma("unroll") for (int _i = 0; _i < 2; ++_i) \
;         __builtin_amdgcn_global_load_lds((const unsigned*)((const char*)(gbase) + (voff)[_i]), (LAS unsigned*)(lds + (bufoff) + ldsw + _i * 8192), 16, 0, 0); } while (0)
; #define PG8_LDA(dst, b, h) do { _Pragma("unroll") for (int m = 0; m < 4; ++m) _Pragma("unroll") for (int k = 0; k < 2; ++k) dst[m][k] = *(const LAS bf16x8*)(lds + PG8_SA(b, h) + aoff + m * 2048 + k * 1024); } while (0)
; #define PG8_LDB(dst, b, h) do { _Pragma("unroll") for (int n = 0; n < 2; ++n) _Pragma("unroll") for (int k = 0; k < 2; ++k) dst[n][k] = *(const LAS bf16x8*)(lds + PG8_SB(b, h) + boff + n * 2048 + k * 1024); } while (0)
; #define PG8_MMA(ai, bj, At, Bt) do { __builtin_amdgcn_s_setprio(1); _Pragma("unroll") for (int m = 0; m < 4; ++m) _Pragma("unroll") for (int n = 0; n < 2; ++n) _Pragma("unroll") for (int k = 0; k < 2; ++k) \
;         acc[ai][bj][m][n] = __builtin_amdgcn_mfma_f32_16x16x32_bf16(Bt[n][k], At[m][k], acc[ai][bj][m][n], 0, 0, 0); __builtin_amdgcn_s_setprio(0); } while (0)
; #define PG8_WAIT_V(n) asm volatile("s_waitcnt vmcnt(" #n ")" ::: "memory")
; #define PG8_WAIT_L(n) asm volatile("s_waitcnt lgkmcnt(" #n ")" ::: "memory")
; #define PG8_BAR __builtin_amdgcn_s_barrier()
; #define PG8_SCHED __builtin_amdgcn_sched_barrier(0)
; template <class Epi, class Sched, bool ALIGN_EPI>
; DI void gemm_phase(LAS unsigned char* lds, const Gemm g, const Sched& S, const Epi& E) {
;     ...
;             PG8_LDB(B0, 0, 0); PG8_LDB(B1, 0, 1); PG8_SCHED; PG8_LDA(At, 0, 0); PG8_STAGE(PG8_SA(1, 1), a1 + hstepA, voffA);
;             PG8_WAIT_V(8); PG8_WAIT_L(0); PG8_BAR; PG8_MMA(0, 0, At, B0); PG8_MMA(0, 1, At, B1); PG8_BAR; PG8_SCHED;
;             PG8_LDA(At, 0, 1); PG8_STAGE(PG8_SB(0, 0), b2, voffB); PG8_STAGE(PG8_SB(0, 1), b2 + hstepB, voffB); PG8_STAGE(PG8_SA(0, 0), a2, voffA);
;             PG8_WAIT_V(8); PG8_WAIT_L(0); PG8_BAR; PG8_MMA(1, 0, At, B0); PG8_MMA(1, 1, At, B1); PG8_BAR; PG8_SCHED;
.LBB0_1237:
	v_add_u32_e32 v147, s45, v1
	ds_read_b128 v[148:151], v147
	ds_read_b128 v[154:157], v147 offset:1024
	ds_read_b128 v[158:161], v147 offset:2048
	ds_read_b128 v[162:165], v147 offset:3072
	v_add_u32_e32 v147, s68, v1
	s_add_u32 s16, s8, s14
	ds_read_b128 v[166:169], v147
	ds_read_b128 v[170:173], v147 offset:1024
	ds_read_b128 v[174:177], v147 offset:2048
	ds_read_b128 v[178:181], v147 offset:3072
	s_addc_u32 s17, s9, s15
	s_add_u32 s16, s16, 0x100
	s_addc_u32 s17, s17, 0
	s_add_u32 s55, s52, s14
	s_addc_u32 s56, s53, s15
	s_cmpk_eq_i32 s14, 0x1500
	s_cselect_b32 s19, s13, s17
	s_cselect_b32 s18, s12, s16
	s_cselect_b32 s17, s1, s56
	s_cselect_b32 s16, s0, s55
	v_lshl_add_u64 v[216:217], v[142:143], 0, s[14:15]
	s_add_i32 m0, s37, 0xc000
	ds_read_b128 v[182:185], v146
	ds_read_b128 v[186:189], v146 offset:1024
	ds_read_b128 v[190:193], v146 offset:2048
	ds_read_b128 v[194:197], v146 offset:3072
	ds_read_b128 v[198:201], v146 offset:4096
	ds_read_b128 v[204:207], v146 offset:5120
	ds_read_b128 v[208:211], v146 offset:6144
	ds_read_b128 v[212:215], v146 offset:7168
	global_load_lds_dwordx4 v[216:217], off
	v_lshl_add_u64 v[216:217], v[144:145], 0, s[14:15]
	s_add_i32 m0, s37, 0xe000
	s_nop 0
	global_load_lds_dwordx4 v[216:217], off
	s_waitcnt vmcnt(8)
	s_waitcnt lgkmcnt(0)
	s_barrier
	s_setprio 1
	s_waitcnt lgkmcnt(0)
	v_mfma_f32_16x16x32_bf16 v[126:129], v[148:151], v[182:185], v[126:129]
	v_mfma_f32_16x16x32_bf16 v[122:125], v[158:161], v[182:185], v[122:125]
	v_mfma_f32_16x16x32_bf16 v[114:117], v[148:151], v[190:193], v[114:117]
	v_mfma_f32_16x16x32_bf16 v[110:113], v[158:161], v[190:193], v[110:113]
	v_mfma_f32_16x16x32_bf16 v[98:101], v[148:151], v[198:201], v[98:101]
	v_mfma_f32_16x16x32_bf16 v[94:97], v[158:161], v[198:201], v[94:97]
	v_mfma_f32_16x16x32_bf16 v[82:85], v[148:151], v[208:211], v[82:85]
	v_mfma_f32_16x16x32_bf16 v[78:81], v[158:161], v[208:211], v[78:81]
	v_mfma_f32_16x16x32_bf16 v[126:129], v[154:157], v[186:189], v[126:129]
	v_mfma_f32_16x16x32_bf16 v[122:125], v[162:165], v[186:189], v[122:125]
	v_mfma_f32_16x16x32_bf16 v[114:117], v[154:157], v[194:197], v[114:117]
	v_mfma_f32_16x16x32_bf16 v[110:113], v[162:165], v[194:197], v[110:113]
	v_mfma_f32_16x16x32_bf16 v[98:101], v[154:157], v[204:207], v[98:101]
	v_mfma_f32_16x16x32_bf16 v[94:97], v[162:165], v[204:207], v[94:97]
	v_mfma_f32_16x16x32_bf16 v[82:85], v[154:157], v[212:215], v[82:85]
	v_mfma_f32_16x16x32_bf16 v[78:81], v[162:165], v[212:215], v[78:81]
	v_mfma_f32_16x16x32_bf16 v[118:121], v[166:169], v[182:185], v[118:121]
	v_mfma_f32_16x16x32_bf16 v[106:109], v[174:177], v[182:185], v[106:109]
	v_mfma_f32_16x16x32_bf16 v[102:105], v[166:169], v[190:193], v[102:105]
	v_mfma_f32_16x16x32_bf16 v[90:93], v[174:177], v[190:193], v[90:93]
	v_mfma_f32_16x16x32_bf16 v[86:89], v[166:169], v[198:201], v[86:89]
	v_mfma_f32_16x16x32_bf16 v[74:77], v[174:177], v[198:201], v[74:77]
	v_mfma_f32_16x16x32_bf16 v[70:73], v[166:169], v[208:211], v[70:73]
	v_mfma_f32_16x16x32_bf16 v[66:69], v[174:177], v[208:211], v[66:69]
	v_mfma_f32_16x16x32_bf16 v[118:121], v[170:173], v[186:189], v[118:121]
	v_mfma_f32_16x16x32_bf16 v[106:109], v[178:181], v[186:189], v[106:109]
	v_mfma_f32_16x16x32_bf16 v[102:105], v[170:173], v[194:197], v[102:105]
	v_mfma_f32_16x16x32_bf16 v[90:93], v[178:181], v[194:197], v[90:93]
	v_mfma_f32_16x16x32_bf16 v[86:89], v[170:173], v[204:207], v[86:89]
	v_mfma_f32_16x16x32_bf16 v[74:77], v[178:181], v[204:207], v[74:77]
	v_mfma_f32_16x16x32_bf16 v[70:73], v[170:173], v[212:215], v[70:73]
	v_mfma_f32_16x16x32_bf16 v[66:69], v[178:181], v[212:215], v[66:69]
	s_setprio 0
	s_barrier
	s_add_i32 s55, s45, s36
	v_lshl_add_u64 v[216:217], s[16:17], 0, v[130:131]
	s_mov_b32 m0, s55
	ds_read_b128 v[182:185], v146 offset:16384
	ds_read_b128 v[186:189], v146 offset:17408
	ds_read_b128 v[190:193], v146 offset:18432
	ds_read_b128 v[194:197], v146 offset:19456
	ds_read_b128 v[198:201], v146 offset:20480
	ds_read_b128 v[204:207], v146 offset:21504
	ds_read_b128 v[208:211], v146 offset:22528
	ds_read_b128 v[212:215], v146 offset:23552
	global_load_lds_dwordx4 v[216:217], off
	s_add_i32 m0, s55, 0x2000
	s_add_u32 s56, s16, 0xb0000
	v_lshl_add_u64 v[218:219], s[16:17], 0, v[132:133]
	s_addc_u32 s57, s17, 0
	s_add_i32 s55, s68, s36
	global_load_lds_dwordx4 v[218:219], off
	v_lshl_add_u64 v[220:221], s[56:57], 0, v[130:131]
	s_mov_b32 m0, s55
	v_lshl_add_u64 v[222:223], s[18:19], 0, v[132:133]
	global_load_lds_dwordx4 v[220:221], off
	v_lshl_add_u64 v[220:221], s[56:57], 0, v[132:133]
	s_add_i32 m0, s55, 0x2000
	s_nop 0
	global_load_lds_dwordx4 v[220:221], off
	v_lshl_add_u64 v[220:221], s[18:19], 0, v[130:131]
	s_mov_b32 m0, s37
	s_nop 0
	global_load_lds_dwordx4 v[220:221], off
	s_mov_b32 m0, s40
	s_nop 0
	global_load_lds_dwordx4 v[222:223], off
	s_waitcnt vmcnt(8)
	s_waitcnt lgkmcnt(0)
	s_barrier
; #define PG8_STAGE(bufoff, gbase, voff) do { _Pragma("unroll") for (int _i = 0; _i < 2; ++_i) \
;         __builtin_amdgcn_global_load_lds((const unsigned*)((const char*)(gbase) + (voff)[_i]), (LAS unsigned*)(lds + (bufoff) + ldsw + _i * 8192), 16, 0, 0); } while (0)
; #define PG8_LDA(dst, b, h) do { _Pragma("unroll") for (int m = 0; m < 4; ++m) _Pragma("unroll") for (int k = 0; k < 2; ++k) dst[m][k] = *(const LAS bf16x8*)(lds + PG8_SA(b, h) + aoff + m * 2048 + k * 1024); } while (0)
; #define PG8_LDB(dst, b, h) do { _Pragma("unroll") for (int n = 0; n < 2; ++n) _Pragma("unroll") for (int k = 0; k < 2; ++k) dst[n][k] = *(const LAS bf16x8*)(lds + PG8_SB(b, h) + boff + n * 2048 + k * 1024); } while (0)
; #define PG8_MMA(ai, bj, At, Bt) do { __builtin_amdgcn_s_setprio(1); _Pragma("unroll") for (int m = 0; m < 4; ++m) _Pragma("unroll") for (int n = 0; n < 2; ++n) _Pragma("unroll") for (int k = 0; k < 2; ++k) \
;         acc[ai][bj][m][n] = __builtin_amdgcn_mfma_f32_16x16x32_bf16(Bt[n][k], At[m][k], acc[ai][bj][m][n], 0, 0, 0); __builtin_amdgcn_s_setprio(0); } while (0)
; #define PG8_WAIT_V(n) asm volatile("s_waitcnt vmcnt(" #n ")" ::: "memory")
; #define PG8_WAIT_L(n) asm volatile("s_waitcnt lgkmcnt(" #n ")" ::: "memory")
; #define PG8_BAR __builtin_amdgcn_s_barrier()
; #define PG8_SCHED __builtin_amdgcn_sched_barrier(0)
; template <class Epi, class Sched, bool ALIGN_EPI>
; DI void gemm_phase(LAS unsigned char* lds, const Gemm g, const Sched& S, const Epi& E) {
;     ...
;             PG8_WAIT_V(8); PG8_WAIT_L(0); PG8_BAR; PG8_MMA(1, 0, At, B0); PG8_MMA(1, 1, At, B1); PG8_BAR; PG8_SCHED;
;             PG8_LDB(B0, 1, 0); PG8_LDB(B1, 1, 1); PG8_SCHED; PG8_LDA(At, 1, 0); PG8_STAGE(PG8_SA(0, 1), a2 + hstepA, voffA);
;             PG8_WAIT_V(8); PG8_WAIT_L(0); PG8_BAR; PG8_MMA(0, 0, At, B0); PG8_MMA(0, 1, At, B1); PG8_BAR; PG8_SCHED;
	s_setprio 1
	s_waitcnt lgkmcnt(0)
	v_mfma_f32_16x16x32_bf16 v[62:65], v[148:151], v[182:185], v[62:65]
	v_mfma_f32_16x16x32_bf16 v[58:61], v[158:161], v[182:185], v[58:61]
	v_mfma_f32_16x16x32_bf16 v[46:49], v[148:151], v[190:193], v[46:49]
	v_mfma_f32_16x16x32_bf16 v[42:45], v[158:161], v[190:193], v[42:45]
	v_mfma_f32_16x16x32_bf16 v[30:33], v[148:151], v[198:201], v[30:33]
	v_mfma_f32_16x16x32_bf16 v[26:29], v[158:161], v[198:201], v[26:29]
	v_mfma_f32_16x16x32_bf16 v[14:17], v[148:151], v[208:211], v[14:17]
	v_mfma_f32_16x16x32_bf16 v[10:13], v[158:161], v[208:211], v[10:13]
	v_mfma_f32_16x16x32_bf16 v[62:65], v[154:157], v[186:189], v[62:65]
	v_mfma_f32_16x16x32_bf16 v[58:61], v[162:165], v[186:189], v[58:61]
	v_mfma_f32_16x16x32_bf16 v[46:49], v[154:157], v[194:197], v[46:49]
	v_mfma_f32_16x16x32_bf16 v[42:45], v[162:165], v[194:197], v[42:45]
	v_mfma_f32_16x16x32_bf16 v[30:33], v[154:157], v[204:207], v[30:33]
	v_mfma_f32_16x16x32_bf16 v[26:29], v[162:165], v[204:207], v[26:29]
	v_mfma_f32_16x16x32_bf16 v[14:17], v[154:157], v[212:215], v[14:17]
	v_mfma_f32_16x16x32_bf16 v[10:13], v[162:165], v[212:215], v[10:13]
	v_mfma_f32_16x16x32_bf16 v[54:57], v[166:169], v[182:185], v[54:57]
	v_mfma_f32_16x16x32_bf16 v[50:53], v[174:177], v[182:185], v[50:53]
	v_mfma_f32_16x16x32_bf16 v[38:41], v[166:169], v[190:193], v[38:41]
	v_mfma_f32_16x16x32_bf16 v[34:37], v[174:177], v[190:193], v[34:37]
	v_mfma_f32_16x16x32_bf16 v[22:25], v[166:169], v[198:201], v[22:25]
	v_mfma_f32_16x16x32_bf16 v[18:21], v[174:177], v[198:201], v[18:21]
	v_mfma_f32_16x16x32_bf16 v[6:9], v[166:169], v[208:211], v[6:9]
	v_mfma_f32_16x16x32_bf16 v[2:5], v[174:177], v[208:211], v[2:5]
	v_mfma_f32_16x16x32_bf16 v[54:57], v[170:173], v[186:189], v[54:57]
	v_mfma_f32_16x16x32_bf16 v[50:53], v[178:181], v[186:189], v[50:53]
	v_mfma_f32_16x16x32_bf16 v[38:41], v[170:173], v[194:197], v[38:41]
	v_mfma_f32_16x16x32_bf16 v[34:37], v[178:181], v[194:197], v[34:37]
	v_mfma_f32_16x16x32_bf16 v[22:25], v[170:173], v[204:207], v[22:25]
	v_mfma_f32_16x16x32_bf16 v[18:21], v[178:181], v[204:207], v[18:21]
	v_mfma_f32_16x16x32_bf16 v[6:9], v[170:173], v[212:215], v[6:9]
	v_mfma_f32_16x16x32_bf16 v[2:5], v[178:181], v[212:215], v[2:5]
	s_setprio 0
	s_barrier
	v_add_u32_e32 v147, s69, v1
	ds_read_b128 v[148:151], v147
	ds_read_b128 v[154:157], v147 offset:1024
	ds_read_b128 v[158:161], v147 offset:2048
	ds_read_b128 v[162:165], v147 offset:3072
	v_add_u32_e32 v147, s72, v1
	ds_read_b128 v[166:169], v147
	ds_read_b128 v[170:173], v147 offset:1024
	ds_read_b128 v[174:177], v147 offset:2048
	ds_read_b128 v[178:181], v147 offset:3072
	s_add_u32 s18, s18, 0xb0000
	s_addc_u32 s19, s19, 0
	s_mov_b32 m0, s41
	v_lshl_add_u64 v[224:225], s[18:19], 0, v[130:131]
	ds_read_b128 v[182:185], v146 offset:32768
	ds_read_b128 v[186:189], v146 offset:33792
	ds_read_b128 v[190:193], v146 offset:34816
	ds_read_b128 v[194:197], v146 offset:35840
	ds_read_b128 v[198:201], v146 offset:36864
	ds_read_b128 v[204:207], v146 offset:37888
	ds_read_b128 v[208:211], v146 offset:38912
	ds_read_b128 v[212:215], v146 offset:39936
	global_load_lds_dwordx4 v[224:225], off
	v_lshl_add_u64 v[224:225], s[18:19], 0, v[132:133]
	s_mov_b32 m0, s42
	s_nop 0
	global_load_lds_dwordx4 v[224:225], off
	s_waitcnt vmcnt(8)
	s_waitcnt lgkmcnt(0)
	s_barrier
	s_setprio 1
	s_waitcnt lgkmcnt(0)
	v_mfma_f32_16x16x32_bf16 v[126:129], v[148:151], v[182:185], v[126:129]
	v_mfma_f32_16x16x32_bf16 v[122:125], v[158:161], v[182:185], v[122:125]
	v_mfma_f32_16x16x32_bf16 v[114:117], v[148:151], v[190:193], v[114:117]
	v_mfma_f32_16x16x32_bf16 v[110:113], v[158:161], v[190:193], v[110:113]
	v_mfma_f32_16x16x32_bf16 v[98:101], v[148:151], v[198:201], v[98:101]
	v_mfma_f32_16x16x32_bf16 v[94:97], v[158:161], v[198:201], v[94:97]
	v_mfma_f32_16x16x32_bf16 v[82:85], v[148:151], v[208:211], v[82:85]
	v_mfma_f32_16x16x32_bf16 v[78:81], v[158:161], v[208:211], v[78:81]
	v_mfma_f32_16x16x32_bf16 v[126:129], v[154:157], v[186:189], v[126:129]
	v_mfma_f32_16x16x32_bf16 v[122:125], v[162:165], v[186:189], v[122:125]
	v_mfma_f32_16x16x32_bf16 v[114:117], v[154:157], v[194:197], v[114:117]
	v_mfma_f32_16x16x32_bf16 v[110:113], v[162:165], v[194:197], v[110:113]
	v_mfma_f32_16x16x32_bf16 v[98:101], v[154:157], v[204:207], v[98:101]
	v_mfma_f32_16x16x32_bf16 v[94:97], v[162:165], v[204:207], v[94:97]
	v_mfma_f32_16x16x32_bf16 v[82:85], v[154:157], v[212:215], v[82:85]
	v_mfma_f32_16x16x32_bf16 v[78:81], v[162:165], v[212:215], v[78:81]
	v_mfma_f32_16x16x32_bf16 v[118:121], v[166:169], v[182:185], v[118:121]
	v_mfma_f32_16x16x32_bf16 v[106:109], v[174:177], v[182:185], v[106:109]
	v_mfma_f32_16x16x32_bf16 v[102:105], v[166:169], v[190:193], v[102:105]
	v_mfma_f32_16x16x32_bf16 v[90:93], v[174:177], v[190:193], v[90:93]
	v_mfma_f32_16x16x32_bf16 v[86:89], v[166:169], v[198:201], v[86:89]
	v_mfma_f32_16x16x32_bf16 v[74:77], v[174:177], v[198:201], v[74:77]
	v_mfma_f32_16x16x32_bf16 v[70:73], v[166:169], v[208:211], v[70:73]
	v_mfma_f32_16x16x32_bf16 v[66:69], v[174:177], v[208:211], v[66:69]
	v_mfma_f32_16x16x32_bf16 v[118:121], v[170:173], v[186:189], v[118:121]
	v_mfma_f32_16x16x32_bf16 v[106:109], v[178:181], v[186:189], v[106:109]
	v_mfma_f32_16x16x32_bf16 v[102:105], v[170:173], v[194:197], v[102:105]
	v_mfma_f32_16x16x32_bf16 v[90:93], v[178:181], v[194:197], v[90:93]
	v_mfma_f32_16x16x32_bf16 v[86:89], v[170:173], v[204:207], v[86:89]
	v_mfma_f32_16x16x32_bf16 v[74:77], v[178:181], v[204:207], v[74:77]
	v_mfma_f32_16x16x32_bf16 v[70:73], v[170:173], v[212:215], v[70:73]
	v_mfma_f32_16x16x32_bf16 v[66:69], v[178:181], v[212:215], v[66:69]
	s_setprio 0
	s_barrier
; #define PG8_STAGE(bufoff, gbase, voff) do { _Pragma("unroll") for (int _i = 0; _i < 2; ++_i) \
;         __builtin_amdgcn_global_load_lds((const unsigned*)((const char*)(gbase) + (voff)[_i]), (LAS unsigned*)(lds + (bufoff) + ldsw + _i * 8192), 16, 0, 0); } while (0)
; #define PG8_LDA(dst, b, h) do { _Pragma("unroll") for (int m = 0; m < 4; ++m) _Pragma("unroll") for (int k = 0; k < 2; ++k) dst[m][k] = *(const LAS bf16x8*)(lds + PG8_SA(b, h) + aoff + m * 2048 + k * 1024); } while (0)
; #define PG8_MMA(ai, bj, At, Bt) do { __builtin_amdgcn_s_setprio(1); _Pragma("unroll") for (int m = 0; m < 4; ++m) _Pragma("unroll") for (int n = 0; n < 2; ++n) _Pragma("unroll") for (int k = 0; k < 2; ++k) \
;         acc[ai][bj][m][n] = __builtin_amdgcn_mfma_f32_16x16x32_bf16(Bt[n][k], At[m][k], acc[ai][bj][m][n], 0, 0, 0); __builtin_amdgcn_s_setprio(0); } while (0)
; #define PG8_WAIT_V(n) asm volatile("s_waitcnt vmcnt(" #n ")" ::: "memory")
; #define PG8_WAIT_L(n) asm volatile("s_waitcnt lgkmcnt(" #n ")" ::: "memory")
; #define PG8_BAR __builtin_amdgcn_s_barrier()
; #define PG8_SCHED __builtin_amdgcn_sched_barrier(0)
; template <class Epi, class Sched, bool ALIGN_EPI>
; DI void gemm_phase(LAS unsigned char* lds, const Gemm g, const Sched& S, const Epi& E) {
;     ...
;             PG8_LDA(At, 1, 1); PG8_STAGE(PG8_SB(1, 0), b3, voffB); PG8_STAGE(PG8_SB(1, 1), b3 + hstepB, voffB); PG8_STAGE(PG8_SA(1, 0), a3, voffA);
;             PG8_WAIT_V(8); PG8_WAIT_L(0); PG8_BAR; PG8_MMA(1, 0, At, B0); PG8_MMA(1, 1, At, B1); PG8_BAR; PG8_SCHED;
;         }
;         if constexpr (ALIGN_EPI) { if (wr == 0) PG8_BAR; }
;         if constexpr (!Epi::AFTER_DRAIN) E(acc, cur, wr, wc, fr, fq);
;         if (!has_next) break;
; #pragma unroll
;         for (int a = 0; a < 2; ++a)
; #pragma unroll
;             for (int b = 0; b < 2; ++b)
; #pragma unroll
;                 for (int m = 0; m < 4; ++m)
; #pragma unroll
;                     for (int n = 0; n < 2; ++n) acc[a][b][m][n] = (f32x4){0.f, 0.f, 0.f, 0.f};
;         cur = nxt; cA = nA; cB = nB; ++ui;
	s_add_i32 s18, s69, s36
	v_lshl_add_u64 v[216:217], v[216:217], 0, s[10:11]
	s_mov_b32 m0, s18
	ds_read_b128 v[182:185], v146 offset:49152
	ds_read_b128 v[186:189], v146 offset:50176
	ds_read_b128 v[190:193], v146 offset:51200
	ds_read_b128 v[194:197], v146 offset:52224
	ds_read_b128 v[198:201], v146 offset:53248
	ds_read_b128 v[204:207], v146 offset:54272
	ds_read_b128 v[208:211], v146 offset:55296
	ds_read_b128 v[212:215], v146 offset:56320
	global_load_lds_dwordx4 v[216:217], off
	s_add_i32 m0, s18, 0x2000
	s_add_u32 s16, s16, 0xb0080
	v_lshl_add_u64 v[216:217], v[218:219], 0, s[10:11]
	s_addc_u32 s17, s17, 0
	s_add_i32 s18, s72, s36
	global_load_lds_dwordx4 v[216:217], off
	v_lshl_add_u64 v[216:217], s[16:17], 0, v[130:131]
	s_mov_b32 m0, s18
	s_nop 0
	global_load_lds_dwordx4 v[216:217], off
	v_lshl_add_u64 v[216:217], s[16:17], 0, v[132:133]
	s_add_i32 m0, s18, 0x2000
	s_nop 0
	global_load_lds_dwordx4 v[216:217], off
	v_lshl_add_u64 v[216:217], v[220:221], 0, s[10:11]
	s_mov_b32 m0, s43
	s_nop 0
	global_load_lds_dwordx4 v[216:217], off
	v_lshl_add_u64 v[216:217], v[222:223], 0, s[10:11]
	s_mov_b32 m0, s44
	s_nop 0
	global_load_lds_dwordx4 v[216:217], off
	s_waitcnt vmcnt(8)
	s_waitcnt lgkmcnt(0)
	s_barrier
	s_setprio 1
	s_waitcnt lgkmcnt(0)
	v_mfma_f32_16x16x32_bf16 v[62:65], v[148:151], v[182:185], v[62:65]
	v_mfma_f32_16x16x32_bf16 v[58:61], v[158:161], v[182:185], v[58:61]
	v_mfma_f32_16x16x32_bf16 v[46:49], v[148:151], v[190:193], v[46:49]
	v_mfma_f32_16x16x32_bf16 v[42:45], v[158:161], v[190:193], v[42:45]
	v_mfma_f32_16x16x32_bf16 v[30:33], v[148:151], v[198:201], v[30:33]
	v_mfma_f32_16x16x32_bf16 v[26:29], v[158:161], v[198:201], v[26:29]
	v_mfma_f32_16x16x32_bf16 v[14:17], v[148:151], v[208:211], v[14:17]
	v_mfma_f32_16x16x32_bf16 v[10:13], v[158:161], v[208:211], v[10:13]
	v_mfma_f32_16x16x32_bf16 v[62:65], v[154:157], v[186:189], v[62:65]
	v_mfma_f32_16x16x32_bf16 v[58:61], v[162:165], v[186:189], v[58:61]
	v_mfma_f32_16x16x32_bf16 v[46:49], v[154:157], v[194:197], v[46:49]
	v_mfma_f32_16x16x32_bf16 v[42:45], v[162:165], v[194:197], v[42:45]
	v_mfma_f32_16x16x32_bf16 v[30:33], v[154:157], v[204:207], v[30:33]
	v_mfma_f32_16x16x32_bf16 v[26:29], v[162:165], v[204:207], v[26:29]
	v_mfma_f32_16x16x32_bf16 v[14:17], v[154:157], v[212:215], v[14:17]
	v_mfma_f32_16x16x32_bf16 v[10:13], v[162:165], v[212:215], v[10:13]
	v_mfma_f32_16x16x32_bf16 v[54:57], v[166:169], v[182:185], v[54:57]
	v_mfma_f32_16x16x32_bf16 v[50:53], v[174:177], v[182:185], v[50:53]
	v_mfma_f32_16x16x32_bf16 v[38:41], v[166:169], v[190:193], v[38:41]
	v_mfma_f32_16x16x32_bf16 v[34:37], v[174:177], v[190:193], v[34:37]
	v_mfma_f32_16x16x32_bf16 v[22:25], v[166:169], v[198:201], v[22:25]
	v_mfma_f32_16x16x32_bf16 v[18:21], v[174:177], v[198:201], v[18:21]
	v_mfma_f32_16x16x32_bf16 v[6:9], v[166:169], v[208:211], v[6:9]
	v_mfma_f32_16x16x32_bf16 v[2:5], v[174:177], v[208:211], v[2:5]
	v_mfma_f32_16x16x32_bf16 v[54:57], v[170:173], v[186:189], v[54:57]
	v_mfma_f32_16x16x32_bf16 v[50:53], v[178:181], v[186:189], v[50:53]
	v_mfma_f32_16x16x32_bf16 v[38:41], v[170:173], v[194:197], v[38:41]
	v_mfma_f32_16x16x32_bf16 v[34:37], v[178:181], v[194:197], v[34:37]
	v_mfma_f32_16x16x32_bf16 v[22:25], v[170:173], v[204:207], v[22:25]
	v_mfma_f32_16x16x32_bf16 v[18:21], v[178:181], v[204:207], v[18:21]
	v_mfma_f32_16x16x32_bf16 v[6:9], v[170:173], v[212:215], v[6:9]
	v_mfma_f32_16x16x32_bf16 v[2:5], v[178:181], v[212:215], v[2:5]
	s_setprio 0
	s_barrier
	s_add_i32 s54, s54, 2
	s_add_u32 s14, s14, 0x100
	s_addc_u32 s15, s15, 0
	s_cmp_gt_u32 s54, 41
	s_cbranch_scc0 .LBB0_1237
	s_add_u32 s14, s52, 0xffffff00
	s_addc_u32 s15, s53, -1
	s_and_b64 vcc, exec, s[6:7]
	s_cbranch_vccnz .LBB0_1240
	v_mov_b32_e32 v2, 0
	s_mov_b32 s2, s73
	s_mov_b32 s22, s74
	s_mov_b64 s[8:9], s[12:13]
	s_mov_b32 s71, s33
	v_mov_b32_e32 v3, v2
	v_mov_b32_e32 v4, v2
	v_mov_b32_e32 v5, v2
	v_mov_b32_e32 v6, v2
	v_mov_b32_e32 v7, v2
	v_mov_b32_e32 v8, v2
	v_mov_b32_e32 v9, v2
	v_mov_b32_e32 v18, v2
	v_mov_b32_e32 v19, v2
	v_mov_b32_e32 v20, v2
	v_mov_b32_e32 v21, v2
	v_mov_b32_e32 v22, v2
	v_mov_b32_e32 v23, v2
	v_mov_b32_e32 v24, v2
	v_mov_b32_e32 v25, v2
	v_mov_b32_e32 v34, v2
	v_mov_b32_e32 v35, v2
	v_mov_b32_e32 v36, v2
	v_mov_b32_e32 v37, v2
	v_mov_b32_e32 v38, v2
	v_mov_b32_e32 v39, v2
	v_mov_b32_e32 v40, v2
	v_mov_b32_e32 v41, v2
	v_mov_b32_e32 v50, v2
	v_mov_b32_e32 v51, v2
	v_mov_b32_e32 v52, v2
	v_mov_b32_e32 v53, v2
	v_mov_b32_e32 v54, v2
	v_mov_b32_e32 v55, v2
	v_mov_b32_e32 v56, v2
	v_mov_b32_e32 v57, v2
	v_mov_b32_e32 v10, v2
	v_mov_b32_e32 v11, v2
	v_mov_b32_e32 v12, v2
	v_mov_b32_e32 v13, v2
	v_mov_b32_e32 v14, v2
	v_mov_b32_e32 v15, v2
	v_mov_b32_e32 v16, v2
	v_mov_b32_e32 v17, v2
	v_mov_b32_e32 v26, v2
	v_mov_b32_e32 v27, v2
	v_mov_b32_e32 v28, v2
	v_mov_b32_e32 v29, v2
	v_mov_b32_e32 v30, v2
	v_mov_b32_e32 v31, v2
	v_mov_b32_e32 v32, v2
	v_mov_b32_e32 v33, v2
	v_mov_b32_e32 v42, v2
	v_mov_b32_e32 v43, v2
	v_mov_b32_e32 v44, v2
	v_mov_b32_e32 v45, v2
	v_mov_b32_e32 v46, v2
	v_mov_b32_e32 v47, v2
	v_mov_b32_e32 v48, v2
	v_mov_b32_e32 v49, v2
	v_mov_b32_e32 v58, v2
	v_mov_b32_e32 v59, v2
	v_mov_b32_e32 v60, v2
	v_mov_b32_e32 v61, v2
	v_mov_b32_e32 v62, v2
	v_mov_b32_e32 v63, v2
	v_mov_b32_e32 v64, v2
	v_mov_b32_e32 v65, v2
	v_mov_b32_e32 v66, v2
	v_mov_b32_e32 v67, v2
	v_mov_b32_e32 v68, v2
	v_mov_b32_e32 v69, v2
	v_mov_b32_e32 v70, v2
	v_mov_b32_e32 v71, v2
	v_mov_b32_e32 v72, v2
	v_mov_b32_e32 v73, v2
	v_mov_b32_e32 v74, v2
	v_mov_b32_e32 v75, v2
	v_mov_b32_e32 v76, v2
	v_mov_b32_e32 v77, v2
	v_mov_b32_e32 v86, v2
	v_mov_b32_e32 v87, v2
	v_mov_b32_e32 v88, v2
	v_mov_b32_e32 v89, v2
	v_mov_b32_e32 v90, v2
	v_mov_b32_e32 v91, v2
	v_mov_b32_e32 v92, v2
	v_mov_b32_e32 v93, v2
	v_mov_b32_e32 v102, v2
	v_mov_b32_e32 v103, v2
	v_mov_b32_e32 v104, v2
	v_mov_b32_e32 v105, v2
	v_mov_b32_e32 v106, v2
	v_mov_b32_e32 v107, v2
	v_mov_b32_e32 v108, v2
	v_mov_b32_e32 v109, v2
	v_mov_b32_e32 v118, v2
	v_mov_b32_e32 v119, v2
	v_mov_b32_e32 v120, v2
	v_mov_b32_e32 v121, v2
	v_mov_b32_e32 v78, v2
	v_mov_b32_e32 v79, v2
	v_mov_b32_e32 v80, v2
	v_mov_b32_e32 v81, v2
	v_mov_b32_e32 v82, v2
	v_mov_b32_e32 v83, v2
	v_mov_b32_e32 v84, v2
	v_mov_b32_e32 v85, v2
	v_mov_b32_e32 v94, v2
	v_mov_b32_e32 v95, v2
	v_mov_b32_e32 v96, v2
	v_mov_b32_e32 v97, v2
	v_mov_b32_e32 v98, v2
	v_mov_b32_e32 v99, v2
	v_mov_b32_e32 v100, v2
	v_mov_b32_e32 v101, v2
	v_mov_b32_e32 v110, v2
	v_mov_b32_e32 v111, v2
	v_mov_b32_e32 v112, v2
	v_mov_b32_e32 v113, v2
	v_mov_b32_e32 v114, v2
	v_mov_b32_e32 v115, v2
	v_mov_b32_e32 v116, v2
	v_mov_b32_e32 v117, v2
	v_mov_b32_e32 v122, v2
	v_mov_b32_e32 v123, v2
	v_mov_b32_e32 v124, v2
	v_mov_b32_e32 v125, v2
	v_mov_b32_e32 v126, v2
	v_mov_b32_e32 v127, v2
	v_mov_b32_e32 v128, v2
	v_mov_b32_e32 v129, v2
	s_andn2_b64 vcc, exec, s[4:5]
	s_cbranch_vccnz .LBB0_1241
	s_branch .LBB0_1242

; #define PG8_STAGE(bufoff, gbase, voff) do { _Pragma("unroll") for (int _i = 0; _i < 2; ++_i) \
;         __builtin_amdgcn_global_load_lds((const unsigned*)((const char*)(gbase) + (voff)[_i]), (LAS unsigned*)(lds + (bufoff) + ldsw + _i * 8192), 16, 0, 0); } while (0)
; #define PG8_LDA(dst, b, h) do { _Pragma("unroll") for (int m = 0; m < 4; ++m) _Pragma("unroll") for (int k = 0; k < 2; ++k) dst[m][k] = *(const LAS bf16x8*)(lds + PG8_SA(b, h) + aoff + m * 2048 + k * 1024); } while (0)
; #define PG8_LDB(dst, b, h) do { _Pragma("unroll") for (int n = 0; n < 2; ++n) _Pragma("unroll") for (int k = 0; k < 2; ++k) dst[n][k] = *(const LAS bf16x8*)(lds + PG8_SB(b, h) + boff + n * 2048 + k * 1024); } while (0)
; #define PG8_MMA(ai, bj, At, Bt) do { __builtin_amdgcn_s_setprio(1); _Pragma("unroll") for (int m = 0; m < 4; ++m) _Pragma("unroll") for (int n = 0; n < 2; ++n) _Pragma("unroll") for (int k = 0; k < 2; ++k) \
;         acc[ai][bj][m][n] = __builtin_amdgcn_mfma_f32_16x16x32_bf16(Bt[n][k], At[m][k], acc[ai][bj][m][n], 0, 0, 0); __builtin_amdgcn_s_setprio(0); } while (0)
; #define PG8_WAIT_V(n) asm volatile("s_waitcnt vmcnt(" #n ")" ::: "memory")
; #define PG8_WAIT_L(n) asm volatile("s_waitcnt lgkmcnt(" #n ")" ::: "memory")
; #define PG8_BAR __builtin_amdgcn_s_barrier()
; #define PG8_SCHED __builtin_amdgcn_sched_barrier(0)
; template <class Epi, class Sched, bool ALIGN_EPI>
; DI void gemm_phase(LAS unsigned char* lds, const Gemm g, const Sched& S, const Epi& E) {
;     ...
;             PG8_LDB(B0, 0, 0); PG8_LDB(B1, 0, 1); PG8_SCHED; PG8_LDA(At, 0, 0); PG8_STAGE(PG8_SA(1, 1), a1 + hstepA, voffA);
;             PG8_WAIT_V(8); PG8_WAIT_L(0); PG8_BAR; PG8_MMA(0, 0, At, B0); PG8_MMA(0, 1, At, B1); PG8_BAR; PG8_SCHED;
;             PG8_LDA(At, 0, 1); PG8_STAGE(PG8_SB(0, 0), b2, voffB); PG8_STAGE(PG8_SB(0, 1), b2 + hstepB, voffB); PG8_STAGE(PG8_SA(0, 0), a2, voffA);
;             PG8_WAIT_V(8); PG8_WAIT_L(0); PG8_BAR; PG8_MMA(1, 0, At, B0); PG8_MMA(1, 1, At, B1); PG8_BAR; PG8_SCHED;
.LBB0_1350:
	ds_read_b128 v[142:145], v151
	ds_read_b128 v[146:149], v151 offset:1024
	ds_read_b128 v[158:161], v151 offset:2048
	ds_read_b128 v[162:165], v151 offset:3072
	ds_read_b128 v[166:169], v153
	ds_read_b128 v[170:173], v153 offset:1024
	ds_read_b128 v[174:177], v153 offset:2048
	ds_read_b128 v[178:181], v153 offset:3072
	s_add_u32 s24, s22, 0xfffc0080
	s_addc_u32 s25, s23, -1
	s_cmp_eq_u32 s56, 12
	s_cselect_b32 s27, s15, s25
	s_cselect_b32 s26, s52, s24
	s_cselect_b32 s25, s13, s55
	s_cselect_b32 s24, s53, s54
	v_lshl_add_u64 v[216:217], s[22:23], 0, v[134:135]
	s_add_i32 m0, s21, 0xc000
	ds_read_b128 v[182:185], v154
	ds_read_b128 v[186:189], v154 offset:1024
	ds_read_b128 v[190:193], v154 offset:2048
	ds_read_b128 v[194:197], v154 offset:3072
	ds_read_b128 v[198:201], v154 offset:4096
	ds_read_b128 v[204:207], v154 offset:5120
	ds_read_b128 v[208:211], v154 offset:6144
	ds_read_b128 v[212:215], v154 offset:7168
	global_load_lds_dwordx4 v[216:217], off
	v_lshl_add_u64 v[216:217], s[22:23], 0, v[136:137]
	s_add_i32 m0, s21, 0xe000
	s_nop 0
	global_load_lds_dwordx4 v[216:217], off
	s_waitcnt vmcnt(8)
	s_waitcnt lgkmcnt(0)
	s_barrier
	s_setprio 1
	s_waitcnt lgkmcnt(0)
	v_mfma_f32_16x16x32_bf16 v[126:129], v[142:145], v[182:185], v[126:129]
	v_mfma_f32_16x16x32_bf16 v[122:125], v[158:161], v[182:185], v[122:125]
	v_mfma_f32_16x16x32_bf16 v[110:113], v[142:145], v[190:193], v[110:113]
	v_mfma_f32_16x16x32_bf16 v[106:109], v[158:161], v[190:193], v[106:109]
	v_mfma_f32_16x16x32_bf16 v[94:97], v[142:145], v[198:201], v[94:97]
	v_mfma_f32_16x16x32_bf16 v[90:93], v[158:161], v[198:201], v[90:93]
	v_mfma_f32_16x16x32_bf16 v[78:81], v[142:145], v[208:211], v[78:81]
	v_mfma_f32_16x16x32_bf16 v[74:77], v[158:161], v[208:211], v[74:77]
	v_mfma_f32_16x16x32_bf16 v[126:129], v[146:149], v[186:189], v[126:129]
	v_mfma_f32_16x16x32_bf16 v[122:125], v[162:165], v[186:189], v[122:125]
	v_mfma_f32_16x16x32_bf16 v[110:113], v[146:149], v[194:197], v[110:113]
	v_mfma_f32_16x16x32_bf16 v[106:109], v[162:165], v[194:197], v[106:109]
	v_mfma_f32_16x16x32_bf16 v[94:97], v[146:149], v[204:207], v[94:97]
	v_mfma_f32_16x16x32_bf16 v[90:93], v[162:165], v[204:207], v[90:93]
	v_mfma_f32_16x16x32_bf16 v[78:81], v[146:149], v[212:215], v[78:81]
	v_mfma_f32_16x16x32_bf16 v[74:77], v[162:165], v[212:215], v[74:77]
	v_mfma_f32_16x16x32_bf16 v[118:121], v[166:169], v[182:185], v[118:121]
	v_mfma_f32_16x16x32_bf16 v[114:117], v[174:177], v[182:185], v[114:117]
	v_mfma_f32_16x16x32_bf16 v[102:105], v[166:169], v[190:193], v[102:105]
	v_mfma_f32_16x16x32_bf16 v[98:101], v[174:177], v[190:193], v[98:101]
	v_mfma_f32_16x16x32_bf16 v[86:89], v[166:169], v[198:201], v[86:89]
	v_mfma_f32_16x16x32_bf16 v[82:85], v[174:177], v[198:201], v[82:85]
	v_mfma_f32_16x16x32_bf16 v[70:73], v[166:169], v[208:211], v[70:73]
	v_mfma_f32_16x16x32_bf16 v[66:69], v[174:177], v[208:211], v[66:69]
	v_mfma_f32_16x16x32_bf16 v[118:121], v[170:173], v[186:189], v[118:121]
	v_mfma_f32_16x16x32_bf16 v[114:117], v[178:181], v[186:189], v[114:117]
	v_mfma_f32_16x16x32_bf16 v[102:105], v[170:173], v[194:197], v[102:105]
	v_mfma_f32_16x16x32_bf16 v[98:101], v[178:181], v[194:197], v[98:101]
	v_mfma_f32_16x16x32_bf16 v[86:89], v[170:173], v[204:207], v[86:89]
	v_mfma_f32_16x16x32_bf16 v[82:85], v[178:181], v[204:207], v[82:85]
	v_mfma_f32_16x16x32_bf16 v[70:73], v[170:173], v[212:215], v[70:73]
	v_mfma_f32_16x16x32_bf16 v[66:69], v[178:181], v[212:215], v[66:69]
	s_setprio 0
	s_barrier
	s_add_i32 s57, s73, s41
	v_lshl_add_u64 v[216:217], s[24:25], 0, v[130:131]
	s_mov_b32 m0, s57
	ds_read_b128 v[182:185], v154 offset:16384
	ds_read_b128 v[186:189], v154 offset:17408
	ds_read_b128 v[190:193], v154 offset:18432
	ds_read_b128 v[194:197], v154 offset:19456
	ds_read_b128 v[198:201], v154 offset:20480
	ds_read_b128 v[204:207], v154 offset:21504
	ds_read_b128 v[208:211], v154 offset:22528
	ds_read_b128 v[212:215], v154 offset:23552
	global_load_lds_dwordx4 v[216:217], off
	s_add_i32 m0, s57, 0x2000
	s_add_u32 s58, s24, 0x40000
	v_lshl_add_u64 v[218:219], s[24:25], 0, v[132:133]
	s_addc_u32 s59, s25, 0
	s_add_i32 s57, s74, s41
	global_load_lds_dwordx4 v[218:219], off
	v_lshl_add_u64 v[220:221], s[58:59], 0, v[130:131]
	s_mov_b32 m0, s57
	v_lshl_add_u64 v[222:223], s[26:27], 0, v[132:133]
	global_load_lds_dwordx4 v[220:221], off
	v_lshl_add_u64 v[220:221], s[58:59], 0, v[132:133]
	s_add_i32 m0, s57, 0x2000
	s_nop 0
	global_load_lds_dwordx4 v[220:221], off
	v_lshl_add_u64 v[220:221], s[26:27], 0, v[130:131]
	s_mov_b32 m0, s21
	s_nop 0
	global_load_lds_dwordx4 v[220:221], off
	s_mov_b32 m0, s42
	s_nop 0
	global_load_lds_dwordx4 v[222:223], off
	s_waitcnt vmcnt(8)
	s_waitcnt lgkmcnt(0)
	s_barrier
; #define PG8_STAGE(bufoff, gbase, voff) do { _Pragma("unroll") for (int _i = 0; _i < 2; ++_i) \
;         __builtin_amdgcn_global_load_lds((const unsigned*)((const char*)(gbase) + (voff)[_i]), (LAS unsigned*)(lds + (bufoff) + ldsw + _i * 8192), 16, 0, 0); } while (0)
; #define PG8_LDA(dst, b, h) do { _Pragma("unroll") for (int m = 0; m < 4; ++m) _Pragma("unroll") for (int k = 0; k < 2; ++k) dst[m][k] = *(const LAS bf16x8*)(lds + PG8_SA(b, h) + aoff + m * 2048 + k * 1024); } while (0)
; #define PG8_LDB(dst, b, h) do { _Pragma("unroll") for (int n = 0; n < 2; ++n) _Pragma("unroll") for (int k = 0; k < 2; ++k) dst[n][k] = *(const LAS bf16x8*)(lds + PG8_SB(b, h) + boff + n * 2048 + k * 1024); } while (0)
; #define PG8_MMA(ai, bj, At, Bt) do { __builtin_amdgcn_s_setprio(1); _Pragma("unroll") for (int m = 0; m < 4; ++m) _Pragma("unroll") for (int n = 0; n < 2; ++n) _Pragma("unroll") for (int k = 0; k < 2; ++k) \
;         acc[ai][bj][m][n] = __builtin_amdgcn_mfma_f32_16x16x32_bf16(Bt[n][k], At[m][k], acc[ai][bj][m][n], 0, 0, 0); __builtin_amdgcn_s_setprio(0); } while (0)
; #define PG8_WAIT_V(n) asm volatile("s_waitcnt vmcnt(" #n ")" ::: "memory")
; #define PG8_WAIT_L(n) asm volatile("s_waitcnt lgkmcnt(" #n ")" ::: "memory")
; #define PG8_BAR __builtin_amdgcn_s_barrier()
; #define PG8_SCHED __builtin_amdgcn_sched_barrier(0)
; template <class Epi, class Sched, bool ALIGN_EPI>
; DI void gemm_phase(LAS unsigned char* lds, const Gemm g, const Sched& S, const Epi& E) {
;     ...
;             PG8_WAIT_V(8); PG8_WAIT_L(0); PG8_BAR; PG8_MMA(1, 0, At, B0); PG8_MMA(1, 1, At, B1); PG8_BAR; PG8_SCHED;
;             PG8_LDB(B0, 1, 0); PG8_LDB(B1, 1, 1); PG8_SCHED; PG8_LDA(At, 1, 0); PG8_STAGE(PG8_SA(0, 1), a2 + hstepA, voffA);
;             PG8_WAIT_V(8); PG8_WAIT_L(0); PG8_BAR; PG8_MMA(0, 0, At, B0); PG8_MMA(0, 1, At, B1); PG8_BAR; PG8_SCHED;
	s_setprio 1
	s_waitcnt lgkmcnt(0)
	v_mfma_f32_16x16x32_bf16 v[62:65], v[142:145], v[182:185], v[62:65]
	v_mfma_f32_16x16x32_bf16 v[58:61], v[158:161], v[182:185], v[58:61]
	v_mfma_f32_16x16x32_bf16 v[46:49], v[142:145], v[190:193], v[46:49]
	v_mfma_f32_16x16x32_bf16 v[42:45], v[158:161], v[190:193], v[42:45]
	v_mfma_f32_16x16x32_bf16 v[30:33], v[142:145], v[198:201], v[30:33]
	v_mfma_f32_16x16x32_bf16 v[26:29], v[158:161], v[198:201], v[26:29]
	v_mfma_f32_16x16x32_bf16 v[14:17], v[142:145], v[208:211], v[14:17]
	v_mfma_f32_16x16x32_bf16 v[10:13], v[158:161], v[208:211], v[10:13]
	v_mfma_f32_16x16x32_bf16 v[62:65], v[146:149], v[186:189], v[62:65]
	v_mfma_f32_16x16x32_bf16 v[58:61], v[162:165], v[186:189], v[58:61]
	v_mfma_f32_16x16x32_bf16 v[46:49], v[146:149], v[194:197], v[46:49]
	v_mfma_f32_16x16x32_bf16 v[42:45], v[162:165], v[194:197], v[42:45]
	v_mfma_f32_16x16x32_bf16 v[30:33], v[146:149], v[204:207], v[30:33]
	v_mfma_f32_16x16x32_bf16 v[26:29], v[162:165], v[204:207], v[26:29]
	v_mfma_f32_16x16x32_bf16 v[14:17], v[146:149], v[212:215], v[14:17]
	v_mfma_f32_16x16x32_bf16 v[10:13], v[162:165], v[212:215], v[10:13]
	v_mfma_f32_16x16x32_bf16 v[54:57], v[166:169], v[182:185], v[54:57]
	v_mfma_f32_16x16x32_bf16 v[50:53], v[174:177], v[182:185], v[50:53]
	v_mfma_f32_16x16x32_bf16 v[38:41], v[166:169], v[190:193], v[38:41]
	v_mfma_f32_16x16x32_bf16 v[34:37], v[174:177], v[190:193], v[34:37]
	v_mfma_f32_16x16x32_bf16 v[22:25], v[166:169], v[198:201], v[22:25]
	v_mfma_f32_16x16x32_bf16 v[18:21], v[174:177], v[198:201], v[18:21]
	v_mfma_f32_16x16x32_bf16 v[6:9], v[166:169], v[208:211], v[6:9]
	v_mfma_f32_16x16x32_bf16 v[2:5], v[174:177], v[208:211], v[2:5]
	v_mfma_f32_16x16x32_bf16 v[54:57], v[170:173], v[186:189], v[54:57]
	v_mfma_f32_16x16x32_bf16 v[50:53], v[178:181], v[186:189], v[50:53]
	v_mfma_f32_16x16x32_bf16 v[38:41], v[170:173], v[194:197], v[38:41]
	v_mfma_f32_16x16x32_bf16 v[34:37], v[178:181], v[194:197], v[34:37]
	v_mfma_f32_16x16x32_bf16 v[22:25], v[170:173], v[204:207], v[22:25]
	v_mfma_f32_16x16x32_bf16 v[18:21], v[178:181], v[204:207], v[18:21]
	v_mfma_f32_16x16x32_bf16 v[6:9], v[170:173], v[212:215], v[6:9]
	v_mfma_f32_16x16x32_bf16 v[2:5], v[178:181], v[212:215], v[2:5]
	s_setprio 0
	s_barrier
	ds_read_b128 v[142:145], v155
	ds_read_b128 v[146:149], v155 offset:1024
	ds_read_b128 v[158:161], v155 offset:2048
	ds_read_b128 v[162:165], v155 offset:3072
	ds_read_b128 v[166:169], v156
	ds_read_b128 v[170:173], v156 offset:1024
	ds_read_b128 v[174:177], v156 offset:2048
	ds_read_b128 v[178:181], v156 offset:3072
	s_add_u32 s26, s26, 0x40000
	s_addc_u32 s27, s27, 0
	s_mov_b32 m0, s43
	v_lshl_add_u64 v[224:225], s[26:27], 0, v[130:131]
	ds_read_b128 v[182:185], v154 offset:32768
	ds_read_b128 v[186:189], v154 offset:33792
	ds_read_b128 v[190:193], v154 offset:34816
	ds_read_b128 v[194:197], v154 offset:35840
	ds_read_b128 v[198:201], v154 offset:36864
	ds_read_b128 v[204:207], v154 offset:37888
	ds_read_b128 v[208:211], v154 offset:38912
	ds_read_b128 v[212:215], v154 offset:39936
	global_load_lds_dwordx4 v[224:225], off
	v_lshl_add_u64 v[224:225], s[26:27], 0, v[132:133]
	s_mov_b32 m0, s44
	s_nop 0
	global_load_lds_dwordx4 v[224:225], off
	s_waitcnt vmcnt(8)
	s_waitcnt lgkmcnt(0)
	s_barrier
	s_setprio 1
	s_waitcnt lgkmcnt(0)
	v_mfma_f32_16x16x32_bf16 v[126:129], v[142:145], v[182:185], v[126:129]
	v_mfma_f32_16x16x32_bf16 v[122:125], v[158:161], v[182:185], v[122:125]
	v_mfma_f32_16x16x32_bf16 v[110:113], v[142:145], v[190:193], v[110:113]
	v_mfma_f32_16x16x32_bf16 v[106:109], v[158:161], v[190:193], v[106:109]
	v_mfma_f32_16x16x32_bf16 v[94:97], v[142:145], v[198:201], v[94:97]
	v_mfma_f32_16x16x32_bf16 v[90:93], v[158:161], v[198:201], v[90:93]
	v_mfma_f32_16x16x32_bf16 v[78:81], v[142:145], v[208:211], v[78:81]
	v_mfma_f32_16x16x32_bf16 v[74:77], v[158:161], v[208:211], v[74:77]
	v_mfma_f32_16x16x32_bf16 v[126:129], v[146:149], v[186:189], v[126:129]
	v_mfma_f32_16x16x32_bf16 v[122:125], v[162:165], v[186:189], v[122:125]
	v_mfma_f32_16x16x32_bf16 v[110:113], v[146:149], v[194:197], v[110:113]
	v_mfma_f32_16x16x32_bf16 v[106:109], v[162:165], v[194:197], v[106:109]
	v_mfma_f32_16x16x32_bf16 v[94:97], v[146:149], v[204:207], v[94:97]
	v_mfma_f32_16x16x32_bf16 v[90:93], v[162:165], v[204:207], v[90:93]
	v_mfma_f32_16x16x32_bf16 v[78:81], v[146:149], v[212:215], v[78:81]
	v_mfma_f32_16x16x32_bf16 v[74:77], v[162:165], v[212:215], v[74:77]
	v_mfma_f32_16x16x32_bf16 v[118:121], v[166:169], v[182:185], v[118:121]
	v_mfma_f32_16x16x32_bf16 v[114:117], v[174:177], v[182:185], v[114:117]
	v_mfma_f32_16x16x32_bf16 v[102:105], v[166:169], v[190:193], v[102:105]
	v_mfma_f32_16x16x32_bf16 v[98:101], v[174:177], v[190:193], v[98:101]
	v_mfma_f32_16x16x32_bf16 v[86:89], v[166:169], v[198:201], v[86:89]
	v_mfma_f32_16x16x32_bf16 v[82:85], v[174:177], v[198:201], v[82:85]
	v_mfma_f32_16x16x32_bf16 v[70:73], v[166:169], v[208:211], v[70:73]
	v_mfma_f32_16x16x32_bf16 v[66:69], v[174:177], v[208:211], v[66:69]
	v_mfma_f32_16x16x32_bf16 v[118:121], v[170:173], v[186:189], v[118:121]
	v_mfma_f32_16x16x32_bf16 v[114:117], v[178:181], v[186:189], v[114:117]
	v_mfma_f32_16x16x32_bf16 v[102:105], v[170:173], v[194:197], v[102:105]
	v_mfma_f32_16x16x32_bf16 v[98:101], v[178:181], v[194:197], v[98:101]
	v_mfma_f32_16x16x32_bf16 v[86:89], v[170:173], v[204:207], v[86:89]
	v_mfma_f32_16x16x32_bf16 v[82:85], v[178:181], v[204:207], v[82:85]
	v_mfma_f32_16x16x32_bf16 v[70:73], v[170:173], v[212:215], v[70:73]
	v_mfma_f32_16x16x32_bf16 v[66:69], v[178:181], v[212:215], v[66:69]
	s_setprio 0
	s_barrier
; #define PG8_STAGE(bufoff, gbase, voff) do { _Pragma("unroll") for (int _i = 0; _i < 2; ++_i) \
;         __builtin_amdgcn_global_load_lds((const unsigned*)((const char*)(gbase) + (voff)[_i]), (LAS unsigned*)(lds + (bufoff) + ldsw + _i * 8192), 16, 0, 0); } while (0)
; #define PG8_LDA(dst, b, h) do { _Pragma("unroll") for (int m = 0; m < 4; ++m) _Pragma("unroll") for (int k = 0; k < 2; ++k) dst[m][k] = *(const LAS bf16x8*)(lds + PG8_SA(b, h) + aoff + m * 2048 + k * 1024); } while (0)
; #define PG8_MMA(ai, bj, At, Bt) do { __builtin_amdgcn_s_setprio(1); _Pragma("unroll") for (int m = 0; m < 4; ++m) _Pragma("unroll") for (int n = 0; n < 2; ++n) _Pragma("unroll") for (int k = 0; k < 2; ++k) \
;         acc[ai][bj][m][n] = __builtin_amdgcn_mfma_f32_16x16x32_bf16(Bt[n][k], At[m][k], acc[ai][bj][m][n], 0, 0, 0); __builtin_amdgcn_s_setprio(0); } while (0)
; #define PG8_WAIT_V(n) asm volatile("s_waitcnt vmcnt(" #n ")" ::: "memory")
; #define PG8_WAIT_L(n) asm volatile("s_waitcnt lgkmcnt(" #n ")" ::: "memory")
; #define PG8_BAR __builtin_amdgcn_s_barrier()
; #define PG8_SCHED __builtin_amdgcn_sched_barrier(0)
; template <class Epi, class Sched, bool ALIGN_EPI>
; DI void gemm_phase(LAS unsigned char* lds, const Gemm g, const Sched& S, const Epi& E) {
;     ...
;             PG8_LDA(At, 1, 1); PG8_STAGE(PG8_SB(1, 0), b3, voffB); PG8_STAGE(PG8_SB(1, 1), b3 + hstepB, voffB); PG8_STAGE(PG8_SA(1, 0), a3, voffA);
;             PG8_WAIT_V(8); PG8_WAIT_L(0); PG8_BAR; PG8_MMA(1, 0, At, B0); PG8_MMA(1, 1, At, B1); PG8_BAR; PG8_SCHED;
;         }
;         if constexpr (ALIGN_EPI) { if (wr == 0) PG8_BAR; }
	s_add_i32 s26, s75, s41
	v_lshl_add_u64 v[216:217], v[216:217], 0, s[8:9]
	s_mov_b32 m0, s26
	ds_read_b128 v[182:185], v154 offset:49152
	ds_read_b128 v[186:189], v154 offset:50176
	ds_read_b128 v[190:193], v154 offset:51200
	ds_read_b128 v[194:197], v154 offset:52224
	ds_read_b128 v[198:201], v154 offset:53248
	ds_read_b128 v[204:207], v154 offset:54272
	ds_read_b128 v[208:211], v154 offset:55296
	ds_read_b128 v[212:215], v154 offset:56320
	global_load_lds_dwordx4 v[216:217], off
	s_add_i32 m0, s26, 0x2000
	s_add_u32 s24, s24, 0x40080
	v_lshl_add_u64 v[216:217], v[218:219], 0, s[8:9]
	s_addc_u32 s25, s25, 0
	s_add_i32 s26, s76, s41
	global_load_lds_dwordx4 v[216:217], off
	v_lshl_add_u64 v[216:217], s[24:25], 0, v[130:131]
	s_mov_b32 m0, s26
	s_nop 0
	global_load_lds_dwordx4 v[216:217], off
	v_lshl_add_u64 v[216:217], s[24:25], 0, v[132:133]
	s_add_i32 m0, s26, 0x2000
	s_nop 0
	global_load_lds_dwordx4 v[216:217], off
	v_lshl_add_u64 v[216:217], v[220:221], 0, s[8:9]
	s_mov_b32 m0, s45
	s_nop 0
	global_load_lds_dwordx4 v[216:217], off
	v_lshl_add_u64 v[216:217], v[222:223], 0, s[8:9]
	s_mov_b32 m0, s68
	s_nop 0
	global_load_lds_dwordx4 v[216:217], off
	s_waitcnt vmcnt(8)
	s_waitcnt lgkmcnt(0)
	s_barrier
	s_setprio 1
	s_waitcnt lgkmcnt(0)
	v_mfma_f32_16x16x32_bf16 v[62:65], v[142:145], v[182:185], v[62:65]
	v_mfma_f32_16x16x32_bf16 v[58:61], v[158:161], v[182:185], v[58:61]
	v_mfma_f32_16x16x32_bf16 v[46:49], v[142:145], v[190:193], v[46:49]
	v_mfma_f32_16x16x32_bf16 v[42:45], v[158:161], v[190:193], v[42:45]
	v_mfma_f32_16x16x32_bf16 v[30:33], v[142:145], v[198:201], v[30:33]
	v_mfma_f32_16x16x32_bf16 v[26:29], v[158:161], v[198:201], v[26:29]
	v_mfma_f32_16x16x32_bf16 v[14:17], v[142:145], v[208:211], v[14:17]
	v_mfma_f32_16x16x32_bf16 v[10:13], v[158:161], v[208:211], v[10:13]
	v_mfma_f32_16x16x32_bf16 v[62:65], v[146:149], v[186:189], v[62:65]
	v_mfma_f32_16x16x32_bf16 v[58:61], v[162:165], v[186:189], v[58:61]
	v_mfma_f32_16x16x32_bf16 v[46:49], v[146:149], v[194:197], v[46:49]
	v_mfma_f32_16x16x32_bf16 v[42:45], v[162:165], v[194:197], v[42:45]
	v_mfma_f32_16x16x32_bf16 v[30:33], v[146:149], v[204:207], v[30:33]
	v_mfma_f32_16x16x32_bf16 v[26:29], v[162:165], v[204:207], v[26:29]
	v_mfma_f32_16x16x32_bf16 v[14:17], v[146:149], v[212:215], v[14:17]
	v_mfma_f32_16x16x32_bf16 v[10:13], v[162:165], v[212:215], v[10:13]
	v_mfma_f32_16x16x32_bf16 v[54:57], v[166:169], v[182:185], v[54:57]
	v_mfma_f32_16x16x32_bf16 v[50:53], v[174:177], v[182:185], v[50:53]
	v_mfma_f32_16x16x32_bf16 v[38:41], v[166:169], v[190:193], v[38:41]
	v_mfma_f32_16x16x32_bf16 v[34:37], v[174:177], v[190:193], v[34:37]
	v_mfma_f32_16x16x32_bf16 v[22:25], v[166:169], v[198:201], v[22:25]
	v_mfma_f32_16x16x32_bf16 v[18:21], v[174:177], v[198:201], v[18:21]
	v_mfma_f32_16x16x32_bf16 v[6:9], v[166:169], v[208:211], v[6:9]
	v_mfma_f32_16x16x32_bf16 v[2:5], v[174:177], v[208:211], v[2:5]
	v_mfma_f32_16x16x32_bf16 v[54:57], v[170:173], v[186:189], v[54:57]
	v_mfma_f32_16x16x32_bf16 v[50:53], v[178:181], v[186:189], v[50:53]
	v_mfma_f32_16x16x32_bf16 v[38:41], v[170:173], v[194:197], v[38:41]
	v_mfma_f32_16x16x32_bf16 v[34:37], v[178:181], v[194:197], v[34:37]
	v_mfma_f32_16x16x32_bf16 v[22:25], v[170:173], v[204:207], v[22:25]
	v_mfma_f32_16x16x32_bf16 v[18:21], v[178:181], v[204:207], v[18:21]
	v_mfma_f32_16x16x32_bf16 v[6:9], v[170:173], v[212:215], v[6:9]
	v_mfma_f32_16x16x32_bf16 v[2:5], v[178:181], v[212:215], v[2:5]
	s_setprio 0
	s_barrier
	s_add_i32 s56, s56, 2
	s_add_u32 s22, s22, 0x100
	s_addc_u32 s23, s23, 0
	s_add_u32 s54, s54, 0x100
	s_addc_u32 s55, s55, 0
	s_cmp_gt_u32 s56, 13
	s_cbranch_scc0 .LBB0_1350
	s_and_b64 vcc, exec, s[10:11]
	s_cbranch_vccz .LBB0_1353
	s_barrier

; #define PG8_STAGE(bufoff, gbase, voff) do { _Pragma("unroll") for (int _i = 0; _i < 2; ++_i) \
;         __builtin_amdgcn_global_load_lds((const unsigned*)((const char*)(gbase) + (voff)[_i]), (LAS unsigned*)(lds + (bufoff) + ldsw + _i * 8192), 16, 0, 0); } while (0)
; #define PG8_LDA(dst, b, h) do { _Pragma("unroll") for (int m = 0; m < 4; ++m) _Pragma("unroll") for (int k = 0; k < 2; ++k) dst[m][k] = *(const LAS bf16x8*)(lds + PG8_SA(b, h) + aoff + m * 2048 + k * 1024); } while (0)
; #define PG8_LDB(dst, b, h) do { _Pragma("unroll") for (int n = 0; n < 2; ++n) _Pragma("unroll") for (int k = 0; k < 2; ++k) dst[n][k] = *(const LAS bf16x8*)(lds + PG8_SB(b, h) + boff + n * 2048 + k * 1024); } while (0)
; #define PG8_MMA(ai, bj, At, Bt) do { __builtin_amdgcn_s_setprio(1); _Pragma("unroll") for (int m = 0; m < 4; ++m) _Pragma("unroll") for (int n = 0; n < 2; ++n) _Pragma("unroll") for (int k = 0; k < 2; ++k) \
;         acc[ai][bj][m][n] = __builtin_amdgcn_mfma_f32_16x16x32_bf16(Bt[n][k], At[m][k], acc[ai][bj][m][n], 0, 0, 0); __builtin_amdgcn_s_setprio(0); } while (0)
; #define PG8_WAIT_V(n) asm volatile("s_waitcnt vmcnt(" #n ")" ::: "memory")
; #define PG8_WAIT_L(n) asm volatile("s_waitcnt lgkmcnt(" #n ")" ::: "memory")
; #define PG8_BAR __builtin_amdgcn_s_barrier()
; #define PG8_SCHED __builtin_amdgcn_sched_barrier(0)
; template <class Epi, class Sched, bool ALIGN_EPI>
; DI void gemm_phase(LAS unsigned char* lds, const Gemm g, const Sched& S, const Epi& E) {
;     ...
;         for (int t = 0; t < nt; t += 2) {
;             const bool last = (t == nt - 2);
;             const char* a1 = cA + (size_t)(t + 1) * kstep;
;             const char* a2 = last ? nA : cA + (size_t)(t + 2) * kstep; const char* b2 = last ? nB : cB + (size_t)(t + 2) * kstep;
;             const char* a3 = a2 + kstep; const char* b3 = b2 + kstep;
;             PG8_LDB(B0, 0, 0); PG8_LDB(B1, 0, 1); PG8_SCHED; PG8_LDA(At, 0, 0); PG8_STAGE(PG8_SA(1, 1), a1 + hstepA, voffA);
;             PG8_WAIT_V(8); PG8_WAIT_L(0); PG8_BAR; PG8_MMA(0, 0, At, B0); PG8_MMA(0, 1, At, B1); PG8_BAR; PG8_SCHED;
;             PG8_LDA(At, 0, 1); PG8_STAGE(PG8_SB(0, 0), b2, voffB); PG8_STAGE(PG8_SB(0, 1), b2 + hstepB, voffB); PG8_STAGE(PG8_SA(0, 0), a2, voffA);
;             PG8_WAIT_V(8); PG8_WAIT_L(0); PG8_BAR; PG8_MMA(1, 0, At, B0); PG8_MMA(1, 1, At, B1); PG8_BAR; PG8_SCHED;
.LBB0_1421:
	ds_read_b128 v[156:159], v149
	ds_read_b128 v[160:163], v149 offset:1024
	ds_read_b128 v[164:167], v149 offset:2048
	ds_read_b128 v[168:171], v149 offset:3072
	ds_read_b128 v[172:175], v150
	ds_read_b128 v[176:179], v150 offset:1024
	ds_read_b128 v[180:183], v150 offset:2048
	ds_read_b128 v[184:187], v150 offset:3072
	s_add_u32 s24, s22, 0xfffc0080
	s_addc_u32 s25, s23, -1
	s_cmp_eq_u32 s56, 12
	s_cselect_b32 s27, s15, s25
	s_cselect_b32 s26, s52, s24
	s_cselect_b32 s25, s13, s55
	s_cselect_b32 s24, s53, s54
	v_lshl_add_u64 v[146:147], s[22:23], 0, v[138:139]
	s_add_i32 m0, s21, 0xc000
	ds_read_b128 v[188:191], v151
	ds_read_b128 v[192:195], v151 offset:1024
	ds_read_b128 v[196:199], v151 offset:2048
	ds_read_b128 v[204:207], v151 offset:3072
	ds_read_b128 v[208:211], v151 offset:4096
	ds_read_b128 v[212:215], v151 offset:5120
	ds_read_b128 v[216:219], v151 offset:6144
	ds_read_b128 v[220:223], v151 offset:7168
	global_load_lds_dwordx4 v[146:147], off
	v_lshl_add_u64 v[146:147], s[22:23], 0, v[140:141]
	s_add_i32 m0, s21, 0xe000
	s_nop 0
	global_load_lds_dwordx4 v[146:147], off
	s_waitcnt vmcnt(8)
	s_waitcnt lgkmcnt(0)
	s_barrier
	s_setprio 1
	s_waitcnt lgkmcnt(0)
	v_mfma_f32_16x16x32_bf16 v[126:129], v[156:159], v[188:191], v[126:129]
	v_mfma_f32_16x16x32_bf16 v[122:125], v[164:167], v[188:191], v[122:125]
	v_mfma_f32_16x16x32_bf16 v[110:113], v[156:159], v[196:199], v[110:113]
	v_mfma_f32_16x16x32_bf16 v[106:109], v[164:167], v[196:199], v[106:109]
	v_mfma_f32_16x16x32_bf16 v[94:97], v[156:159], v[208:211], v[94:97]
	v_mfma_f32_16x16x32_bf16 v[90:93], v[164:167], v[208:211], v[90:93]
	v_mfma_f32_16x16x32_bf16 v[78:81], v[156:159], v[216:219], v[78:81]
	v_mfma_f32_16x16x32_bf16 v[74:77], v[164:167], v[216:219], v[74:77]
	v_mfma_f32_16x16x32_bf16 v[126:129], v[160:163], v[192:195], v[126:129]
	v_mfma_f32_16x16x32_bf16 v[122:125], v[168:171], v[192:195], v[122:125]
	v_mfma_f32_16x16x32_bf16 v[110:113], v[160:163], v[204:207], v[110:113]
	v_mfma_f32_16x16x32_bf16 v[106:109], v[168:171], v[204:207], v[106:109]
	v_mfma_f32_16x16x32_bf16 v[94:97], v[160:163], v[212:215], v[94:97]
	v_mfma_f32_16x16x32_bf16 v[90:93], v[168:171], v[212:215], v[90:93]
	v_mfma_f32_16x16x32_bf16 v[78:81], v[160:163], v[220:223], v[78:81]
	v_mfma_f32_16x16x32_bf16 v[74:77], v[168:171], v[220:223], v[74:77]
	v_mfma_f32_16x16x32_bf16 v[118:121], v[172:175], v[188:191], v[118:121]
	v_mfma_f32_16x16x32_bf16 v[114:117], v[180:183], v[188:191], v[114:117]
	v_mfma_f32_16x16x32_bf16 v[102:105], v[172:175], v[196:199], v[102:105]
	v_mfma_f32_16x16x32_bf16 v[98:101], v[180:183], v[196:199], v[98:101]
	v_mfma_f32_16x16x32_bf16 v[86:89], v[172:175], v[208:211], v[86:89]
	v_mfma_f32_16x16x32_bf16 v[82:85], v[180:183], v[208:211], v[82:85]
	v_mfma_f32_16x16x32_bf16 v[70:73], v[172:175], v[216:219], v[70:73]
	v_mfma_f32_16x16x32_bf16 v[66:69], v[180:183], v[216:219], v[66:69]
	v_mfma_f32_16x16x32_bf16 v[118:121], v[176:179], v[192:195], v[118:121]
	v_mfma_f32_16x16x32_bf16 v[114:117], v[184:187], v[192:195], v[114:117]
	v_mfma_f32_16x16x32_bf16 v[102:105], v[176:179], v[204:207], v[102:105]
	v_mfma_f32_16x16x32_bf16 v[98:101], v[184:187], v[204:207], v[98:101]
	v_mfma_f32_16x16x32_bf16 v[86:89], v[176:179], v[212:215], v[86:89]
	v_mfma_f32_16x16x32_bf16 v[82:85], v[184:187], v[212:215], v[82:85]
	v_mfma_f32_16x16x32_bf16 v[70:73], v[176:179], v[220:223], v[70:73]
	v_mfma_f32_16x16x32_bf16 v[66:69], v[184:187], v[220:223], v[66:69]
	s_setprio 0
	s_barrier
	s_add_i32 s57, s74, s40
	v_lshl_add_u64 v[146:147], s[24:25], 0, v[134:135]
	s_mov_b32 m0, s57
	ds_read_b128 v[188:191], v151 offset:16384
	ds_read_b128 v[192:195], v151 offset:17408
	ds_read_b128 v[196:199], v151 offset:18432
	ds_read_b128 v[204:207], v151 offset:19456
	ds_read_b128 v[208:211], v151 offset:20480
	ds_read_b128 v[212:215], v151 offset:21504
	ds_read_b128 v[216:219], v151 offset:22528
	ds_read_b128 v[220:223], v151 offset:23552
	global_load_lds_dwordx4 v[146:147], off
	s_add_i32 m0, s57, 0x2000
	s_add_u32 s58, s24, 0x40000
	v_lshl_add_u64 v[200:201], s[24:25], 0, v[130:131]
	s_addc_u32 s59, s25, 0
	s_add_i32 s57, s75, s40
	global_load_lds_dwordx4 v[200:201], off
	v_lshl_add_u64 v[224:225], s[58:59], 0, v[134:135]
	s_mov_b32 m0, s57
	v_lshl_add_u64 v[226:227], s[26:27], 0, v[132:133]
	global_load_lds_dwordx4 v[224:225], off
	v_lshl_add_u64 v[224:225], s[58:59], 0, v[130:131]
	s_add_i32 m0, s57, 0x2000
	s_nop 0
	global_load_lds_dwordx4 v[224:225], off
	v_lshl_add_u64 v[224:225], s[26:27], 0, v[136:137]
	s_mov_b32 m0, s21
	s_nop 0
	global_load_lds_dwordx4 v[224:225], off
	s_mov_b32 m0, s43
	s_nop 0
	global_load_lds_dwordx4 v[226:227], off
	s_waitcnt vmcnt(8)
	s_waitcnt lgkmcnt(0)
	s_barrier
; #define PG8_STAGE(bufoff, gbase, voff) do { _Pragma("unroll") for (int _i = 0; _i < 2; ++_i) \
;         __builtin_amdgcn_global_load_lds((const unsigned*)((const char*)(gbase) + (voff)[_i]), (LAS unsigned*)(lds + (bufoff) + ldsw + _i * 8192), 16, 0, 0); } while (0)
; #define PG8_LDA(dst, b, h) do { _Pragma("unroll") for (int m = 0; m < 4; ++m) _Pragma("unroll") for (int k = 0; k < 2; ++k) dst[m][k] = *(const LAS bf16x8*)(lds + PG8_SA(b, h) + aoff + m * 2048 + k * 1024); } while (0)
; #define PG8_LDB(dst, b, h) do { _Pragma("unroll") for (int n = 0; n < 2; ++n) _Pragma("unroll") for (int k = 0; k < 2; ++k) dst[n][k] = *(const LAS bf16x8*)(lds + PG8_SB(b, h) + boff + n * 2048 + k * 1024); } while (0)
; #define PG8_MMA(ai, bj, At, Bt) do { __builtin_amdgcn_s_setprio(1); _Pragma("unroll") for (int m = 0; m < 4; ++m) _Pragma("unroll") for (int n = 0; n < 2; ++n) _Pragma("unroll") for (int k = 0; k < 2; ++k) \
;         acc[ai][bj][m][n] = __builtin_amdgcn_mfma_f32_16x16x32_bf16(Bt[n][k], At[m][k], acc[ai][bj][m][n], 0, 0, 0); __builtin_amdgcn_s_setprio(0); } while (0)
; #define PG8_WAIT_V(n) asm volatile("s_waitcnt vmcnt(" #n ")" ::: "memory")
; #define PG8_WAIT_L(n) asm volatile("s_waitcnt lgkmcnt(" #n ")" ::: "memory")
; #define PG8_BAR __builtin_amdgcn_s_barrier()
; #define PG8_SCHED __builtin_amdgcn_sched_barrier(0)
; template <class Epi, class Sched, bool ALIGN_EPI>
; DI void gemm_phase(LAS unsigned char* lds, const Gemm g, const Sched& S, const Epi& E) {
;     ...
;             PG8_WAIT_V(8); PG8_WAIT_L(0); PG8_BAR; PG8_MMA(0, 0, At, B0); PG8_MMA(0, 1, At, B1); PG8_BAR; PG8_SCHED;
;             PG8_LDA(At, 0, 1); PG8_STAGE(PG8_SB(0, 0), b2, voffB); PG8_STAGE(PG8_SB(0, 1), b2 + hstepB, voffB); PG8_STAGE(PG8_SA(0, 0), a2, voffA);
;             PG8_WAIT_V(8); PG8_WAIT_L(0); PG8_BAR; PG8_MMA(1, 0, At, B0); PG8_MMA(1, 1, At, B1); PG8_BAR; PG8_SCHED;
;             PG8_LDB(B0, 1, 0); PG8_LDB(B1, 1, 1); PG8_SCHED; PG8_LDA(At, 1, 0); PG8_STAGE(PG8_SA(0, 1), a2 + hstepA, voffA);
;             PG8_WAIT_V(8); PG8_WAIT_L(0); PG8_BAR; PG8_MMA(0, 0, At, B0); PG8_MMA(0, 1, At, B1); PG8_BAR; PG8_SCHED;
	s_setprio 1
	s_waitcnt lgkmcnt(0)
	v_mfma_f32_16x16x32_bf16 v[62:65], v[156:159], v[188:191], v[62:65]
	v_mfma_f32_16x16x32_bf16 v[58:61], v[164:167], v[188:191], v[58:61]
	v_mfma_f32_16x16x32_bf16 v[46:49], v[156:159], v[196:199], v[46:49]
	v_mfma_f32_16x16x32_bf16 v[42:45], v[164:167], v[196:199], v[42:45]
	v_mfma_f32_16x16x32_bf16 v[30:33], v[156:159], v[208:211], v[30:33]
	v_mfma_f32_16x16x32_bf16 v[26:29], v[164:167], v[208:211], v[26:29]
	v_mfma_f32_16x16x32_bf16 v[14:17], v[156:159], v[216:219], v[14:17]
	v_mfma_f32_16x16x32_bf16 v[10:13], v[164:167], v[216:219], v[10:13]
	v_mfma_f32_16x16x32_bf16 v[62:65], v[160:163], v[192:195], v[62:65]
	v_mfma_f32_16x16x32_bf16 v[58:61], v[168:171], v[192:195], v[58:61]
	v_mfma_f32_16x16x32_bf16 v[46:49], v[160:163], v[204:207], v[46:49]
	v_mfma_f32_16x16x32_bf16 v[42:45], v[168:171], v[204:207], v[42:45]
	v_mfma_f32_16x16x32_bf16 v[30:33], v[160:163], v[212:215], v[30:33]
	v_mfma_f32_16x16x32_bf16 v[26:29], v[168:171], v[212:215], v[26:29]
	v_mfma_f32_16x16x32_bf16 v[14:17], v[160:163], v[220:223], v[14:17]
	v_mfma_f32_16x16x32_bf16 v[10:13], v[168:171], v[220:223], v[10:13]
	v_mfma_f32_16x16x32_bf16 v[54:57], v[172:175], v[188:191], v[54:57]
	v_mfma_f32_16x16x32_bf16 v[50:53], v[180:183], v[188:191], v[50:53]
	v_mfma_f32_16x16x32_bf16 v[38:41], v[172:175], v[196:199], v[38:41]
	v_mfma_f32_16x16x32_bf16 v[34:37], v[180:183], v[196:199], v[34:37]
	v_mfma_f32_16x16x32_bf16 v[22:25], v[172:175], v[208:211], v[22:25]
	v_mfma_f32_16x16x32_bf16 v[18:21], v[180:183], v[208:211], v[18:21]
	v_mfma_f32_16x16x32_bf16 v[6:9], v[172:175], v[216:219], v[6:9]
	v_mfma_f32_16x16x32_bf16 v[2:5], v[180:183], v[216:219], v[2:5]
	v_mfma_f32_16x16x32_bf16 v[54:57], v[176:179], v[192:195], v[54:57]
	v_mfma_f32_16x16x32_bf16 v[50:53], v[184:187], v[192:195], v[50:53]
	v_mfma_f32_16x16x32_bf16 v[38:41], v[176:179], v[204:207], v[38:41]
	v_mfma_f32_16x16x32_bf16 v[34:37], v[184:187], v[204:207], v[34:37]
	v_mfma_f32_16x16x32_bf16 v[22:25], v[176:179], v[212:215], v[22:25]
	v_mfma_f32_16x16x32_bf16 v[18:21], v[184:187], v[212:215], v[18:21]
	v_mfma_f32_16x16x32_bf16 v[6:9], v[176:179], v[220:223], v[6:9]
	v_mfma_f32_16x16x32_bf16 v[2:5], v[184:187], v[220:223], v[2:5]
	s_setprio 0
	s_barrier
	ds_read_b128 v[156:159], v153
	ds_read_b128 v[160:163], v153 offset:1024
	ds_read_b128 v[164:167], v153 offset:2048
	ds_read_b128 v[168:171], v153 offset:3072
	ds_read_b128 v[172:175], v154
	ds_read_b128 v[176:179], v154 offset:1024
	ds_read_b128 v[180:183], v154 offset:2048
	ds_read_b128 v[184:187], v154 offset:3072
	s_add_u32 s26, s26, 0x40000
	s_addc_u32 s27, s27, 0
	s_mov_b32 m0, s44
	v_lshl_add_u64 v[228:229], s[26:27], 0, v[136:137]
	ds_read_b128 v[188:191], v151 offset:32768
	ds_read_b128 v[192:195], v151 offset:33792
	ds_read_b128 v[196:199], v151 offset:34816
	ds_read_b128 v[204:207], v151 offset:35840
	ds_read_b128 v[208:211], v151 offset:36864
	ds_read_b128 v[212:215], v151 offset:37888
	ds_read_b128 v[216:219], v151 offset:38912
	ds_read_b128 v[220:223], v151 offset:39936
	global_load_lds_dwordx4 v[228:229], off
	v_lshl_add_u64 v[228:229], s[26:27], 0, v[132:133]
	s_mov_b32 m0, s45
	s_nop 0
	global_load_lds_dwordx4 v[228:229], off
	s_waitcnt vmcnt(8)
	s_waitcnt lgkmcnt(0)
	s_barrier
	s_setprio 1
	s_waitcnt lgkmcnt(0)
	v_mfma_f32_16x16x32_bf16 v[126:129], v[156:159], v[188:191], v[126:129]
	v_mfma_f32_16x16x32_bf16 v[122:125], v[164:167], v[188:191], v[122:125]
	v_mfma_f32_16x16x32_bf16 v[110:113], v[156:159], v[196:199], v[110:113]
	v_mfma_f32_16x16x32_bf16 v[106:109], v[164:167], v[196:199], v[106:109]
	v_mfma_f32_16x16x32_bf16 v[94:97], v[156:159], v[208:211], v[94:97]
	v_mfma_f32_16x16x32_bf16 v[90:93], v[164:167], v[208:211], v[90:93]
	v_mfma_f32_16x16x32_bf16 v[78:81], v[156:159], v[216:219], v[78:81]
	v_mfma_f32_16x16x32_bf16 v[74:77], v[164:167], v[216:219], v[74:77]
	v_mfma_f32_16x16x32_bf16 v[126:129], v[160:163], v[192:195], v[126:129]
	v_mfma_f32_16x16x32_bf16 v[122:125], v[168:171], v[192:195], v[122:125]
	v_mfma_f32_16x16x32_bf16 v[110:113], v[160:163], v[204:207], v[110:113]
	v_mfma_f32_16x16x32_bf16 v[106:109], v[168:171], v[204:207], v[106:109]
	v_mfma_f32_16x16x32_bf16 v[94:97], v[160:163], v[212:215], v[94:97]
	v_mfma_f32_16x16x32_bf16 v[90:93], v[168:171], v[212:215], v[90:93]
	v_mfma_f32_16x16x32_bf16 v[78:81], v[160:163], v[220:223], v[78:81]
	v_mfma_f32_16x16x32_bf16 v[74:77], v[168:171], v[220:223], v[74:77]
	v_mfma_f32_16x16x32_bf16 v[118:121], v[172:175], v[188:191], v[118:121]
	v_mfma_f32_16x16x32_bf16 v[114:117], v[180:183], v[188:191], v[114:117]
	v_mfma_f32_16x16x32_bf16 v[102:105], v[172:175], v[196:199], v[102:105]
	v_mfma_f32_16x16x32_bf16 v[98:101], v[180:183], v[196:199], v[98:101]
	v_mfma_f32_16x16x32_bf16 v[86:89], v[172:175], v[208:211], v[86:89]
	v_mfma_f32_16x16x32_bf16 v[82:85], v[180:183], v[208:211], v[82:85]
	v_mfma_f32_16x16x32_bf16 v[70:73], v[172:175], v[216:219], v[70:73]
	v_mfma_f32_16x16x32_bf16 v[66:69], v[180:183], v[216:219], v[66:69]
	v_mfma_f32_16x16x32_bf16 v[118:121], v[176:179], v[192:195], v[118:121]
	v_mfma_f32_16x16x32_bf16 v[114:117], v[184:187], v[192:195], v[114:117]
	v_mfma_f32_16x16x32_bf16 v[102:105], v[176:179], v[204:207], v[102:105]
	v_mfma_f32_16x16x32_bf16 v[98:101], v[184:187], v[204:207], v[98:101]
	v_mfma_f32_16x16x32_bf16 v[86:89], v[176:179], v[212:215], v[86:89]
	v_mfma_f32_16x16x32_bf16 v[82:85], v[184:187], v[212:215], v[82:85]
	v_mfma_f32_16x16x32_bf16 v[70:73], v[176:179], v[220:223], v[70:73]
	v_mfma_f32_16x16x32_bf16 v[66:69], v[184:187], v[220:223], v[66:69]
	s_setprio 0
	s_barrier
; #define PG8_STAGE(bufoff, gbase, voff) do { _Pragma("unroll") for (int _i = 0; _i < 2; ++_i) \
;         __builtin_amdgcn_global_load_lds((const unsigned*)((const char*)(gbase) + (voff)[_i]), (LAS unsigned*)(lds + (bufoff) + ldsw + _i * 8192), 16, 0, 0); } while (0)
; #define PG8_LDA(dst, b, h) do { _Pragma("unroll") for (int m = 0; m < 4; ++m) _Pragma("unroll") for (int k = 0; k < 2; ++k) dst[m][k] = *(const LAS bf16x8*)(lds + PG8_SA(b, h) + aoff + m * 2048 + k * 1024); } while (0)
; #define PG8_MMA(ai, bj, At, Bt) do { __builtin_amdgcn_s_setprio(1); _Pragma("unroll") for (int m = 0; m < 4; ++m) _Pragma("unroll") for (int n = 0; n < 2; ++n) _Pragma("unroll") for (int k = 0; k < 2; ++k) \
;         acc[ai][bj][m][n] = __builtin_amdgcn_mfma_f32_16x16x32_bf16(Bt[n][k], At[m][k], acc[ai][bj][m][n], 0, 0, 0); __builtin_amdgcn_s_setprio(0); } while (0)
; #define PG8_WAIT_V(n) asm volatile("s_waitcnt vmcnt(" #n ")" ::: "memory")
; #define PG8_WAIT_L(n) asm volatile("s_waitcnt lgkmcnt(" #n ")" ::: "memory")
; #define PG8_BAR __builtin_amdgcn_s_barrier()
; #define PG8_SCHED __builtin_amdgcn_sched_barrier(0)
; template <class Epi, class Sched, bool ALIGN_EPI>
; DI void gemm_phase(LAS unsigned char* lds, const Gemm g, const Sched& S, const Epi& E) {
;     ...
;             PG8_LDA(At, 1, 1); PG8_STAGE(PG8_SB(1, 0), b3, voffB); PG8_STAGE(PG8_SB(1, 1), b3 + hstepB, voffB); PG8_STAGE(PG8_SA(1, 0), a3, voffA);
;             PG8_WAIT_V(8); PG8_WAIT_L(0); PG8_BAR; PG8_MMA(1, 0, At, B0); PG8_MMA(1, 1, At, B1); PG8_BAR; PG8_SCHED;
;         }
;         if constexpr (ALIGN_EPI) { if (wr == 0) PG8_BAR; }
;         if constexpr (!Epi::AFTER_DRAIN) E(acc, cur, wr, wc, fr, fq);
;         if (!has_next) break;
	s_add_i32 s26, s77, s40
	v_lshl_add_u64 v[146:147], v[146:147], 0, s[8:9]
	s_mov_b32 m0, s26
	ds_read_b128 v[188:191], v151 offset:49152
	ds_read_b128 v[192:195], v151 offset:50176
	ds_read_b128 v[196:199], v151 offset:51200
	ds_read_b128 v[204:207], v151 offset:52224
	ds_read_b128 v[208:211], v151 offset:53248
	ds_read_b128 v[212:215], v151 offset:54272
	ds_read_b128 v[216:219], v151 offset:55296
	ds_read_b128 v[220:223], v151 offset:56320
	global_load_lds_dwordx4 v[146:147], off
	s_add_i32 m0, s26, 0x2000
	s_add_u32 s24, s24, 0x40080
	v_lshl_add_u64 v[146:147], v[200:201], 0, s[8:9]
	s_addc_u32 s25, s25, 0
	s_add_i32 s26, s78, s40
	global_load_lds_dwordx4 v[146:147], off
	v_lshl_add_u64 v[146:147], s[24:25], 0, v[134:135]
	s_mov_b32 m0, s26
	s_nop 0
	global_load_lds_dwordx4 v[146:147], off
	v_lshl_add_u64 v[146:147], s[24:25], 0, v[130:131]
	s_add_i32 m0, s26, 0x2000
	s_nop 0
	global_load_lds_dwordx4 v[146:147], off
	v_lshl_add_u64 v[146:147], v[224:225], 0, s[8:9]
	s_mov_b32 m0, s69
	s_nop 0
	global_load_lds_dwordx4 v[146:147], off
	v_lshl_add_u64 v[146:147], v[226:227], 0, s[8:9]
	s_mov_b32 m0, s71
	s_nop 0
	global_load_lds_dwordx4 v[146:147], off
	s_waitcnt vmcnt(8)
	s_waitcnt lgkmcnt(0)
	s_barrier
	s_setprio 1
	s_waitcnt lgkmcnt(0)
	v_mfma_f32_16x16x32_bf16 v[62:65], v[156:159], v[188:191], v[62:65]
	v_mfma_f32_16x16x32_bf16 v[58:61], v[164:167], v[188:191], v[58:61]
	v_mfma_f32_16x16x32_bf16 v[46:49], v[156:159], v[196:199], v[46:49]
	v_mfma_f32_16x16x32_bf16 v[42:45], v[164:167], v[196:199], v[42:45]
	v_mfma_f32_16x16x32_bf16 v[30:33], v[156:159], v[208:211], v[30:33]
	v_mfma_f32_16x16x32_bf16 v[26:29], v[164:167], v[208:211], v[26:29]
	v_mfma_f32_16x16x32_bf16 v[14:17], v[156:159], v[216:219], v[14:17]
	v_mfma_f32_16x16x32_bf16 v[10:13], v[164:167], v[216:219], v[10:13]
	v_mfma_f32_16x16x32_bf16 v[62:65], v[160:163], v[192:195], v[62:65]
	v_mfma_f32_16x16x32_bf16 v[58:61], v[168:171], v[192:195], v[58:61]
	v_mfma_f32_16x16x32_bf16 v[46:49], v[160:163], v[204:207], v[46:49]
	v_mfma_f32_16x16x32_bf16 v[42:45], v[168:171], v[204:207], v[42:45]
	v_mfma_f32_16x16x32_bf16 v[30:33], v[160:163], v[212:215], v[30:33]
	v_mfma_f32_16x16x32_bf16 v[26:29], v[168:171], v[212:215], v[26:29]
	v_mfma_f32_16x16x32_bf16 v[14:17], v[160:163], v[220:223], v[14:17]
	v_mfma_f32_16x16x32_bf16 v[10:13], v[168:171], v[220:223], v[10:13]
	v_mfma_f32_16x16x32_bf16 v[54:57], v[172:175], v[188:191], v[54:57]
	v_mfma_f32_16x16x32_bf16 v[50:53], v[180:183], v[188:191], v[50:53]
	v_mfma_f32_16x16x32_bf16 v[38:41], v[172:175], v[196:199], v[38:41]
	v_mfma_f32_16x16x32_bf16 v[34:37], v[180:183], v[196:199], v[34:37]
	v_mfma_f32_16x16x32_bf16 v[22:25], v[172:175], v[208:211], v[22:25]
	v_mfma_f32_16x16x32_bf16 v[18:21], v[180:183], v[208:211], v[18:21]
	v_mfma_f32_16x16x32_bf16 v[6:9], v[172:175], v[216:219], v[6:9]
	v_mfma_f32_16x16x32_bf16 v[2:5], v[180:183], v[216:219], v[2:5]
	v_mfma_f32_16x16x32_bf16 v[54:57], v[176:179], v[192:195], v[54:57]
	v_mfma_f32_16x16x32_bf16 v[50:53], v[184:187], v[192:195], v[50:53]
	v_mfma_f32_16x16x32_bf16 v[38:41], v[176:179], v[204:207], v[38:41]
	v_mfma_f32_16x16x32_bf16 v[34:37], v[184:187], v[204:207], v[34:37]
	v_mfma_f32_16x16x32_bf16 v[22:25], v[176:179], v[212:215], v[22:25]
	v_mfma_f32_16x16x32_bf16 v[18:21], v[184:187], v[212:215], v[18:21]
	v_mfma_f32_16x16x32_bf16 v[6:9], v[176:179], v[220:223], v[6:9]
	v_mfma_f32_16x16x32_bf16 v[2:5], v[184:187], v[220:223], v[2:5]
	s_setprio 0
	s_barrier
	s_add_i32 s56, s56, 2
	s_add_u32 s22, s22, 0x100
	s_addc_u32 s23, s23, 0
	s_add_u32 s54, s54, 0x100
	s_addc_u32 s55, s55, 0
	s_cmp_gt_u32 s56, 13
	s_cbranch_scc0 .LBB0_1421
	s_and_b64 vcc, exec, s[10:11]
	s_cbranch_vccz .LBB0_1424
	s_barrier

; #define PG8_STAGE(bufoff, gbase, voff) do { _Pragma("unroll") for (int _i = 0; _i < 2; ++_i) \
;         __builtin_amdgcn_global_load_lds((const unsigned*)((const char*)(gbase) + (voff)[_i]), (LAS unsigned*)(lds + (bufoff) + ldsw + _i * 8192), 16, 0, 0); } while (0)
; #define PG8_LDA(dst, b, h) do { _Pragma("unroll") for (int m = 0; m < 4; ++m) _Pragma("unroll") for (int k = 0; k < 2; ++k) dst[m][k] = *(const LAS bf16x8*)(lds + PG8_SA(b, h) + aoff + m * 2048 + k * 1024); } while (0)
; #define PG8_LDB(dst, b, h) do { _Pragma("unroll") for (int n = 0; n < 2; ++n) _Pragma("unroll") for (int k = 0; k < 2; ++k) dst[n][k] = *(const LAS bf16x8*)(lds + PG8_SB(b, h) + boff + n * 2048 + k * 1024); } while (0)
; #define PG8_MMA(ai, bj, At, Bt) do { __builtin_amdgcn_s_setprio(1); _Pragma("unroll") for (int m = 0; m < 4; ++m) _Pragma("unroll") for (int n = 0; n < 2; ++n) _Pragma("unroll") for (int k = 0; k < 2; ++k) \
;         acc[ai][bj][m][n] = __builtin_amdgcn_mfma_f32_16x16x32_bf16(Bt[n][k], At[m][k], acc[ai][bj][m][n], 0, 0, 0); __builtin_amdgcn_s_setprio(0); } while (0)
; #define PG8_WAIT_V(n) asm volatile("s_waitcnt vmcnt(" #n ")" ::: "memory")
; #define PG8_WAIT_L(n) asm volatile("s_waitcnt lgkmcnt(" #n ")" ::: "memory")
; #define PG8_BAR __builtin_amdgcn_s_barrier()
; #define PG8_SCHED __builtin_amdgcn_sched_barrier(0)
; template <class Epi, class Sched, bool ALIGN_EPI>
; DI void gemm_phase(LAS unsigned char* lds, const Gemm g, const Sched& S, const Epi& E) {
;     ...
;         for (int t = 0; t < nt; t += 2) {
;             const bool last = (t == nt - 2);
;             const char* a1 = cA + (size_t)(t + 1) * kstep;
;             const char* a2 = last ? nA : cA + (size_t)(t + 2) * kstep; const char* b2 = last ? nB : cB + (size_t)(t + 2) * kstep;
;             const char* a3 = a2 + kstep; const char* b3 = b2 + kstep;
;             PG8_LDB(B0, 0, 0); PG8_LDB(B1, 0, 1); PG8_SCHED; PG8_LDA(At, 0, 0); PG8_STAGE(PG8_SA(1, 1), a1 + hstepA, voffA);
;             PG8_WAIT_V(8); PG8_WAIT_L(0); PG8_BAR; PG8_MMA(0, 0, At, B0); PG8_MMA(0, 1, At, B1); PG8_BAR; PG8_SCHED;
;             PG8_LDA(At, 0, 1); PG8_STAGE(PG8_SB(0, 0), b2, voffB); PG8_STAGE(PG8_SB(0, 1), b2 + hstepB, voffB); PG8_STAGE(PG8_SA(0, 0), a2, voffA);
;             PG8_WAIT_V(8); PG8_WAIT_L(0); PG8_BAR; PG8_MMA(1, 0, At, B0); PG8_MMA(1, 1, At, B1); PG8_BAR; PG8_SCHED;
.LBB0_1536:
	v_add_u32_e32 v147, s45, v1
	ds_read_b128 v[148:151], v147
	ds_read_b128 v[154:157], v147 offset:1024
	ds_read_b128 v[158:161], v147 offset:2048
	ds_read_b128 v[162:165], v147 offset:3072
	v_add_u32_e32 v147, s46, v1
	s_add_u32 s16, s8, s14
	ds_read_b128 v[166:169], v147
	ds_read_b128 v[170:173], v147 offset:1024
	ds_read_b128 v[174:177], v147 offset:2048
	ds_read_b128 v[178:181], v147 offset:3072
	s_addc_u32 s17, s9, s15
	s_add_u32 s16, s16, 0x100
	s_addc_u32 s17, s17, 0
	s_add_u32 s55, s52, s14
	s_addc_u32 s56, s53, s15
	s_cmpk_eq_i32 s14, 0x1500
	s_cselect_b32 s19, s13, s17
	s_cselect_b32 s18, s12, s16
	s_cselect_b32 s17, s1, s56
	s_cselect_b32 s16, s0, s55
	v_lshl_add_u64 v[216:217], v[142:143], 0, s[14:15]
	s_add_i32 m0, s37, 0xc000
	ds_read_b128 v[182:185], v146
	ds_read_b128 v[186:189], v146 offset:1024
	ds_read_b128 v[190:193], v146 offset:2048
	ds_read_b128 v[194:197], v146 offset:3072
	ds_read_b128 v[198:201], v146 offset:4096
	ds_read_b128 v[204:207], v146 offset:5120
	ds_read_b128 v[208:211], v146 offset:6144
	ds_read_b128 v[212:215], v146 offset:7168
	global_load_lds_dwordx4 v[216:217], off
	v_lshl_add_u64 v[216:217], v[144:145], 0, s[14:15]
	s_add_i32 m0, s37, 0xe000
	s_nop 0
	global_load_lds_dwordx4 v[216:217], off
	s_waitcnt vmcnt(8)
	s_waitcnt lgkmcnt(0)
	s_barrier
	s_setprio 1
	s_waitcnt lgkmcnt(0)
	v_mfma_f32_16x16x32_bf16 v[126:129], v[148:151], v[182:185], v[126:129]
	v_mfma_f32_16x16x32_bf16 v[122:125], v[158:161], v[182:185], v[122:125]
	v_mfma_f32_16x16x32_bf16 v[114:117], v[148:151], v[190:193], v[114:117]
	v_mfma_f32_16x16x32_bf16 v[110:113], v[158:161], v[190:193], v[110:113]
	v_mfma_f32_16x16x32_bf16 v[98:101], v[148:151], v[198:201], v[98:101]
	v_mfma_f32_16x16x32_bf16 v[94:97], v[158:161], v[198:201], v[94:97]
	v_mfma_f32_16x16x32_bf16 v[82:85], v[148:151], v[208:211], v[82:85]
	v_mfma_f32_16x16x32_bf16 v[78:81], v[158:161], v[208:211], v[78:81]
	v_mfma_f32_16x16x32_bf16 v[126:129], v[154:157], v[186:189], v[126:129]
	v_mfma_f32_16x16x32_bf16 v[122:125], v[162:165], v[186:189], v[122:125]
	v_mfma_f32_16x16x32_bf16 v[114:117], v[154:157], v[194:197], v[114:117]
	v_mfma_f32_16x16x32_bf16 v[110:113], v[162:165], v[194:197], v[110:113]
	v_mfma_f32_16x16x32_bf16 v[98:101], v[154:157], v[204:207], v[98:101]
	v_mfma_f32_16x16x32_bf16 v[94:97], v[162:165], v[204:207], v[94:97]
	v_mfma_f32_16x16x32_bf16 v[82:85], v[154:157], v[212:215], v[82:85]
	v_mfma_f32_16x16x32_bf16 v[78:81], v[162:165], v[212:215], v[78:81]
	v_mfma_f32_16x16x32_bf16 v[118:121], v[166:169], v[182:185], v[118:121]
	v_mfma_f32_16x16x32_bf16 v[106:109], v[174:177], v[182:185], v[106:109]
	v_mfma_f32_16x16x32_bf16 v[102:105], v[166:169], v[190:193], v[102:105]
	v_mfma_f32_16x16x32_bf16 v[90:93], v[174:177], v[190:193], v[90:93]
	v_mfma_f32_16x16x32_bf16 v[86:89], v[166:169], v[198:201], v[86:89]
	v_mfma_f32_16x16x32_bf16 v[74:77], v[174:177], v[198:201], v[74:77]
	v_mfma_f32_16x16x32_bf16 v[70:73], v[166:169], v[208:211], v[70:73]
	v_mfma_f32_16x16x32_bf16 v[66:69], v[174:177], v[208:211], v[66:69]
	v_mfma_f32_16x16x32_bf16 v[118:121], v[170:173], v[186:189], v[118:121]
	v_mfma_f32_16x16x32_bf16 v[106:109], v[178:181], v[186:189], v[106:109]
	v_mfma_f32_16x16x32_bf16 v[102:105], v[170:173], v[194:197], v[102:105]
	v_mfma_f32_16x16x32_bf16 v[90:93], v[178:181], v[194:197], v[90:93]
	v_mfma_f32_16x16x32_bf16 v[86:89], v[170:173], v[204:207], v[86:89]
	v_mfma_f32_16x16x32_bf16 v[74:77], v[178:181], v[204:207], v[74:77]
	v_mfma_f32_16x16x32_bf16 v[70:73], v[170:173], v[212:215], v[70:73]
	v_mfma_f32_16x16x32_bf16 v[66:69], v[178:181], v[212:215], v[66:69]
	s_setprio 0
	s_barrier
	s_add_i32 s55, s45, s36
	v_lshl_add_u64 v[216:217], s[16:17], 0, v[130:131]
	s_mov_b32 m0, s55
	ds_read_b128 v[182:185], v146 offset:16384
	ds_read_b128 v[186:189], v146 offset:17408
	ds_read_b128 v[190:193], v146 offset:18432
	ds_read_b128 v[194:197], v146 offset:19456
	ds_read_b128 v[198:201], v146 offset:20480
	ds_read_b128 v[204:207], v146 offset:21504
	ds_read_b128 v[208:211], v146 offset:22528
	ds_read_b128 v[212:215], v146 offset:23552
	global_load_lds_dwordx4 v[216:217], off
	s_add_i32 m0, s55, 0x2000
	s_add_u32 s56, s16, 0xb0000
	v_lshl_add_u64 v[218:219], s[16:17], 0, v[132:133]
	s_addc_u32 s57, s17, 0
	s_add_i32 s55, s46, s36
	global_load_lds_dwordx4 v[218:219], off
	v_lshl_add_u64 v[220:221], s[56:57], 0, v[130:131]
	s_mov_b32 m0, s55
	v_lshl_add_u64 v[222:223], s[18:19], 0, v[132:133]
	global_load_lds_dwordx4 v[220:221], off
	v_lshl_add_u64 v[220:221], s[56:57], 0, v[132:133]
	s_add_i32 m0, s55, 0x2000
	s_nop 0
	global_load_lds_dwordx4 v[220:221], off
	v_lshl_add_u64 v[220:221], s[18:19], 0, v[130:131]
	s_mov_b32 m0, s37
	s_nop 0
	global_load_lds_dwordx4 v[220:221], off
	s_mov_b32 m0, s40
	s_nop 0
	global_load_lds_dwordx4 v[222:223], off
	s_waitcnt vmcnt(8)
	s_waitcnt lgkmcnt(0)
	s_barrier
; #define PG8_STAGE(bufoff, gbase, voff) do { _Pragma("unroll") for (int _i = 0; _i < 2; ++_i) \
;         __builtin_amdgcn_global_load_lds((const unsigned*)((const char*)(gbase) + (voff)[_i]), (LAS unsigned*)(lds + (bufoff) + ldsw + _i * 8192), 16, 0, 0); } while (0)
; #define PG8_LDA(dst, b, h) do { _Pragma("unroll") for (int m = 0; m < 4; ++m) _Pragma("unroll") for (int k = 0; k < 2; ++k) dst[m][k] = *(const LAS bf16x8*)(lds + PG8_SA(b, h) + aoff + m * 2048 + k * 1024); } while (0)
; #define PG8_LDB(dst, b, h) do { _Pragma("unroll") for (int n = 0; n < 2; ++n) _Pragma("unroll") for (int k = 0; k < 2; ++k) dst[n][k] = *(const LAS bf16x8*)(lds + PG8_SB(b, h) + boff + n * 2048 + k * 1024); } while (0)
; #define PG8_MMA(ai, bj, At, Bt) do { __builtin_amdgcn_s_setprio(1); _Pragma("unroll") for (int m = 0; m < 4; ++m) _Pragma("unroll") for (int n = 0; n < 2; ++n) _Pragma("unroll") for (int k = 0; k < 2; ++k) \
;         acc[ai][bj][m][n] = __builtin_amdgcn_mfma_f32_16x16x32_bf16(Bt[n][k], At[m][k], acc[ai][bj][m][n], 0, 0, 0); __builtin_amdgcn_s_setprio(0); } while (0)
; #define PG8_WAIT_V(n) asm volatile("s_waitcnt vmcnt(" #n ")" ::: "memory")
; #define PG8_WAIT_L(n) asm volatile("s_waitcnt lgkmcnt(" #n ")" ::: "memory")
; #define PG8_BAR __builtin_amdgcn_s_barrier()
; #define PG8_SCHED __builtin_amdgcn_sched_barrier(0)
; template <class Epi, class Sched, bool ALIGN_EPI>
; DI void gemm_phase(LAS unsigned char* lds, const Gemm g, const Sched& S, const Epi& E) {
;     ...
;             PG8_WAIT_V(8); PG8_WAIT_L(0); PG8_BAR; PG8_MMA(0, 0, At, B0); PG8_MMA(0, 1, At, B1); PG8_BAR; PG8_SCHED;
;             PG8_LDA(At, 0, 1); PG8_STAGE(PG8_SB(0, 0), b2, voffB); PG8_STAGE(PG8_SB(0, 1), b2 + hstepB, voffB); PG8_STAGE(PG8_SA(0, 0), a2, voffA);
;             PG8_WAIT_V(8); PG8_WAIT_L(0); PG8_BAR; PG8_MMA(1, 0, At, B0); PG8_MMA(1, 1, At, B1); PG8_BAR; PG8_SCHED;
;             PG8_LDB(B0, 1, 0); PG8_LDB(B1, 1, 1); PG8_SCHED; PG8_LDA(At, 1, 0); PG8_STAGE(PG8_SA(0, 1), a2 + hstepA, voffA);
;             PG8_WAIT_V(8); PG8_WAIT_L(0); PG8_BAR; PG8_MMA(0, 0, At, B0); PG8_MMA(0, 1, At, B1); PG8_BAR; PG8_SCHED;
	s_setprio 1
	s_waitcnt lgkmcnt(0)
	v_mfma_f32_16x16x32_bf16 v[62:65], v[148:151], v[182:185], v[62:65]
	v_mfma_f32_16x16x32_bf16 v[58:61], v[158:161], v[182:185], v[58:61]
	v_mfma_f32_16x16x32_bf16 v[46:49], v[148:151], v[190:193], v[46:49]
	v_mfma_f32_16x16x32_bf16 v[42:45], v[158:161], v[190:193], v[42:45]
	v_mfma_f32_16x16x32_bf16 v[30:33], v[148:151], v[198:201], v[30:33]
	v_mfma_f32_16x16x32_bf16 v[26:29], v[158:161], v[198:201], v[26:29]
	v_mfma_f32_16x16x32_bf16 v[14:17], v[148:151], v[208:211], v[14:17]
	v_mfma_f32_16x16x32_bf16 v[10:13], v[158:161], v[208:211], v[10:13]
	v_mfma_f32_16x16x32_bf16 v[62:65], v[154:157], v[186:189], v[62:65]
	v_mfma_f32_16x16x32_bf16 v[58:61], v[162:165], v[186:189], v[58:61]
	v_mfma_f32_16x16x32_bf16 v[46:49], v[154:157], v[194:197], v[46:49]
	v_mfma_f32_16x16x32_bf16 v[42:45], v[162:165], v[194:197], v[42:45]
	v_mfma_f32_16x16x32_bf16 v[30:33], v[154:157], v[204:207], v[30:33]
	v_mfma_f32_16x16x32_bf16 v[26:29], v[162:165], v[204:207], v[26:29]
	v_mfma_f32_16x16x32_bf16 v[14:17], v[154:157], v[212:215], v[14:17]
	v_mfma_f32_16x16x32_bf16 v[10:13], v[162:165], v[212:215], v[10:13]
	v_mfma_f32_16x16x32_bf16 v[54:57], v[166:169], v[182:185], v[54:57]
	v_mfma_f32_16x16x32_bf16 v[50:53], v[174:177], v[182:185], v[50:53]
	v_mfma_f32_16x16x32_bf16 v[38:41], v[166:169], v[190:193], v[38:41]
	v_mfma_f32_16x16x32_bf16 v[34:37], v[174:177], v[190:193], v[34:37]
	v_mfma_f32_16x16x32_bf16 v[22:25], v[166:169], v[198:201], v[22:25]
	v_mfma_f32_16x16x32_bf16 v[18:21], v[174:177], v[198:201], v[18:21]
	v_mfma_f32_16x16x32_bf16 v[6:9], v[166:169], v[208:211], v[6:9]
	v_mfma_f32_16x16x32_bf16 v[2:5], v[174:177], v[208:211], v[2:5]
	v_mfma_f32_16x16x32_bf16 v[54:57], v[170:173], v[186:189], v[54:57]
	v_mfma_f32_16x16x32_bf16 v[50:53], v[178:181], v[186:189], v[50:53]
	v_mfma_f32_16x16x32_bf16 v[38:41], v[170:173], v[194:197], v[38:41]
	v_mfma_f32_16x16x32_bf16 v[34:37], v[178:181], v[194:197], v[34:37]
	v_mfma_f32_16x16x32_bf16 v[22:25], v[170:173], v[204:207], v[22:25]
	v_mfma_f32_16x16x32_bf16 v[18:21], v[178:181], v[204:207], v[18:21]
	v_mfma_f32_16x16x32_bf16 v[6:9], v[170:173], v[212:215], v[6:9]
	v_mfma_f32_16x16x32_bf16 v[2:5], v[178:181], v[212:215], v[2:5]
	s_setprio 0
	s_barrier
	v_add_u32_e32 v147, s47, v1
	ds_read_b128 v[148:151], v147
	ds_read_b128 v[154:157], v147 offset:1024
	ds_read_b128 v[158:161], v147 offset:2048
	ds_read_b128 v[162:165], v147 offset:3072
	v_add_u32_e32 v147, s61, v1
	ds_read_b128 v[166:169], v147
	ds_read_b128 v[170:173], v147 offset:1024
	ds_read_b128 v[174:177], v147 offset:2048
	ds_read_b128 v[178:181], v147 offset:3072
	s_add_u32 s18, s18, 0xb0000
	s_addc_u32 s19, s19, 0
	s_mov_b32 m0, s41
	v_lshl_add_u64 v[224:225], s[18:19], 0, v[130:131]
	ds_read_b128 v[182:185], v146 offset:32768
	ds_read_b128 v[186:189], v146 offset:33792
	ds_read_b128 v[190:193], v146 offset:34816
	ds_read_b128 v[194:197], v146 offset:35840
	ds_read_b128 v[198:201], v146 offset:36864
	ds_read_b128 v[204:207], v146 offset:37888
	ds_read_b128 v[208:211], v146 offset:38912
	ds_read_b128 v[212:215], v146 offset:39936
	global_load_lds_dwordx4 v[224:225], off
	v_lshl_add_u64 v[224:225], s[18:19], 0, v[132:133]
	s_mov_b32 m0, s42
	s_nop 0
	global_load_lds_dwordx4 v[224:225], off
	s_waitcnt vmcnt(8)
	s_waitcnt lgkmcnt(0)
	s_barrier
	s_setprio 1
	s_waitcnt lgkmcnt(0)
	v_mfma_f32_16x16x32_bf16 v[126:129], v[148:151], v[182:185], v[126:129]
	v_mfma_f32_16x16x32_bf16 v[122:125], v[158:161], v[182:185], v[122:125]
	v_mfma_f32_16x16x32_bf16 v[114:117], v[148:151], v[190:193], v[114:117]
	v_mfma_f32_16x16x32_bf16 v[110:113], v[158:161], v[190:193], v[110:113]
	v_mfma_f32_16x16x32_bf16 v[98:101], v[148:151], v[198:201], v[98:101]
	v_mfma_f32_16x16x32_bf16 v[94:97], v[158:161], v[198:201], v[94:97]
	v_mfma_f32_16x16x32_bf16 v[82:85], v[148:151], v[208:211], v[82:85]
	v_mfma_f32_16x16x32_bf16 v[78:81], v[158:161], v[208:211], v[78:81]
	v_mfma_f32_16x16x32_bf16 v[126:129], v[154:157], v[186:189], v[126:129]
	v_mfma_f32_16x16x32_bf16 v[122:125], v[162:165], v[186:189], v[122:125]
	v_mfma_f32_16x16x32_bf16 v[114:117], v[154:157], v[194:197], v[114:117]
	v_mfma_f32_16x16x32_bf16 v[110:113], v[162:165], v[194:197], v[110:113]
	v_mfma_f32_16x16x32_bf16 v[98:101], v[154:157], v[204:207], v[98:101]
	v_mfma_f32_16x16x32_bf16 v[94:97], v[162:165], v[204:207], v[94:97]
	v_mfma_f32_16x16x32_bf16 v[82:85], v[154:157], v[212:215], v[82:85]
	v_mfma_f32_16x16x32_bf16 v[78:81], v[162:165], v[212:215], v[78:81]
	v_mfma_f32_16x16x32_bf16 v[118:121], v[166:169], v[182:185], v[118:121]
	v_mfma_f32_16x16x32_bf16 v[106:109], v[174:177], v[182:185], v[106:109]
	v_mfma_f32_16x16x32_bf16 v[102:105], v[166:169], v[190:193], v[102:105]
	v_mfma_f32_16x16x32_bf16 v[90:93], v[174:177], v[190:193], v[90:93]
	v_mfma_f32_16x16x32_bf16 v[86:89], v[166:169], v[198:201], v[86:89]
	v_mfma_f32_16x16x32_bf16 v[74:77], v[174:177], v[198:201], v[74:77]
	v_mfma_f32_16x16x32_bf16 v[70:73], v[166:169], v[208:211], v[70:73]
	v_mfma_f32_16x16x32_bf16 v[66:69], v[174:177], v[208:211], v[66:69]
	v_mfma_f32_16x16x32_bf16 v[118:121], v[170:173], v[186:189], v[118:121]
	v_mfma_f32_16x16x32_bf16 v[106:109], v[178:181], v[186:189], v[106:109]
	v_mfma_f32_16x16x32_bf16 v[102:105], v[170:173], v[194:197], v[102:105]
	v_mfma_f32_16x16x32_bf16 v[90:93], v[178:181], v[194:197], v[90:93]
	v_mfma_f32_16x16x32_bf16 v[86:89], v[170:173], v[204:207], v[86:89]
	v_mfma_f32_16x16x32_bf16 v[74:77], v[178:181], v[204:207], v[74:77]
	v_mfma_f32_16x16x32_bf16 v[70:73], v[170:173], v[212:215], v[70:73]
	v_mfma_f32_16x16x32_bf16 v[66:69], v[178:181], v[212:215], v[66:69]
	s_setprio 0
	s_barrier
; #define PG8_STAGE(bufoff, gbase, voff) do { _Pragma("unroll") for (int _i = 0; _i < 2; ++_i) \
;         __builtin_amdgcn_global_load_lds((const unsigned*)((const char*)(gbase) + (voff)[_i]), (LAS unsigned*)(lds + (bufoff) + ldsw + _i * 8192), 16, 0, 0); } while (0)
; #define PG8_LDA(dst, b, h) do { _Pragma("unroll") for (int m = 0; m < 4; ++m) _Pragma("unroll") for (int k = 0; k < 2; ++k) dst[m][k] = *(const LAS bf16x8*)(lds + PG8_SA(b, h) + aoff + m * 2048 + k * 1024); } while (0)
; #define PG8_MMA(ai, bj, At, Bt) do { __builtin_amdgcn_s_setprio(1); _Pragma("unroll") for (int m = 0; m < 4; ++m) _Pragma("unroll") for (int n = 0; n < 2; ++n) _Pragma("unroll") for (int k = 0; k < 2; ++k) \
;         acc[ai][bj][m][n] = __builtin_amdgcn_mfma_f32_16x16x32_bf16(Bt[n][k], At[m][k], acc[ai][bj][m][n], 0, 0, 0); __builtin_amdgcn_s_setprio(0); } while (0)
; #define PG8_WAIT_V(n) asm volatile("s_waitcnt vmcnt(" #n ")" ::: "memory")
; #define PG8_WAIT_L(n) asm volatile("s_waitcnt lgkmcnt(" #n ")" ::: "memory")
; #define PG8_BAR __builtin_amdgcn_s_barrier()
; #define PG8_SCHED __builtin_amdgcn_sched_barrier(0)
; template <class Epi, class Sched, bool ALIGN_EPI>
; DI void gemm_phase(LAS unsigned char* lds, const Gemm g, const Sched& S, const Epi& E) {
;     ...
;             PG8_LDA(At, 1, 1); PG8_STAGE(PG8_SB(1, 0), b3, voffB); PG8_STAGE(PG8_SB(1, 1), b3 + hstepB, voffB); PG8_STAGE(PG8_SA(1, 0), a3, voffA);
;             PG8_WAIT_V(8); PG8_WAIT_L(0); PG8_BAR; PG8_MMA(1, 0, At, B0); PG8_MMA(1, 1, At, B1); PG8_BAR; PG8_SCHED;
;         }
;         if constexpr (ALIGN_EPI) { if (wr == 0) PG8_BAR; }
;         if constexpr (!Epi::AFTER_DRAIN) E(acc, cur, wr, wc, fr, fq);
;         if (!has_next) break;
; #pragma unroll
;         for (int a = 0; a < 2; ++a)
; #pragma unroll
;             for (int b = 0; b < 2; ++b)
; #pragma unroll
;                 for (int m = 0; m < 4; ++m)
; #pragma unroll
;                     for (int n = 0; n < 2; ++n) acc[a][b][m][n] = (f32x4){0.f, 0.f, 0.f, 0.f};
;         cur = nxt; cA = nA; cB = nB; ++ui;
	s_add_i32 s18, s47, s36
	v_lshl_add_u64 v[216:217], v[216:217], 0, s[10:11]
	s_mov_b32 m0, s18
	ds_read_b128 v[182:185], v146 offset:49152
	ds_read_b128 v[186:189], v146 offset:50176
	ds_read_b128 v[190:193], v146 offset:51200
	ds_read_b128 v[194:197], v146 offset:52224
	ds_read_b128 v[198:201], v146 offset:53248
	ds_read_b128 v[204:207], v146 offset:54272
	ds_read_b128 v[208:211], v146 offset:55296
	ds_read_b128 v[212:215], v146 offset:56320
	global_load_lds_dwordx4 v[216:217], off
	s_add_i32 m0, s18, 0x2000
	s_add_u32 s16, s16, 0xb0080
	v_lshl_add_u64 v[216:217], v[218:219], 0, s[10:11]
	s_addc_u32 s17, s17, 0
	s_add_i32 s18, s61, s36
	global_load_lds_dwordx4 v[216:217], off
	v_lshl_add_u64 v[216:217], s[16:17], 0, v[130:131]
	s_mov_b32 m0, s18
	s_nop 0
	global_load_lds_dwordx4 v[216:217], off
	v_lshl_add_u64 v[216:217], s[16:17], 0, v[132:133]
	s_add_i32 m0, s18, 0x2000
	s_nop 0
	global_load_lds_dwordx4 v[216:217], off
	v_lshl_add_u64 v[216:217], v[220:221], 0, s[10:11]
	s_mov_b32 m0, s43
	s_nop 0
	global_load_lds_dwordx4 v[216:217], off
	v_lshl_add_u64 v[216:217], v[222:223], 0, s[10:11]
	s_mov_b32 m0, s44
	s_nop 0
	global_load_lds_dwordx4 v[216:217], off
	s_waitcnt vmcnt(8)
	s_waitcnt lgkmcnt(0)
	s_barrier
	s_setprio 1
	s_waitcnt lgkmcnt(0)
	v_mfma_f32_16x16x32_bf16 v[62:65], v[148:151], v[182:185], v[62:65]
	v_mfma_f32_16x16x32_bf16 v[58:61], v[158:161], v[182:185], v[58:61]
	v_mfma_f32_16x16x32_bf16 v[46:49], v[148:151], v[190:193], v[46:49]
	v_mfma_f32_16x16x32_bf16 v[42:45], v[158:161], v[190:193], v[42:45]
	v_mfma_f32_16x16x32_bf16 v[30:33], v[148:151], v[198:201], v[30:33]
	v_mfma_f32_16x16x32_bf16 v[26:29], v[158:161], v[198:201], v[26:29]
	v_mfma_f32_16x16x32_bf16 v[14:17], v[148:151], v[208:211], v[14:17]
	v_mfma_f32_16x16x32_bf16 v[10:13], v[158:161], v[208:211], v[10:13]
	v_mfma_f32_16x16x32_bf16 v[62:65], v[154:157], v[186:189], v[62:65]
	v_mfma_f32_16x16x32_bf16 v[58:61], v[162:165], v[186:189], v[58:61]
	v_mfma_f32_16x16x32_bf16 v[46:49], v[154:157], v[194:197], v[46:49]
	v_mfma_f32_16x16x32_bf16 v[42:45], v[162:165], v[194:197], v[42:45]
	v_mfma_f32_16x16x32_bf16 v[30:33], v[154:157], v[204:207], v[30:33]
	v_mfma_f32_16x16x32_bf16 v[26:29], v[162:165], v[204:207], v[26:29]
	v_mfma_f32_16x16x32_bf16 v[14:17], v[154:157], v[212:215], v[14:17]
	v_mfma_f32_16x16x32_bf16 v[10:13], v[162:165], v[212:215], v[10:13]
	v_mfma_f32_16x16x32_bf16 v[54:57], v[166:169], v[182:185], v[54:57]
	v_mfma_f32_16x16x32_bf16 v[50:53], v[174:177], v[182:185], v[50:53]
	v_mfma_f32_16x16x32_bf16 v[38:41], v[166:169], v[190:193], v[38:41]
	v_mfma_f32_16x16x32_bf16 v[34:37], v[174:177], v[190:193], v[34:37]
	v_mfma_f32_16x16x32_bf16 v[22:25], v[166:169], v[198:201], v[22:25]
	v_mfma_f32_16x16x32_bf16 v[18:21], v[174:177], v[198:201], v[18:21]
	v_mfma_f32_16x16x32_bf16 v[6:9], v[166:169], v[208:211], v[6:9]
	v_mfma_f32_16x16x32_bf16 v[2:5], v[174:177], v[208:211], v[2:5]
	v_mfma_f32_16x16x32_bf16 v[54:57], v[170:173], v[186:189], v[54:57]
	v_mfma_f32_16x16x32_bf16 v[50:53], v[178:181], v[186:189], v[50:53]
	v_mfma_f32_16x16x32_bf16 v[38:41], v[170:173], v[194:197], v[38:41]
	v_mfma_f32_16x16x32_bf16 v[34:37], v[178:181], v[194:197], v[34:37]
	v_mfma_f32_16x16x32_bf16 v[22:25], v[170:173], v[204:207], v[22:25]
	v_mfma_f32_16x16x32_bf16 v[18:21], v[178:181], v[204:207], v[18:21]
	v_mfma_f32_16x16x32_bf16 v[6:9], v[170:173], v[212:215], v[6:9]
	v_mfma_f32_16x16x32_bf16 v[2:5], v[178:181], v[212:215], v[2:5]
	s_setprio 0
	s_barrier
	s_add_i32 s54, s54, 2
	s_add_u32 s14, s14, 0x100
	s_addc_u32 s15, s15, 0
	s_cmp_gt_u32 s54, 41
	s_cbranch_scc0 .LBB0_1536
	s_add_u32 s14, s52, 0xffffff00
	s_addc_u32 s15, s53, -1
	s_and_b64 vcc, exec, s[6:7]
	s_cbranch_vccnz .LBB0_1539
	v_mov_b32_e32 v2, 0
	s_mov_b32 s2, s62
	s_mov_b32 s22, s63
	s_mov_b64 s[8:9], s[12:13]
	s_mov_b32 s60, s33
	v_mov_b32_e32 v3, v2
	v_mov_b32_e32 v4, v2
	v_mov_b32_e32 v5, v2
	v_mov_b32_e32 v6, v2
	v_mov_b32_e32 v7, v2
	v_mov_b32_e32 v8, v2
	v_mov_b32_e32 v9, v2
	v_mov_b32_e32 v18, v2
	v_mov_b32_e32 v19, v2
	v_mov_b32_e32 v20, v2
	v_mov_b32_e32 v21, v2
	v_mov_b32_e32 v22, v2
	v_mov_b32_e32 v23, v2
	v_mov_b32_e32 v24, v2
	v_mov_b32_e32 v25, v2
	v_mov_b32_e32 v34, v2
	v_mov_b32_e32 v35, v2
	v_mov_b32_e32 v36, v2
	v_mov_b32_e32 v37, v2
	v_mov_b32_e32 v38, v2
	v_mov_b32_e32 v39, v2
	v_mov_b32_e32 v40, v2
	v_mov_b32_e32 v41, v2
	v_mov_b32_e32 v50, v2
	v_mov_b32_e32 v51, v2
	v_mov_b32_e32 v52, v2
	v_mov_b32_e32 v53, v2
	v_mov_b32_e32 v54, v2
	v_mov_b32_e32 v55, v2
	v_mov_b32_e32 v56, v2
	v_mov_b32_e32 v57, v2
	v_mov_b32_e32 v10, v2
	v_mov_b32_e32 v11, v2
	v_mov_b32_e32 v12, v2
	v_mov_b32_e32 v13, v2
	v_mov_b32_e32 v14, v2
	v_mov_b32_e32 v15, v2
	v_mov_b32_e32 v16, v2
	v_mov_b32_e32 v17, v2
	v_mov_b32_e32 v26, v2
	v_mov_b32_e32 v27, v2
	v_mov_b32_e32 v28, v2
	v_mov_b32_e32 v29, v2
	v_mov_b32_e32 v30, v2
	v_mov_b32_e32 v31, v2
	v_mov_b32_e32 v32, v2
	v_mov_b32_e32 v33, v2
	v_mov_b32_e32 v42, v2
	v_mov_b32_e32 v43, v2
	v_mov_b32_e32 v44, v2
	v_mov_b32_e32 v45, v2
	v_mov_b32_e32 v46, v2
	v_mov_b32_e32 v47, v2
	v_mov_b32_e32 v48, v2
	v_mov_b32_e32 v49, v2
	v_mov_b32_e32 v58, v2
	v_mov_b32_e32 v59, v2
	v_mov_b32_e32 v60, v2
	v_mov_b32_e32 v61, v2
	v_mov_b32_e32 v62, v2
	v_mov_b32_e32 v63, v2
	v_mov_b32_e32 v64, v2
	v_mov_b32_e32 v65, v2
	v_mov_b32_e32 v66, v2
	v_mov_b32_e32 v67, v2
	v_mov_b32_e32 v68, v2
	v_mov_b32_e32 v69, v2
	v_mov_b32_e32 v70, v2
	v_mov_b32_e32 v71, v2
	v_mov_b32_e32 v72, v2
	v_mov_b32_e32 v73, v2
	v_mov_b32_e32 v74, v2
	v_mov_b32_e32 v75, v2
	v_mov_b32_e32 v76, v2
	v_mov_b32_e32 v77, v2
	v_mov_b32_e32 v86, v2
	v_mov_b32_e32 v87, v2
	v_mov_b32_e32 v88, v2
	v_mov_b32_e32 v89, v2
	v_mov_b32_e32 v90, v2
	v_mov_b32_e32 v91, v2
	v_mov_b32_e32 v92, v2
	v_mov_b32_e32 v93, v2
	v_mov_b32_e32 v102, v2
	v_mov_b32_e32 v103, v2
	v_mov_b32_e32 v104, v2
	v_mov_b32_e32 v105, v2
	v_mov_b32_e32 v106, v2
	v_mov_b32_e32 v107, v2
	v_mov_b32_e32 v108, v2
	v_mov_b32_e32 v109, v2
	v_mov_b32_e32 v118, v2
	v_mov_b32_e32 v119, v2
	v_mov_b32_e32 v120, v2
	v_mov_b32_e32 v121, v2
	v_mov_b32_e32 v78, v2
	v_mov_b32_e32 v79, v2
	v_mov_b32_e32 v80, v2
	v_mov_b32_e32 v81, v2
	v_mov_b32_e32 v82, v2
	v_mov_b32_e32 v83, v2
	v_mov_b32_e32 v84, v2
	v_mov_b32_e32 v85, v2
	v_mov_b32_e32 v94, v2
	v_mov_b32_e32 v95, v2
	v_mov_b32_e32 v96, v2
	v_mov_b32_e32 v97, v2
	v_mov_b32_e32 v98, v2
	v_mov_b32_e32 v99, v2
	v_mov_b32_e32 v100, v2
	v_mov_b32_e32 v101, v2
	v_mov_b32_e32 v110, v2
	v_mov_b32_e32 v111, v2
	v_mov_b32_e32 v112, v2
	v_mov_b32_e32 v113, v2
	v_mov_b32_e32 v114, v2
	v_mov_b32_e32 v115, v2
	v_mov_b32_e32 v116, v2
	v_mov_b32_e32 v117, v2
	v_mov_b32_e32 v122, v2
	v_mov_b32_e32 v123, v2
	v_mov_b32_e32 v124, v2
	v_mov_b32_e32 v125, v2
	v_mov_b32_e32 v126, v2
	v_mov_b32_e32 v127, v2
	v_mov_b32_e32 v128, v2
	v_mov_b32_e32 v129, v2
	s_andn2_b64 vcc, exec, s[4:5]
	s_cbranch_vccnz .LBB0_1540
	s_branch .LBB0_1541

; #define PG8_STAGE(bufoff, gbase, voff) do { _Pragma("unroll") for (int _i = 0; _i < 2; ++_i) \
;         __builtin_amdgcn_global_load_lds((const unsigned*)((const char*)(gbase) + (voff)[_i]), (LAS unsigned*)(lds + (bufoff) + ldsw + _i * 8192), 16, 0, 0); } while (0)
; #define PG8_LDA(dst, b, h) do { _Pragma("unroll") for (int m = 0; m < 4; ++m) _Pragma("unroll") for (int k = 0; k < 2; ++k) dst[m][k] = *(const LAS bf16x8*)(lds + PG8_SA(b, h) + aoff + m * 2048 + k * 1024); } while (0)
; #define PG8_LDB(dst, b, h) do { _Pragma("unroll") for (int n = 0; n < 2; ++n) _Pragma("unroll") for (int k = 0; k < 2; ++k) dst[n][k] = *(const LAS bf16x8*)(lds + PG8_SB(b, h) + boff + n * 2048 + k * 1024); } while (0)
; #define PG8_MMA(ai, bj, At, Bt) do { __builtin_amdgcn_s_setprio(1); _Pragma("unroll") for (int m = 0; m < 4; ++m) _Pragma("unroll") for (int n = 0; n < 2; ++n) _Pragma("unroll") for (int k = 0; k < 2; ++k) \
;         acc[ai][bj][m][n] = __builtin_amdgcn_mfma_f32_16x16x32_bf16(Bt[n][k], At[m][k], acc[ai][bj][m][n], 0, 0, 0); __builtin_amdgcn_s_setprio(0); } while (0)
; #define PG8_WAIT_V(n) asm volatile("s_waitcnt vmcnt(" #n ")" ::: "memory")
; #define PG8_WAIT_L(n) asm volatile("s_waitcnt lgkmcnt(" #n ")" ::: "memory")
; #define PG8_BAR __builtin_amdgcn_s_barrier()
; #define PG8_SCHED __builtin_amdgcn_sched_barrier(0)
; template <class Epi, class Sched, bool ALIGN_EPI>
; DI void gemm_phase(LAS unsigned char* lds, const Gemm g, const Sched& S, const Epi& E) {
;     ...
;         for (int t = 0; t < nt; t += 2) {
;             const bool last = (t == nt - 2);
;             const char* a1 = cA + (size_t)(t + 1) * kstep;
;             const char* a2 = last ? nA : cA + (size_t)(t + 2) * kstep; const char* b2 = last ? nB : cB + (size_t)(t + 2) * kstep;
;             const char* a3 = a2 + kstep; const char* b3 = b2 + kstep;
;             PG8_LDB(B0, 0, 0); PG8_LDB(B1, 0, 1); PG8_SCHED; PG8_LDA(At, 0, 0); PG8_STAGE(PG8_SA(1, 1), a1 + hstepA, voffA);
;             PG8_WAIT_V(8); PG8_WAIT_L(0); PG8_BAR; PG8_MMA(0, 0, At, B0); PG8_MMA(0, 1, At, B1); PG8_BAR; PG8_SCHED;
;             PG8_LDA(At, 0, 1); PG8_STAGE(PG8_SB(0, 0), b2, voffB); PG8_STAGE(PG8_SB(0, 1), b2 + hstepB, voffB); PG8_STAGE(PG8_SA(0, 0), a2, voffA);
;             PG8_WAIT_V(8); PG8_WAIT_L(0); PG8_BAR; PG8_MMA(1, 0, At, B0); PG8_MMA(1, 1, At, B1); PG8_BAR; PG8_SCHED;
.LBB0_1641:
	ds_read_b128 v[154:157], v147
	ds_read_b128 v[158:161], v147 offset:1024
	ds_read_b128 v[162:165], v147 offset:2048
	ds_read_b128 v[166:169], v147 offset:3072
	ds_read_b128 v[170:173], v148
	ds_read_b128 v[174:177], v148 offset:1024
	ds_read_b128 v[178:181], v148 offset:2048
	ds_read_b128 v[182:185], v148 offset:3072
	s_add_u32 s24, s22, 0xfffc0080
	s_addc_u32 s25, s23, -1
	s_cmp_eq_u32 s56, 12
	s_cselect_b32 s27, s17, s25
	s_cselect_b32 s26, s52, s24
	s_cselect_b32 s25, s15, s55
	s_cselect_b32 s24, s53, s54
	v_lshl_add_u64 v[220:221], s[22:23], 0, v[138:139]
	s_add_i32 m0, s13, 0xc000
	ds_read_b128 v[186:189], v149
	ds_read_b128 v[190:193], v149 offset:1024
	ds_read_b128 v[194:197], v149 offset:2048
	ds_read_b128 v[198:201], v149 offset:3072
	ds_read_b128 v[204:207], v149 offset:4096
	ds_read_b128 v[208:211], v149 offset:5120
	ds_read_b128 v[212:215], v149 offset:6144
	ds_read_b128 v[216:219], v149 offset:7168
	global_load_lds_dwordx4 v[220:221], off
	v_lshl_add_u64 v[220:221], s[22:23], 0, v[140:141]
	s_add_i32 m0, s13, 0xe000
	s_nop 0
	global_load_lds_dwordx4 v[220:221], off
	s_waitcnt vmcnt(8)
	s_waitcnt lgkmcnt(0)
	s_barrier
	s_setprio 1
	s_waitcnt lgkmcnt(0)
	v_mfma_f32_16x16x32_bf16 v[126:129], v[154:157], v[186:189], v[126:129]
	v_mfma_f32_16x16x32_bf16 v[122:125], v[162:165], v[186:189], v[122:125]
	v_mfma_f32_16x16x32_bf16 v[118:121], v[154:157], v[194:197], v[118:121]
	v_mfma_f32_16x16x32_bf16 v[114:117], v[162:165], v[194:197], v[114:117]
	v_mfma_f32_16x16x32_bf16 v[102:105], v[154:157], v[204:207], v[102:105]
	v_mfma_f32_16x16x32_bf16 v[98:101], v[162:165], v[204:207], v[98:101]
	v_mfma_f32_16x16x32_bf16 v[86:89], v[154:157], v[212:215], v[86:89]
	v_mfma_f32_16x16x32_bf16 v[82:85], v[162:165], v[212:215], v[82:85]
	v_mfma_f32_16x16x32_bf16 v[126:129], v[158:161], v[190:193], v[126:129]
	v_mfma_f32_16x16x32_bf16 v[122:125], v[166:169], v[190:193], v[122:125]
	v_mfma_f32_16x16x32_bf16 v[118:121], v[158:161], v[198:201], v[118:121]
	v_mfma_f32_16x16x32_bf16 v[114:117], v[166:169], v[198:201], v[114:117]
	v_mfma_f32_16x16x32_bf16 v[102:105], v[158:161], v[208:211], v[102:105]
	v_mfma_f32_16x16x32_bf16 v[98:101], v[166:169], v[208:211], v[98:101]
	v_mfma_f32_16x16x32_bf16 v[86:89], v[158:161], v[216:219], v[86:89]
	v_mfma_f32_16x16x32_bf16 v[82:85], v[166:169], v[216:219], v[82:85]
	v_mfma_f32_16x16x32_bf16 v[110:113], v[170:173], v[186:189], v[110:113]
	v_mfma_f32_16x16x32_bf16 v[106:109], v[178:181], v[186:189], v[106:109]
	v_mfma_f32_16x16x32_bf16 v[94:97], v[170:173], v[194:197], v[94:97]
	v_mfma_f32_16x16x32_bf16 v[90:93], v[178:181], v[194:197], v[90:93]
	v_mfma_f32_16x16x32_bf16 v[78:81], v[170:173], v[204:207], v[78:81]
	v_mfma_f32_16x16x32_bf16 v[74:77], v[178:181], v[204:207], v[74:77]
	v_mfma_f32_16x16x32_bf16 v[70:73], v[170:173], v[212:215], v[70:73]
	v_mfma_f32_16x16x32_bf16 v[66:69], v[178:181], v[212:215], v[66:69]
	v_mfma_f32_16x16x32_bf16 v[110:113], v[174:177], v[190:193], v[110:113]
	v_mfma_f32_16x16x32_bf16 v[106:109], v[182:185], v[190:193], v[106:109]
	v_mfma_f32_16x16x32_bf16 v[94:97], v[174:177], v[198:201], v[94:97]
	v_mfma_f32_16x16x32_bf16 v[90:93], v[182:185], v[198:201], v[90:93]
	v_mfma_f32_16x16x32_bf16 v[78:81], v[174:177], v[208:211], v[78:81]
	v_mfma_f32_16x16x32_bf16 v[74:77], v[182:185], v[208:211], v[74:77]
	v_mfma_f32_16x16x32_bf16 v[70:73], v[174:177], v[216:219], v[70:73]
	v_mfma_f32_16x16x32_bf16 v[66:69], v[182:185], v[216:219], v[66:69]
	s_setprio 0
	s_barrier
	s_add_i32 s57, s63, s40
	v_lshl_add_u64 v[220:221], s[24:25], 0, v[134:135]
	s_mov_b32 m0, s57
	ds_read_b128 v[186:189], v149 offset:16384
	ds_read_b128 v[190:193], v149 offset:17408
	ds_read_b128 v[194:197], v149 offset:18432
	ds_read_b128 v[198:201], v149 offset:19456
	ds_read_b128 v[204:207], v149 offset:20480
	ds_read_b128 v[208:211], v149 offset:21504
	ds_read_b128 v[212:215], v149 offset:22528
	ds_read_b128 v[216:219], v149 offset:23552
	global_load_lds_dwordx4 v[220:221], off
	s_add_i32 m0, s57, 0x2000
	s_add_u32 s58, s24, 0x40000
	v_lshl_add_u64 v[222:223], s[24:25], 0, v[130:131]
	s_addc_u32 s59, s25, 0
	s_add_i32 s57, s64, s40
	global_load_lds_dwordx4 v[222:223], off
	v_lshl_add_u64 v[224:225], s[58:59], 0, v[134:135]
	s_mov_b32 m0, s57
	v_lshl_add_u64 v[226:227], s[26:27], 0, v[132:133]
	global_load_lds_dwordx4 v[224:225], off
	v_lshl_add_u64 v[224:225], s[58:59], 0, v[130:131]
	s_add_i32 m0, s57, 0x2000
	s_nop 0
	global_load_lds_dwordx4 v[224:225], off
	v_lshl_add_u64 v[224:225], s[26:27], 0, v[136:137]
	s_mov_b32 m0, s13
	s_nop 0
	global_load_lds_dwordx4 v[224:225], off
	s_mov_b32 m0, s43
	s_nop 0
	global_load_lds_dwordx4 v[226:227], off
	s_waitcnt vmcnt(8)
	s_waitcnt lgkmcnt(0)
	s_barrier
; #define PG8_STAGE(bufoff, gbase, voff) do { _Pragma("unroll") for (int _i = 0; _i < 2; ++_i) \
;         __builtin_amdgcn_global_load_lds((const unsigned*)((const char*)(gbase) + (voff)[_i]), (LAS unsigned*)(lds + (bufoff) + ldsw + _i * 8192), 16, 0, 0); } while (0)
; #define PG8_LDA(dst, b, h) do { _Pragma("unroll") for (int m = 0; m < 4; ++m) _Pragma("unroll") for (int k = 0; k < 2; ++k) dst[m][k] = *(const LAS bf16x8*)(lds + PG8_SA(b, h) + aoff + m * 2048 + k * 1024); } while (0)
; #define PG8_LDB(dst, b, h) do { _Pragma("unroll") for (int n = 0; n < 2; ++n) _Pragma("unroll") for (int k = 0; k < 2; ++k) dst[n][k] = *(const LAS bf16x8*)(lds + PG8_SB(b, h) + boff + n * 2048 + k * 1024); } while (0)
; #define PG8_MMA(ai, bj, At, Bt) do { __builtin_amdgcn_s_setprio(1); _Pragma("unroll") for (int m = 0; m < 4; ++m) _Pragma("unroll") for (int n = 0; n < 2; ++n) _Pragma("unroll") for (int k = 0; k < 2; ++k) \
;         acc[ai][bj][m][n] = __builtin_amdgcn_mfma_f32_16x16x32_bf16(Bt[n][k], At[m][k], acc[ai][bj][m][n], 0, 0, 0); __builtin_amdgcn_s_setprio(0); } while (0)
; #define PG8_WAIT_V(n) asm volatile("s_waitcnt vmcnt(" #n ")" ::: "memory")
; #define PG8_WAIT_L(n) asm volatile("s_waitcnt lgkmcnt(" #n ")" ::: "memory")
; #define PG8_BAR __builtin_amdgcn_s_barrier()
; #define PG8_SCHED __builtin_amdgcn_sched_barrier(0)
; template <class Epi, class Sched, bool ALIGN_EPI>
; DI void gemm_phase(LAS unsigned char* lds, const Gemm g, const Sched& S, const Epi& E) {
;     ...
;             PG8_WAIT_V(8); PG8_WAIT_L(0); PG8_BAR; PG8_MMA(0, 0, At, B0); PG8_MMA(0, 1, At, B1); PG8_BAR; PG8_SCHED;
;             PG8_LDA(At, 0, 1); PG8_STAGE(PG8_SB(0, 0), b2, voffB); PG8_STAGE(PG8_SB(0, 1), b2 + hstepB, voffB); PG8_STAGE(PG8_SA(0, 0), a2, voffA);
;             PG8_WAIT_V(8); PG8_WAIT_L(0); PG8_BAR; PG8_MMA(1, 0, At, B0); PG8_MMA(1, 1, At, B1); PG8_BAR; PG8_SCHED;
;             PG8_LDB(B0, 1, 0); PG8_LDB(B1, 1, 1); PG8_SCHED; PG8_LDA(At, 1, 0); PG8_STAGE(PG8_SA(0, 1), a2 + hstepA, voffA);
;             PG8_WAIT_V(8); PG8_WAIT_L(0); PG8_BAR; PG8_MMA(0, 0, At, B0); PG8_MMA(0, 1, At, B1); PG8_BAR; PG8_SCHED;
	s_setprio 1
	s_waitcnt lgkmcnt(0)
	v_mfma_f32_16x16x32_bf16 v[62:65], v[154:157], v[186:189], v[62:65]
	v_mfma_f32_16x16x32_bf16 v[58:61], v[162:165], v[186:189], v[58:61]
	v_mfma_f32_16x16x32_bf16 v[54:57], v[154:157], v[194:197], v[54:57]
	v_mfma_f32_16x16x32_bf16 v[50:53], v[162:165], v[194:197], v[50:53]
	v_mfma_f32_16x16x32_bf16 v[38:41], v[154:157], v[204:207], v[38:41]
	v_mfma_f32_16x16x32_bf16 v[34:37], v[162:165], v[204:207], v[34:37]
	v_mfma_f32_16x16x32_bf16 v[22:25], v[154:157], v[212:215], v[22:25]
	v_mfma_f32_16x16x32_bf16 v[18:21], v[162:165], v[212:215], v[18:21]
	v_mfma_f32_16x16x32_bf16 v[62:65], v[158:161], v[190:193], v[62:65]
	v_mfma_f32_16x16x32_bf16 v[58:61], v[166:169], v[190:193], v[58:61]
	v_mfma_f32_16x16x32_bf16 v[54:57], v[158:161], v[198:201], v[54:57]
	v_mfma_f32_16x16x32_bf16 v[50:53], v[166:169], v[198:201], v[50:53]
	v_mfma_f32_16x16x32_bf16 v[38:41], v[158:161], v[208:211], v[38:41]
	v_mfma_f32_16x16x32_bf16 v[34:37], v[166:169], v[208:211], v[34:37]
	v_mfma_f32_16x16x32_bf16 v[22:25], v[158:161], v[216:219], v[22:25]
	v_mfma_f32_16x16x32_bf16 v[18:21], v[166:169], v[216:219], v[18:21]
	v_mfma_f32_16x16x32_bf16 v[46:49], v[170:173], v[186:189], v[46:49]
	v_mfma_f32_16x16x32_bf16 v[42:45], v[178:181], v[186:189], v[42:45]
	v_mfma_f32_16x16x32_bf16 v[30:33], v[170:173], v[194:197], v[30:33]
	v_mfma_f32_16x16x32_bf16 v[26:29], v[178:181], v[194:197], v[26:29]
	v_mfma_f32_16x16x32_bf16 v[14:17], v[170:173], v[204:207], v[14:17]
	v_mfma_f32_16x16x32_bf16 v[10:13], v[178:181], v[204:207], v[10:13]
	v_mfma_f32_16x16x32_bf16 v[6:9], v[170:173], v[212:215], v[6:9]
	v_mfma_f32_16x16x32_bf16 v[2:5], v[178:181], v[212:215], v[2:5]
	v_mfma_f32_16x16x32_bf16 v[46:49], v[174:177], v[190:193], v[46:49]
	v_mfma_f32_16x16x32_bf16 v[42:45], v[182:185], v[190:193], v[42:45]
	v_mfma_f32_16x16x32_bf16 v[30:33], v[174:177], v[198:201], v[30:33]
	v_mfma_f32_16x16x32_bf16 v[26:29], v[182:185], v[198:201], v[26:29]
	v_mfma_f32_16x16x32_bf16 v[14:17], v[174:177], v[208:211], v[14:17]
	v_mfma_f32_16x16x32_bf16 v[10:13], v[182:185], v[208:211], v[10:13]
	v_mfma_f32_16x16x32_bf16 v[6:9], v[174:177], v[216:219], v[6:9]
	v_mfma_f32_16x16x32_bf16 v[2:5], v[182:185], v[216:219], v[2:5]
	s_setprio 0
	s_barrier
	ds_read_b128 v[154:157], v150
	ds_read_b128 v[158:161], v150 offset:1024
	ds_read_b128 v[162:165], v150 offset:2048
	ds_read_b128 v[166:169], v150 offset:3072
	ds_read_b128 v[170:173], v151
	ds_read_b128 v[174:177], v151 offset:1024
	ds_read_b128 v[178:181], v151 offset:2048
	ds_read_b128 v[182:185], v151 offset:3072
	s_add_u32 s26, s26, 0x40000
	s_addc_u32 s27, s27, 0
	s_mov_b32 m0, s44
	v_lshl_add_u64 v[228:229], s[26:27], 0, v[136:137]
	ds_read_b128 v[186:189], v149 offset:32768
	ds_read_b128 v[190:193], v149 offset:33792
	ds_read_b128 v[194:197], v149 offset:34816
	ds_read_b128 v[198:201], v149 offset:35840
	ds_read_b128 v[204:207], v149 offset:36864
	ds_read_b128 v[208:211], v149 offset:37888
	ds_read_b128 v[212:215], v149 offset:38912
	ds_read_b128 v[216:219], v149 offset:39936
	global_load_lds_dwordx4 v[228:229], off
	v_lshl_add_u64 v[228:229], s[26:27], 0, v[132:133]
	s_mov_b32 m0, s45
	s_nop 0
	global_load_lds_dwordx4 v[228:229], off
	s_waitcnt vmcnt(8)
	s_waitcnt lgkmcnt(0)
	s_barrier
	s_setprio 1
	s_waitcnt lgkmcnt(0)
	v_mfma_f32_16x16x32_bf16 v[126:129], v[154:157], v[186:189], v[126:129]
	v_mfma_f32_16x16x32_bf16 v[122:125], v[162:165], v[186:189], v[122:125]
	v_mfma_f32_16x16x32_bf16 v[118:121], v[154:157], v[194:197], v[118:121]
	v_mfma_f32_16x16x32_bf16 v[114:117], v[162:165], v[194:197], v[114:117]
	v_mfma_f32_16x16x32_bf16 v[102:105], v[154:157], v[204:207], v[102:105]
	v_mfma_f32_16x16x32_bf16 v[98:101], v[162:165], v[204:207], v[98:101]
	v_mfma_f32_16x16x32_bf16 v[86:89], v[154:157], v[212:215], v[86:89]
	v_mfma_f32_16x16x32_bf16 v[82:85], v[162:165], v[212:215], v[82:85]
	v_mfma_f32_16x16x32_bf16 v[126:129], v[158:161], v[190:193], v[126:129]
	v_mfma_f32_16x16x32_bf16 v[122:125], v[166:169], v[190:193], v[122:125]
	v_mfma_f32_16x16x32_bf16 v[118:121], v[158:161], v[198:201], v[118:121]
	v_mfma_f32_16x16x32_bf16 v[114:117], v[166:169], v[198:201], v[114:117]
	v_mfma_f32_16x16x32_bf16 v[102:105], v[158:161], v[208:211], v[102:105]
	v_mfma_f32_16x16x32_bf16 v[98:101], v[166:169], v[208:211], v[98:101]
	v_mfma_f32_16x16x32_bf16 v[86:89], v[158:161], v[216:219], v[86:89]
	v_mfma_f32_16x16x32_bf16 v[82:85], v[166:169], v[216:219], v[82:85]
	v_mfma_f32_16x16x32_bf16 v[110:113], v[170:173], v[186:189], v[110:113]
	v_mfma_f32_16x16x32_bf16 v[106:109], v[178:181], v[186:189], v[106:109]
	v_mfma_f32_16x16x32_bf16 v[94:97], v[170:173], v[194:197], v[94:97]
	v_mfma_f32_16x16x32_bf16 v[90:93], v[178:181], v[194:197], v[90:93]
	v_mfma_f32_16x16x32_bf16 v[78:81], v[170:173], v[204:207], v[78:81]
	v_mfma_f32_16x16x32_bf16 v[74:77], v[178:181], v[204:207], v[74:77]
	v_mfma_f32_16x16x32_bf16 v[70:73], v[170:173], v[212:215], v[70:73]
	v_mfma_f32_16x16x32_bf16 v[66:69], v[178:181], v[212:215], v[66:69]
	v_mfma_f32_16x16x32_bf16 v[110:113], v[174:177], v[190:193], v[110:113]
	v_mfma_f32_16x16x32_bf16 v[106:109], v[182:185], v[190:193], v[106:109]
	v_mfma_f32_16x16x32_bf16 v[94:97], v[174:177], v[198:201], v[94:97]
	v_mfma_f32_16x16x32_bf16 v[90:93], v[182:185], v[198:201], v[90:93]
	v_mfma_f32_16x16x32_bf16 v[78:81], v[174:177], v[208:211], v[78:81]
	v_mfma_f32_16x16x32_bf16 v[74:77], v[182:185], v[208:211], v[74:77]
	v_mfma_f32_16x16x32_bf16 v[70:73], v[174:177], v[216:219], v[70:73]
	v_mfma_f32_16x16x32_bf16 v[66:69], v[182:185], v[216:219], v[66:69]
	s_setprio 0
	s_barrier
; #define PG8_STAGE(bufoff, gbase, voff) do { _Pragma("unroll") for (int _i = 0; _i < 2; ++_i) \
;         __builtin_amdgcn_global_load_lds((const unsigned*)((const char*)(gbase) + (voff)[_i]), (LAS unsigned*)(lds + (bufoff) + ldsw + _i * 8192), 16, 0, 0); } while (0)
; #define PG8_LDA(dst, b, h) do { _Pragma("unroll") for (int m = 0; m < 4; ++m) _Pragma("unroll") for (int k = 0; k < 2; ++k) dst[m][k] = *(const LAS bf16x8*)(lds + PG8_SA(b, h) + aoff + m * 2048 + k * 1024); } while (0)
; #define PG8_MMA(ai, bj, At, Bt) do { __builtin_amdgcn_s_setprio(1); _Pragma("unroll") for (int m = 0; m < 4; ++m) _Pragma("unroll") for (int n = 0; n < 2; ++n) _Pragma("unroll") for (int k = 0; k < 2; ++k) \
;         acc[ai][bj][m][n] = __builtin_amdgcn_mfma_f32_16x16x32_bf16(Bt[n][k], At[m][k], acc[ai][bj][m][n], 0, 0, 0); __builtin_amdgcn_s_setprio(0); } while (0)
; #define PG8_WAIT_V(n) asm volatile("s_waitcnt vmcnt(" #n ")" ::: "memory")
; #define PG8_WAIT_L(n) asm volatile("s_waitcnt lgkmcnt(" #n ")" ::: "memory")
; #define PG8_BAR __builtin_amdgcn_s_barrier()
; #define PG8_SCHED __builtin_amdgcn_sched_barrier(0)
; template <class Epi, class Sched, bool ALIGN_EPI>
; DI void gemm_phase(LAS unsigned char* lds, const Gemm g, const Sched& S, const Epi& E) {
;     ...
;             PG8_LDA(At, 1, 1); PG8_STAGE(PG8_SB(1, 0), b3, voffB); PG8_STAGE(PG8_SB(1, 1), b3 + hstepB, voffB); PG8_STAGE(PG8_SA(1, 0), a3, voffA);
;             PG8_WAIT_V(8); PG8_WAIT_L(0); PG8_BAR; PG8_MMA(1, 0, At, B0); PG8_MMA(1, 1, At, B1); PG8_BAR; PG8_SCHED;
;         }
;         if constexpr (ALIGN_EPI) { if (wr == 0) PG8_BAR; }
;         if constexpr (!Epi::AFTER_DRAIN) E(acc, cur, wr, wc, fr, fq);
;         if (!has_next) break;
	s_add_i32 s26, s68, s40
	v_lshl_add_u64 v[220:221], v[220:221], 0, s[8:9]
	s_mov_b32 m0, s26
	ds_read_b128 v[186:189], v149 offset:49152
	ds_read_b128 v[190:193], v149 offset:50176
	ds_read_b128 v[194:197], v149 offset:51200
	ds_read_b128 v[198:201], v149 offset:52224
	ds_read_b128 v[204:207], v149 offset:53248
	ds_read_b128 v[208:211], v149 offset:54272
	ds_read_b128 v[212:215], v149 offset:55296
	ds_read_b128 v[216:219], v149 offset:56320
	global_load_lds_dwordx4 v[220:221], off
	s_add_i32 m0, s26, 0x2000
	s_add_u32 s24, s24, 0x40080
	v_lshl_add_u64 v[220:221], v[222:223], 0, s[8:9]
	s_addc_u32 s25, s25, 0
	s_add_i32 s26, s69, s40
	global_load_lds_dwordx4 v[220:221], off
	v_lshl_add_u64 v[220:221], s[24:25], 0, v[134:135]
	s_mov_b32 m0, s26
	s_nop 0
	global_load_lds_dwordx4 v[220:221], off
	v_lshl_add_u64 v[220:221], s[24:25], 0, v[130:131]
	s_add_i32 m0, s26, 0x2000
	s_nop 0
	global_load_lds_dwordx4 v[220:221], off
	v_lshl_add_u64 v[220:221], v[224:225], 0, s[8:9]
	s_mov_b32 m0, s47
	s_nop 0
	global_load_lds_dwordx4 v[220:221], off
	v_lshl_add_u64 v[220:221], v[226:227], 0, s[8:9]
	s_mov_b32 m0, s60
	s_nop 0
	global_load_lds_dwordx4 v[220:221], off
	s_waitcnt vmcnt(8)
	s_waitcnt lgkmcnt(0)
	s_barrier
	s_setprio 1
	s_waitcnt lgkmcnt(0)
	v_mfma_f32_16x16x32_bf16 v[62:65], v[154:157], v[186:189], v[62:65]
	v_mfma_f32_16x16x32_bf16 v[58:61], v[162:165], v[186:189], v[58:61]
	v_mfma_f32_16x16x32_bf16 v[54:57], v[154:157], v[194:197], v[54:57]
	v_mfma_f32_16x16x32_bf16 v[50:53], v[162:165], v[194:197], v[50:53]
	v_mfma_f32_16x16x32_bf16 v[38:41], v[154:157], v[204:207], v[38:41]
	v_mfma_f32_16x16x32_bf16 v[34:37], v[162:165], v[204:207], v[34:37]
	v_mfma_f32_16x16x32_bf16 v[22:25], v[154:157], v[212:215], v[22:25]
	v_mfma_f32_16x16x32_bf16 v[18:21], v[162:165], v[212:215], v[18:21]
	v_mfma_f32_16x16x32_bf16 v[62:65], v[158:161], v[190:193], v[62:65]
	v_mfma_f32_16x16x32_bf16 v[58:61], v[166:169], v[190:193], v[58:61]
	v_mfma_f32_16x16x32_bf16 v[54:57], v[158:161], v[198:201], v[54:57]
	v_mfma_f32_16x16x32_bf16 v[50:53], v[166:169], v[198:201], v[50:53]
	v_mfma_f32_16x16x32_bf16 v[38:41], v[158:161], v[208:211], v[38:41]
	v_mfma_f32_16x16x32_bf16 v[34:37], v[166:169], v[208:211], v[34:37]
	v_mfma_f32_16x16x32_bf16 v[22:25], v[158:161], v[216:219], v[22:25]
	v_mfma_f32_16x16x32_bf16 v[18:21], v[166:169], v[216:219], v[18:21]
	v_mfma_f32_16x16x32_bf16 v[46:49], v[170:173], v[186:189], v[46:49]
	v_mfma_f32_16x16x32_bf16 v[42:45], v[178:181], v[186:189], v[42:45]
	v_mfma_f32_16x16x32_bf16 v[30:33], v[170:173], v[194:197], v[30:33]
	v_mfma_f32_16x16x32_bf16 v[26:29], v[178:181], v[194:197], v[26:29]
	v_mfma_f32_16x16x32_bf16 v[14:17], v[170:173], v[204:207], v[14:17]
	v_mfma_f32_16x16x32_bf16 v[10:13], v[178:181], v[204:207], v[10:13]
	v_mfma_f32_16x16x32_bf16 v[6:9], v[170:173], v[212:215], v[6:9]
	v_mfma_f32_16x16x32_bf16 v[2:5], v[178:181], v[212:215], v[2:5]
	v_mfma_f32_16x16x32_bf16 v[46:49], v[174:177], v[190:193], v[46:49]
	v_mfma_f32_16x16x32_bf16 v[42:45], v[182:185], v[190:193], v[42:45]
	v_mfma_f32_16x16x32_bf16 v[30:33], v[174:177], v[198:201], v[30:33]
	v_mfma_f32_16x16x32_bf16 v[26:29], v[182:185], v[198:201], v[26:29]
	v_mfma_f32_16x16x32_bf16 v[14:17], v[174:177], v[208:211], v[14:17]
	v_mfma_f32_16x16x32_bf16 v[10:13], v[182:185], v[208:211], v[10:13]
	v_mfma_f32_16x16x32_bf16 v[6:9], v[174:177], v[216:219], v[6:9]
	v_mfma_f32_16x16x32_bf16 v[2:5], v[182:185], v[216:219], v[2:5]
	s_setprio 0
	s_barrier
	s_add_i32 s56, s56, 2
	s_add_u32 s22, s22, 0x100
	s_addc_u32 s23, s23, 0
	s_add_u32 s54, s54, 0x100
	s_addc_u32 s55, s55, 0
	s_cmp_gt_u32 s56, 13
	s_cbranch_scc0 .LBB0_1641
	s_and_b64 vcc, exec, s[10:11]
	s_cbranch_vccz .LBB0_1644
	s_barrier

; #define LBAR() do { asm volatile("s_waitcnt lgkmcnt(0)" ::: "memory"); __builtin_amdgcn_s_barrier(); asm volatile("" ::: "memory"); } while (0)
; #define SCHEDB() __builtin_amdgcn_sched_barrier(0)
; #define MMA8(acc0, acc1, f0, f1, bop) do { _Pragma("unroll") for (int ks_ = 0; ks_ < 4; ++ks_) { acc0 = MFMA32(f0[ks_], bop[ks_], acc0); acc1 = MFMA32(f1[ks_], bop[ks_], acc1); } } while (0)
; #define GDMA(chunk) do { if ((chunk) < 64) { const unsigned char* g_ = src + (size_t)(chunk) * GSLOT + (size_t)(lw * 64 + lane) * 16; LAS unsigned char* d_ = c.lds + ((chunk) % 3) * GSLOT + lw * 1024; \
;         _Pragma("unroll") for (int p = 0; p < 10; ++p) __builtin_amdgcn_global_load_lds((const unsigned*)(g_ + p * 4096), (LAS unsigned*)(d_ + p * 4096), 16, 0, 0); } } while (0)
; DI void gdn_step(const Ctx& c, const int n, const int vt, const LAS unsigned char* lds0, f32x16& S0, f32x16& S1, const float gl, bf16_t* proj, const int b, const int h) {
;     ...
;     for (int r = 0; r < 16; ++r) { S0[r] *= gl; S1[r] *= gl; }
;     SCHEDB();
;     MMA8(S0, S1, fa, fb, vb);
;     MMA8(o[0], o[1], fc, fd, vb);
; DI void gdn_scan(const Ctx& c, int bh, const unsigned char* gbase, const float* GL, bf16_t* proj, const float* normw) {
;     ...
;         for (int n = 0; n < 64; ++n) {
;             if (wid >= 2) { if (n + 2 < 64 && n > 0) asm volatile("s_waitcnt vmcnt(10)" ::: "memory"); else asm volatile("s_waitcnt vmcnt(0)" ::: "memory"); }
;             LBAR();
;             if (wid >= 2) { if (n > 0) GDMA(n + 2); }
;             else gdn_step(c, n, wid, sl_base, S0, S1, glds[n], proj, b, h);
;         }
.LBB0_2182:
	s_add_u32 s64, s64, 0xa000
	s_addc_u32 s65, s65, 0
	s_add_i32 s12, s12, 4
	s_nop 4
	s_nop 0
	s_cmp_eq_u32 s64, 0x280000
	s_mov_b32 s81, s33
	s_cbranch_scc1 .LBB0_2193

; #define LAS __attribute__((address_space(3)))
; DI float bflo(unsigned w) { return __uint_as_float(w << 16); }
; DI float bfhi(unsigned w) { return __uint_as_float(w & 0xffff0000u); }
; #define GLOAD4(dst, mat, mt) do { _Pragma("unroll") for (int ks_ = 0; ks_ < 4; ++ks_) dst[ks_] = GFRAG(mat, mt, ks_); } while (0)
; #define SCHEDB() __builtin_amdgcn_sched_barrier(0)
; #define MMA8(acc0, acc1, f0, f1, bop) do { _Pragma("unroll") for (int ks_ = 0; ks_ < 4; ++ks_) { acc0 = MFMA32(f0[ks_], bop[ks_], acc0); acc1 = MFMA32(f1[ks_], bop[ks_], acc1); } } while (0)
; DI void gdn_step(const Ctx& c, const int n, const int vt, const LAS unsigned char* lds0, f32x16& S0, f32x16& S1, const float gl, bf16_t* proj, const int b, const int h) {
;     const int lane = c.lane, hi = lane >> 5;
;     const LAS unsigned char* sl = lds0 + (n % 3) * GSLOT;
;     bf16x8 sb[4]; sb[0] = pack8(S0, 0); sb[1] = pack8(S0, 1); sb[2] = pack8(S1, 0); sb[3] = pack8(S1, 1);
;     f32x16 vn[2], o[2];
; #pragma unroll
;     for (int ct = 0; ct < 2; ++ct) { const u32x4 u0 = *(const LAS u32x4*)(sl + 4 * 8192 + ((ct * 2 + vt) * 64 + lane) * 32), u1 = *(const LAS u32x4*)(sl + 4 * 8192 + ((ct * 2 + vt) * 64 + lane) * 32 + 16);
;         vn[ct][0] = bflo(u0.x); vn[ct][1] = bfhi(u0.x); vn[ct][2] = bflo(u0.y); vn[ct][3] = bfhi(u0.y); vn[ct][4] = bflo(u0.z); vn[ct][5] = bfhi(u0.z); vn[ct][6] = bflo(u0.w); vn[ct][7] = bfhi(u0.w);
;         vn[ct][8] = bflo(u1.x); vn[ct][9] = bfhi(u1.x); vn[ct][10] = bflo(u1.y); vn[ct][11] = bfhi(u1.y); vn[ct][12] = bflo(u1.z); vn[ct][13] = bfhi(u1.z); vn[ct][14] = bflo(u1.w); vn[ct][15] = bfhi(u1.w);
; #pragma unroll
;         for (int r = 0; r < 16; ++r) o[ct][r] = 0.f; }
;     ...
;     bf16x8 fa[4], fb[4], fc[4], fd[4];
;     GLOAD4(fa, 0, 0); GLOAD4(fb, 0, 1); GLOAD4(fc, 1, 0); GLOAD4(fd, 1, 1); SCHEDB();
;     MMA8(vn[0], vn[1], fa, fb, sb); SCHEDB();
;     GLOAD4(fa, 3, 0); GLOAD4(fb, 3, 1); SCHEDB();
;     MMA8(o[0], o[1], fc, fd, sb); SCHEDB();
;     GLOAD4(fc, 2, 0); GLOAD4(fd, 2, 1); SCHEDB();
;     bf16x8 vb[4]; vb[0] = pack8(vn[0], 0); vb[1] = pack8(vn[0], 1); vb[2] = pack8(vn[1], 0); vb[3] = pack8(vn[1], 1);
; #pragma unroll
;     for (int r = 0; r < 16; ++r) { S0[r] *= gl; S1[r] *= gl; }
.LBB0_2188:
	s_waitcnt lgkmcnt(0)
	s_barrier
	s_add_i32 s33, s81, 1
	s_mov_b64 s[66:67], -1
	s_and_b64 vcc, exec, s[18:19]
	s_cbranch_vccz .LBB0_2190
	s_mul_i32 s66, s33, 0xab
	s_bfe_u32 s66, s66, 0x70009
	s_mul_i32 s66, s66, 3
	s_sub_i32 s66, s33, s66
	s_and_b32 s66, s66, 0xff
	s_mul_i32 s66, s66, 0xa000
	s_addk_i32 s66, 0x100
	v_mov_b32_e32 v3, s12
	s_add_i32 s67, s66, s72
	ds_read_b32 v8, v3
	v_add_u32_e32 v3, s67, v128
	ds_read_b128 v[50:53], v3 offset:32768
	ds_read_b128 v[54:57], v3 offset:32784
	v_cvt_pk_bf16_f32 v4, v18, v19
	v_cvt_pk_bf16_f32 v5, v20, v21
	v_cvt_pk_bf16_f32 v6, v22, v23
	s_waitcnt lgkmcnt(0)
	v_lshlrev_b32_e32 v66, 16, v50
	v_and_b32_e32 v67, 0xffff0000, v50
	v_lshlrev_b32_e32 v68, 16, v51
	v_and_b32_e32 v69, 0xffff0000, v51
	v_lshlrev_b32_e32 v70, 16, v52
	v_and_b32_e32 v71, 0xffff0000, v52
	v_lshlrev_b32_e32 v72, 16, v53
	v_and_b32_e32 v73, 0xffff0000, v53
	v_lshlrev_b32_e32 v74, 16, v54
	v_and_b32_e32 v75, 0xffff0000, v54
	v_lshlrev_b32_e32 v76, 16, v55
	v_and_b32_e32 v77, 0xffff0000, v55
	v_lshlrev_b32_e32 v78, 16, v56
	v_and_b32_e32 v79, 0xffff0000, v56
	v_lshlrev_b32_e32 v80, 16, v57
	v_and_b32_e32 v81, 0xffff0000, v57
	ds_read_b128 v[50:53], v3 offset:36864
	ds_read_b128 v[54:57], v3 offset:36880
	v_add_u32_e32 v3, s66, v129
	v_cvt_pk_bf16_f32 v7, v24, v25
	v_cvt_pk_bf16_f32 v10, v26, v27
	s_waitcnt lgkmcnt(0)
	v_lshlrev_b32_e32 v82, 16, v50
	v_and_b32_e32 v83, 0xffff0000, v50
	v_lshlrev_b32_e32 v84, 16, v51
	v_and_b32_e32 v85, 0xffff0000, v51
	v_lshlrev_b32_e32 v86, 16, v52
	v_and_b32_e32 v87, 0xffff0000, v52
	v_lshlrev_b32_e32 v88, 16, v53
	v_and_b32_e32 v89, 0xffff0000, v53
	v_lshlrev_b32_e32 v90, 16, v54
	v_and_b32_e32 v91, 0xffff0000, v54
	v_lshlrev_b32_e32 v92, 16, v55
	v_and_b32_e32 v93, 0xffff0000, v55
	v_lshlrev_b32_e32 v94, 16, v56
	v_and_b32_e32 v95, 0xffff0000, v56
	v_lshlrev_b32_e32 v96, 16, v57
	v_and_b32_e32 v97, 0xffff0000, v57
	ds_read_b128 v[50:53], v3
	ds_read_b128 v[54:57], v3 offset:1024
	ds_read_b128 v[58:61], v3 offset:2048
	ds_read_b128 v[62:65], v3 offset:3072
	ds_read_b128 v[98:101], v3 offset:4096
	ds_read_b128 v[102:105], v3 offset:5120
	ds_read_b128 v[106:109], v3 offset:6144
	ds_read_b128 v[140:143], v3 offset:7168
	ds_read_b128 v[110:113], v3 offset:8192
	ds_read_b128 v[144:147], v3 offset:9216
	ds_read_b128 v[148:151], v3 offset:10240
	ds_read_b128 v[154:157], v3 offset:11264
	ds_read_b128 v[158:161], v3 offset:12288
	ds_read_b128 v[162:165], v3 offset:13312
	ds_read_b128 v[166:169], v3 offset:14336
	ds_read_b128 v[170:173], v3 offset:15360
	v_cvt_pk_bf16_f32 v11, v28, v29
	v_cvt_pk_bf16_f32 v12, v30, v31
	v_cvt_pk_bf16_f32 v13, v32, v33
	v_cvt_pk_bf16_f32 v14, v34, v35
	v_cvt_pk_bf16_f32 v15, v36, v37
	v_cvt_pk_bf16_f32 v16, v38, v39
	v_cvt_pk_bf16_f32 v17, v40, v41
	v_cvt_pk_bf16_f32 v136, v42, v43
	v_cvt_pk_bf16_f32 v137, v44, v45
	v_cvt_pk_bf16_f32 v138, v46, v47
	v_cvt_pk_bf16_f32 v139, v48, v49
	s_waitcnt lgkmcnt(0)
	v_mfma_f32_32x32x16_bf16 v[66:81], v[50:53], v[4:7], v[66:81]
	ds_read_b128 v[174:177], v3 offset:24576
	ds_read_b128 v[178:181], v3 offset:25600
	ds_read_b128 v[182:185], v3 offset:26624
	ds_read_b128 v[186:189], v3 offset:27648
	ds_read_b128 v[190:193], v3 offset:28672
	ds_read_b128 v[194:197], v3 offset:29696
	ds_read_b128 v[198:201], v3 offset:30720
	ds_read_b128 v[204:207], v3 offset:31744
	v_mfma_f32_32x32x16_bf16 v[66:81], v[54:57], v[10:13], v[66:81]
	v_mfma_f32_32x32x16_bf16 v[82:97], v[98:101], v[4:7], v[82:97]
	v_mfma_f32_32x32x16_bf16 v[66:81], v[58:61], v[14:17], v[66:81]
	v_mfma_f32_32x32x16_bf16 v[82:97], v[102:105], v[10:13], v[82:97]
	v_mfma_f32_32x32x16_bf16 v[66:81], v[62:65], v[136:139], v[66:81]
	v_mfma_f32_32x32x16_bf16 v[82:97], v[106:109], v[14:17], v[82:97]
	v_mfma_f32_32x32x16_bf16 v[98:113], v[110:113], v[4:7], 0
	v_mfma_f32_32x32x16_bf16 v[50:65], v[158:161], v[4:7], 0
	v_mfma_f32_32x32x16_bf16 v[98:113], v[144:147], v[10:13], v[98:113]
	v_mfma_f32_32x32x16_bf16 v[50:65], v[162:165], v[10:13], v[50:65]
	v_mfma_f32_32x32x16_bf16 v[98:113], v[148:151], v[14:17], v[98:113]
	v_mfma_f32_32x32x16_bf16 v[50:65], v[166:169], v[14:17], v[50:65]
	v_mfma_f32_32x32x16_bf16 v[98:113], v[154:157], v[136:139], v[98:113]
	v_mfma_f32_32x32x16_bf16 v[50:65], v[170:173], v[136:139], v[50:65]
	ds_read_b128 v[4:7], v3 offset:16384
	ds_read_b128 v[10:13], v3 offset:17408
	ds_read_b128 v[14:17], v3 offset:18432
	ds_read_b128 v[144:147], v3 offset:19456
	ds_read_b128 v[148:151], v3 offset:20480
	ds_read_b128 v[154:157], v3 offset:21504
	ds_read_b128 v[158:161], v3 offset:22528
	ds_read_b128 v[162:165], v3 offset:23552
	v_mfma_f32_32x32x16_bf16 v[82:97], v[140:143], v[136:139], v[82:97]
	v_cvt_pk_bf16_f32 v136, v66, v67
	v_cvt_pk_bf16_f32 v137, v68, v69
	v_cvt_pk_bf16_f32 v138, v70, v71
	v_cvt_pk_bf16_f32 v139, v72, v73
	v_cvt_pk_bf16_f32 v140, v74, v75
	v_cvt_pk_bf16_f32 v141, v76, v77
	v_cvt_pk_bf16_f32 v142, v78, v79
	v_cvt_pk_bf16_f32 v143, v80, v81
	s_nop 3
	v_cvt_pk_bf16_f32 v166, v82, v83
	v_cvt_pk_bf16_f32 v167, v84, v85
	v_cvt_pk_bf16_f32 v168, v86, v87
	v_cvt_pk_bf16_f32 v169, v88, v89
	v_cvt_pk_bf16_f32 v170, v90, v91
	v_cvt_pk_bf16_f32 v171, v92, v93
	v_cvt_pk_bf16_f32 v172, v94, v95
	v_cvt_pk_bf16_f32 v173, v96, v97
	v_pk_mul_f32 v[32:33], v[32:33], v[8:9] op_sel_hi:[1,0]
	v_pk_mul_f32 v[30:31], v[30:31], v[8:9] op_sel_hi:[1,0]
	v_pk_mul_f32 v[28:29], v[28:29], v[8:9] op_sel_hi:[1,0]
	v_pk_mul_f32 v[26:27], v[26:27], v[8:9] op_sel_hi:[1,0]
	v_pk_mul_f32 v[24:25], v[24:25], v[8:9] op_sel_hi:[1,0]
	v_pk_mul_f32 v[22:23], v[22:23], v[8:9] op_sel_hi:[1,0]
	v_pk_mul_f32 v[20:21], v[20:21], v[8:9] op_sel_hi:[1,0]
	v_pk_mul_f32 v[18:19], v[18:19], v[8:9] op_sel_hi:[1,0]
	v_pk_mul_f32 v[48:49], v[48:49], v[8:9] op_sel_hi:[1,0]
	v_pk_mul_f32 v[46:47], v[46:47], v[8:9] op_sel_hi:[1,0]
	v_pk_mul_f32 v[44:45], v[44:45], v[8:9] op_sel_hi:[1,0]
	v_pk_mul_f32 v[42:43], v[42:43], v[8:9] op_sel_hi:[1,0]
	v_pk_mul_f32 v[40:41], v[40:41], v[8:9] op_sel_hi:[1,0]
	v_pk_mul_f32 v[38:39], v[38:39], v[8:9] op_sel_hi:[1,0]
	v_pk_mul_f32 v[36:37], v[36:37], v[8:9] op_sel_hi:[1,0]
	v_pk_mul_f32 v[34:35], v[34:35], v[8:9] op_sel_hi:[1,0]
	s_waitcnt lgkmcnt(0)
; #define LAS __attribute__((address_space(3)))
; DI bf16_t f2bf(float f) { return (bf16_t)(pk2(f, 0.f) & 0xffffu); }
; DI int crow(int r, int hi) { return (r & 3) + 8 * (r >> 2) + 4 * hi; }
; #define MMA8(acc0, acc1, f0, f1, bop) do { _Pragma("unroll") for (int ks_ = 0; ks_ < 4; ++ks_) { acc0 = MFMA32(f0[ks_], bop[ks_], acc0); acc1 = MFMA32(f1[ks_], bop[ks_], acc1); } } while (0)
; DI void gdn_step(const Ctx& c, const int n, const int vt, const LAS unsigned char* lds0, f32x16& S0, f32x16& S1, const float gl, bf16_t* proj, const int b, const int h) {
;     ...
;     MMA8(S0, S1, fa, fb, vb);
;     MMA8(o[0], o[1], fc, fd, vb);
;     ...
;     LAS bf16_t* ot = (LAS bf16_t*)(lds0 + OT_OFF + (n & 1) * 9216) + crow(0, hi) * 72 + 32 * vt + (lane & 31);
; #pragma unroll
;     for (int ct = 0; ct < 2; ++ct)
; #pragma unroll
;         for (int r = 0; r < 16; ++r) ot[(32 * ct + (r & 3) + 8 * (r >> 2)) * 72] = f2bf(o[ct][r]);
	v_mfma_f32_32x32x16_bf16 v[98:113], v[4:7], v[136:139], v[98:113]
	s_bitcmp1_b32 s33, 0
	s_cselect_b32 s66, 0x2400, 0
	v_add_u32_e32 v3, s66, v130
	s_mov_b64 s[66:67], 0
	v_mfma_f32_32x32x16_bf16 v[98:113], v[10:13], v[140:143], v[98:113]
	v_mfma_f32_32x32x16_bf16 v[98:113], v[14:17], v[166:169], v[98:113]
	v_mfma_f32_32x32x16_bf16 v[50:65], v[148:151], v[136:139], v[50:65]
	v_mfma_f32_32x32x16_bf16 v[98:113], v[144:147], v[170:173], v[98:113]
	v_mfma_f32_32x32x16_bf16 v[50:65], v[154:157], v[140:143], v[50:65]
	s_nop 10
	v_cvt_pk_bf16_f32 v4, v98, s0
	ds_write_b16 v3, v4
	v_cvt_pk_bf16_f32 v4, v99, s0
	ds_write_b16 v3, v4 offset:144
	v_cvt_pk_bf16_f32 v4, v100, s0
	ds_write_b16 v3, v4 offset:288
	v_cvt_pk_bf16_f32 v4, v101, s0
	v_mfma_f32_32x32x16_bf16 v[50:65], v[158:161], v[166:169], v[50:65]
	ds_write_b16 v3, v4 offset:432
	v_cvt_pk_bf16_f32 v4, v102, s0
	ds_write_b16 v3, v4 offset:1152
	v_cvt_pk_bf16_f32 v4, v103, s0
	ds_write_b16 v3, v4 offset:1296
	v_cvt_pk_bf16_f32 v4, v104, s0
	ds_write_b16 v3, v4 offset:1440
	v_cvt_pk_bf16_f32 v4, v105, s0
	v_mfma_f32_32x32x16_bf16 v[18:33], v[174:177], v[136:139], v[18:33]
	ds_write_b16 v3, v4 offset:1584
	v_cvt_pk_bf16_f32 v4, v106, s0
	ds_write_b16 v3, v4 offset:2304
	v_cvt_pk_bf16_f32 v4, v107, s0
	ds_write_b16 v3, v4 offset:2448
	v_cvt_pk_bf16_f32 v4, v108, s0
	ds_write_b16 v3, v4 offset:2592
	v_mfma_f32_32x32x16_bf16 v[34:49], v[190:193], v[136:139], v[34:49]
	v_cvt_pk_bf16_f32 v4, v109, s0
	ds_write_b16 v3, v4 offset:2736
	v_cvt_pk_bf16_f32 v4, v110, s0
	ds_write_b16 v3, v4 offset:3456
	v_cvt_pk_bf16_f32 v4, v111, s0
	ds_write_b16 v3, v4 offset:3600
	v_cvt_pk_bf16_f32 v4, v112, s0
	v_mfma_f32_32x32x16_bf16 v[50:65], v[162:165], v[170:173], v[50:65]
	ds_write_b16 v3, v4 offset:3744
	v_cvt_pk_bf16_f32 v4, v113, s0
	ds_write_b16 v3, v4 offset:3888
	v_mfma_f32_32x32x16_bf16 v[18:33], v[178:181], v[140:143], v[18:33]
	s_nop 7
	v_cvt_pk_bf16_f32 v4, v50, s0
	ds_write_b16 v3, v4 offset:4608
	v_cvt_pk_bf16_f32 v4, v51, s0
	ds_write_b16 v3, v4 offset:4752
	v_cvt_pk_bf16_f32 v4, v52, s0
	ds_write_b16 v3, v4 offset:4896
	v_cvt_pk_bf16_f32 v4, v53, s0
	v_mfma_f32_32x32x16_bf16 v[34:49], v[194:197], v[140:143], v[34:49]
	ds_write_b16 v3, v4 offset:5040
	v_cvt_pk_bf16_f32 v4, v54, s0
	ds_write_b16 v3, v4 offset:5760
	v_cvt_pk_bf16_f32 v4, v55, s0
	ds_write_b16 v3, v4 offset:5904
	v_cvt_pk_bf16_f32 v4, v56, s0
	ds_write_b16 v3, v4 offset:6048
	v_cvt_pk_bf16_f32 v4, v57, s0
	v_mfma_f32_32x32x16_bf16 v[18:33], v[182:185], v[166:169], v[18:33]
	ds_write_b16 v3, v4 offset:6192
	v_cvt_pk_bf16_f32 v4, v58, s0
	ds_write_b16 v3, v4 offset:6912
	v_cvt_pk_bf16_f32 v4, v59, s0
	ds_write_b16 v3, v4 offset:7056
	v_cvt_pk_bf16_f32 v4, v60, s0
	ds_write_b16 v3, v4 offset:7200
	v_mfma_f32_32x32x16_bf16 v[34:49], v[198:201], v[166:169], v[34:49]
	v_cvt_pk_bf16_f32 v4, v61, s0
	ds_write_b16 v3, v4 offset:7344
	v_cvt_pk_bf16_f32 v4, v62, s0
	ds_write_b16 v3, v4 offset:8064
	v_cvt_pk_bf16_f32 v4, v63, s0
	ds_write_b16 v3, v4 offset:8208
	v_cvt_pk_bf16_f32 v4, v64, s0
	ds_write_b16 v3, v4 offset:8352
	v_cvt_pk_bf16_f32 v4, v65, s0
	v_mfma_f32_32x32x16_bf16 v[18:33], v[186:189], v[170:173], v[18:33]
	ds_write_b16 v3, v4 offset:8496
	v_mfma_f32_32x32x16_bf16 v[34:49], v[204:207], v[170:173], v[34:49]

; #define LBAR() do { asm volatile("s_waitcnt lgkmcnt(0)" ::: "memory"); __builtin_amdgcn_s_barrier(); asm volatile("" ::: "memory"); } while (0)
; #define GZLOAD(ZR, chunk) do { const bf16_t* zp_ = proj + (size_t)(b * SEQ + (chunk) * 64 + lane) * NINP + C_GZ + h * 64 + 32 * hc; \
;         _Pragma("unroll") for (int k = 0; k < 4; ++k) ZR[k] = *(const u32x4*)(zp_ + 8 * k); } while (0)
; DI void gdn_scan(const Ctx& c, int bh, const unsigned char* gbase, const float* GL, bf16_t* proj, const float* normw) {
;     ...
;     if (wid >= 6) {
;         const int hc = wid - 6;
;         u32x4 zA[4], zB[4];
;         GZLOAD(zA, 0);
;         for (int n = 0; n < 64; n += 2) {
;             LBAR(); if (n > 0) GHELP(n - 1, zB); GZLOAD(zB, n + 1);
;             LBAR(); GHELP(n, zA); { const int nx = n + 2 < 64 ? n + 2 : 63; GZLOAD(zA, nx); }
.LBB0_2196:
	v_mov_b64_e32 v[18:19], s[8:9]
	v_mad_i64_i32 v[32:33], s[82:83], v16, s79, v[18:19]
	global_load_dwordx4 v[16:19], v[32:33], off offset:3120
	global_load_dwordx4 v[24:27], v[32:33], off offset:3104
	global_load_dwordx4 v[28:31], v[32:33], off offset:3088
	s_nop 0
	global_load_dwordx4 v[32:35], v[32:33], off offset:3072
	s_waitcnt lgkmcnt(0)
	s_barrier
	s_cmp_eq_u32 s65, 0
	s_mov_b32 s33, 0
	s_cbranch_scc1 .Lnwl_init_1
	v_add_u32_e32 v40, 0x20600, v135
	ds_read_b128 v[66:69], v40
	ds_read_b128 v[52:55], v40 offset:16
	ds_read_b128 v[44:47], v40 offset:32
	ds_read_b128 v[36:39], v40 offset:48
	ds_read_b128 v[70:73], v40 offset:64
	ds_read_b128 v[56:59], v40 offset:80
	ds_read_b128 v[48:51], v40 offset:96
	ds_read_b128 v[40:43], v40 offset:112
	s_waitcnt lgkmcnt(0)
	v_and_b32_e32 v75, 0xffff0000, v52
	v_and_b32_e32 v74, 0xffff0000, v66
	v_lshlrev_b32_e32 v61, 16, v52
	v_lshlrev_b32_e32 v60, 16, v66
	v_pk_mul_f32 v[74:75], v[74:75], v[74:75]
	v_and_b32_e32 v77, 0xffff0000, v36
	v_pk_fma_f32 v[60:61], v[60:61], v[60:61], v[74:75]
	v_lshlrev_b32_e32 v75, 16, v53
	v_lshlrev_b32_e32 v74, 16, v67
	v_pk_fma_f32 v[60:61], v[74:75], v[74:75], v[60:61]
	v_and_b32_e32 v75, 0xffff0000, v53
	v_and_b32_e32 v74, 0xffff0000, v67
	v_pk_fma_f32 v[60:61], v[74:75], v[74:75], v[60:61]
	v_lshlrev_b32_e32 v75, 16, v54
	v_lshlrev_b32_e32 v74, 16, v68
	v_pk_fma_f32 v[60:61], v[74:75], v[74:75], v[60:61]
	v_and_b32_e32 v75, 0xffff0000, v54
	v_and_b32_e32 v74, 0xffff0000, v68
	v_pk_fma_f32 v[60:61], v[74:75], v[74:75], v[60:61]
	v_lshlrev_b32_e32 v75, 16, v55
	v_lshlrev_b32_e32 v74, 16, v69
	v_pk_fma_f32 v[60:61], v[74:75], v[74:75], v[60:61]
	v_and_b32_e32 v75, 0xffff0000, v55
	v_and_b32_e32 v74, 0xffff0000, v69
	v_and_b32_e32 v76, 0xffff0000, v44
	v_pk_fma_f32 v[60:61], v[74:75], v[74:75], v[60:61]
	v_lshlrev_b32_e32 v75, 16, v36
	v_lshlrev_b32_e32 v74, 16, v44
	v_pk_mul_f32 v[76:77], v[76:77], v[76:77]
	v_and_b32_e32 v79, 0xffff0000, v56
	v_pk_fma_f32 v[74:75], v[74:75], v[74:75], v[76:77]
	v_lshlrev_b32_e32 v77, 16, v37
	v_lshlrev_b32_e32 v76, 16, v45
	v_pk_fma_f32 v[74:75], v[76:77], v[76:77], v[74:75]
	v_and_b32_e32 v77, 0xffff0000, v37
	v_and_b32_e32 v76, 0xffff0000, v45
	v_pk_fma_f32 v[74:75], v[76:77], v[76:77], v[74:75]
	v_lshlrev_b32_e32 v77, 16, v38
	v_lshlrev_b32_e32 v76, 16, v46
	v_pk_fma_f32 v[74:75], v[76:77], v[76:77], v[74:75]
	v_and_b32_e32 v77, 0xffff0000, v38
	v_and_b32_e32 v76, 0xffff0000, v46
	v_pk_fma_f32 v[74:75], v[76:77], v[76:77], v[74:75]
	v_lshlrev_b32_e32 v77, 16, v39
	v_lshlrev_b32_e32 v76, 16, v47
	v_pk_fma_f32 v[74:75], v[76:77], v[76:77], v[74:75]
	v_and_b32_e32 v77, 0xffff0000, v39
	v_and_b32_e32 v76, 0xffff0000, v47
	v_and_b32_e32 v78, 0xffff0000, v70
	v_pk_fma_f32 v[74:75], v[76:77], v[76:77], v[74:75]
	v_lshlrev_b32_e32 v77, 16, v56
	v_lshlrev_b32_e32 v76, 16, v70
	v_pk_mul_f32 v[78:79], v[78:79], v[78:79]
	v_and_b32_e32 v81, 0xffff0000, v40
	v_pk_fma_f32 v[76:77], v[76:77], v[76:77], v[78:79]
	v_lshlrev_b32_e32 v79, 16, v57
	v_lshlrev_b32_e32 v78, 16, v71
	v_pk_fma_f32 v[76:77], v[78:79], v[78:79], v[76:77]
	v_and_b32_e32 v79, 0xffff0000, v57
	v_and_b32_e32 v78, 0xffff0000, v71
	v_pk_fma_f32 v[76:77], v[78:79], v[78:79], v[76:77]
	v_lshlrev_b32_e32 v79, 16, v58
	v_lshlrev_b32_e32 v78, 16, v72
	v_pk_fma_f32 v[76:77], v[78:79], v[78:79], v[76:77]
	v_and_b32_e32 v79, 0xffff0000, v58
	v_and_b32_e32 v78, 0xffff0000, v72
	v_pk_fma_f32 v[76:77], v[78:79], v[78:79], v[76:77]
	v_lshlrev_b32_e32 v79, 16, v59
	v_lshlrev_b32_e32 v78, 16, v73
	v_pk_fma_f32 v[76:77], v[78:79], v[78:79], v[76:77]
	v_and_b32_e32 v79, 0xffff0000, v59
	v_and_b32_e32 v78, 0xffff0000, v73
	v_and_b32_e32 v80, 0xffff0000, v48
	v_pk_fma_f32 v[76:77], v[78:79], v[78:79], v[76:77]
	v_lshlrev_b32_e32 v79, 16, v40
	v_lshlrev_b32_e32 v78, 16, v48
	v_pk_mul_f32 v[80:81], v[80:81], v[80:81]
	v_add_f32_e32 v60, v60, v61
	v_pk_fma_f32 v[78:79], v[78:79], v[78:79], v[80:81]
	v_lshlrev_b32_e32 v81, 16, v41
	v_lshlrev_b32_e32 v80, 16, v49
	v_pk_fma_f32 v[78:79], v[80:81], v[80:81], v[78:79]
	v_and_b32_e32 v81, 0xffff0000, v41
	v_and_b32_e32 v80, 0xffff0000, v49
	v_pk_fma_f32 v[78:79], v[80:81], v[80:81], v[78:79]
	v_lshlrev_b32_e32 v81, 16, v42
	v_lshlrev_b32_e32 v80, 16, v50
	v_pk_fma_f32 v[78:79], v[80:81], v[80:81], v[78:79]
	v_and_b32_e32 v81, 0xffff0000, v42
	v_and_b32_e32 v80, 0xffff0000, v50
	v_add_f32_e32 v60, v60, v74
	v_pk_fma_f32 v[78:79], v[80:81], v[80:81], v[78:79]
	v_lshlrev_b32_e32 v81, 16, v43
	v_lshlrev_b32_e32 v80, 16, v51
	v_add_f32_e32 v60, v60, v75
	v_pk_fma_f32 v[78:79], v[80:81], v[80:81], v[78:79]
	v_and_b32_e32 v81, 0xffff0000, v43
	v_and_b32_e32 v80, 0xffff0000, v51
	v_add_f32_e32 v60, v60, v76
	v_pk_fma_f32 v[78:79], v[80:81], v[80:81], v[78:79]
	v_add_f32_e32 v60, v60, v77
	v_add_f32_e32 v60, v60, v78
	v_add_f32_e32 v60, v60, v79
	v_fmamk_f32 v60, v60, 0x3c800000, v134
	v_rsq_f32_e32 v62, v60
	v_add_u32_e32 v65, s65, v3
	v_mov_b64_e32 v[60:61], s[8:9]
	v_cndmask_b32_e64 v72, v72, v68, s[6:7]
	s_waitcnt vmcnt(8)
	v_lshlrev_b32_e32 v68, 16, v20
	v_mad_i64_i32 v[60:61], s[82:83], v65, s79, v[60:61]
	v_cndmask_b32_e64 v65, v73, v69, s[6:7]
	v_and_b32_e32 v69, 0xffff0000, v20
	v_mul_f32_e32 v20, 0xbfb8aa3b, v68
	v_cndmask_b32_e64 v73, v71, v67, s[6:7]
	v_exp_f32_e32 v20, v20
	v_mul_f32_e32 v67, 0xbfb8aa3b, v69
	v_exp_f32_e32 v67, v67
	v_mov_b32_e32 v90, s75
	v_add_f32_e32 v20, 1.0, v20
	v_cndmask_b32_e64 v71, v70, v66, s[6:7]
	v_rcp_f32_e32 v66, v20
	v_add_f32_e32 v20, 1.0, v67
	v_rcp_f32_e32 v67, v20
	v_lshlrev_b32_e32 v70, 16, v71
	v_and_b32_e32 v71, 0xffff0000, v71
	v_pk_mul_f32 v[66:67], v[66:67], v[68:69]
	v_lshlrev_b32_e32 v68, 16, v21
	s_waitcnt lgkmcnt(0)
	v_pk_mul_f32 v[74:75], v[208:209], v[62:63] op_sel_hi:[1,0]
	v_and_b32_e32 v69, 0xffff0000, v21
	v_mul_f32_e32 v20, 0xbfb8aa3b, v68
	v_pk_mul_f32 v[70:71], v[74:75], v[70:71]
	v_exp_f32_e32 v21, v20
	v_mul_f32_e32 v20, 0xbfb8aa3b, v69
	v_pk_mul_f32 v[66:67], v[66:67], v[70:71]
	v_exp_f32_e32 v70, v20
	v_add_f32_e32 v21, 1.0, v21
	v_cvt_pk_bf16_f32 v20, v66, v67
	v_rcp_f32_e32 v66, v21
	v_add_f32_e32 v21, 1.0, v70
	v_rcp_f32_e32 v67, v21
	v_pk_mul_f32 v[76:77], v[210:211], v[62:63] op_sel_hi:[1,0]
	v_lshlrev_b32_e32 v70, 16, v73
	v_and_b32_e32 v71, 0xffff0000, v73
	v_pk_mul_f32 v[66:67], v[66:67], v[68:69]
	v_lshlrev_b32_e32 v68, 16, v22
	v_and_b32_e32 v69, 0xffff0000, v22
	v_mul_f32_e32 v21, 0xbfb8aa3b, v68
	v_pk_mul_f32 v[70:71], v[76:77], v[70:71]
	v_exp_f32_e32 v22, v21
	v_mul_f32_e32 v21, 0xbfb8aa3b, v69
	v_pk_mul_f32 v[66:67], v[66:67], v[70:71]
	v_exp_f32_e32 v70, v21
	v_add_f32_e32 v22, 1.0, v22
	v_cvt_pk_bf16_f32 v21, v66, v67
	v_rcp_f32_e32 v66, v22
	v_add_f32_e32 v22, 1.0, v70
	v_rcp_f32_e32 v67, v22
	v_pk_mul_f32 v[78:79], v[212:213], v[62:63] op_sel_hi:[1,0]
	v_lshlrev_b32_e32 v70, 16, v72
	v_and_b32_e32 v71, 0xffff0000, v72
	v_pk_mul_f32 v[66:67], v[66:67], v[68:69]
	v_lshlrev_b32_e32 v68, 16, v23
	v_and_b32_e32 v69, 0xffff0000, v23
	v_mul_f32_e32 v22, 0xbfb8aa3b, v68
	v_pk_mul_f32 v[70:71], v[78:79], v[70:71]
	v_exp_f32_e32 v23, v22
	v_mul_f32_e32 v22, 0xbfb8aa3b, v69
	v_pk_mul_f32 v[66:67], v[66:67], v[70:71]
	v_exp_f32_e32 v70, v22
	v_cndmask_b32_e64 v58, v58, v54, s[6:7]
	v_lshlrev_b32_e32 v54, 16, v12
	v_add_f32_e32 v23, 1.0, v23
	v_cndmask_b32_e64 v59, v59, v55, s[6:7]
	v_and_b32_e32 v55, 0xffff0000, v12
	v_mul_f32_e32 v12, 0xbfb8aa3b, v54
	v_cvt_pk_bf16_f32 v22, v66, v67
	v_rcp_f32_e32 v66, v23
	v_add_f32_e32 v23, 1.0, v70
	v_lshlrev_b32_e32 v70, 16, v65
	v_and_b32_e32 v71, 0xffff0000, v65
	v_cndmask_b32_e64 v65, v57, v53, s[6:7]
	v_exp_f32_e32 v12, v12
	v_mul_f32_e32 v53, 0xbfb8aa3b, v55
	v_exp_f32_e32 v53, v53
	v_rcp_f32_e32 v67, v23
	v_add_f32_e32 v12, 1.0, v12
	v_pk_mul_f32 v[80:81], v[214:215], v[62:63] op_sel_hi:[1,0]
	v_cndmask_b32_e64 v57, v56, v52, s[6:7]
	v_rcp_f32_e32 v52, v12
	v_add_f32_e32 v12, 1.0, v53
	v_pk_mul_f32 v[70:71], v[80:81], v[70:71]
	v_pk_mul_f32 v[66:67], v[66:67], v[68:69]
	v_rcp_f32_e32 v53, v12
	v_pk_mul_f32 v[66:67], v[66:67], v[70:71]
	v_lshlrev_b32_e32 v56, 16, v57
	v_cvt_pk_bf16_f32 v23, v66, v67
	global_store_dwordx4 v[60:61], v[20:23], off
	v_and_b32_e32 v57, 0xffff0000, v57
	v_pk_mul_f32 v[52:53], v[52:53], v[54:55]
	v_pk_mul_f32 v[22:23], v[216:217], v[62:63] op_sel_hi:[1,0]
	v_pk_mul_f32 v[20:21], v[218:219], v[62:63] op_sel_hi:[1,0]
	v_pk_mul_f32 v[22:23], v[22:23], v[56:57]
	v_and_b32_e32 v55, 0xffff0000, v65
	v_pk_mul_f32 v[22:23], v[52:53], v[22:23]
	v_lshlrev_b32_e32 v52, 16, v13
	v_and_b32_e32 v53, 0xffff0000, v13
	v_mul_f32_e32 v12, 0xbfb8aa3b, v52
	v_exp_f32_e32 v13, v12
	v_mul_f32_e32 v12, 0xbfb8aa3b, v53
	v_exp_f32_e32 v54, v12
	v_cvt_pk_bf16_f32 v12, v22, v23
	v_add_f32_e32 v13, 1.0, v13
	v_rcp_f32_e32 v22, v13
	v_add_f32_e32 v13, 1.0, v54
	v_rcp_f32_e32 v23, v13
	v_lshlrev_b32_e32 v54, 16, v65
	v_pk_mul_f32 v[20:21], v[20:21], v[54:55]
	v_pk_mul_f32 v[68:69], v[220:221], v[62:63] op_sel_hi:[1,0]
	v_pk_mul_f32 v[22:23], v[22:23], v[52:53]
	v_and_b32_e32 v53, 0xffff0000, v58
	v_pk_mul_f32 v[20:21], v[22:23], v[20:21]
	v_lshlrev_b32_e32 v22, 16, v14
	v_and_b32_e32 v23, 0xffff0000, v14
	v_mul_f32_e32 v13, 0xbfb8aa3b, v22
	v_exp_f32_e32 v14, v13
	v_mul_f32_e32 v13, 0xbfb8aa3b, v23
	v_exp_f32_e32 v52, v13
	v_cvt_pk_bf16_f32 v13, v20, v21
	v_add_f32_e32 v14, 1.0, v14
	v_rcp_f32_e32 v20, v14
	v_add_f32_e32 v14, 1.0, v52
	v_rcp_f32_e32 v21, v14
	v_lshlrev_b32_e32 v52, 16, v58
	v_pk_mul_f32 v[52:53], v[68:69], v[52:53]
	v_pk_mul_f32 v[66:67], v[222:223], v[62:63] op_sel_hi:[1,0]
	v_pk_mul_f32 v[20:21], v[20:21], v[22:23]
	v_lshlrev_b32_e32 v22, 16, v15
	v_and_b32_e32 v23, 0xffff0000, v15
	v_mul_f32_e32 v14, 0xbfb8aa3b, v22
	v_exp_f32_e32 v15, v14
	v_mul_f32_e32 v14, 0xbfb8aa3b, v23
	v_pk_mul_f32 v[20:21], v[20:21], v[52:53]
	v_exp_f32_e32 v52, v14
	v_add_f32_e32 v15, 1.0, v15
	v_cvt_pk_bf16_f32 v14, v20, v21
	v_rcp_f32_e32 v20, v15
	v_add_f32_e32 v15, 1.0, v52
	v_rcp_f32_e32 v21, v15
	v_lshlrev_b32_e32 v52, 16, v59
	v_and_b32_e32 v53, 0xffff0000, v59
	v_pk_mul_f32 v[52:53], v[66:67], v[52:53]
	v_pk_mul_f32 v[54:55], v[20:21], v[22:23]
	v_pk_mul_f32 v[56:57], v[54:55], v[52:53]
	v_cndmask_b32_e64 v50, v50, v46, s[6:7]
	v_lshlrev_b32_e32 v46, 16, v8
	v_cvt_pk_bf16_f32 v15, v56, v57
	v_cndmask_b32_e64 v51, v51, v47, s[6:7]
	v_and_b32_e32 v47, 0xffff0000, v8
	v_mul_f32_e32 v8, 0xbfb8aa3b, v46
	global_store_dwordx4 v[60:61], v[12:15], off offset:16
	v_exp_f32_e32 v8, v8
	v_cndmask_b32_e64 v41, v41, v37, s[6:7]
	s_waitcnt lgkmcnt(0)
; #define LBAR() do { asm volatile("s_waitcnt lgkmcnt(0)" ::: "memory"); __builtin_amdgcn_s_barrier(); asm volatile("" ::: "memory"); } while (0)
; #define GZLOAD(ZR, chunk) do { const bf16_t* zp_ = proj + (size_t)(b * SEQ + (chunk) * 64 + lane) * NINP + C_GZ + h * 64 + 32 * hc; \
;         _Pragma("unroll") for (int k = 0; k < 4; ++k) ZR[k] = *(const u32x4*)(zp_ + 8 * k); } while (0)
; DI void gdn_scan(const Ctx& c, int bh, const unsigned char* gbase, const float* GL, bf16_t* proj, const float* normw) {
;     ...
;             LBAR(); GHELP(n, zA); { const int nx = n + 2 < 64 ? n + 2 : 63; GZLOAD(zA, nx); }
	v_pk_mul_f32 v[12:13], v[226:227], v[62:63] op_sel_hi:[1,0]
	v_pk_mul_f32 v[22:23], v[228:229], v[62:63] op_sel_hi:[1,0]
	v_cndmask_b32_e64 v52, v49, v45, s[6:7]
	v_mul_f32_e32 v45, 0xbfb8aa3b, v47
	v_exp_f32_e32 v45, v45
	v_add_f32_e32 v8, 1.0, v8
	v_cndmask_b32_e64 v49, v48, v44, s[6:7]
	v_rcp_f32_e32 v44, v8
	v_add_f32_e32 v8, 1.0, v45
	v_rcp_f32_e32 v45, v8
	v_pk_mul_f32 v[14:15], v[224:225], v[62:63] op_sel_hi:[1,0]
	v_lshlrev_b32_e32 v48, 16, v49
	v_and_b32_e32 v49, 0xffff0000, v49
	v_pk_mul_f32 v[14:15], v[14:15], v[48:49]
	v_pk_mul_f32 v[44:45], v[44:45], v[46:47]
	v_and_b32_e32 v47, 0xffff0000, v52
	v_pk_mul_f32 v[14:15], v[44:45], v[14:15]
	v_lshlrev_b32_e32 v44, 16, v9
	v_and_b32_e32 v45, 0xffff0000, v9
	v_mul_f32_e32 v8, 0xbfb8aa3b, v44
	v_exp_f32_e32 v9, v8
	v_mul_f32_e32 v8, 0xbfb8aa3b, v45
	v_exp_f32_e32 v46, v8
	v_cvt_pk_bf16_f32 v8, v14, v15
	v_add_f32_e32 v9, 1.0, v9
	v_rcp_f32_e32 v14, v9
	v_add_f32_e32 v9, 1.0, v46
	v_rcp_f32_e32 v15, v9
	v_lshlrev_b32_e32 v46, 16, v52
	v_pk_mul_f32 v[12:13], v[12:13], v[46:47]
	v_pk_mul_f32 v[20:21], v[230:231], v[62:63] op_sel_hi:[1,0]
	v_pk_mul_f32 v[14:15], v[14:15], v[44:45]
	v_and_b32_e32 v45, 0xffff0000, v50
	v_pk_mul_f32 v[12:13], v[14:15], v[12:13]
	v_lshlrev_b32_e32 v14, 16, v10
	v_and_b32_e32 v15, 0xffff0000, v10
	v_mul_f32_e32 v9, 0xbfb8aa3b, v14
	v_exp_f32_e32 v10, v9
	v_mul_f32_e32 v9, 0xbfb8aa3b, v15
	v_exp_f32_e32 v44, v9
	v_cvt_pk_bf16_f32 v9, v12, v13
	v_add_f32_e32 v10, 1.0, v10
	v_rcp_f32_e32 v12, v10
	v_add_f32_e32 v10, 1.0, v44
	v_rcp_f32_e32 v13, v10
	v_lshlrev_b32_e32 v44, 16, v50
	v_pk_mul_f32 v[22:23], v[22:23], v[44:45]
	v_cndmask_b32_e64 v37, v40, v36, s[6:7]
	v_pk_mul_f32 v[12:13], v[12:13], v[14:15]
	v_lshlrev_b32_e32 v14, 16, v11
	v_and_b32_e32 v15, 0xffff0000, v11
	v_mul_f32_e32 v10, 0xbfb8aa3b, v14
	v_exp_f32_e32 v11, v10
	v_mul_f32_e32 v10, 0xbfb8aa3b, v15
	v_pk_mul_f32 v[12:13], v[12:13], v[22:23]
	v_exp_f32_e32 v22, v10
	v_add_f32_e32 v11, 1.0, v11
	v_cvt_pk_bf16_f32 v10, v12, v13
	v_rcp_f32_e32 v12, v11
	v_add_f32_e32 v11, 1.0, v22
	v_rcp_f32_e32 v13, v11
	v_lshlrev_b32_e32 v22, 16, v51
	v_and_b32_e32 v23, 0xffff0000, v51
	v_pk_mul_f32 v[20:21], v[20:21], v[22:23]
	v_pk_mul_f32 v[22:23], v[12:13], v[14:15]
	v_pk_mul_f32 v[44:45], v[22:23], v[20:21]
	v_cvt_pk_bf16_f32 v11, v44, v45
	global_store_dwordx4 v[60:61], v[8:11], off offset:32
	v_lshlrev_b32_e32 v36, 16, v37
	v_and_b32_e32 v37, 0xffff0000, v37
	s_waitcnt lgkmcnt(0)
	v_pk_mul_f32 v[8:9], v[234:235], v[62:63] op_sel_hi:[1,0]
	v_pk_mul_f32 v[14:15], v[236:237], v[62:63] op_sel_hi:[1,0]
	v_lshlrev_b32_e32 v20, 16, v4
	v_and_b32_e32 v21, 0xffff0000, v4
	v_mul_f32_e32 v4, 0xbfb8aa3b, v20
	v_pk_mul_f32 v[10:11], v[232:233], v[62:63] op_sel_hi:[1,0]
	v_pk_mul_f32 v[12:13], v[238:239], v[62:63] op_sel_hi:[1,0]
	v_exp_f32_e32 v4, v4
	v_mul_f32_e32 v22, 0xbfb8aa3b, v21
	v_exp_f32_e32 v23, v22
	v_pk_mul_f32 v[10:11], v[10:11], v[36:37]
	v_add_f32_e32 v4, 1.0, v4
	v_rcp_f32_e32 v22, v4
	v_add_f32_e32 v4, 1.0, v23
	v_rcp_f32_e32 v23, v4
	v_cndmask_b32_e64 v38, v42, v38, s[6:7]
	v_cndmask_b32_e64 v39, v43, v39, s[6:7]
	s_mov_b32 s33, s65
	v_pk_mul_f32 v[20:21], v[22:23], v[20:21]
	v_and_b32_e32 v23, 0xffff0000, v41
	v_pk_mul_f32 v[10:11], v[20:21], v[10:11]
	v_lshlrev_b32_e32 v20, 16, v5
	v_and_b32_e32 v21, 0xffff0000, v5
	v_mul_f32_e32 v4, 0xbfb8aa3b, v20
	v_exp_f32_e32 v5, v4
	v_mul_f32_e32 v4, 0xbfb8aa3b, v21
	v_exp_f32_e32 v22, v4
	v_cvt_pk_bf16_f32 v4, v10, v11
	v_add_f32_e32 v5, 1.0, v5
	v_rcp_f32_e32 v10, v5
	v_add_f32_e32 v5, 1.0, v22
	v_rcp_f32_e32 v11, v5
	v_lshlrev_b32_e32 v22, 16, v41
	v_pk_mul_f32 v[8:9], v[8:9], v[22:23]
	v_pk_mul_f32 v[10:11], v[10:11], v[20:21]
	s_nop 0
	v_pk_mul_f32 v[8:9], v[10:11], v[8:9]
	v_lshlrev_b32_e32 v10, 16, v6
	v_and_b32_e32 v11, 0xffff0000, v6
	v_mul_f32_e32 v5, 0xbfb8aa3b, v10
	v_exp_f32_e32 v6, v5
	v_mul_f32_e32 v5, 0xbfb8aa3b, v11
	v_exp_f32_e32 v20, v5
	v_cvt_pk_bf16_f32 v5, v8, v9
	v_add_f32_e32 v6, 1.0, v6
	v_rcp_f32_e32 v8, v6
	v_add_f32_e32 v6, 1.0, v20
	v_rcp_f32_e32 v9, v6
	v_lshlrev_b32_e32 v20, 16, v38
	v_and_b32_e32 v21, 0xffff0000, v38
	v_pk_mul_f32 v[14:15], v[14:15], v[20:21]
	v_pk_mul_f32 v[8:9], v[8:9], v[10:11]
	v_lshlrev_b32_e32 v10, 16, v7
	v_and_b32_e32 v11, 0xffff0000, v7
	v_mul_f32_e32 v6, 0xbfb8aa3b, v10
	v_exp_f32_e32 v7, v6
	v_mul_f32_e32 v6, 0xbfb8aa3b, v11
	v_pk_mul_f32 v[8:9], v[8:9], v[14:15]
	v_exp_f32_e32 v14, v6
	v_add_f32_e32 v7, 1.0, v7
	v_cvt_pk_bf16_f32 v6, v8, v9
	v_rcp_f32_e32 v8, v7
	v_add_f32_e32 v7, 1.0, v14
	v_rcp_f32_e32 v9, v7
	v_lshlrev_b32_e32 v14, 16, v39
	v_and_b32_e32 v15, 0xffff0000, v39
	v_pk_mul_f32 v[12:13], v[12:13], v[14:15]
	v_pk_mul_f32 v[8:9], v[8:9], v[10:11]
	s_nop 0
	v_pk_mul_f32 v[8:9], v[8:9], v[12:13]
	s_nop 0
	v_cvt_pk_bf16_f32 v7, v8, v9
	global_store_dwordx4 v[60:61], v[4:7], off offset:48
	s_branch .LBB0_2195

; #define PG8_STAGE(bufoff, gbase, voff) do { _Pragma("unroll") for (int _i = 0; _i < 2; ++_i) \
;         __builtin_amdgcn_global_load_lds((const unsigned*)((const char*)(gbase) + (voff)[_i]), (LAS unsigned*)(lds + (bufoff) + ldsw + _i * 8192), 16, 0, 0); } while (0)
; #define PG8_LDA(dst, b, h) do { _Pragma("unroll") for (int m = 0; m < 4; ++m) _Pragma("unroll") for (int k = 0; k < 2; ++k) dst[m][k] = *(const LAS bf16x8*)(lds + PG8_SA(b, h) + aoff + m * 2048 + k * 1024); } while (0)
; #define PG8_LDB(dst, b, h) do { _Pragma("unroll") for (int n = 0; n < 2; ++n) _Pragma("unroll") for (int k = 0; k < 2; ++k) dst[n][k] = *(const LAS bf16x8*)(lds + PG8_SB(b, h) + boff + n * 2048 + k * 1024); } while (0)
; #define PG8_MMA(ai, bj, At, Bt) do { __builtin_amdgcn_s_setprio(1); _Pragma("unroll") for (int m = 0; m < 4; ++m) _Pragma("unroll") for (int n = 0; n < 2; ++n) _Pragma("unroll") for (int k = 0; k < 2; ++k) \
;         acc[ai][bj][m][n] = __builtin_amdgcn_mfma_f32_16x16x32_bf16(Bt[n][k], At[m][k], acc[ai][bj][m][n], 0, 0, 0); __builtin_amdgcn_s_setprio(0); } while (0)
; #define PG8_WAIT_V(n) asm volatile("s_waitcnt vmcnt(" #n ")" ::: "memory")
; #define PG8_WAIT_L(n) asm volatile("s_waitcnt lgkmcnt(" #n ")" ::: "memory")
; #define PG8_BAR __builtin_amdgcn_s_barrier()
; #define PG8_SCHED __builtin_amdgcn_sched_barrier(0)
; template <class Epi, class Sched, bool ALIGN_EPI>
; DI void gemm_phase(LAS unsigned char* lds, const Gemm g, const Sched& S, const Epi& E) {
;     ...
;         for (int t = 0; t < nt; t += 2) {
;             const bool last = (t == nt - 2);
;             const char* a1 = cA + (size_t)(t + 1) * kstep;
;             const char* a2 = last ? nA : cA + (size_t)(t + 2) * kstep; const char* b2 = last ? nB : cB + (size_t)(t + 2) * kstep;
;             const char* a3 = a2 + kstep; const char* b3 = b2 + kstep;
;             PG8_LDB(B0, 0, 0); PG8_LDB(B1, 0, 1); PG8_SCHED; PG8_LDA(At, 0, 0); PG8_STAGE(PG8_SA(1, 1), a1 + hstepA, voffA);
;             PG8_WAIT_V(8); PG8_WAIT_L(0); PG8_BAR; PG8_MMA(0, 0, At, B0); PG8_MMA(0, 1, At, B1); PG8_BAR; PG8_SCHED;
;             PG8_LDA(At, 0, 1); PG8_STAGE(PG8_SB(0, 0), b2, voffB); PG8_STAGE(PG8_SB(0, 1), b2 + hstepB, voffB); PG8_STAGE(PG8_SA(0, 0), a2, voffA);
;             PG8_WAIT_V(8); PG8_WAIT_L(0); PG8_BAR; PG8_MMA(1, 0, At, B0); PG8_MMA(1, 1, At, B1); PG8_BAR; PG8_SCHED;
.LBB0_2315:
	v_add_u32_e32 v150, s48, v148
	ds_read_b128 v[154:157], v150
	ds_read_b128 v[158:161], v150 offset:1024
	ds_read_b128 v[162:165], v150 offset:2048
	ds_read_b128 v[166:169], v150 offset:3072
	v_add_u32_e32 v150, s49, v148
	s_add_u32 s20, s10, s0
	ds_read_b128 v[170:173], v150
	ds_read_b128 v[174:177], v150 offset:1024
	ds_read_b128 v[178:181], v150 offset:2048
	ds_read_b128 v[182:185], v150 offset:3072
	s_addc_u32 s21, s11, s1
	s_add_u32 s20, s20, 0x100
	s_addc_u32 s21, s21, 0
	s_add_u32 s58, s54, s0
	s_addc_u32 s59, s55, s1
	s_cmpk_eq_i32 s0, 0x700
	s_cselect_b32 s23, s19, s21
	s_cselect_b32 s22, s18, s20
	s_cselect_b32 s21, s15, s59
	s_cselect_b32 s20, s56, s58
	v_lshl_add_u64 v[150:151], v[144:145], 0, s[0:1]
	s_add_i32 m0, s42, 0xc000
	ds_read_b128 v[186:189], v149
	ds_read_b128 v[190:193], v149 offset:1024
	ds_read_b128 v[194:197], v149 offset:2048
	ds_read_b128 v[198:201], v149 offset:3072
	ds_read_b128 v[204:207], v149 offset:4096
	ds_read_b128 v[208:211], v149 offset:5120
	ds_read_b128 v[212:215], v149 offset:6144
	ds_read_b128 v[216:219], v149 offset:7168
	global_load_lds_dwordx4 v[150:151], off
	v_lshl_add_u64 v[150:151], v[146:147], 0, s[0:1]
	s_add_i32 m0, s42, 0xe000
	s_nop 0
	global_load_lds_dwordx4 v[150:151], off
	s_waitcnt vmcnt(8)
	s_waitcnt lgkmcnt(0)
	s_barrier
	s_setprio 1
	s_waitcnt lgkmcnt(0)
	v_mfma_f32_16x16x32_bf16 v[124:127], v[154:157], v[186:189], v[124:127]
	v_mfma_f32_16x16x32_bf16 v[120:123], v[162:165], v[186:189], v[120:123]
	v_mfma_f32_16x16x32_bf16 v[112:115], v[154:157], v[194:197], v[112:115]
	v_mfma_f32_16x16x32_bf16 v[104:107], v[162:165], v[194:197], v[104:107]
	v_mfma_f32_16x16x32_bf16 v[96:99], v[154:157], v[204:207], v[96:99]
	v_mfma_f32_16x16x32_bf16 v[88:91], v[162:165], v[204:207], v[88:91]
	v_mfma_f32_16x16x32_bf16 v[80:83], v[154:157], v[212:215], v[80:83]
	v_mfma_f32_16x16x32_bf16 v[72:75], v[162:165], v[212:215], v[72:75]
	v_mfma_f32_16x16x32_bf16 v[124:127], v[158:161], v[190:193], v[124:127]
	v_mfma_f32_16x16x32_bf16 v[120:123], v[166:169], v[190:193], v[120:123]
	v_mfma_f32_16x16x32_bf16 v[112:115], v[158:161], v[198:201], v[112:115]
	v_mfma_f32_16x16x32_bf16 v[104:107], v[166:169], v[198:201], v[104:107]
	v_mfma_f32_16x16x32_bf16 v[96:99], v[158:161], v[208:211], v[96:99]
	v_mfma_f32_16x16x32_bf16 v[88:91], v[166:169], v[208:211], v[88:91]
	v_mfma_f32_16x16x32_bf16 v[80:83], v[158:161], v[216:219], v[80:83]
	v_mfma_f32_16x16x32_bf16 v[72:75], v[166:169], v[216:219], v[72:75]
	v_mfma_f32_16x16x32_bf16 v[116:119], v[170:173], v[186:189], v[116:119]
	v_mfma_f32_16x16x32_bf16 v[108:111], v[178:181], v[186:189], v[108:111]
	v_mfma_f32_16x16x32_bf16 v[100:103], v[170:173], v[194:197], v[100:103]
	v_mfma_f32_16x16x32_bf16 v[92:95], v[178:181], v[194:197], v[92:95]
	v_mfma_f32_16x16x32_bf16 v[84:87], v[170:173], v[204:207], v[84:87]
	v_mfma_f32_16x16x32_bf16 v[76:79], v[178:181], v[204:207], v[76:79]
	v_mfma_f32_16x16x32_bf16 v[68:71], v[170:173], v[212:215], v[68:71]
	v_mfma_f32_16x16x32_bf16 v[64:67], v[178:181], v[212:215], v[64:67]
	v_mfma_f32_16x16x32_bf16 v[116:119], v[174:177], v[190:193], v[116:119]
	v_mfma_f32_16x16x32_bf16 v[108:111], v[182:185], v[190:193], v[108:111]
	v_mfma_f32_16x16x32_bf16 v[100:103], v[174:177], v[198:201], v[100:103]
	v_mfma_f32_16x16x32_bf16 v[92:95], v[182:185], v[198:201], v[92:95]
	v_mfma_f32_16x16x32_bf16 v[84:87], v[174:177], v[208:211], v[84:87]
	v_mfma_f32_16x16x32_bf16 v[76:79], v[182:185], v[208:211], v[76:79]
	v_mfma_f32_16x16x32_bf16 v[68:71], v[174:177], v[216:219], v[68:71]
	v_mfma_f32_16x16x32_bf16 v[64:67], v[182:185], v[216:219], v[64:67]
	s_setprio 0
	s_barrier
	s_add_i32 s58, s48, s41
	v_lshl_add_u64 v[150:151], s[20:21], 0, v[130:131]
	s_mov_b32 m0, s58
	ds_read_b128 v[186:189], v149 offset:16384
	ds_read_b128 v[190:193], v149 offset:17408
	ds_read_b128 v[194:197], v149 offset:18432
	ds_read_b128 v[198:201], v149 offset:19456
	ds_read_b128 v[204:207], v149 offset:20480
	ds_read_b128 v[208:211], v149 offset:21504
	ds_read_b128 v[212:215], v149 offset:22528
	ds_read_b128 v[216:219], v149 offset:23552
	global_load_lds_dwordx4 v[150:151], off
	s_add_i32 m0, s58, 0x2000
	s_add_u32 s58, s20, 0x40000
	v_lshl_add_u64 v[220:221], s[20:21], 0, v[134:135]
	s_addc_u32 s59, s21, 0
	s_add_i32 s60, s49, s41
	global_load_lds_dwordx4 v[220:221], off
	v_lshl_add_u64 v[222:223], s[58:59], 0, v[130:131]
	s_mov_b32 m0, s60
	v_lshl_add_u64 v[224:225], s[22:23], 0, v[132:133]
	global_load_lds_dwordx4 v[222:223], off
	v_lshl_add_u64 v[222:223], s[58:59], 0, v[134:135]
	s_add_i32 m0, s60, 0x2000
	s_nop 0
	global_load_lds_dwordx4 v[222:223], off
	v_lshl_add_u64 v[222:223], s[22:23], 0, v[128:129]
	s_mov_b32 m0, s42
	s_nop 0
	global_load_lds_dwordx4 v[222:223], off
	s_mov_b32 m0, s43
	s_nop 0
	global_load_lds_dwordx4 v[224:225], off
	s_waitcnt vmcnt(8)
	s_waitcnt lgkmcnt(0)
	s_barrier
; #define PG8_STAGE(bufoff, gbase, voff) do { _Pragma("unroll") for (int _i = 0; _i < 2; ++_i) \
;         __builtin_amdgcn_global_load_lds((const unsigned*)((const char*)(gbase) + (voff)[_i]), (LAS unsigned*)(lds + (bufoff) + ldsw + _i * 8192), 16, 0, 0); } while (0)
; #define PG8_LDA(dst, b, h) do { _Pragma("unroll") for (int m = 0; m < 4; ++m) _Pragma("unroll") for (int k = 0; k < 2; ++k) dst[m][k] = *(const LAS bf16x8*)(lds + PG8_SA(b, h) + aoff + m * 2048 + k * 1024); } while (0)
; #define PG8_LDB(dst, b, h) do { _Pragma("unroll") for (int n = 0; n < 2; ++n) _Pragma("unroll") for (int k = 0; k < 2; ++k) dst[n][k] = *(const LAS bf16x8*)(lds + PG8_SB(b, h) + boff + n * 2048 + k * 1024); } while (0)
; #define PG8_MMA(ai, bj, At, Bt) do { __builtin_amdgcn_s_setprio(1); _Pragma("unroll") for (int m = 0; m < 4; ++m) _Pragma("unroll") for (int n = 0; n < 2; ++n) _Pragma("unroll") for (int k = 0; k < 2; ++k) \
;         acc[ai][bj][m][n] = __builtin_amdgcn_mfma_f32_16x16x32_bf16(Bt[n][k], At[m][k], acc[ai][bj][m][n], 0, 0, 0); __builtin_amdgcn_s_setprio(0); } while (0)
; #define PG8_WAIT_V(n) asm volatile("s_waitcnt vmcnt(" #n ")" ::: "memory")
; #define PG8_WAIT_L(n) asm volatile("s_waitcnt lgkmcnt(" #n ")" ::: "memory")
; #define PG8_BAR __builtin_amdgcn_s_barrier()
; #define PG8_SCHED __builtin_amdgcn_sched_barrier(0)
; template <class Epi, class Sched, bool ALIGN_EPI>
; DI void gemm_phase(LAS unsigned char* lds, const Gemm g, const Sched& S, const Epi& E) {
;     ...
;             PG8_WAIT_V(8); PG8_WAIT_L(0); PG8_BAR; PG8_MMA(0, 0, At, B0); PG8_MMA(0, 1, At, B1); PG8_BAR; PG8_SCHED;
;             PG8_LDA(At, 0, 1); PG8_STAGE(PG8_SB(0, 0), b2, voffB); PG8_STAGE(PG8_SB(0, 1), b2 + hstepB, voffB); PG8_STAGE(PG8_SA(0, 0), a2, voffA);
;             PG8_WAIT_V(8); PG8_WAIT_L(0); PG8_BAR; PG8_MMA(1, 0, At, B0); PG8_MMA(1, 1, At, B1); PG8_BAR; PG8_SCHED;
;             PG8_LDB(B0, 1, 0); PG8_LDB(B1, 1, 1); PG8_SCHED; PG8_LDA(At, 1, 0); PG8_STAGE(PG8_SA(0, 1), a2 + hstepA, voffA);
;             PG8_WAIT_V(8); PG8_WAIT_L(0); PG8_BAR; PG8_MMA(0, 0, At, B0); PG8_MMA(0, 1, At, B1); PG8_BAR; PG8_SCHED;
	s_setprio 1
	s_waitcnt lgkmcnt(0)
	v_mfma_f32_16x16x32_bf16 v[60:63], v[154:157], v[186:189], v[60:63]
	v_mfma_f32_16x16x32_bf16 v[56:59], v[162:165], v[186:189], v[56:59]
	v_mfma_f32_16x16x32_bf16 v[44:47], v[154:157], v[194:197], v[44:47]
	v_mfma_f32_16x16x32_bf16 v[40:43], v[162:165], v[194:197], v[40:43]
	v_mfma_f32_16x16x32_bf16 v[28:31], v[154:157], v[204:207], v[28:31]
	v_mfma_f32_16x16x32_bf16 v[24:27], v[162:165], v[204:207], v[24:27]
	v_mfma_f32_16x16x32_bf16 v[12:15], v[154:157], v[212:215], v[12:15]
	v_mfma_f32_16x16x32_bf16 v[8:11], v[162:165], v[212:215], v[8:11]
	v_mfma_f32_16x16x32_bf16 v[60:63], v[158:161], v[190:193], v[60:63]
	v_mfma_f32_16x16x32_bf16 v[56:59], v[166:169], v[190:193], v[56:59]
	v_mfma_f32_16x16x32_bf16 v[44:47], v[158:161], v[198:201], v[44:47]
	v_mfma_f32_16x16x32_bf16 v[40:43], v[166:169], v[198:201], v[40:43]
	v_mfma_f32_16x16x32_bf16 v[28:31], v[158:161], v[208:211], v[28:31]
	v_mfma_f32_16x16x32_bf16 v[24:27], v[166:169], v[208:211], v[24:27]
	v_mfma_f32_16x16x32_bf16 v[12:15], v[158:161], v[216:219], v[12:15]
	v_mfma_f32_16x16x32_bf16 v[8:11], v[166:169], v[216:219], v[8:11]
	v_mfma_f32_16x16x32_bf16 v[52:55], v[170:173], v[186:189], v[52:55]
	v_mfma_f32_16x16x32_bf16 v[48:51], v[178:181], v[186:189], v[48:51]
	v_mfma_f32_16x16x32_bf16 v[36:39], v[170:173], v[194:197], v[36:39]
	v_mfma_f32_16x16x32_bf16 v[32:35], v[178:181], v[194:197], v[32:35]
	v_mfma_f32_16x16x32_bf16 v[20:23], v[170:173], v[204:207], v[20:23]
	v_mfma_f32_16x16x32_bf16 v[16:19], v[178:181], v[204:207], v[16:19]
	v_mfma_f32_16x16x32_bf16 v[4:7], v[170:173], v[212:215], v[4:7]
	v_mfma_f32_16x16x32_bf16 v[0:3], v[178:181], v[212:215], v[0:3]
	v_mfma_f32_16x16x32_bf16 v[52:55], v[174:177], v[190:193], v[52:55]
	v_mfma_f32_16x16x32_bf16 v[48:51], v[182:185], v[190:193], v[48:51]
	v_mfma_f32_16x16x32_bf16 v[36:39], v[174:177], v[198:201], v[36:39]
	v_mfma_f32_16x16x32_bf16 v[32:35], v[182:185], v[198:201], v[32:35]
	v_mfma_f32_16x16x32_bf16 v[20:23], v[174:177], v[208:211], v[20:23]
	v_mfma_f32_16x16x32_bf16 v[16:19], v[182:185], v[208:211], v[16:19]
	v_mfma_f32_16x16x32_bf16 v[4:7], v[174:177], v[216:219], v[4:7]
	v_mfma_f32_16x16x32_bf16 v[0:3], v[182:185], v[216:219], v[0:3]
	s_setprio 0
	s_barrier
	v_add_u32_e32 v153, s50, v148
	ds_read_b128 v[154:157], v153
	ds_read_b128 v[158:161], v153 offset:1024
	ds_read_b128 v[162:165], v153 offset:2048
	ds_read_b128 v[166:169], v153 offset:3072
	v_add_u32_e32 v153, s52, v148
	ds_read_b128 v[170:173], v153
	ds_read_b128 v[174:177], v153 offset:1024
	ds_read_b128 v[178:181], v153 offset:2048
	ds_read_b128 v[182:185], v153 offset:3072
	s_add_u32 s22, s22, 0xd0000
	s_addc_u32 s23, s23, 0
	s_mov_b32 m0, s44
	v_lshl_add_u64 v[226:227], s[22:23], 0, v[128:129]
	ds_read_b128 v[186:189], v149 offset:32768
	ds_read_b128 v[190:193], v149 offset:33792
	ds_read_b128 v[194:197], v149 offset:34816
	ds_read_b128 v[198:201], v149 offset:35840
	ds_read_b128 v[204:207], v149 offset:36864
	ds_read_b128 v[208:211], v149 offset:37888
	ds_read_b128 v[212:215], v149 offset:38912
	ds_read_b128 v[216:219], v149 offset:39936
	global_load_lds_dwordx4 v[226:227], off
	v_lshl_add_u64 v[226:227], s[22:23], 0, v[132:133]
	s_mov_b32 m0, s45
	s_nop 0
	global_load_lds_dwordx4 v[226:227], off
	s_waitcnt vmcnt(8)
	s_waitcnt lgkmcnt(0)
	s_barrier
	s_setprio 1
	s_waitcnt lgkmcnt(0)
	v_mfma_f32_16x16x32_bf16 v[124:127], v[154:157], v[186:189], v[124:127]
	v_mfma_f32_16x16x32_bf16 v[120:123], v[162:165], v[186:189], v[120:123]
	v_mfma_f32_16x16x32_bf16 v[112:115], v[154:157], v[194:197], v[112:115]
	v_mfma_f32_16x16x32_bf16 v[104:107], v[162:165], v[194:197], v[104:107]
	v_mfma_f32_16x16x32_bf16 v[96:99], v[154:157], v[204:207], v[96:99]
	v_mfma_f32_16x16x32_bf16 v[88:91], v[162:165], v[204:207], v[88:91]
	v_mfma_f32_16x16x32_bf16 v[80:83], v[154:157], v[212:215], v[80:83]
	v_mfma_f32_16x16x32_bf16 v[72:75], v[162:165], v[212:215], v[72:75]
	v_mfma_f32_16x16x32_bf16 v[124:127], v[158:161], v[190:193], v[124:127]
	v_mfma_f32_16x16x32_bf16 v[120:123], v[166:169], v[190:193], v[120:123]
	v_mfma_f32_16x16x32_bf16 v[112:115], v[158:161], v[198:201], v[112:115]
	v_mfma_f32_16x16x32_bf16 v[104:107], v[166:169], v[198:201], v[104:107]
	v_mfma_f32_16x16x32_bf16 v[96:99], v[158:161], v[208:211], v[96:99]
	v_mfma_f32_16x16x32_bf16 v[88:91], v[166:169], v[208:211], v[88:91]
	v_mfma_f32_16x16x32_bf16 v[80:83], v[158:161], v[216:219], v[80:83]
	v_mfma_f32_16x16x32_bf16 v[72:75], v[166:169], v[216:219], v[72:75]
	v_mfma_f32_16x16x32_bf16 v[116:119], v[170:173], v[186:189], v[116:119]
	v_mfma_f32_16x16x32_bf16 v[108:111], v[178:181], v[186:189], v[108:111]
	v_mfma_f32_16x16x32_bf16 v[100:103], v[170:173], v[194:197], v[100:103]
	v_mfma_f32_16x16x32_bf16 v[92:95], v[178:181], v[194:197], v[92:95]
	v_mfma_f32_16x16x32_bf16 v[84:87], v[170:173], v[204:207], v[84:87]
	v_mfma_f32_16x16x32_bf16 v[76:79], v[178:181], v[204:207], v[76:79]
	v_mfma_f32_16x16x32_bf16 v[68:71], v[170:173], v[212:215], v[68:71]
	v_mfma_f32_16x16x32_bf16 v[64:67], v[178:181], v[212:215], v[64:67]
	v_mfma_f32_16x16x32_bf16 v[116:119], v[174:177], v[190:193], v[116:119]
	v_mfma_f32_16x16x32_bf16 v[108:111], v[182:185], v[190:193], v[108:111]
	v_mfma_f32_16x16x32_bf16 v[100:103], v[174:177], v[198:201], v[100:103]
	v_mfma_f32_16x16x32_bf16 v[92:95], v[182:185], v[198:201], v[92:95]
	v_mfma_f32_16x16x32_bf16 v[84:87], v[174:177], v[208:211], v[84:87]
	v_mfma_f32_16x16x32_bf16 v[76:79], v[182:185], v[208:211], v[76:79]
	v_mfma_f32_16x16x32_bf16 v[68:71], v[174:177], v[216:219], v[68:71]
	v_mfma_f32_16x16x32_bf16 v[64:67], v[182:185], v[216:219], v[64:67]
	s_setprio 0
	s_barrier
; #define PG8_STAGE(bufoff, gbase, voff) do { _Pragma("unroll") for (int _i = 0; _i < 2; ++_i) \
;         __builtin_amdgcn_global_load_lds((const unsigned*)((const char*)(gbase) + (voff)[_i]), (LAS unsigned*)(lds + (bufoff) + ldsw + _i * 8192), 16, 0, 0); } while (0)
; #define PG8_LDA(dst, b, h) do { _Pragma("unroll") for (int m = 0; m < 4; ++m) _Pragma("unroll") for (int k = 0; k < 2; ++k) dst[m][k] = *(const LAS bf16x8*)(lds + PG8_SA(b, h) + aoff + m * 2048 + k * 1024); } while (0)
; #define PG8_MMA(ai, bj, At, Bt) do { __builtin_amdgcn_s_setprio(1); _Pragma("unroll") for (int m = 0; m < 4; ++m) _Pragma("unroll") for (int n = 0; n < 2; ++n) _Pragma("unroll") for (int k = 0; k < 2; ++k) \
;         acc[ai][bj][m][n] = __builtin_amdgcn_mfma_f32_16x16x32_bf16(Bt[n][k], At[m][k], acc[ai][bj][m][n], 0, 0, 0); __builtin_amdgcn_s_setprio(0); } while (0)
; #define PG8_WAIT_V(n) asm volatile("s_waitcnt vmcnt(" #n ")" ::: "memory")
; #define PG8_WAIT_L(n) asm volatile("s_waitcnt lgkmcnt(" #n ")" ::: "memory")
; #define PG8_BAR __builtin_amdgcn_s_barrier()
; #define PG8_SCHED __builtin_amdgcn_sched_barrier(0)
; template <class Epi, class Sched, bool ALIGN_EPI>
; DI void gemm_phase(LAS unsigned char* lds, const Gemm g, const Sched& S, const Epi& E) {
;     ...
;             PG8_LDA(At, 1, 1); PG8_STAGE(PG8_SB(1, 0), b3, voffB); PG8_STAGE(PG8_SB(1, 1), b3 + hstepB, voffB); PG8_STAGE(PG8_SA(1, 0), a3, voffA);
;             PG8_WAIT_V(8); PG8_WAIT_L(0); PG8_BAR; PG8_MMA(1, 0, At, B0); PG8_MMA(1, 1, At, B1); PG8_BAR; PG8_SCHED;
;         }
;         if constexpr (ALIGN_EPI) { if (wr == 0) PG8_BAR; }
;         if constexpr (!Epi::AFTER_DRAIN) E(acc, cur, wr, wc, fr, fq);
;         if (!has_next) break;
; #pragma unroll
;         for (int a = 0; a < 2; ++a)
; #pragma unroll
;             for (int b = 0; b < 2; ++b)
; #pragma unroll
;                 for (int m = 0; m < 4; ++m)
; #pragma unroll
;                     for (int n = 0; n < 2; ++n) acc[a][b][m][n] = (f32x4){0.f, 0.f, 0.f, 0.f};
;         cur = nxt; cA = nA; cB = nB; ++ui;
	s_add_i32 s22, s50, s41
	v_lshl_add_u64 v[150:151], v[150:151], 0, s[12:13]
	s_mov_b32 m0, s22
	ds_read_b128 v[186:189], v149 offset:49152
	ds_read_b128 v[190:193], v149 offset:50176
	ds_read_b128 v[194:197], v149 offset:51200
	ds_read_b128 v[198:201], v149 offset:52224
	ds_read_b128 v[204:207], v149 offset:53248
	ds_read_b128 v[208:211], v149 offset:54272
	ds_read_b128 v[212:215], v149 offset:55296
	ds_read_b128 v[216:219], v149 offset:56320
	global_load_lds_dwordx4 v[150:151], off
	s_add_i32 m0, s22, 0x2000
	s_add_u32 s20, s20, 0x40080
	v_lshl_add_u64 v[150:151], v[220:221], 0, s[12:13]
	s_addc_u32 s21, s21, 0
	s_add_i32 s22, s52, s41
	global_load_lds_dwordx4 v[150:151], off
	v_lshl_add_u64 v[150:151], s[20:21], 0, v[130:131]
	s_mov_b32 m0, s22
	s_nop 0
	global_load_lds_dwordx4 v[150:151], off
	v_lshl_add_u64 v[150:151], s[20:21], 0, v[134:135]
	s_add_i32 m0, s22, 0x2000
	s_nop 0
	global_load_lds_dwordx4 v[150:151], off
	v_lshl_add_u64 v[150:151], v[222:223], 0, s[12:13]
	s_mov_b32 m0, s46
	s_nop 0
	global_load_lds_dwordx4 v[150:151], off
	v_lshl_add_u64 v[150:151], v[224:225], 0, s[12:13]
	s_mov_b32 m0, s47
	s_nop 0
	global_load_lds_dwordx4 v[150:151], off
	s_waitcnt vmcnt(8)
	s_waitcnt lgkmcnt(0)
	s_barrier
	s_setprio 1
	s_waitcnt lgkmcnt(0)
	v_mfma_f32_16x16x32_bf16 v[60:63], v[154:157], v[186:189], v[60:63]
	v_mfma_f32_16x16x32_bf16 v[56:59], v[162:165], v[186:189], v[56:59]
	v_mfma_f32_16x16x32_bf16 v[44:47], v[154:157], v[194:197], v[44:47]
	v_mfma_f32_16x16x32_bf16 v[40:43], v[162:165], v[194:197], v[40:43]
	v_mfma_f32_16x16x32_bf16 v[28:31], v[154:157], v[204:207], v[28:31]
	v_mfma_f32_16x16x32_bf16 v[24:27], v[162:165], v[204:207], v[24:27]
	v_mfma_f32_16x16x32_bf16 v[12:15], v[154:157], v[212:215], v[12:15]
	v_mfma_f32_16x16x32_bf16 v[8:11], v[162:165], v[212:215], v[8:11]
	v_mfma_f32_16x16x32_bf16 v[60:63], v[158:161], v[190:193], v[60:63]
	v_mfma_f32_16x16x32_bf16 v[56:59], v[166:169], v[190:193], v[56:59]
	v_mfma_f32_16x16x32_bf16 v[44:47], v[158:161], v[198:201], v[44:47]
	v_mfma_f32_16x16x32_bf16 v[40:43], v[166:169], v[198:201], v[40:43]
	v_mfma_f32_16x16x32_bf16 v[28:31], v[158:161], v[208:211], v[28:31]
	v_mfma_f32_16x16x32_bf16 v[24:27], v[166:169], v[208:211], v[24:27]
	v_mfma_f32_16x16x32_bf16 v[12:15], v[158:161], v[216:219], v[12:15]
	v_mfma_f32_16x16x32_bf16 v[8:11], v[166:169], v[216:219], v[8:11]
	v_mfma_f32_16x16x32_bf16 v[52:55], v[170:173], v[186:189], v[52:55]
	v_mfma_f32_16x16x32_bf16 v[48:51], v[178:181], v[186:189], v[48:51]
	v_mfma_f32_16x16x32_bf16 v[36:39], v[170:173], v[194:197], v[36:39]
	v_mfma_f32_16x16x32_bf16 v[32:35], v[178:181], v[194:197], v[32:35]
	v_mfma_f32_16x16x32_bf16 v[20:23], v[170:173], v[204:207], v[20:23]
	v_mfma_f32_16x16x32_bf16 v[16:19], v[178:181], v[204:207], v[16:19]
	v_mfma_f32_16x16x32_bf16 v[4:7], v[170:173], v[212:215], v[4:7]
	v_mfma_f32_16x16x32_bf16 v[0:3], v[178:181], v[212:215], v[0:3]
	v_mfma_f32_16x16x32_bf16 v[52:55], v[174:177], v[190:193], v[52:55]
	v_mfma_f32_16x16x32_bf16 v[48:51], v[182:185], v[190:193], v[48:51]
	v_mfma_f32_16x16x32_bf16 v[36:39], v[174:177], v[198:201], v[36:39]
	v_mfma_f32_16x16x32_bf16 v[32:35], v[182:185], v[198:201], v[32:35]
	v_mfma_f32_16x16x32_bf16 v[20:23], v[174:177], v[208:211], v[20:23]
	v_mfma_f32_16x16x32_bf16 v[16:19], v[182:185], v[208:211], v[16:19]
	v_mfma_f32_16x16x32_bf16 v[4:7], v[174:177], v[216:219], v[4:7]
	v_mfma_f32_16x16x32_bf16 v[0:3], v[182:185], v[216:219], v[0:3]
	s_setprio 0
	s_barrier
	s_add_i32 s57, s57, 2
	s_add_u32 s0, s0, 0x100
	s_addc_u32 s1, s1, 0
	s_cmp_gt_u32 s57, 13
	s_cbranch_scc0 .LBB0_2315
	s_add_u32 s0, s54, 0xffffff00
	s_addc_u32 s1, s55, -1
	s_and_b64 vcc, exec, s[6:7]
	s_cbranch_vccnz .LBB0_2318
	v_mov_b32_e32 v0, 0
	s_mov_b32 s8, s14
	s_mov_b32 s26, s53
	s_mov_b64 s[10:11], s[18:19]
	s_mov_b32 s51, s33
	v_mov_b32_e32 v1, v0
	v_mov_b32_e32 v2, v0
	v_mov_b32_e32 v3, v0
	v_mov_b32_e32 v4, v0
	v_mov_b32_e32 v5, v0
	v_mov_b32_e32 v6, v0
	v_mov_b32_e32 v7, v0
	v_mov_b32_e32 v16, v0
	v_mov_b32_e32 v17, v0
	v_mov_b32_e32 v18, v0
	v_mov_b32_e32 v19, v0
	v_mov_b32_e32 v20, v0
	v_mov_b32_e32 v21, v0
	v_mov_b32_e32 v22, v0
	v_mov_b32_e32 v23, v0
	v_mov_b32_e32 v32, v0
	v_mov_b32_e32 v33, v0
	v_mov_b32_e32 v34, v0
	v_mov_b32_e32 v35, v0
	v_mov_b32_e32 v36, v0
	v_mov_b32_e32 v37, v0
	v_mov_b32_e32 v38, v0
	v_mov_b32_e32 v39, v0
	v_mov_b32_e32 v48, v0
	v_mov_b32_e32 v49, v0
	v_mov_b32_e32 v50, v0
	v_mov_b32_e32 v51, v0
	v_mov_b32_e32 v52, v0
	v_mov_b32_e32 v53, v0
	v_mov_b32_e32 v54, v0
	v_mov_b32_e32 v55, v0
	v_mov_b32_e32 v8, v0
	v_mov_b32_e32 v9, v0
	v_mov_b32_e32 v10, v0
	v_mov_b32_e32 v11, v0
	v_mov_b32_e32 v12, v0
	v_mov_b32_e32 v13, v0
	v_mov_b32_e32 v14, v0
	v_mov_b32_e32 v15, v0
	v_mov_b32_e32 v24, v0
	v_mov_b32_e32 v25, v0
	v_mov_b32_e32 v26, v0
	v_mov_b32_e32 v27, v0
	v_mov_b32_e32 v28, v0
	v_mov_b32_e32 v29, v0
	v_mov_b32_e32 v30, v0
	v_mov_b32_e32 v31, v0
	v_mov_b32_e32 v40, v0
	v_mov_b32_e32 v41, v0
	v_mov_b32_e32 v42, v0
	v_mov_b32_e32 v43, v0
	v_mov_b32_e32 v44, v0
	v_mov_b32_e32 v45, v0
	v_mov_b32_e32 v46, v0
	v_mov_b32_e32 v47, v0
	v_mov_b32_e32 v56, v0
	v_mov_b32_e32 v57, v0
	v_mov_b32_e32 v58, v0
	v_mov_b32_e32 v59, v0
	v_mov_b32_e32 v60, v0
	v_mov_b32_e32 v61, v0
	v_mov_b32_e32 v62, v0
	v_mov_b32_e32 v63, v0
	v_mov_b32_e32 v64, v0
	v_mov_b32_e32 v65, v0
	v_mov_b32_e32 v66, v0
	v_mov_b32_e32 v67, v0
	v_mov_b32_e32 v68, v0
	v_mov_b32_e32 v69, v0
	v_mov_b32_e32 v70, v0
	v_mov_b32_e32 v71, v0
	v_mov_b32_e32 v76, v0
	v_mov_b32_e32 v77, v0
	v_mov_b32_e32 v78, v0
	v_mov_b32_e32 v79, v0
	v_mov_b32_e32 v84, v0
	v_mov_b32_e32 v85, v0
	v_mov_b32_e32 v86, v0
	v_mov_b32_e32 v87, v0
	v_mov_b32_e32 v92, v0
	v_mov_b32_e32 v93, v0
	v_mov_b32_e32 v94, v0
	v_mov_b32_e32 v95, v0
	v_mov_b32_e32 v100, v0
	v_mov_b32_e32 v101, v0
	v_mov_b32_e32 v102, v0
	v_mov_b32_e32 v103, v0
	v_mov_b32_e32 v108, v0
	v_mov_b32_e32 v109, v0
	v_mov_b32_e32 v110, v0
	v_mov_b32_e32 v111, v0
	v_mov_b32_e32 v116, v0
	v_mov_b32_e32 v117, v0
	v_mov_b32_e32 v118, v0
	v_mov_b32_e32 v119, v0
	v_mov_b32_e32 v72, v0
	v_mov_b32_e32 v73, v0
	v_mov_b32_e32 v74, v0
	v_mov_b32_e32 v75, v0
	v_mov_b32_e32 v80, v0
	v_mov_b32_e32 v81, v0
	v_mov_b32_e32 v82, v0
	v_mov_b32_e32 v83, v0
	v_mov_b32_e32 v88, v0
	v_mov_b32_e32 v89, v0
	v_mov_b32_e32 v90, v0
	v_mov_b32_e32 v91, v0
	v_mov_b32_e32 v96, v0
	v_mov_b32_e32 v97, v0
	v_mov_b32_e32 v98, v0
	v_mov_b32_e32 v99, v0
	v_mov_b32_e32 v104, v0
	v_mov_b32_e32 v105, v0
	v_mov_b32_e32 v106, v0
	v_mov_b32_e32 v107, v0
	v_mov_b32_e32 v112, v0
	v_mov_b32_e32 v113, v0
	v_mov_b32_e32 v114, v0
	v_mov_b32_e32 v115, v0
	v_mov_b32_e32 v120, v0
	v_mov_b32_e32 v121, v0
	v_mov_b32_e32 v122, v0
	v_mov_b32_e32 v123, v0
	v_mov_b32_e32 v124, v0
	v_mov_b32_e32 v125, v0
	v_mov_b32_e32 v126, v0
	v_mov_b32_e32 v127, v0
	s_andn2_b64 vcc, exec, s[4:5]
	s_cbranch_vccnz .LBB0_2319
	s_branch .LBB0_2320

; #define PG8_STAGE(bufoff, gbase, voff) do { _Pragma("unroll") for (int _i = 0; _i < 2; ++_i) \
;         __builtin_amdgcn_global_load_lds((const unsigned*)((const char*)(gbase) + (voff)[_i]), (LAS unsigned*)(lds + (bufoff) + ldsw + _i * 8192), 16, 0, 0); } while (0)
; #define PG8_LDA(dst, b, h) do { _Pragma("unroll") for (int m = 0; m < 4; ++m) _Pragma("unroll") for (int k = 0; k < 2; ++k) dst[m][k] = *(const LAS bf16x8*)(lds + PG8_SA(b, h) + aoff + m * 2048 + k * 1024); } while (0)
; #define PG8_LDB(dst, b, h) do { _Pragma("unroll") for (int n = 0; n < 2; ++n) _Pragma("unroll") for (int k = 0; k < 2; ++k) dst[n][k] = *(const LAS bf16x8*)(lds + PG8_SB(b, h) + boff + n * 2048 + k * 1024); } while (0)
; #define PG8_MMA(ai, bj, At, Bt) do { __builtin_amdgcn_s_setprio(1); _Pragma("unroll") for (int m = 0; m < 4; ++m) _Pragma("unroll") for (int n = 0; n < 2; ++n) _Pragma("unroll") for (int k = 0; k < 2; ++k) \
;         acc[ai][bj][m][n] = __builtin_amdgcn_mfma_f32_16x16x32_bf16(Bt[n][k], At[m][k], acc[ai][bj][m][n], 0, 0, 0); __builtin_amdgcn_s_setprio(0); } while (0)
; #define PG8_WAIT_V(n) asm volatile("s_waitcnt vmcnt(" #n ")" ::: "memory")
; #define PG8_WAIT_L(n) asm volatile("s_waitcnt lgkmcnt(" #n ")" ::: "memory")
; #define PG8_BAR __builtin_amdgcn_s_barrier()
; #define PG8_SCHED __builtin_amdgcn_sched_barrier(0)
; template <class Epi, class Sched, bool ALIGN_EPI>
; DI void gemm_phase(LAS unsigned char* lds, const Gemm g, const Sched& S, const Epi& E) {
;     ...
;         for (int t = 0; t < nt; t += 2) {
;             const bool last = (t == nt - 2);
;             const char* a1 = cA + (size_t)(t + 1) * kstep;
;             const char* a2 = last ? nA : cA + (size_t)(t + 2) * kstep; const char* b2 = last ? nB : cB + (size_t)(t + 2) * kstep;
;             const char* a3 = a2 + kstep; const char* b3 = b2 + kstep;
;             PG8_LDB(B0, 0, 0); PG8_LDB(B1, 0, 1); PG8_SCHED; PG8_LDA(At, 0, 0); PG8_STAGE(PG8_SA(1, 1), a1 + hstepA, voffA);
;             PG8_WAIT_V(8); PG8_WAIT_L(0); PG8_BAR; PG8_MMA(0, 0, At, B0); PG8_MMA(0, 1, At, B1); PG8_BAR; PG8_SCHED;
;             PG8_LDA(At, 0, 1); PG8_STAGE(PG8_SB(0, 0), b2, voffB); PG8_STAGE(PG8_SB(0, 1), b2 + hstepB, voffB); PG8_STAGE(PG8_SA(0, 0), a2, voffA);
;             PG8_WAIT_V(8); PG8_WAIT_L(0); PG8_BAR; PG8_MMA(1, 0, At, B0); PG8_MMA(1, 1, At, B1); PG8_BAR; PG8_SCHED;
.LBB0_2424:
	ds_read_b128 v[164:167], v158
	ds_read_b128 v[168:171], v158 offset:1024
	ds_read_b128 v[172:175], v158 offset:2048
	ds_read_b128 v[176:179], v158 offset:3072
	ds_read_b128 v[180:183], v159
	ds_read_b128 v[184:187], v159 offset:1024
	ds_read_b128 v[188:191], v159 offset:2048
	ds_read_b128 v[192:195], v159 offset:3072
	s_add_u32 s24, s22, 0xfffc0080
	s_addc_u32 s25, s23, -1
	s_cmp_eq_u32 s58, 12
	s_cselect_b32 s27, s15, s25
	s_cselect_b32 s26, s54, s24
	s_cselect_b32 s25, s13, s57
	s_cselect_b32 s24, s55, s56
	v_lshl_add_u64 v[144:145], s[22:23], 0, v[136:137]
	s_add_i32 m0, s21, 0xc000
	ds_read_b128 v[196:199], v160
	ds_read_b128 v[204:207], v160 offset:1024
	ds_read_b128 v[208:211], v160 offset:2048
	ds_read_b128 v[212:215], v160 offset:3072
	ds_read_b128 v[216:219], v160 offset:4096
	ds_read_b128 v[220:223], v160 offset:5120
	ds_read_b128 v[224:227], v160 offset:6144
	ds_read_b128 v[228:231], v160 offset:7168
	global_load_lds_dwordx4 v[144:145], off
	v_lshl_add_u64 v[144:145], s[22:23], 0, v[138:139]
	s_add_i32 m0, s21, 0xe000
	s_nop 0
	global_load_lds_dwordx4 v[144:145], off
	s_waitcnt vmcnt(8)
	s_waitcnt lgkmcnt(0)
	s_barrier
	s_setprio 1
	s_waitcnt lgkmcnt(0)
	v_mfma_f32_16x16x32_bf16 v[124:127], v[164:167], v[196:199], v[124:127]
	v_mfma_f32_16x16x32_bf16 v[120:123], v[172:175], v[196:199], v[120:123]
	v_mfma_f32_16x16x32_bf16 v[108:111], v[164:167], v[208:211], v[108:111]
	v_mfma_f32_16x16x32_bf16 v[104:107], v[172:175], v[208:211], v[104:107]
	v_mfma_f32_16x16x32_bf16 v[92:95], v[164:167], v[216:219], v[92:95]
	v_mfma_f32_16x16x32_bf16 v[88:91], v[172:175], v[216:219], v[88:91]
	v_mfma_f32_16x16x32_bf16 v[76:79], v[164:167], v[224:227], v[76:79]
	v_mfma_f32_16x16x32_bf16 v[72:75], v[172:175], v[224:227], v[72:75]
	v_mfma_f32_16x16x32_bf16 v[124:127], v[168:171], v[204:207], v[124:127]
	v_mfma_f32_16x16x32_bf16 v[120:123], v[176:179], v[204:207], v[120:123]
	v_mfma_f32_16x16x32_bf16 v[108:111], v[168:171], v[212:215], v[108:111]
	v_mfma_f32_16x16x32_bf16 v[104:107], v[176:179], v[212:215], v[104:107]
	v_mfma_f32_16x16x32_bf16 v[92:95], v[168:171], v[220:223], v[92:95]
	v_mfma_f32_16x16x32_bf16 v[88:91], v[176:179], v[220:223], v[88:91]
	v_mfma_f32_16x16x32_bf16 v[76:79], v[168:171], v[228:231], v[76:79]
	v_mfma_f32_16x16x32_bf16 v[72:75], v[176:179], v[228:231], v[72:75]
	v_mfma_f32_16x16x32_bf16 v[116:119], v[180:183], v[196:199], v[116:119]
	v_mfma_f32_16x16x32_bf16 v[112:115], v[188:191], v[196:199], v[112:115]
	v_mfma_f32_16x16x32_bf16 v[100:103], v[180:183], v[208:211], v[100:103]
	v_mfma_f32_16x16x32_bf16 v[96:99], v[188:191], v[208:211], v[96:99]
	v_mfma_f32_16x16x32_bf16 v[84:87], v[180:183], v[216:219], v[84:87]
	v_mfma_f32_16x16x32_bf16 v[80:83], v[188:191], v[216:219], v[80:83]
	v_mfma_f32_16x16x32_bf16 v[68:71], v[180:183], v[224:227], v[68:71]
	v_mfma_f32_16x16x32_bf16 v[64:67], v[188:191], v[224:227], v[64:67]
	v_mfma_f32_16x16x32_bf16 v[116:119], v[184:187], v[204:207], v[116:119]
	v_mfma_f32_16x16x32_bf16 v[112:115], v[192:195], v[204:207], v[112:115]
	v_mfma_f32_16x16x32_bf16 v[100:103], v[184:187], v[212:215], v[100:103]
	v_mfma_f32_16x16x32_bf16 v[96:99], v[192:195], v[212:215], v[96:99]
	v_mfma_f32_16x16x32_bf16 v[84:87], v[184:187], v[220:223], v[84:87]
	v_mfma_f32_16x16x32_bf16 v[80:83], v[192:195], v[220:223], v[80:83]
	v_mfma_f32_16x16x32_bf16 v[68:71], v[184:187], v[228:231], v[68:71]
	v_mfma_f32_16x16x32_bf16 v[64:67], v[192:195], v[228:231], v[64:67]
	s_setprio 0
	s_barrier
	s_add_i32 s59, s49, s38
	v_lshl_add_u64 v[144:145], s[24:25], 0, v[132:133]
	s_mov_b32 m0, s59
	ds_read_b128 v[196:199], v160 offset:16384
	ds_read_b128 v[204:207], v160 offset:17408
	ds_read_b128 v[208:211], v160 offset:18432
	ds_read_b128 v[212:215], v160 offset:19456
	ds_read_b128 v[216:219], v160 offset:20480
	ds_read_b128 v[220:223], v160 offset:21504
	ds_read_b128 v[224:227], v160 offset:22528
	ds_read_b128 v[228:231], v160 offset:23552
	global_load_lds_dwordx4 v[144:145], off
	s_add_i32 m0, s59, 0x2000
	s_add_u32 s60, s24, 0x40000
	v_lshl_add_u64 v[200:201], s[24:25], 0, v[128:129]
	s_addc_u32 s61, s25, 0
	s_add_i32 s59, s50, s38
	global_load_lds_dwordx4 v[200:201], off
	v_lshl_add_u64 v[232:233], s[60:61], 0, v[132:133]
	s_mov_b32 m0, s59
	v_lshl_add_u64 v[234:235], s[26:27], 0, v[130:131]
	global_load_lds_dwordx4 v[232:233], off
	v_lshl_add_u64 v[232:233], s[60:61], 0, v[128:129]
	s_add_i32 m0, s59, 0x2000
	s_nop 0
	global_load_lds_dwordx4 v[232:233], off
	v_lshl_add_u64 v[232:233], s[26:27], 0, v[134:135]
	s_mov_b32 m0, s21
	s_nop 0
	global_load_lds_dwordx4 v[232:233], off
	s_mov_b32 m0, s41
	s_nop 0
	global_load_lds_dwordx4 v[234:235], off
	s_waitcnt vmcnt(8)
	s_waitcnt lgkmcnt(0)
	s_barrier
; #define PG8_STAGE(bufoff, gbase, voff) do { _Pragma("unroll") for (int _i = 0; _i < 2; ++_i) \
;         __builtin_amdgcn_global_load_lds((const unsigned*)((const char*)(gbase) + (voff)[_i]), (LAS unsigned*)(lds + (bufoff) + ldsw + _i * 8192), 16, 0, 0); } while (0)
; #define PG8_LDA(dst, b, h) do { _Pragma("unroll") for (int m = 0; m < 4; ++m) _Pragma("unroll") for (int k = 0; k < 2; ++k) dst[m][k] = *(const LAS bf16x8*)(lds + PG8_SA(b, h) + aoff + m * 2048 + k * 1024); } while (0)
; #define PG8_LDB(dst, b, h) do { _Pragma("unroll") for (int n = 0; n < 2; ++n) _Pragma("unroll") for (int k = 0; k < 2; ++k) dst[n][k] = *(const LAS bf16x8*)(lds + PG8_SB(b, h) + boff + n * 2048 + k * 1024); } while (0)
; #define PG8_MMA(ai, bj, At, Bt) do { __builtin_amdgcn_s_setprio(1); _Pragma("unroll") for (int m = 0; m < 4; ++m) _Pragma("unroll") for (int n = 0; n < 2; ++n) _Pragma("unroll") for (int k = 0; k < 2; ++k) \
;         acc[ai][bj][m][n] = __builtin_amdgcn_mfma_f32_16x16x32_bf16(Bt[n][k], At[m][k], acc[ai][bj][m][n], 0, 0, 0); __builtin_amdgcn_s_setprio(0); } while (0)
; #define PG8_WAIT_V(n) asm volatile("s_waitcnt vmcnt(" #n ")" ::: "memory")
; #define PG8_WAIT_L(n) asm volatile("s_waitcnt lgkmcnt(" #n ")" ::: "memory")
; #define PG8_BAR __builtin_amdgcn_s_barrier()
; #define PG8_SCHED __builtin_amdgcn_sched_barrier(0)
; template <class Epi, class Sched, bool ALIGN_EPI>
; DI void gemm_phase(LAS unsigned char* lds, const Gemm g, const Sched& S, const Epi& E) {
;     ...
;             PG8_WAIT_V(8); PG8_WAIT_L(0); PG8_BAR; PG8_MMA(0, 0, At, B0); PG8_MMA(0, 1, At, B1); PG8_BAR; PG8_SCHED;
;             PG8_LDA(At, 0, 1); PG8_STAGE(PG8_SB(0, 0), b2, voffB); PG8_STAGE(PG8_SB(0, 1), b2 + hstepB, voffB); PG8_STAGE(PG8_SA(0, 0), a2, voffA);
;             PG8_WAIT_V(8); PG8_WAIT_L(0); PG8_BAR; PG8_MMA(1, 0, At, B0); PG8_MMA(1, 1, At, B1); PG8_BAR; PG8_SCHED;
;             PG8_LDB(B0, 1, 0); PG8_LDB(B1, 1, 1); PG8_SCHED; PG8_LDA(At, 1, 0); PG8_STAGE(PG8_SA(0, 1), a2 + hstepA, voffA);
;             PG8_WAIT_V(8); PG8_WAIT_L(0); PG8_BAR; PG8_MMA(0, 0, At, B0); PG8_MMA(0, 1, At, B1); PG8_BAR; PG8_SCHED;
	s_setprio 1
	s_waitcnt lgkmcnt(0)
	v_mfma_f32_16x16x32_bf16 v[60:63], v[164:167], v[196:199], v[60:63]
	v_mfma_f32_16x16x32_bf16 v[56:59], v[172:175], v[196:199], v[56:59]
	v_mfma_f32_16x16x32_bf16 v[44:47], v[164:167], v[208:211], v[44:47]
	v_mfma_f32_16x16x32_bf16 v[40:43], v[172:175], v[208:211], v[40:43]
	v_mfma_f32_16x16x32_bf16 v[28:31], v[164:167], v[216:219], v[28:31]
	v_mfma_f32_16x16x32_bf16 v[24:27], v[172:175], v[216:219], v[24:27]
	v_mfma_f32_16x16x32_bf16 v[12:15], v[164:167], v[224:227], v[12:15]
	v_mfma_f32_16x16x32_bf16 v[8:11], v[172:175], v[224:227], v[8:11]
	v_mfma_f32_16x16x32_bf16 v[60:63], v[168:171], v[204:207], v[60:63]
	v_mfma_f32_16x16x32_bf16 v[56:59], v[176:179], v[204:207], v[56:59]
	v_mfma_f32_16x16x32_bf16 v[44:47], v[168:171], v[212:215], v[44:47]
	v_mfma_f32_16x16x32_bf16 v[40:43], v[176:179], v[212:215], v[40:43]
	v_mfma_f32_16x16x32_bf16 v[28:31], v[168:171], v[220:223], v[28:31]
	v_mfma_f32_16x16x32_bf16 v[24:27], v[176:179], v[220:223], v[24:27]
	v_mfma_f32_16x16x32_bf16 v[12:15], v[168:171], v[228:231], v[12:15]
	v_mfma_f32_16x16x32_bf16 v[8:11], v[176:179], v[228:231], v[8:11]
	v_mfma_f32_16x16x32_bf16 v[52:55], v[180:183], v[196:199], v[52:55]
	v_mfma_f32_16x16x32_bf16 v[48:51], v[188:191], v[196:199], v[48:51]
	v_mfma_f32_16x16x32_bf16 v[36:39], v[180:183], v[208:211], v[36:39]
	v_mfma_f32_16x16x32_bf16 v[32:35], v[188:191], v[208:211], v[32:35]
	v_mfma_f32_16x16x32_bf16 v[20:23], v[180:183], v[216:219], v[20:23]
	v_mfma_f32_16x16x32_bf16 v[16:19], v[188:191], v[216:219], v[16:19]
	v_mfma_f32_16x16x32_bf16 v[4:7], v[180:183], v[224:227], v[4:7]
	v_mfma_f32_16x16x32_bf16 v[0:3], v[188:191], v[224:227], v[0:3]
	v_mfma_f32_16x16x32_bf16 v[52:55], v[184:187], v[204:207], v[52:55]
	v_mfma_f32_16x16x32_bf16 v[48:51], v[192:195], v[204:207], v[48:51]
	v_mfma_f32_16x16x32_bf16 v[36:39], v[184:187], v[212:215], v[36:39]
	v_mfma_f32_16x16x32_bf16 v[32:35], v[192:195], v[212:215], v[32:35]
	v_mfma_f32_16x16x32_bf16 v[20:23], v[184:187], v[220:223], v[20:23]
	v_mfma_f32_16x16x32_bf16 v[16:19], v[192:195], v[220:223], v[16:19]
	v_mfma_f32_16x16x32_bf16 v[4:7], v[184:187], v[228:231], v[4:7]
	v_mfma_f32_16x16x32_bf16 v[0:3], v[192:195], v[228:231], v[0:3]
	s_setprio 0
	s_barrier
	ds_read_b128 v[164:167], v161
	ds_read_b128 v[168:171], v161 offset:1024
	ds_read_b128 v[172:175], v161 offset:2048
	ds_read_b128 v[176:179], v161 offset:3072
	ds_read_b128 v[180:183], v162
	ds_read_b128 v[184:187], v162 offset:1024
	ds_read_b128 v[188:191], v162 offset:2048
	ds_read_b128 v[192:195], v162 offset:3072
	s_add_u32 s26, s26, 0x40000
	s_addc_u32 s27, s27, 0
	s_mov_b32 m0, s42
	v_lshl_add_u64 v[236:237], s[26:27], 0, v[134:135]
	ds_read_b128 v[196:199], v160 offset:32768
	ds_read_b128 v[204:207], v160 offset:33792
	ds_read_b128 v[208:211], v160 offset:34816
	ds_read_b128 v[212:215], v160 offset:35840
	ds_read_b128 v[216:219], v160 offset:36864
	ds_read_b128 v[220:223], v160 offset:37888
	ds_read_b128 v[224:227], v160 offset:38912
	ds_read_b128 v[228:231], v160 offset:39936
	global_load_lds_dwordx4 v[236:237], off
	v_lshl_add_u64 v[236:237], s[26:27], 0, v[130:131]
	s_mov_b32 m0, s43
	s_nop 0
	global_load_lds_dwordx4 v[236:237], off
	s_waitcnt vmcnt(8)
	s_waitcnt lgkmcnt(0)
	s_barrier
	s_setprio 1
	s_waitcnt lgkmcnt(0)
	v_mfma_f32_16x16x32_bf16 v[124:127], v[164:167], v[196:199], v[124:127]
	v_mfma_f32_16x16x32_bf16 v[120:123], v[172:175], v[196:199], v[120:123]
	v_mfma_f32_16x16x32_bf16 v[108:111], v[164:167], v[208:211], v[108:111]
	v_mfma_f32_16x16x32_bf16 v[104:107], v[172:175], v[208:211], v[104:107]
	v_mfma_f32_16x16x32_bf16 v[92:95], v[164:167], v[216:219], v[92:95]
	v_mfma_f32_16x16x32_bf16 v[88:91], v[172:175], v[216:219], v[88:91]
	v_mfma_f32_16x16x32_bf16 v[76:79], v[164:167], v[224:227], v[76:79]
	v_mfma_f32_16x16x32_bf16 v[72:75], v[172:175], v[224:227], v[72:75]
	v_mfma_f32_16x16x32_bf16 v[124:127], v[168:171], v[204:207], v[124:127]
	v_mfma_f32_16x16x32_bf16 v[120:123], v[176:179], v[204:207], v[120:123]
	v_mfma_f32_16x16x32_bf16 v[108:111], v[168:171], v[212:215], v[108:111]
	v_mfma_f32_16x16x32_bf16 v[104:107], v[176:179], v[212:215], v[104:107]
	v_mfma_f32_16x16x32_bf16 v[92:95], v[168:171], v[220:223], v[92:95]
	v_mfma_f32_16x16x32_bf16 v[88:91], v[176:179], v[220:223], v[88:91]
	v_mfma_f32_16x16x32_bf16 v[76:79], v[168:171], v[228:231], v[76:79]
	v_mfma_f32_16x16x32_bf16 v[72:75], v[176:179], v[228:231], v[72:75]
	v_mfma_f32_16x16x32_bf16 v[116:119], v[180:183], v[196:199], v[116:119]
	v_mfma_f32_16x16x32_bf16 v[112:115], v[188:191], v[196:199], v[112:115]
	v_mfma_f32_16x16x32_bf16 v[100:103], v[180:183], v[208:211], v[100:103]
	v_mfma_f32_16x16x32_bf16 v[96:99], v[188:191], v[208:211], v[96:99]
	v_mfma_f32_16x16x32_bf16 v[84:87], v[180:183], v[216:219], v[84:87]
	v_mfma_f32_16x16x32_bf16 v[80:83], v[188:191], v[216:219], v[80:83]
	v_mfma_f32_16x16x32_bf16 v[68:71], v[180:183], v[224:227], v[68:71]
	v_mfma_f32_16x16x32_bf16 v[64:67], v[188:191], v[224:227], v[64:67]
	v_mfma_f32_16x16x32_bf16 v[116:119], v[184:187], v[204:207], v[116:119]
	v_mfma_f32_16x16x32_bf16 v[112:115], v[192:195], v[204:207], v[112:115]
	v_mfma_f32_16x16x32_bf16 v[100:103], v[184:187], v[212:215], v[100:103]
	v_mfma_f32_16x16x32_bf16 v[96:99], v[192:195], v[212:215], v[96:99]
	v_mfma_f32_16x16x32_bf16 v[84:87], v[184:187], v[220:223], v[84:87]
	v_mfma_f32_16x16x32_bf16 v[80:83], v[192:195], v[220:223], v[80:83]
	v_mfma_f32_16x16x32_bf16 v[68:71], v[184:187], v[228:231], v[68:71]
	v_mfma_f32_16x16x32_bf16 v[64:67], v[192:195], v[228:231], v[64:67]
	s_setprio 0
	s_barrier
; #define PG8_STAGE(bufoff, gbase, voff) do { _Pragma("unroll") for (int _i = 0; _i < 2; ++_i) \
;         __builtin_amdgcn_global_load_lds((const unsigned*)((const char*)(gbase) + (voff)[_i]), (LAS unsigned*)(lds + (bufoff) + ldsw + _i * 8192), 16, 0, 0); } while (0)
; #define PG8_LDA(dst, b, h) do { _Pragma("unroll") for (int m = 0; m < 4; ++m) _Pragma("unroll") for (int k = 0; k < 2; ++k) dst[m][k] = *(const LAS bf16x8*)(lds + PG8_SA(b, h) + aoff + m * 2048 + k * 1024); } while (0)
; #define PG8_MMA(ai, bj, At, Bt) do { __builtin_amdgcn_s_setprio(1); _Pragma("unroll") for (int m = 0; m < 4; ++m) _Pragma("unroll") for (int n = 0; n < 2; ++n) _Pragma("unroll") for (int k = 0; k < 2; ++k) \
;         acc[ai][bj][m][n] = __builtin_amdgcn_mfma_f32_16x16x32_bf16(Bt[n][k], At[m][k], acc[ai][bj][m][n], 0, 0, 0); __builtin_amdgcn_s_setprio(0); } while (0)
; #define PG8_WAIT_V(n) asm volatile("s_waitcnt vmcnt(" #n ")" ::: "memory")
; #define PG8_WAIT_L(n) asm volatile("s_waitcnt lgkmcnt(" #n ")" ::: "memory")
; #define PG8_BAR __builtin_amdgcn_s_barrier()
; #define PG8_SCHED __builtin_amdgcn_sched_barrier(0)
; template <class Epi, class Sched, bool ALIGN_EPI>
; DI void gemm_phase(LAS unsigned char* lds, const Gemm g, const Sched& S, const Epi& E) {
;     ...
;             PG8_LDA(At, 1, 1); PG8_STAGE(PG8_SB(1, 0), b3, voffB); PG8_STAGE(PG8_SB(1, 1), b3 + hstepB, voffB); PG8_STAGE(PG8_SA(1, 0), a3, voffA);
;             PG8_WAIT_V(8); PG8_WAIT_L(0); PG8_BAR; PG8_MMA(1, 0, At, B0); PG8_MMA(1, 1, At, B1); PG8_BAR; PG8_SCHED;
;         }
;         if constexpr (ALIGN_EPI) { if (wr == 0) PG8_BAR; }
;         if constexpr (!Epi::AFTER_DRAIN) E(acc, cur, wr, wc, fr, fq);
;         if (!has_next) break;
	s_add_i32 s26, s52, s38
	v_lshl_add_u64 v[144:145], v[144:145], 0, s[8:9]
	s_mov_b32 m0, s26
	ds_read_b128 v[196:199], v160 offset:49152
	ds_read_b128 v[204:207], v160 offset:50176
	ds_read_b128 v[208:211], v160 offset:51200
	ds_read_b128 v[212:215], v160 offset:52224
	ds_read_b128 v[216:219], v160 offset:53248
	ds_read_b128 v[220:223], v160 offset:54272
	ds_read_b128 v[224:227], v160 offset:55296
	ds_read_b128 v[228:231], v160 offset:56320
	global_load_lds_dwordx4 v[144:145], off
	s_add_i32 m0, s26, 0x2000
	s_add_u32 s24, s24, 0x40080
	v_lshl_add_u64 v[144:145], v[200:201], 0, s[8:9]
	s_addc_u32 s25, s25, 0
	s_add_i32 s26, s53, s38
	global_load_lds_dwordx4 v[144:145], off
	v_lshl_add_u64 v[144:145], s[24:25], 0, v[132:133]
	s_mov_b32 m0, s26
	s_nop 0
	global_load_lds_dwordx4 v[144:145], off
	v_lshl_add_u64 v[144:145], s[24:25], 0, v[128:129]
	s_add_i32 m0, s26, 0x2000
	s_nop 0
	global_load_lds_dwordx4 v[144:145], off
	v_lshl_add_u64 v[144:145], v[232:233], 0, s[8:9]
	s_mov_b32 m0, s45
	s_nop 0
	global_load_lds_dwordx4 v[144:145], off
	v_lshl_add_u64 v[144:145], v[234:235], 0, s[8:9]
	s_mov_b32 m0, s46
	s_nop 0
	global_load_lds_dwordx4 v[144:145], off
	s_waitcnt vmcnt(8)
	s_waitcnt lgkmcnt(0)
	s_barrier
	s_setprio 1
	s_waitcnt lgkmcnt(0)
	v_mfma_f32_16x16x32_bf16 v[60:63], v[164:167], v[196:199], v[60:63]
	v_mfma_f32_16x16x32_bf16 v[56:59], v[172:175], v[196:199], v[56:59]
	v_mfma_f32_16x16x32_bf16 v[44:47], v[164:167], v[208:211], v[44:47]
	v_mfma_f32_16x16x32_bf16 v[40:43], v[172:175], v[208:211], v[40:43]
	v_mfma_f32_16x16x32_bf16 v[28:31], v[164:167], v[216:219], v[28:31]
	v_mfma_f32_16x16x32_bf16 v[24:27], v[172:175], v[216:219], v[24:27]
	v_mfma_f32_16x16x32_bf16 v[12:15], v[164:167], v[224:227], v[12:15]
	v_mfma_f32_16x16x32_bf16 v[8:11], v[172:175], v[224:227], v[8:11]
	v_mfma_f32_16x16x32_bf16 v[60:63], v[168:171], v[204:207], v[60:63]
	v_mfma_f32_16x16x32_bf16 v[56:59], v[176:179], v[204:207], v[56:59]
	v_mfma_f32_16x16x32_bf16 v[44:47], v[168:171], v[212:215], v[44:47]
	v_mfma_f32_16x16x32_bf16 v[40:43], v[176:179], v[212:215], v[40:43]
	v_mfma_f32_16x16x32_bf16 v[28:31], v[168:171], v[220:223], v[28:31]
	v_mfma_f32_16x16x32_bf16 v[24:27], v[176:179], v[220:223], v[24:27]
	v_mfma_f32_16x16x32_bf16 v[12:15], v[168:171], v[228:231], v[12:15]
	v_mfma_f32_16x16x32_bf16 v[8:11], v[176:179], v[228:231], v[8:11]
	v_mfma_f32_16x16x32_bf16 v[52:55], v[180:183], v[196:199], v[52:55]
	v_mfma_f32_16x16x32_bf16 v[48:51], v[188:191], v[196:199], v[48:51]
	v_mfma_f32_16x16x32_bf16 v[36:39], v[180:183], v[208:211], v[36:39]
	v_mfma_f32_16x16x32_bf16 v[32:35], v[188:191], v[208:211], v[32:35]
	v_mfma_f32_16x16x32_bf16 v[20:23], v[180:183], v[216:219], v[20:23]
	v_mfma_f32_16x16x32_bf16 v[16:19], v[188:191], v[216:219], v[16:19]
	v_mfma_f32_16x16x32_bf16 v[4:7], v[180:183], v[224:227], v[4:7]
	v_mfma_f32_16x16x32_bf16 v[0:3], v[188:191], v[224:227], v[0:3]
	v_mfma_f32_16x16x32_bf16 v[52:55], v[184:187], v[204:207], v[52:55]
	v_mfma_f32_16x16x32_bf16 v[48:51], v[192:195], v[204:207], v[48:51]
	v_mfma_f32_16x16x32_bf16 v[36:39], v[184:187], v[212:215], v[36:39]
	v_mfma_f32_16x16x32_bf16 v[32:35], v[192:195], v[212:215], v[32:35]
	v_mfma_f32_16x16x32_bf16 v[20:23], v[184:187], v[220:223], v[20:23]
	v_mfma_f32_16x16x32_bf16 v[16:19], v[192:195], v[220:223], v[16:19]
	v_mfma_f32_16x16x32_bf16 v[4:7], v[184:187], v[228:231], v[4:7]
	v_mfma_f32_16x16x32_bf16 v[0:3], v[192:195], v[228:231], v[0:3]
	s_setprio 0
	s_barrier
	s_add_i32 s58, s58, 2
	s_add_u32 s22, s22, 0x100
	s_addc_u32 s23, s23, 0
	s_add_u32 s56, s56, 0x100
	s_addc_u32 s57, s57, 0
	s_cmp_gt_u32 s58, 13
	s_cbranch_scc0 .LBB0_2424
	s_and_b64 vcc, exec, s[10:11]
	s_cbranch_vccz .LBB0_2427
	s_barrier

; #define PG8_STAGE(bufoff, gbase, voff) do { _Pragma("unroll") for (int _i = 0; _i < 2; ++_i) \
;         __builtin_amdgcn_global_load_lds((const unsigned*)((const char*)(gbase) + (voff)[_i]), (LAS unsigned*)(lds + (bufoff) + ldsw + _i * 8192), 16, 0, 0); } while (0)
; #define PG8_LDA(dst, b, h) do { _Pragma("unroll") for (int m = 0; m < 4; ++m) _Pragma("unroll") for (int k = 0; k < 2; ++k) dst[m][k] = *(const LAS bf16x8*)(lds + PG8_SA(b, h) + aoff + m * 2048 + k * 1024); } while (0)
; #define PG8_LDB(dst, b, h) do { _Pragma("unroll") for (int n = 0; n < 2; ++n) _Pragma("unroll") for (int k = 0; k < 2; ++k) dst[n][k] = *(const LAS bf16x8*)(lds + PG8_SB(b, h) + boff + n * 2048 + k * 1024); } while (0)
; #define PG8_MMA(ai, bj, At, Bt) do { __builtin_amdgcn_s_setprio(1); _Pragma("unroll") for (int m = 0; m < 4; ++m) _Pragma("unroll") for (int n = 0; n < 2; ++n) _Pragma("unroll") for (int k = 0; k < 2; ++k) \
;         acc[ai][bj][m][n] = __builtin_amdgcn_mfma_f32_16x16x32_bf16(Bt[n][k], At[m][k], acc[ai][bj][m][n], 0, 0, 0); __builtin_amdgcn_s_setprio(0); } while (0)
; #define PG8_WAIT_V(n) asm volatile("s_waitcnt vmcnt(" #n ")" ::: "memory")
; #define PG8_WAIT_L(n) asm volatile("s_waitcnt lgkmcnt(" #n ")" ::: "memory")
; #define PG8_BAR __builtin_amdgcn_s_barrier()
; #define PG8_SCHED __builtin_amdgcn_sched_barrier(0)
; template <class Epi, class Sched, bool ALIGN_EPI>
; DI void gemm_phase(LAS unsigned char* lds, const Gemm g, const Sched& S, const Epi& E) {
;     ...
;         for (int t = 0; t < nt; t += 2) {
;             const bool last = (t == nt - 2);
;             const char* a1 = cA + (size_t)(t + 1) * kstep;
;             const char* a2 = last ? nA : cA + (size_t)(t + 2) * kstep; const char* b2 = last ? nB : cB + (size_t)(t + 2) * kstep;
;             const char* a3 = a2 + kstep; const char* b3 = b2 + kstep;
;             PG8_LDB(B0, 0, 0); PG8_LDB(B1, 0, 1); PG8_SCHED; PG8_LDA(At, 0, 0); PG8_STAGE(PG8_SA(1, 1), a1 + hstepA, voffA);
;             PG8_WAIT_V(8); PG8_WAIT_L(0); PG8_BAR; PG8_MMA(0, 0, At, B0); PG8_MMA(0, 1, At, B1); PG8_BAR; PG8_SCHED;
;             PG8_LDA(At, 0, 1); PG8_STAGE(PG8_SB(0, 0), b2, voffB); PG8_STAGE(PG8_SB(0, 1), b2 + hstepB, voffB); PG8_STAGE(PG8_SA(0, 0), a2, voffA);
;             PG8_WAIT_V(8); PG8_WAIT_L(0); PG8_BAR; PG8_MMA(1, 0, At, B0); PG8_MMA(1, 1, At, B1); PG8_BAR; PG8_SCHED;
.LBB0_2451:
	s_add_u32 s45, s28, s44
	s_addc_u32 s50, s29, 0
	s_add_u32 s48, s45, 0x100
	s_addc_u32 s49, s50, 0
	s_and_b64 s[46:47], s[42:43], exec
	s_cselect_b32 s47, s27, s49
	s_cselect_b32 s46, s77, s48
	s_add_u32 s44, s22, s44
	s_addc_u32 s48, s23, 0
	s_add_u32 s44, s44, 0x100
	s_addc_u32 s48, s48, 0
	s_and_b64 s[42:43], s[42:43], exec
	s_cselect_b32 s49, s25, s48
	s_cselect_b32 s48, s78, s44
	s_add_u32 s52, s45, 0x10080
	ds_read_b128 v[158:161], v142
	ds_read_b128 v[162:165], v142 offset:1024
	ds_read_b128 v[166:169], v142 offset:2048
	ds_read_b128 v[170:173], v142 offset:3072
	ds_read_b128 v[174:177], v143
	ds_read_b128 v[178:181], v143 offset:1024
	ds_read_b128 v[182:185], v143 offset:2048
	ds_read_b128 v[186:189], v143 offset:3072
	s_addc_u32 s53, s50, 0
	s_add_i32 s84, s68, s59
	s_add_i32 m0, s21, 0xc000
	s_add_i32 s89, s21, 0xe000
	s_add_i32 s81, s84, 0x2000
	s_add_u32 s50, s48, 0x10000
	s_addc_u32 s51, s49, 0
	s_add_i32 s83, s69, s59
	s_add_i32 s82, s83, 0x2000
	s_add_u32 s44, s46, 0x10000
	s_addc_u32 s45, s47, 0
	s_add_i32 s80, s75, s59
	s_add_i32 s79, s80, 0x2000
	s_add_u32 s42, s48, 0x10080
	s_addc_u32 s43, s49, 0
	s_add_i32 s88, s76, s59
	s_add_i32 s85, s88, 0x2000
	v_lshl_add_u64 v[224:225], s[52:53], 0, v[128:129]
	ds_read_b128 v[190:193], v144
	ds_read_b128 v[194:197], v144 offset:1024
	ds_read_b128 v[198:201], v144 offset:2048
	ds_read_b128 v[204:207], v144 offset:3072
	ds_read_b128 v[208:211], v144 offset:4096
	ds_read_b128 v[212:215], v144 offset:5120
	ds_read_b128 v[216:219], v144 offset:6144
	ds_read_b128 v[220:223], v144 offset:7168
	global_load_lds_dwordx4 v[224:225], off
	v_lshl_add_u64 v[224:225], s[52:53], 0, v[132:133]
	s_mov_b32 m0, s89
	s_nop 0
	global_load_lds_dwordx4 v[224:225], off
	s_waitcnt vmcnt(8)
	s_waitcnt lgkmcnt(0)
	s_barrier
	s_setprio 1
	s_waitcnt lgkmcnt(0)
	v_mfma_f32_16x16x32_bf16 v[124:127], v[158:161], v[190:193], v[124:127]
	v_mfma_f32_16x16x32_bf16 v[120:123], v[166:169], v[190:193], v[120:123]
	v_mfma_f32_16x16x32_bf16 v[116:119], v[158:161], v[198:201], v[116:119]
	v_mfma_f32_16x16x32_bf16 v[112:115], v[166:169], v[198:201], v[112:115]
	v_mfma_f32_16x16x32_bf16 v[100:103], v[158:161], v[208:211], v[100:103]
	v_mfma_f32_16x16x32_bf16 v[96:99], v[166:169], v[208:211], v[96:99]
	v_mfma_f32_16x16x32_bf16 v[84:87], v[158:161], v[216:219], v[84:87]
	v_mfma_f32_16x16x32_bf16 v[80:83], v[166:169], v[216:219], v[80:83]
	v_mfma_f32_16x16x32_bf16 v[124:127], v[162:165], v[194:197], v[124:127]
	v_mfma_f32_16x16x32_bf16 v[120:123], v[170:173], v[194:197], v[120:123]
	v_mfma_f32_16x16x32_bf16 v[116:119], v[162:165], v[204:207], v[116:119]
	v_mfma_f32_16x16x32_bf16 v[112:115], v[170:173], v[204:207], v[112:115]
	v_mfma_f32_16x16x32_bf16 v[100:103], v[162:165], v[212:215], v[100:103]
	v_mfma_f32_16x16x32_bf16 v[96:99], v[170:173], v[212:215], v[96:99]
	v_mfma_f32_16x16x32_bf16 v[84:87], v[162:165], v[220:223], v[84:87]
	v_mfma_f32_16x16x32_bf16 v[80:83], v[170:173], v[220:223], v[80:83]
	v_mfma_f32_16x16x32_bf16 v[108:111], v[174:177], v[190:193], v[108:111]
	v_mfma_f32_16x16x32_bf16 v[104:107], v[182:185], v[190:193], v[104:107]
	v_mfma_f32_16x16x32_bf16 v[92:95], v[174:177], v[198:201], v[92:95]
	v_mfma_f32_16x16x32_bf16 v[88:91], v[182:185], v[198:201], v[88:91]
	v_mfma_f32_16x16x32_bf16 v[76:79], v[174:177], v[208:211], v[76:79]
	v_mfma_f32_16x16x32_bf16 v[72:75], v[182:185], v[208:211], v[72:75]
	v_mfma_f32_16x16x32_bf16 v[68:71], v[174:177], v[216:219], v[68:71]
	v_mfma_f32_16x16x32_bf16 v[64:67], v[182:185], v[216:219], v[64:67]
	v_mfma_f32_16x16x32_bf16 v[108:111], v[178:181], v[194:197], v[108:111]
	v_mfma_f32_16x16x32_bf16 v[104:107], v[186:189], v[194:197], v[104:107]
	v_mfma_f32_16x16x32_bf16 v[92:95], v[178:181], v[204:207], v[92:95]
	v_mfma_f32_16x16x32_bf16 v[88:91], v[186:189], v[204:207], v[88:91]
	v_mfma_f32_16x16x32_bf16 v[76:79], v[178:181], v[212:215], v[76:79]
	v_mfma_f32_16x16x32_bf16 v[72:75], v[186:189], v[212:215], v[72:75]
	v_mfma_f32_16x16x32_bf16 v[68:71], v[178:181], v[220:223], v[68:71]
	v_mfma_f32_16x16x32_bf16 v[64:67], v[186:189], v[220:223], v[64:67]
	s_setprio 0
	s_barrier
	s_mov_b32 m0, s84
	v_lshl_add_u64 v[224:225], s[48:49], 0, v[130:131]
	ds_read_b128 v[190:193], v144 offset:16384
	ds_read_b128 v[194:197], v144 offset:17408
	ds_read_b128 v[198:201], v144 offset:18432
	ds_read_b128 v[204:207], v144 offset:19456
	ds_read_b128 v[208:211], v144 offset:20480
	ds_read_b128 v[212:215], v144 offset:21504
	ds_read_b128 v[216:219], v144 offset:22528
	ds_read_b128 v[220:223], v144 offset:23552
	global_load_lds_dwordx4 v[224:225], off
	v_lshl_add_u64 v[226:227], s[48:49], 0, v[134:135]
	s_mov_b32 m0, s81
	v_lshl_add_u64 v[228:229], s[50:51], 0, v[130:131]
	global_load_lds_dwordx4 v[226:227], off
	s_mov_b32 m0, s83
	v_lshl_add_u64 v[230:231], s[46:47], 0, v[132:133]
	global_load_lds_dwordx4 v[228:229], off
	v_lshl_add_u64 v[228:229], s[50:51], 0, v[134:135]
	s_mov_b32 m0, s82
	s_nop 0
	global_load_lds_dwordx4 v[228:229], off
	v_lshl_add_u64 v[228:229], s[46:47], 0, v[128:129]
	s_mov_b32 m0, s21
	s_nop 0
	global_load_lds_dwordx4 v[228:229], off
	s_mov_b32 m0, s60
	s_nop 0
	global_load_lds_dwordx4 v[230:231], off
	s_waitcnt vmcnt(8)
	s_waitcnt lgkmcnt(0)
	s_barrier
; #define PG8_STAGE(bufoff, gbase, voff) do { _Pragma("unroll") for (int _i = 0; _i < 2; ++_i) \
;         __builtin_amdgcn_global_load_lds((const unsigned*)((const char*)(gbase) + (voff)[_i]), (LAS unsigned*)(lds + (bufoff) + ldsw + _i * 8192), 16, 0, 0); } while (0)
; #define PG8_LDA(dst, b, h) do { _Pragma("unroll") for (int m = 0; m < 4; ++m) _Pragma("unroll") for (int k = 0; k < 2; ++k) dst[m][k] = *(const LAS bf16x8*)(lds + PG8_SA(b, h) + aoff + m * 2048 + k * 1024); } while (0)
; #define PG8_LDB(dst, b, h) do { _Pragma("unroll") for (int n = 0; n < 2; ++n) _Pragma("unroll") for (int k = 0; k < 2; ++k) dst[n][k] = *(const LAS bf16x8*)(lds + PG8_SB(b, h) + boff + n * 2048 + k * 1024); } while (0)
; #define PG8_MMA(ai, bj, At, Bt) do { __builtin_amdgcn_s_setprio(1); _Pragma("unroll") for (int m = 0; m < 4; ++m) _Pragma("unroll") for (int n = 0; n < 2; ++n) _Pragma("unroll") for (int k = 0; k < 2; ++k) \
;         acc[ai][bj][m][n] = __builtin_amdgcn_mfma_f32_16x16x32_bf16(Bt[n][k], At[m][k], acc[ai][bj][m][n], 0, 0, 0); __builtin_amdgcn_s_setprio(0); } while (0)
; #define PG8_WAIT_V(n) asm volatile("s_waitcnt vmcnt(" #n ")" ::: "memory")
; #define PG8_WAIT_L(n) asm volatile("s_waitcnt lgkmcnt(" #n ")" ::: "memory")
; #define PG8_BAR __builtin_amdgcn_s_barrier()
; #define PG8_SCHED __builtin_amdgcn_sched_barrier(0)
; template <class Epi, class Sched, bool ALIGN_EPI>
; DI void gemm_phase(LAS unsigned char* lds, const Gemm g, const Sched& S, const Epi& E) {
;     ...
;             PG8_WAIT_V(8); PG8_WAIT_L(0); PG8_BAR; PG8_MMA(0, 0, At, B0); PG8_MMA(0, 1, At, B1); PG8_BAR; PG8_SCHED;
;             PG8_LDA(At, 0, 1); PG8_STAGE(PG8_SB(0, 0), b2, voffB); PG8_STAGE(PG8_SB(0, 1), b2 + hstepB, voffB); PG8_STAGE(PG8_SA(0, 0), a2, voffA);
;             PG8_WAIT_V(8); PG8_WAIT_L(0); PG8_BAR; PG8_MMA(1, 0, At, B0); PG8_MMA(1, 1, At, B1); PG8_BAR; PG8_SCHED;
;             PG8_LDB(B0, 1, 0); PG8_LDB(B1, 1, 1); PG8_SCHED; PG8_LDA(At, 1, 0); PG8_STAGE(PG8_SA(0, 1), a2 + hstepA, voffA);
;             PG8_WAIT_V(8); PG8_WAIT_L(0); PG8_BAR; PG8_MMA(0, 0, At, B0); PG8_MMA(0, 1, At, B1); PG8_BAR; PG8_SCHED;
	s_setprio 1
	s_waitcnt lgkmcnt(0)
	v_mfma_f32_16x16x32_bf16 v[60:63], v[158:161], v[190:193], v[60:63]
	v_mfma_f32_16x16x32_bf16 v[56:59], v[166:169], v[190:193], v[56:59]
	v_mfma_f32_16x16x32_bf16 v[52:55], v[158:161], v[198:201], v[52:55]
	v_mfma_f32_16x16x32_bf16 v[48:51], v[166:169], v[198:201], v[48:51]
	v_mfma_f32_16x16x32_bf16 v[36:39], v[158:161], v[208:211], v[36:39]
	v_mfma_f32_16x16x32_bf16 v[32:35], v[166:169], v[208:211], v[32:35]
	v_mfma_f32_16x16x32_bf16 v[20:23], v[158:161], v[216:219], v[20:23]
	v_mfma_f32_16x16x32_bf16 v[16:19], v[166:169], v[216:219], v[16:19]
	v_mfma_f32_16x16x32_bf16 v[60:63], v[162:165], v[194:197], v[60:63]
	v_mfma_f32_16x16x32_bf16 v[56:59], v[170:173], v[194:197], v[56:59]
	v_mfma_f32_16x16x32_bf16 v[52:55], v[162:165], v[204:207], v[52:55]
	v_mfma_f32_16x16x32_bf16 v[48:51], v[170:173], v[204:207], v[48:51]
	v_mfma_f32_16x16x32_bf16 v[36:39], v[162:165], v[212:215], v[36:39]
	v_mfma_f32_16x16x32_bf16 v[32:35], v[170:173], v[212:215], v[32:35]
	v_mfma_f32_16x16x32_bf16 v[20:23], v[162:165], v[220:223], v[20:23]
	v_mfma_f32_16x16x32_bf16 v[16:19], v[170:173], v[220:223], v[16:19]
	v_mfma_f32_16x16x32_bf16 v[44:47], v[174:177], v[190:193], v[44:47]
	v_mfma_f32_16x16x32_bf16 v[40:43], v[182:185], v[190:193], v[40:43]
	v_mfma_f32_16x16x32_bf16 v[28:31], v[174:177], v[198:201], v[28:31]
	v_mfma_f32_16x16x32_bf16 v[24:27], v[182:185], v[198:201], v[24:27]
	v_mfma_f32_16x16x32_bf16 v[12:15], v[174:177], v[208:211], v[12:15]
	v_mfma_f32_16x16x32_bf16 v[8:11], v[182:185], v[208:211], v[8:11]
	v_mfma_f32_16x16x32_bf16 v[4:7], v[174:177], v[216:219], v[4:7]
	v_mfma_f32_16x16x32_bf16 v[0:3], v[182:185], v[216:219], v[0:3]
	v_mfma_f32_16x16x32_bf16 v[44:47], v[178:181], v[194:197], v[44:47]
	v_mfma_f32_16x16x32_bf16 v[40:43], v[186:189], v[194:197], v[40:43]
	v_mfma_f32_16x16x32_bf16 v[28:31], v[178:181], v[204:207], v[28:31]
	v_mfma_f32_16x16x32_bf16 v[24:27], v[186:189], v[204:207], v[24:27]
	v_mfma_f32_16x16x32_bf16 v[12:15], v[178:181], v[212:215], v[12:15]
	v_mfma_f32_16x16x32_bf16 v[8:11], v[186:189], v[212:215], v[8:11]
	v_mfma_f32_16x16x32_bf16 v[4:7], v[178:181], v[220:223], v[4:7]
	v_mfma_f32_16x16x32_bf16 v[0:3], v[186:189], v[220:223], v[0:3]
	s_setprio 0
	s_barrier
	ds_read_b128 v[158:161], v145
	ds_read_b128 v[162:165], v145 offset:1024
	ds_read_b128 v[166:169], v145 offset:2048
	ds_read_b128 v[170:173], v145 offset:3072
	ds_read_b128 v[174:177], v156
	ds_read_b128 v[178:181], v156 offset:1024
	ds_read_b128 v[182:185], v156 offset:2048
	ds_read_b128 v[186:189], v156 offset:3072
	s_mov_b32 m0, s61
	v_lshl_add_u64 v[232:233], s[44:45], 0, v[128:129]
	ds_read_b128 v[190:193], v144 offset:32768
	ds_read_b128 v[194:197], v144 offset:33792
	ds_read_b128 v[198:201], v144 offset:34816
	ds_read_b128 v[204:207], v144 offset:35840
	ds_read_b128 v[208:211], v144 offset:36864
	ds_read_b128 v[212:215], v144 offset:37888
	ds_read_b128 v[216:219], v144 offset:38912
	ds_read_b128 v[220:223], v144 offset:39936
	global_load_lds_dwordx4 v[232:233], off
	v_lshl_add_u64 v[232:233], s[44:45], 0, v[132:133]
	s_mov_b32 m0, s62
	s_nop 0
	global_load_lds_dwordx4 v[232:233], off
	s_waitcnt vmcnt(8)
	s_waitcnt lgkmcnt(0)
	s_barrier
	s_setprio 1
	s_waitcnt lgkmcnt(0)
	v_mfma_f32_16x16x32_bf16 v[124:127], v[158:161], v[190:193], v[124:127]
	v_mfma_f32_16x16x32_bf16 v[120:123], v[166:169], v[190:193], v[120:123]
	v_mfma_f32_16x16x32_bf16 v[116:119], v[158:161], v[198:201], v[116:119]
	v_mfma_f32_16x16x32_bf16 v[112:115], v[166:169], v[198:201], v[112:115]
	v_mfma_f32_16x16x32_bf16 v[100:103], v[158:161], v[208:211], v[100:103]
	v_mfma_f32_16x16x32_bf16 v[96:99], v[166:169], v[208:211], v[96:99]
	v_mfma_f32_16x16x32_bf16 v[84:87], v[158:161], v[216:219], v[84:87]
	v_mfma_f32_16x16x32_bf16 v[80:83], v[166:169], v[216:219], v[80:83]
	v_mfma_f32_16x16x32_bf16 v[124:127], v[162:165], v[194:197], v[124:127]
	v_mfma_f32_16x16x32_bf16 v[120:123], v[170:173], v[194:197], v[120:123]
	v_mfma_f32_16x16x32_bf16 v[116:119], v[162:165], v[204:207], v[116:119]
	v_mfma_f32_16x16x32_bf16 v[112:115], v[170:173], v[204:207], v[112:115]
	v_mfma_f32_16x16x32_bf16 v[100:103], v[162:165], v[212:215], v[100:103]
	v_mfma_f32_16x16x32_bf16 v[96:99], v[170:173], v[212:215], v[96:99]
	v_mfma_f32_16x16x32_bf16 v[84:87], v[162:165], v[220:223], v[84:87]
	v_mfma_f32_16x16x32_bf16 v[80:83], v[170:173], v[220:223], v[80:83]
	v_mfma_f32_16x16x32_bf16 v[108:111], v[174:177], v[190:193], v[108:111]
	v_mfma_f32_16x16x32_bf16 v[104:107], v[182:185], v[190:193], v[104:107]
	v_mfma_f32_16x16x32_bf16 v[92:95], v[174:177], v[198:201], v[92:95]
	v_mfma_f32_16x16x32_bf16 v[88:91], v[182:185], v[198:201], v[88:91]
	v_mfma_f32_16x16x32_bf16 v[76:79], v[174:177], v[208:211], v[76:79]
	v_mfma_f32_16x16x32_bf16 v[72:75], v[182:185], v[208:211], v[72:75]
	v_mfma_f32_16x16x32_bf16 v[68:71], v[174:177], v[216:219], v[68:71]
	v_mfma_f32_16x16x32_bf16 v[64:67], v[182:185], v[216:219], v[64:67]
	v_mfma_f32_16x16x32_bf16 v[108:111], v[178:181], v[194:197], v[108:111]
	v_mfma_f32_16x16x32_bf16 v[104:107], v[186:189], v[194:197], v[104:107]
	v_mfma_f32_16x16x32_bf16 v[92:95], v[178:181], v[204:207], v[92:95]
	v_mfma_f32_16x16x32_bf16 v[88:91], v[186:189], v[204:207], v[88:91]
	v_mfma_f32_16x16x32_bf16 v[76:79], v[178:181], v[212:215], v[76:79]
	v_mfma_f32_16x16x32_bf16 v[72:75], v[186:189], v[212:215], v[72:75]
	v_mfma_f32_16x16x32_bf16 v[68:71], v[178:181], v[220:223], v[68:71]
	v_mfma_f32_16x16x32_bf16 v[64:67], v[186:189], v[220:223], v[64:67]
	s_setprio 0
	s_barrier
; #define PG8_STAGE(bufoff, gbase, voff) do { _Pragma("unroll") for (int _i = 0; _i < 2; ++_i) \
;         __builtin_amdgcn_global_load_lds((const unsigned*)((const char*)(gbase) + (voff)[_i]), (LAS unsigned*)(lds + (bufoff) + ldsw + _i * 8192), 16, 0, 0); } while (0)
; #define PG8_LDA(dst, b, h) do { _Pragma("unroll") for (int m = 0; m < 4; ++m) _Pragma("unroll") for (int k = 0; k < 2; ++k) dst[m][k] = *(const LAS bf16x8*)(lds + PG8_SA(b, h) + aoff + m * 2048 + k * 1024); } while (0)
; #define PG8_MMA(ai, bj, At, Bt) do { __builtin_amdgcn_s_setprio(1); _Pragma("unroll") for (int m = 0; m < 4; ++m) _Pragma("unroll") for (int n = 0; n < 2; ++n) _Pragma("unroll") for (int k = 0; k < 2; ++k) \
;         acc[ai][bj][m][n] = __builtin_amdgcn_mfma_f32_16x16x32_bf16(Bt[n][k], At[m][k], acc[ai][bj][m][n], 0, 0, 0); __builtin_amdgcn_s_setprio(0); } while (0)
; #define PG8_WAIT_V(n) asm volatile("s_waitcnt vmcnt(" #n ")" ::: "memory")
; #define PG8_WAIT_L(n) asm volatile("s_waitcnt lgkmcnt(" #n ")" ::: "memory")
; #define PG8_BAR __builtin_amdgcn_s_barrier()
; #define PG8_SCHED __builtin_amdgcn_sched_barrier(0)
; template <class Epi, class Sched, bool ALIGN_EPI>
; DI void gemm_phase(LAS unsigned char* lds, const Gemm g, const Sched& S, const Epi& E) {
;     ...
;             PG8_LDA(At, 1, 1); PG8_STAGE(PG8_SB(1, 0), b3, voffB); PG8_STAGE(PG8_SB(1, 1), b3 + hstepB, voffB); PG8_STAGE(PG8_SA(1, 0), a3, voffA);
;             PG8_WAIT_V(8); PG8_WAIT_L(0); PG8_BAR; PG8_MMA(1, 0, At, B0); PG8_MMA(1, 1, At, B1); PG8_BAR; PG8_SCHED;
;         }
;         if constexpr (ALIGN_EPI) { if (wr == 0) PG8_BAR; }
;         if constexpr (!Epi::AFTER_DRAIN) E(acc, cur, wr, wc, fr, fq);
;         if (!has_next) break;
	s_mov_b32 m0, s80
	v_lshl_add_u64 v[224:225], v[224:225], 0, s[8:9]
	ds_read_b128 v[190:193], v144 offset:49152
	ds_read_b128 v[194:197], v144 offset:50176
	ds_read_b128 v[198:201], v144 offset:51200
	ds_read_b128 v[204:207], v144 offset:52224
	ds_read_b128 v[208:211], v144 offset:53248
	ds_read_b128 v[212:215], v144 offset:54272
	ds_read_b128 v[216:219], v144 offset:55296
	ds_read_b128 v[220:223], v144 offset:56320
	global_load_lds_dwordx4 v[224:225], off
	v_lshl_add_u64 v[224:225], v[226:227], 0, s[8:9]
	s_mov_b32 m0, s79
	s_nop 0
	global_load_lds_dwordx4 v[224:225], off
	v_lshl_add_u64 v[224:225], s[42:43], 0, v[130:131]
	s_mov_b32 m0, s88
	s_nop 0
	global_load_lds_dwordx4 v[224:225], off
	v_lshl_add_u64 v[224:225], s[42:43], 0, v[134:135]
	s_mov_b32 m0, s85
	s_nop 0
	global_load_lds_dwordx4 v[224:225], off
	v_lshl_add_u64 v[224:225], v[228:229], 0, s[8:9]
	s_mov_b32 m0, s63
	s_nop 0
	global_load_lds_dwordx4 v[224:225], off
	v_lshl_add_u64 v[224:225], v[230:231], 0, s[8:9]
	s_mov_b32 m0, s64
	s_nop 0
	global_load_lds_dwordx4 v[224:225], off
	s_waitcnt vmcnt(8)
	s_waitcnt lgkmcnt(0)
	s_barrier
	s_setprio 1
	s_waitcnt lgkmcnt(0)
	v_mfma_f32_16x16x32_bf16 v[60:63], v[158:161], v[190:193], v[60:63]
	v_mfma_f32_16x16x32_bf16 v[56:59], v[166:169], v[190:193], v[56:59]
	v_mfma_f32_16x16x32_bf16 v[52:55], v[158:161], v[198:201], v[52:55]
	v_mfma_f32_16x16x32_bf16 v[48:51], v[166:169], v[198:201], v[48:51]
	v_mfma_f32_16x16x32_bf16 v[36:39], v[158:161], v[208:211], v[36:39]
	v_mfma_f32_16x16x32_bf16 v[32:35], v[166:169], v[208:211], v[32:35]
	v_mfma_f32_16x16x32_bf16 v[20:23], v[158:161], v[216:219], v[20:23]
	v_mfma_f32_16x16x32_bf16 v[16:19], v[166:169], v[216:219], v[16:19]
	v_mfma_f32_16x16x32_bf16 v[60:63], v[162:165], v[194:197], v[60:63]
	v_mfma_f32_16x16x32_bf16 v[56:59], v[170:173], v[194:197], v[56:59]
	v_mfma_f32_16x16x32_bf16 v[52:55], v[162:165], v[204:207], v[52:55]
	v_mfma_f32_16x16x32_bf16 v[48:51], v[170:173], v[204:207], v[48:51]
	v_mfma_f32_16x16x32_bf16 v[36:39], v[162:165], v[212:215], v[36:39]
	v_mfma_f32_16x16x32_bf16 v[32:35], v[170:173], v[212:215], v[32:35]
	v_mfma_f32_16x16x32_bf16 v[20:23], v[162:165], v[220:223], v[20:23]
	v_mfma_f32_16x16x32_bf16 v[16:19], v[170:173], v[220:223], v[16:19]
	v_mfma_f32_16x16x32_bf16 v[44:47], v[174:177], v[190:193], v[44:47]
	v_mfma_f32_16x16x32_bf16 v[40:43], v[182:185], v[190:193], v[40:43]
	v_mfma_f32_16x16x32_bf16 v[28:31], v[174:177], v[198:201], v[28:31]
	v_mfma_f32_16x16x32_bf16 v[24:27], v[182:185], v[198:201], v[24:27]
	v_mfma_f32_16x16x32_bf16 v[12:15], v[174:177], v[208:211], v[12:15]
	v_mfma_f32_16x16x32_bf16 v[8:11], v[182:185], v[208:211], v[8:11]
	v_mfma_f32_16x16x32_bf16 v[4:7], v[174:177], v[216:219], v[4:7]
	v_mfma_f32_16x16x32_bf16 v[0:3], v[182:185], v[216:219], v[0:3]
	v_mfma_f32_16x16x32_bf16 v[44:47], v[178:181], v[194:197], v[44:47]
	v_mfma_f32_16x16x32_bf16 v[40:43], v[186:189], v[194:197], v[40:43]
	v_mfma_f32_16x16x32_bf16 v[28:31], v[178:181], v[204:207], v[28:31]
	v_mfma_f32_16x16x32_bf16 v[24:27], v[186:189], v[204:207], v[24:27]
	v_mfma_f32_16x16x32_bf16 v[12:15], v[178:181], v[212:215], v[12:15]
	v_mfma_f32_16x16x32_bf16 v[8:11], v[186:189], v[212:215], v[8:11]
	v_mfma_f32_16x16x32_bf16 v[4:7], v[178:181], v[220:223], v[4:7]
	v_mfma_f32_16x16x32_bf16 v[0:3], v[186:189], v[220:223], v[0:3]
	s_setprio 0
	s_barrier
	s_movk_i32 s44, 0x100
	s_andn2_b64 vcc, exec, s[40:41]
	s_mov_b64 s[42:43], -1
	s_mov_b64 s[40:41], 0
	s_cbranch_vccz .LBB0_2451
	s_and_b64 vcc, exec, s[10:11]
	s_cbranch_vccz .LBB0_2454
	s_barrier

; #define PG8_STAGE(bufoff, gbase, voff) do { _Pragma("unroll") for (int _i = 0; _i < 2; ++_i) \
;         __builtin_amdgcn_global_load_lds((const unsigned*)((const char*)(gbase) + (voff)[_i]), (LAS unsigned*)(lds + (bufoff) + ldsw + _i * 8192), 16, 0, 0); } while (0)
; #define PG8_LDA(dst, b, h) do { _Pragma("unroll") for (int m = 0; m < 4; ++m) _Pragma("unroll") for (int k = 0; k < 2; ++k) dst[m][k] = *(const LAS bf16x8*)(lds + PG8_SA(b, h) + aoff + m * 2048 + k * 1024); } while (0)
; #define PG8_LDB(dst, b, h) do { _Pragma("unroll") for (int n = 0; n < 2; ++n) _Pragma("unroll") for (int k = 0; k < 2; ++k) dst[n][k] = *(const LAS bf16x8*)(lds + PG8_SB(b, h) + boff + n * 2048 + k * 1024); } while (0)
; #define PG8_MMA(ai, bj, At, Bt) do { __builtin_amdgcn_s_setprio(1); _Pragma("unroll") for (int m = 0; m < 4; ++m) _Pragma("unroll") for (int n = 0; n < 2; ++n) _Pragma("unroll") for (int k = 0; k < 2; ++k) \
;         acc[ai][bj][m][n] = __builtin_amdgcn_mfma_f32_16x16x32_bf16(Bt[n][k], At[m][k], acc[ai][bj][m][n], 0, 0, 0); __builtin_amdgcn_s_setprio(0); } while (0)
; #define PG8_WAIT_V(n) asm volatile("s_waitcnt vmcnt(" #n ")" ::: "memory")
; #define PG8_WAIT_L(n) asm volatile("s_waitcnt lgkmcnt(" #n ")" ::: "memory")
; #define PG8_BAR __builtin_amdgcn_s_barrier()
; #define PG8_SCHED __builtin_amdgcn_sched_barrier(0)
; template <class Epi, class Sched, bool ALIGN_EPI>
; DI void gemm_phase(LAS unsigned char* lds, const Gemm g, const Sched& S, const Epi& E) {
;     ...
;         for (int t = 0; t < nt; t += 2) {
;             const bool last = (t == nt - 2);
;             const char* a1 = cA + (size_t)(t + 1) * kstep;
;             const char* a2 = last ? nA : cA + (size_t)(t + 2) * kstep; const char* b2 = last ? nB : cB + (size_t)(t + 2) * kstep;
;             const char* a3 = a2 + kstep; const char* b3 = b2 + kstep;
;             PG8_LDB(B0, 0, 0); PG8_LDB(B1, 0, 1); PG8_SCHED; PG8_LDA(At, 0, 0); PG8_STAGE(PG8_SA(1, 1), a1 + hstepA, voffA);
;             PG8_WAIT_V(8); PG8_WAIT_L(0); PG8_BAR; PG8_MMA(0, 0, At, B0); PG8_MMA(0, 1, At, B1); PG8_BAR; PG8_SCHED;
.LBB0_2467:
	s_add_u32 s27, s18, s26
	s_addc_u32 s38, s19, 0
	s_add_u32 s36, s27, 0x100
	s_addc_u32 s37, s38, 0
	s_and_b64 s[28:29], s[24:25], exec
	s_cselect_b32 s29, s61, s37
	s_cselect_b32 s28, s62, s36
	s_add_u32 s26, s20, s26
	s_addc_u32 s36, s21, 0
	s_add_u32 s26, s26, 0x100
	s_addc_u32 s36, s36, 0
	s_and_b64 s[24:25], s[24:25], exec
	s_cselect_b32 s37, s63, s36
	s_cselect_b32 s36, s64, s26
	s_add_u32 s40, s27, 0x10080
	ds_read_b128 v[148:151], v142
	ds_read_b128 v[154:157], v142 offset:1024
	ds_read_b128 v[158:161], v142 offset:2048
	ds_read_b128 v[162:165], v142 offset:3072
	ds_read_b128 v[166:169], v143
	ds_read_b128 v[170:173], v143 offset:1024
	ds_read_b128 v[174:177], v143 offset:2048
	ds_read_b128 v[178:181], v143 offset:3072
	s_addc_u32 s41, s38, 0
	s_add_i32 s71, s56, s47
	s_add_i32 m0, s48, 0xc000
	s_add_i32 s74, s48, 0xe000
	s_add_i32 s67, s71, 0x2000
	s_add_u32 s38, s36, 0x10000
	s_addc_u32 s39, s37, 0
	s_add_i32 s69, s57, s47
	s_add_i32 s68, s69, 0x2000
	s_add_u32 s26, s28, 0x10000
	s_addc_u32 s27, s29, 0
	s_add_i32 s66, s58, s47
	s_add_i32 s65, s66, 0x2000
	s_add_u32 s24, s36, 0x10080
	s_addc_u32 s25, s37, 0
	s_add_i32 s73, s59, s47
	s_add_i32 s72, s73, 0x2000
	v_lshl_add_u64 v[216:217], s[40:41], 0, v[134:135]
	ds_read_b128 v[182:185], v144
	ds_read_b128 v[186:189], v144 offset:1024
	ds_read_b128 v[190:193], v144 offset:2048
	ds_read_b128 v[194:197], v144 offset:3072
	ds_read_b128 v[198:201], v144 offset:4096
	ds_read_b128 v[204:207], v144 offset:5120
	ds_read_b128 v[208:211], v144 offset:6144
	ds_read_b128 v[212:215], v144 offset:7168
	global_load_lds_dwordx4 v[216:217], off
	v_lshl_add_u64 v[216:217], s[40:41], 0, v[130:131]
	s_mov_b32 m0, s74
	s_nop 0
	global_load_lds_dwordx4 v[216:217], off
	s_waitcnt vmcnt(8)
	s_waitcnt lgkmcnt(0)
	s_barrier
	s_setprio 1
	s_waitcnt lgkmcnt(0)
	v_mfma_f32_16x16x32_bf16 v[124:127], v[148:151], v[182:185], v[124:127]
	v_mfma_f32_16x16x32_bf16 v[120:123], v[158:161], v[182:185], v[120:123]
	v_mfma_f32_16x16x32_bf16 v[116:119], v[148:151], v[190:193], v[116:119]
	v_mfma_f32_16x16x32_bf16 v[112:115], v[158:161], v[190:193], v[112:115]
	v_mfma_f32_16x16x32_bf16 v[100:103], v[148:151], v[198:201], v[100:103]
	v_mfma_f32_16x16x32_bf16 v[96:99], v[158:161], v[198:201], v[96:99]
	v_mfma_f32_16x16x32_bf16 v[84:87], v[148:151], v[208:211], v[84:87]
	v_mfma_f32_16x16x32_bf16 v[80:83], v[158:161], v[208:211], v[80:83]
	v_mfma_f32_16x16x32_bf16 v[124:127], v[154:157], v[186:189], v[124:127]
	v_mfma_f32_16x16x32_bf16 v[120:123], v[162:165], v[186:189], v[120:123]
	v_mfma_f32_16x16x32_bf16 v[116:119], v[154:157], v[194:197], v[116:119]
	v_mfma_f32_16x16x32_bf16 v[112:115], v[162:165], v[194:197], v[112:115]
	v_mfma_f32_16x16x32_bf16 v[100:103], v[154:157], v[204:207], v[100:103]
	v_mfma_f32_16x16x32_bf16 v[96:99], v[162:165], v[204:207], v[96:99]
	v_mfma_f32_16x16x32_bf16 v[84:87], v[154:157], v[212:215], v[84:87]
	v_mfma_f32_16x16x32_bf16 v[80:83], v[162:165], v[212:215], v[80:83]
	v_mfma_f32_16x16x32_bf16 v[108:111], v[166:169], v[182:185], v[108:111]
	v_mfma_f32_16x16x32_bf16 v[104:107], v[174:177], v[182:185], v[104:107]
	v_mfma_f32_16x16x32_bf16 v[92:95], v[166:169], v[190:193], v[92:95]
	v_mfma_f32_16x16x32_bf16 v[88:91], v[174:177], v[190:193], v[88:91]
	v_mfma_f32_16x16x32_bf16 v[76:79], v[166:169], v[198:201], v[76:79]
	v_mfma_f32_16x16x32_bf16 v[72:75], v[174:177], v[198:201], v[72:75]
	v_mfma_f32_16x16x32_bf16 v[68:71], v[166:169], v[208:211], v[68:71]
	v_mfma_f32_16x16x32_bf16 v[64:67], v[174:177], v[208:211], v[64:67]
	v_mfma_f32_16x16x32_bf16 v[108:111], v[170:173], v[186:189], v[108:111]
	v_mfma_f32_16x16x32_bf16 v[104:107], v[178:181], v[186:189], v[104:107]
	v_mfma_f32_16x16x32_bf16 v[92:95], v[170:173], v[194:197], v[92:95]
	v_mfma_f32_16x16x32_bf16 v[88:91], v[178:181], v[194:197], v[88:91]
	v_mfma_f32_16x16x32_bf16 v[76:79], v[170:173], v[204:207], v[76:79]
	v_mfma_f32_16x16x32_bf16 v[72:75], v[178:181], v[204:207], v[72:75]
	v_mfma_f32_16x16x32_bf16 v[68:71], v[170:173], v[212:215], v[68:71]
	v_mfma_f32_16x16x32_bf16 v[64:67], v[178:181], v[212:215], v[64:67]
	s_setprio 0
	s_barrier
	s_mov_b32 m0, s71
	v_lshl_add_u64 v[216:217], s[36:37], 0, v[132:133]
	ds_read_b128 v[182:185], v144 offset:16384
	ds_read_b128 v[186:189], v144 offset:17408
	ds_read_b128 v[190:193], v144 offset:18432
	ds_read_b128 v[194:197], v144 offset:19456
	ds_read_b128 v[198:201], v144 offset:20480
	ds_read_b128 v[204:207], v144 offset:21504
	ds_read_b128 v[208:211], v144 offset:22528
	ds_read_b128 v[212:215], v144 offset:23552
	global_load_lds_dwordx4 v[216:217], off
	v_lshl_add_u64 v[218:219], s[36:37], 0, v[128:129]
	s_mov_b32 m0, s67
	v_lshl_add_u64 v[220:221], s[38:39], 0, v[132:133]
	global_load_lds_dwordx4 v[218:219], off
	s_mov_b32 m0, s69
	v_lshl_add_u64 v[222:223], s[28:29], 0, v[130:131]
	global_load_lds_dwordx4 v[220:221], off
	v_lshl_add_u64 v[220:221], s[38:39], 0, v[128:129]
	s_mov_b32 m0, s68
	s_nop 0
	global_load_lds_dwordx4 v[220:221], off
	v_lshl_add_u64 v[220:221], s[28:29], 0, v[134:135]
	s_mov_b32 m0, s48
	s_nop 0
	global_load_lds_dwordx4 v[220:221], off
	s_mov_b32 m0, s50
	s_nop 0
	global_load_lds_dwordx4 v[222:223], off
	s_waitcnt vmcnt(8)
	s_waitcnt lgkmcnt(0)
	s_barrier
; #define PG8_STAGE(bufoff, gbase, voff) do { _Pragma("unroll") for (int _i = 0; _i < 2; ++_i) \
;         __builtin_amdgcn_global_load_lds((const unsigned*)((const char*)(gbase) + (voff)[_i]), (LAS unsigned*)(lds + (bufoff) + ldsw + _i * 8192), 16, 0, 0); } while (0)
; #define PG8_LDA(dst, b, h) do { _Pragma("unroll") for (int m = 0; m < 4; ++m) _Pragma("unroll") for (int k = 0; k < 2; ++k) dst[m][k] = *(const LAS bf16x8*)(lds + PG8_SA(b, h) + aoff + m * 2048 + k * 1024); } while (0)
; #define PG8_LDB(dst, b, h) do { _Pragma("unroll") for (int n = 0; n < 2; ++n) _Pragma("unroll") for (int k = 0; k < 2; ++k) dst[n][k] = *(const LAS bf16x8*)(lds + PG8_SB(b, h) + boff + n * 2048 + k * 1024); } while (0)
; #define PG8_MMA(ai, bj, At, Bt) do { __builtin_amdgcn_s_setprio(1); _Pragma("unroll") for (int m = 0; m < 4; ++m) _Pragma("unroll") for (int n = 0; n < 2; ++n) _Pragma("unroll") for (int k = 0; k < 2; ++k) \
;         acc[ai][bj][m][n] = __builtin_amdgcn_mfma_f32_16x16x32_bf16(Bt[n][k], At[m][k], acc[ai][bj][m][n], 0, 0, 0); __builtin_amdgcn_s_setprio(0); } while (0)
; #define PG8_WAIT_V(n) asm volatile("s_waitcnt vmcnt(" #n ")" ::: "memory")
; #define PG8_WAIT_L(n) asm volatile("s_waitcnt lgkmcnt(" #n ")" ::: "memory")
; #define PG8_BAR __builtin_amdgcn_s_barrier()
; #define PG8_SCHED __builtin_amdgcn_sched_barrier(0)
; template <class Epi, class Sched, bool ALIGN_EPI>
; DI void gemm_phase(LAS unsigned char* lds, const Gemm g, const Sched& S, const Epi& E) {
;     ...
;             PG8_WAIT_V(8); PG8_WAIT_L(0); PG8_BAR; PG8_MMA(0, 0, At, B0); PG8_MMA(0, 1, At, B1); PG8_BAR; PG8_SCHED;
;             PG8_LDA(At, 0, 1); PG8_STAGE(PG8_SB(0, 0), b2, voffB); PG8_STAGE(PG8_SB(0, 1), b2 + hstepB, voffB); PG8_STAGE(PG8_SA(0, 0), a2, voffA);
;             PG8_WAIT_V(8); PG8_WAIT_L(0); PG8_BAR; PG8_MMA(1, 0, At, B0); PG8_MMA(1, 1, At, B1); PG8_BAR; PG8_SCHED;
;             PG8_LDB(B0, 1, 0); PG8_LDB(B1, 1, 1); PG8_SCHED; PG8_LDA(At, 1, 0); PG8_STAGE(PG8_SA(0, 1), a2 + hstepA, voffA);
;             PG8_WAIT_V(8); PG8_WAIT_L(0); PG8_BAR; PG8_MMA(0, 0, At, B0); PG8_MMA(0, 1, At, B1); PG8_BAR; PG8_SCHED;
	s_setprio 1
	s_waitcnt lgkmcnt(0)
	v_mfma_f32_16x16x32_bf16 v[60:63], v[148:151], v[182:185], v[60:63]
	v_mfma_f32_16x16x32_bf16 v[56:59], v[158:161], v[182:185], v[56:59]
	v_mfma_f32_16x16x32_bf16 v[52:55], v[148:151], v[190:193], v[52:55]
	v_mfma_f32_16x16x32_bf16 v[48:51], v[158:161], v[190:193], v[48:51]
	v_mfma_f32_16x16x32_bf16 v[36:39], v[148:151], v[198:201], v[36:39]
	v_mfma_f32_16x16x32_bf16 v[32:35], v[158:161], v[198:201], v[32:35]
	v_mfma_f32_16x16x32_bf16 v[20:23], v[148:151], v[208:211], v[20:23]
	v_mfma_f32_16x16x32_bf16 v[16:19], v[158:161], v[208:211], v[16:19]
	v_mfma_f32_16x16x32_bf16 v[60:63], v[154:157], v[186:189], v[60:63]
	v_mfma_f32_16x16x32_bf16 v[56:59], v[162:165], v[186:189], v[56:59]
	v_mfma_f32_16x16x32_bf16 v[52:55], v[154:157], v[194:197], v[52:55]
	v_mfma_f32_16x16x32_bf16 v[48:51], v[162:165], v[194:197], v[48:51]
	v_mfma_f32_16x16x32_bf16 v[36:39], v[154:157], v[204:207], v[36:39]
	v_mfma_f32_16x16x32_bf16 v[32:35], v[162:165], v[204:207], v[32:35]
	v_mfma_f32_16x16x32_bf16 v[20:23], v[154:157], v[212:215], v[20:23]
	v_mfma_f32_16x16x32_bf16 v[16:19], v[162:165], v[212:215], v[16:19]
	v_mfma_f32_16x16x32_bf16 v[44:47], v[166:169], v[182:185], v[44:47]
	v_mfma_f32_16x16x32_bf16 v[40:43], v[174:177], v[182:185], v[40:43]
	v_mfma_f32_16x16x32_bf16 v[28:31], v[166:169], v[190:193], v[28:31]
	v_mfma_f32_16x16x32_bf16 v[24:27], v[174:177], v[190:193], v[24:27]
	v_mfma_f32_16x16x32_bf16 v[12:15], v[166:169], v[198:201], v[12:15]
	v_mfma_f32_16x16x32_bf16 v[8:11], v[174:177], v[198:201], v[8:11]
	v_mfma_f32_16x16x32_bf16 v[4:7], v[166:169], v[208:211], v[4:7]
	v_mfma_f32_16x16x32_bf16 v[0:3], v[174:177], v[208:211], v[0:3]
	v_mfma_f32_16x16x32_bf16 v[44:47], v[170:173], v[186:189], v[44:47]
	v_mfma_f32_16x16x32_bf16 v[40:43], v[178:181], v[186:189], v[40:43]
	v_mfma_f32_16x16x32_bf16 v[28:31], v[170:173], v[194:197], v[28:31]
	v_mfma_f32_16x16x32_bf16 v[24:27], v[178:181], v[194:197], v[24:27]
	v_mfma_f32_16x16x32_bf16 v[12:15], v[170:173], v[204:207], v[12:15]
	v_mfma_f32_16x16x32_bf16 v[8:11], v[178:181], v[204:207], v[8:11]
	v_mfma_f32_16x16x32_bf16 v[4:7], v[170:173], v[212:215], v[4:7]
	v_mfma_f32_16x16x32_bf16 v[0:3], v[178:181], v[212:215], v[0:3]
	s_setprio 0
	s_barrier
	ds_read_b128 v[148:151], v145
	ds_read_b128 v[154:157], v145 offset:1024
	ds_read_b128 v[158:161], v145 offset:2048
	ds_read_b128 v[162:165], v145 offset:3072
	ds_read_b128 v[166:169], v146
	ds_read_b128 v[170:173], v146 offset:1024
	ds_read_b128 v[174:177], v146 offset:2048
	ds_read_b128 v[178:181], v146 offset:3072
	s_mov_b32 m0, s51
	v_lshl_add_u64 v[224:225], s[26:27], 0, v[134:135]
	ds_read_b128 v[182:185], v144 offset:32768
	ds_read_b128 v[186:189], v144 offset:33792
	ds_read_b128 v[190:193], v144 offset:34816
	ds_read_b128 v[194:197], v144 offset:35840
	ds_read_b128 v[198:201], v144 offset:36864
	ds_read_b128 v[204:207], v144 offset:37888
	ds_read_b128 v[208:211], v144 offset:38912
	ds_read_b128 v[212:215], v144 offset:39936
	global_load_lds_dwordx4 v[224:225], off
	v_lshl_add_u64 v[224:225], s[26:27], 0, v[130:131]
	s_mov_b32 m0, s52
	s_nop 0
	global_load_lds_dwordx4 v[224:225], off
	s_waitcnt vmcnt(8)
	s_waitcnt lgkmcnt(0)
	s_barrier
	s_setprio 1
	s_waitcnt lgkmcnt(0)
	v_mfma_f32_16x16x32_bf16 v[124:127], v[148:151], v[182:185], v[124:127]
	v_mfma_f32_16x16x32_bf16 v[120:123], v[158:161], v[182:185], v[120:123]
	v_mfma_f32_16x16x32_bf16 v[116:119], v[148:151], v[190:193], v[116:119]
	v_mfma_f32_16x16x32_bf16 v[112:115], v[158:161], v[190:193], v[112:115]
	v_mfma_f32_16x16x32_bf16 v[100:103], v[148:151], v[198:201], v[100:103]
	v_mfma_f32_16x16x32_bf16 v[96:99], v[158:161], v[198:201], v[96:99]
	v_mfma_f32_16x16x32_bf16 v[84:87], v[148:151], v[208:211], v[84:87]
	v_mfma_f32_16x16x32_bf16 v[80:83], v[158:161], v[208:211], v[80:83]
	v_mfma_f32_16x16x32_bf16 v[124:127], v[154:157], v[186:189], v[124:127]
	v_mfma_f32_16x16x32_bf16 v[120:123], v[162:165], v[186:189], v[120:123]
	v_mfma_f32_16x16x32_bf16 v[116:119], v[154:157], v[194:197], v[116:119]
	v_mfma_f32_16x16x32_bf16 v[112:115], v[162:165], v[194:197], v[112:115]
	v_mfma_f32_16x16x32_bf16 v[100:103], v[154:157], v[204:207], v[100:103]
	v_mfma_f32_16x16x32_bf16 v[96:99], v[162:165], v[204:207], v[96:99]
	v_mfma_f32_16x16x32_bf16 v[84:87], v[154:157], v[212:215], v[84:87]
	v_mfma_f32_16x16x32_bf16 v[80:83], v[162:165], v[212:215], v[80:83]
	v_mfma_f32_16x16x32_bf16 v[108:111], v[166:169], v[182:185], v[108:111]
	v_mfma_f32_16x16x32_bf16 v[104:107], v[174:177], v[182:185], v[104:107]
	v_mfma_f32_16x16x32_bf16 v[92:95], v[166:169], v[190:193], v[92:95]
	v_mfma_f32_16x16x32_bf16 v[88:91], v[174:177], v[190:193], v[88:91]
	v_mfma_f32_16x16x32_bf16 v[76:79], v[166:169], v[198:201], v[76:79]
	v_mfma_f32_16x16x32_bf16 v[72:75], v[174:177], v[198:201], v[72:75]
	v_mfma_f32_16x16x32_bf16 v[68:71], v[166:169], v[208:211], v[68:71]
	v_mfma_f32_16x16x32_bf16 v[64:67], v[174:177], v[208:211], v[64:67]
	v_mfma_f32_16x16x32_bf16 v[108:111], v[170:173], v[186:189], v[108:111]
	v_mfma_f32_16x16x32_bf16 v[104:107], v[178:181], v[186:189], v[104:107]
	v_mfma_f32_16x16x32_bf16 v[92:95], v[170:173], v[194:197], v[92:95]
	v_mfma_f32_16x16x32_bf16 v[88:91], v[178:181], v[194:197], v[88:91]
	v_mfma_f32_16x16x32_bf16 v[76:79], v[170:173], v[204:207], v[76:79]
	v_mfma_f32_16x16x32_bf16 v[72:75], v[178:181], v[204:207], v[72:75]
	v_mfma_f32_16x16x32_bf16 v[68:71], v[170:173], v[212:215], v[68:71]
	v_mfma_f32_16x16x32_bf16 v[64:67], v[178:181], v[212:215], v[64:67]
	s_setprio 0
	s_barrier
; #define PG8_STAGE(bufoff, gbase, voff) do { _Pragma("unroll") for (int _i = 0; _i < 2; ++_i) \
;         __builtin_amdgcn_global_load_lds((const unsigned*)((const char*)(gbase) + (voff)[_i]), (LAS unsigned*)(lds + (bufoff) + ldsw + _i * 8192), 16, 0, 0); } while (0)
; #define PG8_LDA(dst, b, h) do { _Pragma("unroll") for (int m = 0; m < 4; ++m) _Pragma("unroll") for (int k = 0; k < 2; ++k) dst[m][k] = *(const LAS bf16x8*)(lds + PG8_SA(b, h) + aoff + m * 2048 + k * 1024); } while (0)
; #define PG8_MMA(ai, bj, At, Bt) do { __builtin_amdgcn_s_setprio(1); _Pragma("unroll") for (int m = 0; m < 4; ++m) _Pragma("unroll") for (int n = 0; n < 2; ++n) _Pragma("unroll") for (int k = 0; k < 2; ++k) \
;         acc[ai][bj][m][n] = __builtin_amdgcn_mfma_f32_16x16x32_bf16(Bt[n][k], At[m][k], acc[ai][bj][m][n], 0, 0, 0); __builtin_amdgcn_s_setprio(0); } while (0)
; #define PG8_WAIT_V(n) asm volatile("s_waitcnt vmcnt(" #n ")" ::: "memory")
; #define PG8_WAIT_L(n) asm volatile("s_waitcnt lgkmcnt(" #n ")" ::: "memory")
; #define PG8_BAR __builtin_amdgcn_s_barrier()
; #define PG8_SCHED __builtin_amdgcn_sched_barrier(0)
; template <class Epi, class Sched, bool ALIGN_EPI>
; DI void gemm_phase(LAS unsigned char* lds, const Gemm g, const Sched& S, const Epi& E) {
;     ...
;             PG8_LDA(At, 1, 1); PG8_STAGE(PG8_SB(1, 0), b3, voffB); PG8_STAGE(PG8_SB(1, 1), b3 + hstepB, voffB); PG8_STAGE(PG8_SA(1, 0), a3, voffA);
;             PG8_WAIT_V(8); PG8_WAIT_L(0); PG8_BAR; PG8_MMA(1, 0, At, B0); PG8_MMA(1, 1, At, B1); PG8_BAR; PG8_SCHED;
;         }
;         if constexpr (ALIGN_EPI) { if (wr == 0) PG8_BAR; }
;         if constexpr (!Epi::AFTER_DRAIN) E(acc, cur, wr, wc, fr, fq);
;         if (!has_next) break;
	s_mov_b32 m0, s66
	v_lshl_add_u64 v[216:217], v[216:217], 0, s[14:15]
	ds_read_b128 v[182:185], v144 offset:49152
	ds_read_b128 v[186:189], v144 offset:50176
	ds_read_b128 v[190:193], v144 offset:51200
	ds_read_b128 v[194:197], v144 offset:52224
	ds_read_b128 v[198:201], v144 offset:53248
	ds_read_b128 v[204:207], v144 offset:54272
	ds_read_b128 v[208:211], v144 offset:55296
	ds_read_b128 v[212:215], v144 offset:56320
	global_load_lds_dwordx4 v[216:217], off
	v_lshl_add_u64 v[216:217], v[218:219], 0, s[14:15]
	s_mov_b32 m0, s65
	s_nop 0
	global_load_lds_dwordx4 v[216:217], off
	v_lshl_add_u64 v[216:217], s[24:25], 0, v[132:133]
	s_mov_b32 m0, s73
	s_nop 0
	global_load_lds_dwordx4 v[216:217], off
	v_lshl_add_u64 v[216:217], s[24:25], 0, v[128:129]
	s_mov_b32 m0, s72
	s_nop 0
	global_load_lds_dwordx4 v[216:217], off
	v_lshl_add_u64 v[216:217], v[220:221], 0, s[14:15]
	s_mov_b32 m0, s54
	s_nop 0
	global_load_lds_dwordx4 v[216:217], off
	v_lshl_add_u64 v[216:217], v[222:223], 0, s[14:15]
	s_mov_b32 m0, s55
	s_nop 0
	global_load_lds_dwordx4 v[216:217], off
	s_waitcnt vmcnt(8)
	s_waitcnt lgkmcnt(0)
	s_barrier
	s_setprio 1
	s_waitcnt lgkmcnt(0)
	v_mfma_f32_16x16x32_bf16 v[60:63], v[148:151], v[182:185], v[60:63]
	v_mfma_f32_16x16x32_bf16 v[56:59], v[158:161], v[182:185], v[56:59]
	v_mfma_f32_16x16x32_bf16 v[52:55], v[148:151], v[190:193], v[52:55]
	v_mfma_f32_16x16x32_bf16 v[48:51], v[158:161], v[190:193], v[48:51]
	v_mfma_f32_16x16x32_bf16 v[36:39], v[148:151], v[198:201], v[36:39]
	v_mfma_f32_16x16x32_bf16 v[32:35], v[158:161], v[198:201], v[32:35]
	v_mfma_f32_16x16x32_bf16 v[20:23], v[148:151], v[208:211], v[20:23]
	v_mfma_f32_16x16x32_bf16 v[16:19], v[158:161], v[208:211], v[16:19]
	v_mfma_f32_16x16x32_bf16 v[60:63], v[154:157], v[186:189], v[60:63]
	v_mfma_f32_16x16x32_bf16 v[56:59], v[162:165], v[186:189], v[56:59]
	v_mfma_f32_16x16x32_bf16 v[52:55], v[154:157], v[194:197], v[52:55]
	v_mfma_f32_16x16x32_bf16 v[48:51], v[162:165], v[194:197], v[48:51]
	v_mfma_f32_16x16x32_bf16 v[36:39], v[154:157], v[204:207], v[36:39]
	v_mfma_f32_16x16x32_bf16 v[32:35], v[162:165], v[204:207], v[32:35]
	v_mfma_f32_16x16x32_bf16 v[20:23], v[154:157], v[212:215], v[20:23]
	v_mfma_f32_16x16x32_bf16 v[16:19], v[162:165], v[212:215], v[16:19]
	v_mfma_f32_16x16x32_bf16 v[44:47], v[166:169], v[182:185], v[44:47]
	v_mfma_f32_16x16x32_bf16 v[40:43], v[174:177], v[182:185], v[40:43]
	v_mfma_f32_16x16x32_bf16 v[28:31], v[166:169], v[190:193], v[28:31]
	v_mfma_f32_16x16x32_bf16 v[24:27], v[174:177], v[190:193], v[24:27]
	v_mfma_f32_16x16x32_bf16 v[12:15], v[166:169], v[198:201], v[12:15]
	v_mfma_f32_16x16x32_bf16 v[8:11], v[174:177], v[198:201], v[8:11]
	v_mfma_f32_16x16x32_bf16 v[4:7], v[166:169], v[208:211], v[4:7]
	v_mfma_f32_16x16x32_bf16 v[0:3], v[174:177], v[208:211], v[0:3]
	v_mfma_f32_16x16x32_bf16 v[44:47], v[170:173], v[186:189], v[44:47]
	v_mfma_f32_16x16x32_bf16 v[40:43], v[178:181], v[186:189], v[40:43]
	v_mfma_f32_16x16x32_bf16 v[28:31], v[170:173], v[194:197], v[28:31]
	v_mfma_f32_16x16x32_bf16 v[24:27], v[178:181], v[194:197], v[24:27]
	v_mfma_f32_16x16x32_bf16 v[12:15], v[170:173], v[204:207], v[12:15]
	v_mfma_f32_16x16x32_bf16 v[8:11], v[178:181], v[204:207], v[8:11]
	v_mfma_f32_16x16x32_bf16 v[4:7], v[170:173], v[212:215], v[4:7]
	v_mfma_f32_16x16x32_bf16 v[0:3], v[178:181], v[212:215], v[0:3]
	s_setprio 0
	s_barrier
	s_movk_i32 s26, 0x100
	s_andn2_b64 vcc, exec, s[22:23]
	s_mov_b64 s[24:25], -1
	s_mov_b64 s[22:23], 0
	s_cbranch_vccz .LBB0_2467
	s_and_b64 vcc, exec, s[16:17]
	s_cbranch_vccz .LBB0_2470
	s_barrier

; #define PG8_STAGE(bufoff, gbase, voff) do { _Pragma("unroll") for (int _i = 0; _i < 2; ++_i) \
;         __builtin_amdgcn_global_load_lds((const unsigned*)((const char*)(gbase) + (voff)[_i]), (LAS unsigned*)(lds + (bufoff) + ldsw + _i * 8192), 16, 0, 0); } while (0)
; #define PG8_LDA(dst, b, h) do { _Pragma("unroll") for (int m = 0; m < 4; ++m) _Pragma("unroll") for (int k = 0; k < 2; ++k) dst[m][k] = *(const LAS bf16x8*)(lds + PG8_SA(b, h) + aoff + m * 2048 + k * 1024); } while (0)
; #define PG8_LDB(dst, b, h) do { _Pragma("unroll") for (int n = 0; n < 2; ++n) _Pragma("unroll") for (int k = 0; k < 2; ++k) dst[n][k] = *(const LAS bf16x8*)(lds + PG8_SB(b, h) + boff + n * 2048 + k * 1024); } while (0)
; #define PG8_MMA(ai, bj, At, Bt) do { __builtin_amdgcn_s_setprio(1); _Pragma("unroll") for (int m = 0; m < 4; ++m) _Pragma("unroll") for (int n = 0; n < 2; ++n) _Pragma("unroll") for (int k = 0; k < 2; ++k) \
;         acc[ai][bj][m][n] = __builtin_amdgcn_mfma_f32_16x16x32_bf16(Bt[n][k], At[m][k], acc[ai][bj][m][n], 0, 0, 0); __builtin_amdgcn_s_setprio(0); } while (0)
; #define PG8_WAIT_V(n) asm volatile("s_waitcnt vmcnt(" #n ")" ::: "memory")
; #define PG8_BAR __builtin_amdgcn_s_barrier()
; template <class Epi, class Sched, bool ALIGN_EPI>
; DI void gemm_phase(LAS unsigned char* lds, const Gemm g, const Sched& S, const Epi& E) {
;     ...
;         const char* nA = has_next ? (const char*)g.A + (size_t)nxt.pm * tstepA : cA; const char* nB = has_next ? (const char*)g.Bt + (size_t)nxt.pn * tstepB : cB;
;         for (int t = 0; t < nt; t += 2) {
;             const bool last = (t == nt - 2);
;             const char* a1 = cA + (size_t)(t + 1) * kstep;
;             const char* a2 = last ? nA : cA + (size_t)(t + 2) * kstep; const char* b2 = last ? nB : cB + (size_t)(t + 2) * kstep;
;             const char* a3 = a2 + kstep; const char* b3 = b2 + kstep;
;             PG8_LDB(B0, 0, 0); PG8_LDB(B1, 0, 1); PG8_SCHED; PG8_LDA(At, 0, 0); PG8_STAGE(PG8_SA(1, 1), a1 + hstepA, voffA);
;             PG8_WAIT_V(8); PG8_WAIT_L(0); PG8_BAR; PG8_MMA(0, 0, At, B0); PG8_MMA(0, 1, At, B1); PG8_BAR; PG8_SCHED;
;             PG8_LDA(At, 0, 1); PG8_STAGE(PG8_SB(0, 0), b2, voffB); PG8_STAGE(PG8_SB(0, 1), b2 + hstepB, voffB); PG8_STAGE(PG8_SA(0, 0), a2, voffA);
;             PG8_WAIT_V(8); PG8_WAIT_L(0); PG8_BAR; PG8_MMA(1, 0, At, B0); PG8_MMA(1, 1, At, B1); PG8_BAR; PG8_SCHED;
.LBB0_2548:
	v_add_u32_e32 v150, s43, v144
	ds_read_b128 v[146:149], v150
	ds_read_b128 v[154:157], v150 offset:1024
	ds_read_b128 v[158:161], v150 offset:2048
	ds_read_b128 v[162:165], v150 offset:3072
	v_add_u32_e32 v150, s44, v144
	s_add_u32 s16, s8, s14
	ds_read_b128 v[166:169], v150
	ds_read_b128 v[170:173], v150 offset:1024
	ds_read_b128 v[174:177], v150 offset:2048
	ds_read_b128 v[178:181], v150 offset:3072
	s_addc_u32 s17, s9, s15
	s_add_u32 s16, s16, 0x100
	s_addc_u32 s17, s17, 0
	s_add_u32 s53, s50, s14
	s_addc_u32 s54, s51, s15
	s_cmpk_eq_i32 s14, 0x1500
	s_cselect_b32 s19, s13, s17
	s_cselect_b32 s18, s12, s16
	s_cselect_b32 s17, s1, s54
	s_cselect_b32 s16, s0, s53
	v_lshl_add_u64 v[150:151], v[140:141], 0, s[14:15]
	s_add_i32 m0, s37, 0xc000
	ds_read_b128 v[182:185], v145
	ds_read_b128 v[186:189], v145 offset:1024
	ds_read_b128 v[190:193], v145 offset:2048
	ds_read_b128 v[194:197], v145 offset:3072
	ds_read_b128 v[198:201], v145 offset:4096
	ds_read_b128 v[204:207], v145 offset:5120
	ds_read_b128 v[208:211], v145 offset:6144
	ds_read_b128 v[212:215], v145 offset:7168
	global_load_lds_dwordx4 v[150:151], off
	v_lshl_add_u64 v[150:151], v[142:143], 0, s[14:15]
	s_add_i32 m0, s37, 0xe000
	s_nop 0
	global_load_lds_dwordx4 v[150:151], off
	s_waitcnt vmcnt(8)
	s_waitcnt lgkmcnt(0)
	s_barrier
	s_setprio 1
	s_waitcnt lgkmcnt(0)
	v_mfma_f32_16x16x32_bf16 v[124:127], v[146:149], v[182:185], v[124:127]
	v_mfma_f32_16x16x32_bf16 v[120:123], v[158:161], v[182:185], v[120:123]
	v_mfma_f32_16x16x32_bf16 v[112:115], v[146:149], v[190:193], v[112:115]
	v_mfma_f32_16x16x32_bf16 v[108:111], v[158:161], v[190:193], v[108:111]
	v_mfma_f32_16x16x32_bf16 v[96:99], v[146:149], v[198:201], v[96:99]
	v_mfma_f32_16x16x32_bf16 v[92:95], v[158:161], v[198:201], v[92:95]
	v_mfma_f32_16x16x32_bf16 v[80:83], v[146:149], v[208:211], v[80:83]
	v_mfma_f32_16x16x32_bf16 v[76:79], v[158:161], v[208:211], v[76:79]
	v_mfma_f32_16x16x32_bf16 v[124:127], v[154:157], v[186:189], v[124:127]
	v_mfma_f32_16x16x32_bf16 v[120:123], v[162:165], v[186:189], v[120:123]
	v_mfma_f32_16x16x32_bf16 v[112:115], v[154:157], v[194:197], v[112:115]
	v_mfma_f32_16x16x32_bf16 v[108:111], v[162:165], v[194:197], v[108:111]
	v_mfma_f32_16x16x32_bf16 v[96:99], v[154:157], v[204:207], v[96:99]
	v_mfma_f32_16x16x32_bf16 v[92:95], v[162:165], v[204:207], v[92:95]
	v_mfma_f32_16x16x32_bf16 v[80:83], v[154:157], v[212:215], v[80:83]
	v_mfma_f32_16x16x32_bf16 v[76:79], v[162:165], v[212:215], v[76:79]
	v_mfma_f32_16x16x32_bf16 v[116:119], v[166:169], v[182:185], v[116:119]
	v_mfma_f32_16x16x32_bf16 v[104:107], v[174:177], v[182:185], v[104:107]
	v_mfma_f32_16x16x32_bf16 v[100:103], v[166:169], v[190:193], v[100:103]
	v_mfma_f32_16x16x32_bf16 v[88:91], v[174:177], v[190:193], v[88:91]
	v_mfma_f32_16x16x32_bf16 v[84:87], v[166:169], v[198:201], v[84:87]
	v_mfma_f32_16x16x32_bf16 v[72:75], v[174:177], v[198:201], v[72:75]
	v_mfma_f32_16x16x32_bf16 v[68:71], v[166:169], v[208:211], v[68:71]
	v_mfma_f32_16x16x32_bf16 v[64:67], v[174:177], v[208:211], v[64:67]
	v_mfma_f32_16x16x32_bf16 v[116:119], v[170:173], v[186:189], v[116:119]
	v_mfma_f32_16x16x32_bf16 v[104:107], v[178:181], v[186:189], v[104:107]
	v_mfma_f32_16x16x32_bf16 v[100:103], v[170:173], v[194:197], v[100:103]
	v_mfma_f32_16x16x32_bf16 v[88:91], v[178:181], v[194:197], v[88:91]
	v_mfma_f32_16x16x32_bf16 v[84:87], v[170:173], v[204:207], v[84:87]
	v_mfma_f32_16x16x32_bf16 v[72:75], v[178:181], v[204:207], v[72:75]
	v_mfma_f32_16x16x32_bf16 v[68:71], v[170:173], v[212:215], v[68:71]
	v_mfma_f32_16x16x32_bf16 v[64:67], v[178:181], v[212:215], v[64:67]
	s_setprio 0
	s_barrier
	s_add_i32 s53, s43, s36
	v_lshl_add_u64 v[150:151], s[16:17], 0, v[128:129]
	s_mov_b32 m0, s53
	ds_read_b128 v[182:185], v145 offset:16384
	ds_read_b128 v[186:189], v145 offset:17408
	ds_read_b128 v[190:193], v145 offset:18432
	ds_read_b128 v[194:197], v145 offset:19456
	ds_read_b128 v[198:201], v145 offset:20480
	ds_read_b128 v[204:207], v145 offset:21504
	ds_read_b128 v[208:211], v145 offset:22528
	ds_read_b128 v[212:215], v145 offset:23552
	global_load_lds_dwordx4 v[150:151], off
	s_add_i32 m0, s53, 0x2000
	s_add_u32 s54, s16, 0xb0000
	v_lshl_add_u64 v[216:217], s[16:17], 0, v[130:131]
	s_addc_u32 s55, s17, 0
	s_add_i32 s53, s44, s36
	global_load_lds_dwordx4 v[216:217], off
	v_lshl_add_u64 v[218:219], s[54:55], 0, v[128:129]
	s_mov_b32 m0, s53
	v_lshl_add_u64 v[220:221], s[18:19], 0, v[130:131]
	global_load_lds_dwordx4 v[218:219], off
	v_lshl_add_u64 v[218:219], s[54:55], 0, v[130:131]
	s_add_i32 m0, s53, 0x2000
	s_nop 0
	global_load_lds_dwordx4 v[218:219], off
	v_lshl_add_u64 v[218:219], s[18:19], 0, v[128:129]
	s_mov_b32 m0, s37
	s_nop 0
	global_load_lds_dwordx4 v[218:219], off
	s_mov_b32 m0, s38
	s_nop 0
	global_load_lds_dwordx4 v[220:221], off
	s_waitcnt vmcnt(8)
	s_waitcnt lgkmcnt(0)
	s_barrier
; #define PG8_STAGE(bufoff, gbase, voff) do { _Pragma("unroll") for (int _i = 0; _i < 2; ++_i) \
;         __builtin_amdgcn_global_load_lds((const unsigned*)((const char*)(gbase) + (voff)[_i]), (LAS unsigned*)(lds + (bufoff) + ldsw + _i * 8192), 16, 0, 0); } while (0)
; #define PG8_LDA(dst, b, h) do { _Pragma("unroll") for (int m = 0; m < 4; ++m) _Pragma("unroll") for (int k = 0; k < 2; ++k) dst[m][k] = *(const LAS bf16x8*)(lds + PG8_SA(b, h) + aoff + m * 2048 + k * 1024); } while (0)
; #define PG8_LDB(dst, b, h) do { _Pragma("unroll") for (int n = 0; n < 2; ++n) _Pragma("unroll") for (int k = 0; k < 2; ++k) dst[n][k] = *(const LAS bf16x8*)(lds + PG8_SB(b, h) + boff + n * 2048 + k * 1024); } while (0)
; #define PG8_MMA(ai, bj, At, Bt) do { __builtin_amdgcn_s_setprio(1); _Pragma("unroll") for (int m = 0; m < 4; ++m) _Pragma("unroll") for (int n = 0; n < 2; ++n) _Pragma("unroll") for (int k = 0; k < 2; ++k) \
;         acc[ai][bj][m][n] = __builtin_amdgcn_mfma_f32_16x16x32_bf16(Bt[n][k], At[m][k], acc[ai][bj][m][n], 0, 0, 0); __builtin_amdgcn_s_setprio(0); } while (0)
; #define PG8_WAIT_V(n) asm volatile("s_waitcnt vmcnt(" #n ")" ::: "memory")
; #define PG8_WAIT_L(n) asm volatile("s_waitcnt lgkmcnt(" #n ")" ::: "memory")
; #define PG8_BAR __builtin_amdgcn_s_barrier()
; #define PG8_SCHED __builtin_amdgcn_sched_barrier(0)
; template <class Epi, class Sched, bool ALIGN_EPI>
; DI void gemm_phase(LAS unsigned char* lds, const Gemm g, const Sched& S, const Epi& E) {
;     ...
;             PG8_WAIT_V(8); PG8_WAIT_L(0); PG8_BAR; PG8_MMA(1, 0, At, B0); PG8_MMA(1, 1, At, B1); PG8_BAR; PG8_SCHED;
;             PG8_LDB(B0, 1, 0); PG8_LDB(B1, 1, 1); PG8_SCHED; PG8_LDA(At, 1, 0); PG8_STAGE(PG8_SA(0, 1), a2 + hstepA, voffA);
;             PG8_WAIT_V(8); PG8_WAIT_L(0); PG8_BAR; PG8_MMA(0, 0, At, B0); PG8_MMA(0, 1, At, B1); PG8_BAR; PG8_SCHED;
	s_setprio 1
	s_waitcnt lgkmcnt(0)
	v_mfma_f32_16x16x32_bf16 v[60:63], v[146:149], v[182:185], v[60:63]
	v_mfma_f32_16x16x32_bf16 v[56:59], v[158:161], v[182:185], v[56:59]
	v_mfma_f32_16x16x32_bf16 v[44:47], v[146:149], v[190:193], v[44:47]
	v_mfma_f32_16x16x32_bf16 v[40:43], v[158:161], v[190:193], v[40:43]
	v_mfma_f32_16x16x32_bf16 v[28:31], v[146:149], v[198:201], v[28:31]
	v_mfma_f32_16x16x32_bf16 v[24:27], v[158:161], v[198:201], v[24:27]
	v_mfma_f32_16x16x32_bf16 v[12:15], v[146:149], v[208:211], v[12:15]
	v_mfma_f32_16x16x32_bf16 v[8:11], v[158:161], v[208:211], v[8:11]
	v_mfma_f32_16x16x32_bf16 v[60:63], v[154:157], v[186:189], v[60:63]
	v_mfma_f32_16x16x32_bf16 v[56:59], v[162:165], v[186:189], v[56:59]
	v_mfma_f32_16x16x32_bf16 v[44:47], v[154:157], v[194:197], v[44:47]
	v_mfma_f32_16x16x32_bf16 v[40:43], v[162:165], v[194:197], v[40:43]
	v_mfma_f32_16x16x32_bf16 v[28:31], v[154:157], v[204:207], v[28:31]
	v_mfma_f32_16x16x32_bf16 v[24:27], v[162:165], v[204:207], v[24:27]
	v_mfma_f32_16x16x32_bf16 v[12:15], v[154:157], v[212:215], v[12:15]
	v_mfma_f32_16x16x32_bf16 v[8:11], v[162:165], v[212:215], v[8:11]
	v_mfma_f32_16x16x32_bf16 v[52:55], v[166:169], v[182:185], v[52:55]
	v_mfma_f32_16x16x32_bf16 v[48:51], v[174:177], v[182:185], v[48:51]
	v_mfma_f32_16x16x32_bf16 v[36:39], v[166:169], v[190:193], v[36:39]
	v_mfma_f32_16x16x32_bf16 v[32:35], v[174:177], v[190:193], v[32:35]
	v_mfma_f32_16x16x32_bf16 v[20:23], v[166:169], v[198:201], v[20:23]
	v_mfma_f32_16x16x32_bf16 v[16:19], v[174:177], v[198:201], v[16:19]
	v_mfma_f32_16x16x32_bf16 v[4:7], v[166:169], v[208:211], v[4:7]
	v_mfma_f32_16x16x32_bf16 v[0:3], v[174:177], v[208:211], v[0:3]
	v_mfma_f32_16x16x32_bf16 v[52:55], v[170:173], v[186:189], v[52:55]
	v_mfma_f32_16x16x32_bf16 v[48:51], v[178:181], v[186:189], v[48:51]
	v_mfma_f32_16x16x32_bf16 v[36:39], v[170:173], v[194:197], v[36:39]
	v_mfma_f32_16x16x32_bf16 v[32:35], v[178:181], v[194:197], v[32:35]
	v_mfma_f32_16x16x32_bf16 v[20:23], v[170:173], v[204:207], v[20:23]
	v_mfma_f32_16x16x32_bf16 v[16:19], v[178:181], v[204:207], v[16:19]
	v_mfma_f32_16x16x32_bf16 v[4:7], v[170:173], v[212:215], v[4:7]
	v_mfma_f32_16x16x32_bf16 v[0:3], v[178:181], v[212:215], v[0:3]
	s_setprio 0
	s_barrier
	v_add_u32_e32 v153, s45, v144
	ds_read_b128 v[146:149], v153
	ds_read_b128 v[154:157], v153 offset:1024
	ds_read_b128 v[158:161], v153 offset:2048
	ds_read_b128 v[162:165], v153 offset:3072
	v_add_u32_e32 v153, s47, v144
	ds_read_b128 v[166:169], v153
	ds_read_b128 v[170:173], v153 offset:1024
	ds_read_b128 v[174:177], v153 offset:2048
	ds_read_b128 v[178:181], v153 offset:3072
	s_add_u32 s18, s18, 0xb0000
	s_addc_u32 s19, s19, 0
	s_mov_b32 m0, s39
	v_lshl_add_u64 v[222:223], s[18:19], 0, v[128:129]
	ds_read_b128 v[182:185], v145 offset:32768
	ds_read_b128 v[186:189], v145 offset:33792
	ds_read_b128 v[190:193], v145 offset:34816
	ds_read_b128 v[194:197], v145 offset:35840
	ds_read_b128 v[198:201], v145 offset:36864
	ds_read_b128 v[204:207], v145 offset:37888
	ds_read_b128 v[208:211], v145 offset:38912
	ds_read_b128 v[212:215], v145 offset:39936
	global_load_lds_dwordx4 v[222:223], off
	v_lshl_add_u64 v[222:223], s[18:19], 0, v[130:131]
	s_mov_b32 m0, s40
	s_nop 0
	global_load_lds_dwordx4 v[222:223], off
	s_waitcnt vmcnt(8)
	s_waitcnt lgkmcnt(0)
	s_barrier
	s_setprio 1
	s_waitcnt lgkmcnt(0)
	v_mfma_f32_16x16x32_bf16 v[124:127], v[146:149], v[182:185], v[124:127]
	v_mfma_f32_16x16x32_bf16 v[120:123], v[158:161], v[182:185], v[120:123]
	v_mfma_f32_16x16x32_bf16 v[112:115], v[146:149], v[190:193], v[112:115]
	v_mfma_f32_16x16x32_bf16 v[108:111], v[158:161], v[190:193], v[108:111]
	v_mfma_f32_16x16x32_bf16 v[96:99], v[146:149], v[198:201], v[96:99]
	v_mfma_f32_16x16x32_bf16 v[92:95], v[158:161], v[198:201], v[92:95]
	v_mfma_f32_16x16x32_bf16 v[80:83], v[146:149], v[208:211], v[80:83]
	v_mfma_f32_16x16x32_bf16 v[76:79], v[158:161], v[208:211], v[76:79]
	v_mfma_f32_16x16x32_bf16 v[124:127], v[154:157], v[186:189], v[124:127]
	v_mfma_f32_16x16x32_bf16 v[120:123], v[162:165], v[186:189], v[120:123]
	v_mfma_f32_16x16x32_bf16 v[112:115], v[154:157], v[194:197], v[112:115]
	v_mfma_f32_16x16x32_bf16 v[108:111], v[162:165], v[194:197], v[108:111]
	v_mfma_f32_16x16x32_bf16 v[96:99], v[154:157], v[204:207], v[96:99]
	v_mfma_f32_16x16x32_bf16 v[92:95], v[162:165], v[204:207], v[92:95]
	v_mfma_f32_16x16x32_bf16 v[80:83], v[154:157], v[212:215], v[80:83]
	v_mfma_f32_16x16x32_bf16 v[76:79], v[162:165], v[212:215], v[76:79]
	v_mfma_f32_16x16x32_bf16 v[116:119], v[166:169], v[182:185], v[116:119]
	v_mfma_f32_16x16x32_bf16 v[104:107], v[174:177], v[182:185], v[104:107]
	v_mfma_f32_16x16x32_bf16 v[100:103], v[166:169], v[190:193], v[100:103]
	v_mfma_f32_16x16x32_bf16 v[88:91], v[174:177], v[190:193], v[88:91]
	v_mfma_f32_16x16x32_bf16 v[84:87], v[166:169], v[198:201], v[84:87]
	v_mfma_f32_16x16x32_bf16 v[72:75], v[174:177], v[198:201], v[72:75]
	v_mfma_f32_16x16x32_bf16 v[68:71], v[166:169], v[208:211], v[68:71]
	v_mfma_f32_16x16x32_bf16 v[64:67], v[174:177], v[208:211], v[64:67]
	v_mfma_f32_16x16x32_bf16 v[116:119], v[170:173], v[186:189], v[116:119]
	v_mfma_f32_16x16x32_bf16 v[104:107], v[178:181], v[186:189], v[104:107]
	v_mfma_f32_16x16x32_bf16 v[100:103], v[170:173], v[194:197], v[100:103]
	v_mfma_f32_16x16x32_bf16 v[88:91], v[178:181], v[194:197], v[88:91]
	v_mfma_f32_16x16x32_bf16 v[84:87], v[170:173], v[204:207], v[84:87]
	v_mfma_f32_16x16x32_bf16 v[72:75], v[178:181], v[204:207], v[72:75]
	v_mfma_f32_16x16x32_bf16 v[68:71], v[170:173], v[212:215], v[68:71]
	v_mfma_f32_16x16x32_bf16 v[64:67], v[178:181], v[212:215], v[64:67]
	s_setprio 0
	s_barrier
; #define PG8_STAGE(bufoff, gbase, voff) do { _Pragma("unroll") for (int _i = 0; _i < 2; ++_i) \
;         __builtin_amdgcn_global_load_lds((const unsigned*)((const char*)(gbase) + (voff)[_i]), (LAS unsigned*)(lds + (bufoff) + ldsw + _i * 8192), 16, 0, 0); } while (0)
; #define PG8_LDA(dst, b, h) do { _Pragma("unroll") for (int m = 0; m < 4; ++m) _Pragma("unroll") for (int k = 0; k < 2; ++k) dst[m][k] = *(const LAS bf16x8*)(lds + PG8_SA(b, h) + aoff + m * 2048 + k * 1024); } while (0)
; #define PG8_MMA(ai, bj, At, Bt) do { __builtin_amdgcn_s_setprio(1); _Pragma("unroll") for (int m = 0; m < 4; ++m) _Pragma("unroll") for (int n = 0; n < 2; ++n) _Pragma("unroll") for (int k = 0; k < 2; ++k) \
;         acc[ai][bj][m][n] = __builtin_amdgcn_mfma_f32_16x16x32_bf16(Bt[n][k], At[m][k], acc[ai][bj][m][n], 0, 0, 0); __builtin_amdgcn_s_setprio(0); } while (0)
; #define PG8_WAIT_V(n) asm volatile("s_waitcnt vmcnt(" #n ")" ::: "memory")
; #define PG8_WAIT_L(n) asm volatile("s_waitcnt lgkmcnt(" #n ")" ::: "memory")
; #define PG8_BAR __builtin_amdgcn_s_barrier()
; #define PG8_SCHED __builtin_amdgcn_sched_barrier(0)
; template <class Epi, class Sched, bool ALIGN_EPI>
; DI void gemm_phase(LAS unsigned char* lds, const Gemm g, const Sched& S, const Epi& E) {
;     ...
;             PG8_LDA(At, 1, 1); PG8_STAGE(PG8_SB(1, 0), b3, voffB); PG8_STAGE(PG8_SB(1, 1), b3 + hstepB, voffB); PG8_STAGE(PG8_SA(1, 0), a3, voffA);
;             PG8_WAIT_V(8); PG8_WAIT_L(0); PG8_BAR; PG8_MMA(1, 0, At, B0); PG8_MMA(1, 1, At, B1); PG8_BAR; PG8_SCHED;
;         }
;         if constexpr (ALIGN_EPI) { if (wr == 0) PG8_BAR; }
;         if constexpr (!Epi::AFTER_DRAIN) E(acc, cur, wr, wc, fr, fq);
;         if (!has_next) break;
; #pragma unroll
;         for (int a = 0; a < 2; ++a)
; #pragma unroll
;             for (int b = 0; b < 2; ++b)
; #pragma unroll
;                 for (int m = 0; m < 4; ++m)
; #pragma unroll
;                     for (int n = 0; n < 2; ++n) acc[a][b][m][n] = (f32x4){0.f, 0.f, 0.f, 0.f};
	s_add_i32 s18, s45, s36
	v_lshl_add_u64 v[150:151], v[150:151], 0, s[10:11]
	s_mov_b32 m0, s18
	ds_read_b128 v[182:185], v145 offset:49152
	ds_read_b128 v[186:189], v145 offset:50176
	ds_read_b128 v[190:193], v145 offset:51200
	ds_read_b128 v[194:197], v145 offset:52224
	ds_read_b128 v[198:201], v145 offset:53248
	ds_read_b128 v[204:207], v145 offset:54272
	ds_read_b128 v[208:211], v145 offset:55296
	ds_read_b128 v[212:215], v145 offset:56320
	global_load_lds_dwordx4 v[150:151], off
	s_add_i32 m0, s18, 0x2000
	s_add_u32 s16, s16, 0xb0080
	v_lshl_add_u64 v[150:151], v[216:217], 0, s[10:11]
	s_addc_u32 s17, s17, 0
	s_add_i32 s18, s47, s36
	global_load_lds_dwordx4 v[150:151], off
	v_lshl_add_u64 v[150:151], s[16:17], 0, v[128:129]
	s_mov_b32 m0, s18
	s_nop 0
	global_load_lds_dwordx4 v[150:151], off
	v_lshl_add_u64 v[150:151], s[16:17], 0, v[130:131]
	s_add_i32 m0, s18, 0x2000
	s_nop 0
	global_load_lds_dwordx4 v[150:151], off
	v_lshl_add_u64 v[150:151], v[218:219], 0, s[10:11]
	s_mov_b32 m0, s41
	s_nop 0
	global_load_lds_dwordx4 v[150:151], off
	v_lshl_add_u64 v[150:151], v[220:221], 0, s[10:11]
	s_mov_b32 m0, s42
	s_nop 0
	global_load_lds_dwordx4 v[150:151], off
	s_waitcnt vmcnt(8)
	s_waitcnt lgkmcnt(0)
	s_barrier
	s_setprio 1
	s_waitcnt lgkmcnt(0)
	v_mfma_f32_16x16x32_bf16 v[60:63], v[146:149], v[182:185], v[60:63]
	v_mfma_f32_16x16x32_bf16 v[56:59], v[158:161], v[182:185], v[56:59]
	v_mfma_f32_16x16x32_bf16 v[44:47], v[146:149], v[190:193], v[44:47]
	v_mfma_f32_16x16x32_bf16 v[40:43], v[158:161], v[190:193], v[40:43]
	v_mfma_f32_16x16x32_bf16 v[28:31], v[146:149], v[198:201], v[28:31]
	v_mfma_f32_16x16x32_bf16 v[24:27], v[158:161], v[198:201], v[24:27]
	v_mfma_f32_16x16x32_bf16 v[12:15], v[146:149], v[208:211], v[12:15]
	v_mfma_f32_16x16x32_bf16 v[8:11], v[158:161], v[208:211], v[8:11]
	v_mfma_f32_16x16x32_bf16 v[60:63], v[154:157], v[186:189], v[60:63]
	v_mfma_f32_16x16x32_bf16 v[56:59], v[162:165], v[186:189], v[56:59]
	v_mfma_f32_16x16x32_bf16 v[44:47], v[154:157], v[194:197], v[44:47]
	v_mfma_f32_16x16x32_bf16 v[40:43], v[162:165], v[194:197], v[40:43]
	v_mfma_f32_16x16x32_bf16 v[28:31], v[154:157], v[204:207], v[28:31]
	v_mfma_f32_16x16x32_bf16 v[24:27], v[162:165], v[204:207], v[24:27]
	v_mfma_f32_16x16x32_bf16 v[12:15], v[154:157], v[212:215], v[12:15]
	v_mfma_f32_16x16x32_bf16 v[8:11], v[162:165], v[212:215], v[8:11]
	v_mfma_f32_16x16x32_bf16 v[52:55], v[166:169], v[182:185], v[52:55]
	v_mfma_f32_16x16x32_bf16 v[48:51], v[174:177], v[182:185], v[48:51]
	v_mfma_f32_16x16x32_bf16 v[36:39], v[166:169], v[190:193], v[36:39]
	v_mfma_f32_16x16x32_bf16 v[32:35], v[174:177], v[190:193], v[32:35]
	v_mfma_f32_16x16x32_bf16 v[20:23], v[166:169], v[198:201], v[20:23]
	v_mfma_f32_16x16x32_bf16 v[16:19], v[174:177], v[198:201], v[16:19]
	v_mfma_f32_16x16x32_bf16 v[4:7], v[166:169], v[208:211], v[4:7]
	v_mfma_f32_16x16x32_bf16 v[0:3], v[174:177], v[208:211], v[0:3]
	v_mfma_f32_16x16x32_bf16 v[52:55], v[170:173], v[186:189], v[52:55]
	v_mfma_f32_16x16x32_bf16 v[48:51], v[178:181], v[186:189], v[48:51]
	v_mfma_f32_16x16x32_bf16 v[36:39], v[170:173], v[194:197], v[36:39]
	v_mfma_f32_16x16x32_bf16 v[32:35], v[178:181], v[194:197], v[32:35]
	v_mfma_f32_16x16x32_bf16 v[20:23], v[170:173], v[204:207], v[20:23]
	v_mfma_f32_16x16x32_bf16 v[16:19], v[178:181], v[204:207], v[16:19]
	v_mfma_f32_16x16x32_bf16 v[4:7], v[170:173], v[212:215], v[4:7]
	v_mfma_f32_16x16x32_bf16 v[0:3], v[178:181], v[212:215], v[0:3]
	s_setprio 0
	s_barrier
	s_add_i32 s52, s52, 2
	s_add_u32 s14, s14, 0x100
	s_addc_u32 s15, s15, 0
	s_cmp_gt_u32 s52, 41
	s_cbranch_scc0 .LBB0_2548
	s_add_u32 s14, s50, 0xffffff00
	s_addc_u32 s15, s51, -1
	s_and_b64 vcc, exec, s[6:7]
	s_cbranch_vccnz .LBB0_2551
	v_mov_b32_e32 v0, 0
	s_mov_b32 s2, s48
	s_mov_b32 s22, s49
	s_mov_b64 s[8:9], s[12:13]
	s_mov_b32 s46, s33
	v_mov_b32_e32 v1, v0
	v_mov_b32_e32 v2, v0
	v_mov_b32_e32 v3, v0
	v_mov_b32_e32 v4, v0
	v_mov_b32_e32 v5, v0
	v_mov_b32_e32 v6, v0
	v_mov_b32_e32 v7, v0
	v_mov_b32_e32 v16, v0
	v_mov_b32_e32 v17, v0
	v_mov_b32_e32 v18, v0
	v_mov_b32_e32 v19, v0
	v_mov_b32_e32 v20, v0
	v_mov_b32_e32 v21, v0
	v_mov_b32_e32 v22, v0
	v_mov_b32_e32 v23, v0
	v_mov_b32_e32 v32, v0
	v_mov_b32_e32 v33, v0
	v_mov_b32_e32 v34, v0
	v_mov_b32_e32 v35, v0
	v_mov_b32_e32 v36, v0
	v_mov_b32_e32 v37, v0
	v_mov_b32_e32 v38, v0
	v_mov_b32_e32 v39, v0
	v_mov_b32_e32 v48, v0
	v_mov_b32_e32 v49, v0
	v_mov_b32_e32 v50, v0
	v_mov_b32_e32 v51, v0
	v_mov_b32_e32 v52, v0
	v_mov_b32_e32 v53, v0
	v_mov_b32_e32 v54, v0
	v_mov_b32_e32 v55, v0
	v_mov_b32_e32 v8, v0
	v_mov_b32_e32 v9, v0
	v_mov_b32_e32 v10, v0
	v_mov_b32_e32 v11, v0
	v_mov_b32_e32 v12, v0
	v_mov_b32_e32 v13, v0
	v_mov_b32_e32 v14, v0
	v_mov_b32_e32 v15, v0
	v_mov_b32_e32 v24, v0
	v_mov_b32_e32 v25, v0
	v_mov_b32_e32 v26, v0
	v_mov_b32_e32 v27, v0
	v_mov_b32_e32 v28, v0
	v_mov_b32_e32 v29, v0
	v_mov_b32_e32 v30, v0
	v_mov_b32_e32 v31, v0
	v_mov_b32_e32 v40, v0
	v_mov_b32_e32 v41, v0
	v_mov_b32_e32 v42, v0
	v_mov_b32_e32 v43, v0
	v_mov_b32_e32 v44, v0
	v_mov_b32_e32 v45, v0
	v_mov_b32_e32 v46, v0
	v_mov_b32_e32 v47, v0
	v_mov_b32_e32 v56, v0
	v_mov_b32_e32 v57, v0
	v_mov_b32_e32 v58, v0
	v_mov_b32_e32 v59, v0
	v_mov_b32_e32 v60, v0
	v_mov_b32_e32 v61, v0
	v_mov_b32_e32 v62, v0
	v_mov_b32_e32 v63, v0
	v_mov_b32_e32 v64, v0
	v_mov_b32_e32 v65, v0
	v_mov_b32_e32 v66, v0
	v_mov_b32_e32 v67, v0
	v_mov_b32_e32 v68, v0
	v_mov_b32_e32 v69, v0
	v_mov_b32_e32 v70, v0
	v_mov_b32_e32 v71, v0
	v_mov_b32_e32 v72, v0
	v_mov_b32_e32 v73, v0
	v_mov_b32_e32 v74, v0
	v_mov_b32_e32 v75, v0
	v_mov_b32_e32 v84, v0
	v_mov_b32_e32 v85, v0
	v_mov_b32_e32 v86, v0
	v_mov_b32_e32 v87, v0
	v_mov_b32_e32 v88, v0
	v_mov_b32_e32 v89, v0
	v_mov_b32_e32 v90, v0
	v_mov_b32_e32 v91, v0
	v_mov_b32_e32 v100, v0
	v_mov_b32_e32 v101, v0
	v_mov_b32_e32 v102, v0
	v_mov_b32_e32 v103, v0
	v_mov_b32_e32 v104, v0
	v_mov_b32_e32 v105, v0
	v_mov_b32_e32 v106, v0
	v_mov_b32_e32 v107, v0
	v_mov_b32_e32 v116, v0
	v_mov_b32_e32 v117, v0
	v_mov_b32_e32 v118, v0
	v_mov_b32_e32 v119, v0
	v_mov_b32_e32 v76, v0
	v_mov_b32_e32 v77, v0
	v_mov_b32_e32 v78, v0
	v_mov_b32_e32 v79, v0
	v_mov_b32_e32 v80, v0
	v_mov_b32_e32 v81, v0
	v_mov_b32_e32 v82, v0
	v_mov_b32_e32 v83, v0
	v_mov_b32_e32 v92, v0
	v_mov_b32_e32 v93, v0
	v_mov_b32_e32 v94, v0
	v_mov_b32_e32 v95, v0
	v_mov_b32_e32 v96, v0
	v_mov_b32_e32 v97, v0
	v_mov_b32_e32 v98, v0
	v_mov_b32_e32 v99, v0
	v_mov_b32_e32 v108, v0
	v_mov_b32_e32 v109, v0
	v_mov_b32_e32 v110, v0
	v_mov_b32_e32 v111, v0
	v_mov_b32_e32 v112, v0
	v_mov_b32_e32 v113, v0
	v_mov_b32_e32 v114, v0
	v_mov_b32_e32 v115, v0
	v_mov_b32_e32 v120, v0
	v_mov_b32_e32 v121, v0
	v_mov_b32_e32 v122, v0
	v_mov_b32_e32 v123, v0
	v_mov_b32_e32 v124, v0
	v_mov_b32_e32 v125, v0
	v_mov_b32_e32 v126, v0
	v_mov_b32_e32 v127, v0
	s_andn2_b64 vcc, exec, s[4:5]
	s_cbranch_vccnz .LBB0_2552
	s_branch .LBB0_2553

; #define PG8_STAGE(bufoff, gbase, voff) do { _Pragma("unroll") for (int _i = 0; _i < 2; ++_i) \
;         __builtin_amdgcn_global_load_lds((const unsigned*)((const char*)(gbase) + (voff)[_i]), (LAS unsigned*)(lds + (bufoff) + ldsw + _i * 8192), 16, 0, 0); } while (0)
; #define PG8_LDA(dst, b, h) do { _Pragma("unroll") for (int m = 0; m < 4; ++m) _Pragma("unroll") for (int k = 0; k < 2; ++k) dst[m][k] = *(const LAS bf16x8*)(lds + PG8_SA(b, h) + aoff + m * 2048 + k * 1024); } while (0)
; #define PG8_LDB(dst, b, h) do { _Pragma("unroll") for (int n = 0; n < 2; ++n) _Pragma("unroll") for (int k = 0; k < 2; ++k) dst[n][k] = *(const LAS bf16x8*)(lds + PG8_SB(b, h) + boff + n * 2048 + k * 1024); } while (0)
; #define PG8_MMA(ai, bj, At, Bt) do { __builtin_amdgcn_s_setprio(1); _Pragma("unroll") for (int m = 0; m < 4; ++m) _Pragma("unroll") for (int n = 0; n < 2; ++n) _Pragma("unroll") for (int k = 0; k < 2; ++k) \
;         acc[ai][bj][m][n] = __builtin_amdgcn_mfma_f32_16x16x32_bf16(Bt[n][k], At[m][k], acc[ai][bj][m][n], 0, 0, 0); __builtin_amdgcn_s_setprio(0); } while (0)
; #define PG8_WAIT_V(n) asm volatile("s_waitcnt vmcnt(" #n ")" ::: "memory")
; #define PG8_BAR __builtin_amdgcn_s_barrier()
; template <class Epi, class Sched, bool ALIGN_EPI>
; DI void gemm_phase(LAS unsigned char* lds, const Gemm g, const Sched& S, const Epi& E) {
;     ...
;         const char* nA = has_next ? (const char*)g.A + (size_t)nxt.pm * tstepA : cA; const char* nB = has_next ? (const char*)g.Bt + (size_t)nxt.pn * tstepB : cB;
;         for (int t = 0; t < nt; t += 2) {
;             const bool last = (t == nt - 2);
;             const char* a1 = cA + (size_t)(t + 1) * kstep;
;             const char* a2 = last ? nA : cA + (size_t)(t + 2) * kstep; const char* b2 = last ? nB : cB + (size_t)(t + 2) * kstep;
;             const char* a3 = a2 + kstep; const char* b3 = b2 + kstep;
;             PG8_LDB(B0, 0, 0); PG8_LDB(B1, 0, 1); PG8_SCHED; PG8_LDA(At, 0, 0); PG8_STAGE(PG8_SA(1, 1), a1 + hstepA, voffA);
;             PG8_WAIT_V(8); PG8_WAIT_L(0); PG8_BAR; PG8_MMA(0, 0, At, B0); PG8_MMA(0, 1, At, B1); PG8_BAR; PG8_SCHED;
;             PG8_LDA(At, 0, 1); PG8_STAGE(PG8_SB(0, 0), b2, voffB); PG8_STAGE(PG8_SB(0, 1), b2 + hstepB, voffB); PG8_STAGE(PG8_SA(0, 0), a2, voffA);
;             PG8_WAIT_V(8); PG8_WAIT_L(0); PG8_BAR; PG8_MMA(1, 0, At, B0); PG8_MMA(1, 1, At, B1); PG8_BAR; PG8_SCHED;
.LBB0_2661:
	ds_read_b128 v[140:143], v150
	ds_read_b128 v[144:147], v150 offset:1024
	ds_read_b128 v[156:159], v150 offset:2048
	ds_read_b128 v[160:163], v150 offset:3072
	ds_read_b128 v[164:167], v151
	ds_read_b128 v[168:171], v151 offset:1024
	ds_read_b128 v[172:175], v151 offset:2048
	ds_read_b128 v[176:179], v151 offset:3072
	s_add_u32 s24, s22, 0xfffc0080
	s_addc_u32 s25, s23, -1
	s_cmp_eq_u32 s52, 12
	s_cselect_b32 s27, s15, s25
	s_cselect_b32 s26, s48, s24
	s_cselect_b32 s25, s13, s51
	s_cselect_b32 s24, s49, s50
	v_lshl_add_u64 v[212:213], s[22:23], 0, v[132:133]
	s_add_i32 m0, s21, 0xc000
	ds_read_b128 v[180:183], v152
	ds_read_b128 v[184:187], v152 offset:1024
	ds_read_b128 v[188:191], v152 offset:2048
	ds_read_b128 v[192:195], v152 offset:3072
	ds_read_b128 v[196:199], v152 offset:4096
	ds_read_b128 v[200:203], v152 offset:5120
	ds_read_b128 v[204:207], v152 offset:6144
	ds_read_b128 v[208:211], v152 offset:7168
	global_load_lds_dwordx4 v[212:213], off
	v_lshl_add_u64 v[212:213], s[22:23], 0, v[134:135]
	s_add_i32 m0, s21, 0xe000
	s_nop 0
	global_load_lds_dwordx4 v[212:213], off
	s_waitcnt vmcnt(8)
	s_waitcnt lgkmcnt(0)
	s_barrier
	s_setprio 1
	s_waitcnt lgkmcnt(0)
	v_mfma_f32_16x16x32_bf16 v[124:127], v[140:143], v[180:183], v[124:127]
	v_mfma_f32_16x16x32_bf16 v[120:123], v[156:159], v[180:183], v[120:123]
	v_mfma_f32_16x16x32_bf16 v[108:111], v[140:143], v[188:191], v[108:111]
	v_mfma_f32_16x16x32_bf16 v[104:107], v[156:159], v[188:191], v[104:107]
	v_mfma_f32_16x16x32_bf16 v[92:95], v[140:143], v[196:199], v[92:95]
	v_mfma_f32_16x16x32_bf16 v[88:91], v[156:159], v[196:199], v[88:91]
	v_mfma_f32_16x16x32_bf16 v[76:79], v[140:143], v[204:207], v[76:79]
	v_mfma_f32_16x16x32_bf16 v[72:75], v[156:159], v[204:207], v[72:75]
	v_mfma_f32_16x16x32_bf16 v[124:127], v[144:147], v[184:187], v[124:127]
	v_mfma_f32_16x16x32_bf16 v[120:123], v[160:163], v[184:187], v[120:123]
	v_mfma_f32_16x16x32_bf16 v[108:111], v[144:147], v[192:195], v[108:111]
	v_mfma_f32_16x16x32_bf16 v[104:107], v[160:163], v[192:195], v[104:107]
	v_mfma_f32_16x16x32_bf16 v[92:95], v[144:147], v[200:203], v[92:95]
	v_mfma_f32_16x16x32_bf16 v[88:91], v[160:163], v[200:203], v[88:91]
	v_mfma_f32_16x16x32_bf16 v[76:79], v[144:147], v[208:211], v[76:79]
	v_mfma_f32_16x16x32_bf16 v[72:75], v[160:163], v[208:211], v[72:75]
	v_mfma_f32_16x16x32_bf16 v[116:119], v[164:167], v[180:183], v[116:119]
	v_mfma_f32_16x16x32_bf16 v[112:115], v[172:175], v[180:183], v[112:115]
	v_mfma_f32_16x16x32_bf16 v[100:103], v[164:167], v[188:191], v[100:103]
	v_mfma_f32_16x16x32_bf16 v[96:99], v[172:175], v[188:191], v[96:99]
	v_mfma_f32_16x16x32_bf16 v[84:87], v[164:167], v[196:199], v[84:87]
	v_mfma_f32_16x16x32_bf16 v[80:83], v[172:175], v[196:199], v[80:83]
	v_mfma_f32_16x16x32_bf16 v[68:71], v[164:167], v[204:207], v[68:71]
	v_mfma_f32_16x16x32_bf16 v[64:67], v[172:175], v[204:207], v[64:67]
	v_mfma_f32_16x16x32_bf16 v[116:119], v[168:171], v[184:187], v[116:119]
	v_mfma_f32_16x16x32_bf16 v[112:115], v[176:179], v[184:187], v[112:115]
	v_mfma_f32_16x16x32_bf16 v[100:103], v[168:171], v[192:195], v[100:103]
	v_mfma_f32_16x16x32_bf16 v[96:99], v[176:179], v[192:195], v[96:99]
	v_mfma_f32_16x16x32_bf16 v[84:87], v[168:171], v[200:203], v[84:87]
	v_mfma_f32_16x16x32_bf16 v[80:83], v[176:179], v[200:203], v[80:83]
	v_mfma_f32_16x16x32_bf16 v[68:71], v[168:171], v[208:211], v[68:71]
	v_mfma_f32_16x16x32_bf16 v[64:67], v[176:179], v[208:211], v[64:67]
	s_setprio 0
	s_barrier
	s_add_i32 s53, s43, s37
	v_lshl_add_u64 v[212:213], s[24:25], 0, v[128:129]
	s_mov_b32 m0, s53
	ds_read_b128 v[180:183], v152 offset:16384
	ds_read_b128 v[184:187], v152 offset:17408
	ds_read_b128 v[188:191], v152 offset:18432
	ds_read_b128 v[192:195], v152 offset:19456
	ds_read_b128 v[196:199], v152 offset:20480
	ds_read_b128 v[200:203], v152 offset:21504
	ds_read_b128 v[204:207], v152 offset:22528
	ds_read_b128 v[208:211], v152 offset:23552
	global_load_lds_dwordx4 v[212:213], off
	s_add_i32 m0, s53, 0x2000
	s_add_u32 s54, s24, 0x40000
	v_lshl_add_u64 v[214:215], s[24:25], 0, v[130:131]
	s_addc_u32 s55, s25, 0
	s_add_i32 s53, s44, s37
	global_load_lds_dwordx4 v[214:215], off
	v_lshl_add_u64 v[216:217], s[54:55], 0, v[128:129]
	s_mov_b32 m0, s53
	v_lshl_add_u64 v[218:219], s[26:27], 0, v[130:131]
	global_load_lds_dwordx4 v[216:217], off
	v_lshl_add_u64 v[216:217], s[54:55], 0, v[130:131]
	s_add_i32 m0, s53, 0x2000
	s_nop 0
	global_load_lds_dwordx4 v[216:217], off
	v_lshl_add_u64 v[216:217], s[26:27], 0, v[128:129]
	s_mov_b32 m0, s21
	s_nop 0
	global_load_lds_dwordx4 v[216:217], off
	s_mov_b32 m0, s38
	s_nop 0
	global_load_lds_dwordx4 v[218:219], off
	s_waitcnt vmcnt(8)
	s_waitcnt lgkmcnt(0)
	s_barrier
; #define PG8_STAGE(bufoff, gbase, voff) do { _Pragma("unroll") for (int _i = 0; _i < 2; ++_i) \
;         __builtin_amdgcn_global_load_lds((const unsigned*)((const char*)(gbase) + (voff)[_i]), (LAS unsigned*)(lds + (bufoff) + ldsw + _i * 8192), 16, 0, 0); } while (0)
; #define PG8_LDA(dst, b, h) do { _Pragma("unroll") for (int m = 0; m < 4; ++m) _Pragma("unroll") for (int k = 0; k < 2; ++k) dst[m][k] = *(const LAS bf16x8*)(lds + PG8_SA(b, h) + aoff + m * 2048 + k * 1024); } while (0)
; #define PG8_LDB(dst, b, h) do { _Pragma("unroll") for (int n = 0; n < 2; ++n) _Pragma("unroll") for (int k = 0; k < 2; ++k) dst[n][k] = *(const LAS bf16x8*)(lds + PG8_SB(b, h) + boff + n * 2048 + k * 1024); } while (0)
; #define PG8_MMA(ai, bj, At, Bt) do { __builtin_amdgcn_s_setprio(1); _Pragma("unroll") for (int m = 0; m < 4; ++m) _Pragma("unroll") for (int n = 0; n < 2; ++n) _Pragma("unroll") for (int k = 0; k < 2; ++k) \
;         acc[ai][bj][m][n] = __builtin_amdgcn_mfma_f32_16x16x32_bf16(Bt[n][k], At[m][k], acc[ai][bj][m][n], 0, 0, 0); __builtin_amdgcn_s_setprio(0); } while (0)
; #define PG8_WAIT_V(n) asm volatile("s_waitcnt vmcnt(" #n ")" ::: "memory")
; #define PG8_WAIT_L(n) asm volatile("s_waitcnt lgkmcnt(" #n ")" ::: "memory")
; #define PG8_BAR __builtin_amdgcn_s_barrier()
; #define PG8_SCHED __builtin_amdgcn_sched_barrier(0)
; template <class Epi, class Sched, bool ALIGN_EPI>
; DI void gemm_phase(LAS unsigned char* lds, const Gemm g, const Sched& S, const Epi& E) {
;     ...
;             PG8_WAIT_V(8); PG8_WAIT_L(0); PG8_BAR; PG8_MMA(1, 0, At, B0); PG8_MMA(1, 1, At, B1); PG8_BAR; PG8_SCHED;
;             PG8_LDB(B0, 1, 0); PG8_LDB(B1, 1, 1); PG8_SCHED; PG8_LDA(At, 1, 0); PG8_STAGE(PG8_SA(0, 1), a2 + hstepA, voffA);
;             PG8_WAIT_V(8); PG8_WAIT_L(0); PG8_BAR; PG8_MMA(0, 0, At, B0); PG8_MMA(0, 1, At, B1); PG8_BAR; PG8_SCHED;
	s_setprio 1
	s_waitcnt lgkmcnt(0)
	v_mfma_f32_16x16x32_bf16 v[60:63], v[140:143], v[180:183], v[60:63]
	v_mfma_f32_16x16x32_bf16 v[56:59], v[156:159], v[180:183], v[56:59]
	v_mfma_f32_16x16x32_bf16 v[44:47], v[140:143], v[188:191], v[44:47]
	v_mfma_f32_16x16x32_bf16 v[40:43], v[156:159], v[188:191], v[40:43]
	v_mfma_f32_16x16x32_bf16 v[28:31], v[140:143], v[196:199], v[28:31]
	v_mfma_f32_16x16x32_bf16 v[24:27], v[156:159], v[196:199], v[24:27]
	v_mfma_f32_16x16x32_bf16 v[12:15], v[140:143], v[204:207], v[12:15]
	v_mfma_f32_16x16x32_bf16 v[8:11], v[156:159], v[204:207], v[8:11]
	v_mfma_f32_16x16x32_bf16 v[60:63], v[144:147], v[184:187], v[60:63]
	v_mfma_f32_16x16x32_bf16 v[56:59], v[160:163], v[184:187], v[56:59]
	v_mfma_f32_16x16x32_bf16 v[44:47], v[144:147], v[192:195], v[44:47]
	v_mfma_f32_16x16x32_bf16 v[40:43], v[160:163], v[192:195], v[40:43]
	v_mfma_f32_16x16x32_bf16 v[28:31], v[144:147], v[200:203], v[28:31]
	v_mfma_f32_16x16x32_bf16 v[24:27], v[160:163], v[200:203], v[24:27]
	v_mfma_f32_16x16x32_bf16 v[12:15], v[144:147], v[208:211], v[12:15]
	v_mfma_f32_16x16x32_bf16 v[8:11], v[160:163], v[208:211], v[8:11]
	v_mfma_f32_16x16x32_bf16 v[52:55], v[164:167], v[180:183], v[52:55]
	v_mfma_f32_16x16x32_bf16 v[48:51], v[172:175], v[180:183], v[48:51]
	v_mfma_f32_16x16x32_bf16 v[36:39], v[164:167], v[188:191], v[36:39]
	v_mfma_f32_16x16x32_bf16 v[32:35], v[172:175], v[188:191], v[32:35]
	v_mfma_f32_16x16x32_bf16 v[20:23], v[164:167], v[196:199], v[20:23]
	v_mfma_f32_16x16x32_bf16 v[16:19], v[172:175], v[196:199], v[16:19]
	v_mfma_f32_16x16x32_bf16 v[4:7], v[164:167], v[204:207], v[4:7]
	v_mfma_f32_16x16x32_bf16 v[0:3], v[172:175], v[204:207], v[0:3]
	v_mfma_f32_16x16x32_bf16 v[52:55], v[168:171], v[184:187], v[52:55]
	v_mfma_f32_16x16x32_bf16 v[48:51], v[176:179], v[184:187], v[48:51]
	v_mfma_f32_16x16x32_bf16 v[36:39], v[168:171], v[192:195], v[36:39]
	v_mfma_f32_16x16x32_bf16 v[32:35], v[176:179], v[192:195], v[32:35]
	v_mfma_f32_16x16x32_bf16 v[20:23], v[168:171], v[200:203], v[20:23]
	v_mfma_f32_16x16x32_bf16 v[16:19], v[176:179], v[200:203], v[16:19]
	v_mfma_f32_16x16x32_bf16 v[4:7], v[168:171], v[208:211], v[4:7]
	v_mfma_f32_16x16x32_bf16 v[0:3], v[176:179], v[208:211], v[0:3]
	s_setprio 0
	s_barrier
	ds_read_b128 v[140:143], v153
	ds_read_b128 v[144:147], v153 offset:1024
	ds_read_b128 v[156:159], v153 offset:2048
	ds_read_b128 v[160:163], v153 offset:3072
	ds_read_b128 v[164:167], v154
	ds_read_b128 v[168:171], v154 offset:1024
	ds_read_b128 v[172:175], v154 offset:2048
	ds_read_b128 v[176:179], v154 offset:3072
	s_add_u32 s26, s26, 0x40000
	s_addc_u32 s27, s27, 0
	s_mov_b32 m0, s39
	v_lshl_add_u64 v[220:221], s[26:27], 0, v[128:129]
	ds_read_b128 v[180:183], v152 offset:32768
	ds_read_b128 v[184:187], v152 offset:33792
	ds_read_b128 v[188:191], v152 offset:34816
	ds_read_b128 v[192:195], v152 offset:35840
	ds_read_b128 v[196:199], v152 offset:36864
	ds_read_b128 v[200:203], v152 offset:37888
	ds_read_b128 v[204:207], v152 offset:38912
	ds_read_b128 v[208:211], v152 offset:39936
	global_load_lds_dwordx4 v[220:221], off
	v_lshl_add_u64 v[220:221], s[26:27], 0, v[130:131]
	s_mov_b32 m0, s40
	s_nop 0
	global_load_lds_dwordx4 v[220:221], off
	s_waitcnt vmcnt(8)
	s_waitcnt lgkmcnt(0)
	s_barrier
	s_setprio 1
	s_waitcnt lgkmcnt(0)
	v_mfma_f32_16x16x32_bf16 v[124:127], v[140:143], v[180:183], v[124:127]
	v_mfma_f32_16x16x32_bf16 v[120:123], v[156:159], v[180:183], v[120:123]
	v_mfma_f32_16x16x32_bf16 v[108:111], v[140:143], v[188:191], v[108:111]
	v_mfma_f32_16x16x32_bf16 v[104:107], v[156:159], v[188:191], v[104:107]
	v_mfma_f32_16x16x32_bf16 v[92:95], v[140:143], v[196:199], v[92:95]
	v_mfma_f32_16x16x32_bf16 v[88:91], v[156:159], v[196:199], v[88:91]
	v_mfma_f32_16x16x32_bf16 v[76:79], v[140:143], v[204:207], v[76:79]
	v_mfma_f32_16x16x32_bf16 v[72:75], v[156:159], v[204:207], v[72:75]
	v_mfma_f32_16x16x32_bf16 v[124:127], v[144:147], v[184:187], v[124:127]
	v_mfma_f32_16x16x32_bf16 v[120:123], v[160:163], v[184:187], v[120:123]
	v_mfma_f32_16x16x32_bf16 v[108:111], v[144:147], v[192:195], v[108:111]
	v_mfma_f32_16x16x32_bf16 v[104:107], v[160:163], v[192:195], v[104:107]
	v_mfma_f32_16x16x32_bf16 v[92:95], v[144:147], v[200:203], v[92:95]
	v_mfma_f32_16x16x32_bf16 v[88:91], v[160:163], v[200:203], v[88:91]
	v_mfma_f32_16x16x32_bf16 v[76:79], v[144:147], v[208:211], v[76:79]
	v_mfma_f32_16x16x32_bf16 v[72:75], v[160:163], v[208:211], v[72:75]
	v_mfma_f32_16x16x32_bf16 v[116:119], v[164:167], v[180:183], v[116:119]
	v_mfma_f32_16x16x32_bf16 v[112:115], v[172:175], v[180:183], v[112:115]
	v_mfma_f32_16x16x32_bf16 v[100:103], v[164:167], v[188:191], v[100:103]
	v_mfma_f32_16x16x32_bf16 v[96:99], v[172:175], v[188:191], v[96:99]
	v_mfma_f32_16x16x32_bf16 v[84:87], v[164:167], v[196:199], v[84:87]
	v_mfma_f32_16x16x32_bf16 v[80:83], v[172:175], v[196:199], v[80:83]
	v_mfma_f32_16x16x32_bf16 v[68:71], v[164:167], v[204:207], v[68:71]
	v_mfma_f32_16x16x32_bf16 v[64:67], v[172:175], v[204:207], v[64:67]
	v_mfma_f32_16x16x32_bf16 v[116:119], v[168:171], v[184:187], v[116:119]
	v_mfma_f32_16x16x32_bf16 v[112:115], v[176:179], v[184:187], v[112:115]
	v_mfma_f32_16x16x32_bf16 v[100:103], v[168:171], v[192:195], v[100:103]
	v_mfma_f32_16x16x32_bf16 v[96:99], v[176:179], v[192:195], v[96:99]
	v_mfma_f32_16x16x32_bf16 v[84:87], v[168:171], v[200:203], v[84:87]
	v_mfma_f32_16x16x32_bf16 v[80:83], v[176:179], v[200:203], v[80:83]
	v_mfma_f32_16x16x32_bf16 v[68:71], v[168:171], v[208:211], v[68:71]
	v_mfma_f32_16x16x32_bf16 v[64:67], v[176:179], v[208:211], v[64:67]
	s_setprio 0
	s_barrier
; #define PG8_STAGE(bufoff, gbase, voff) do { _Pragma("unroll") for (int _i = 0; _i < 2; ++_i) \
;         __builtin_amdgcn_global_load_lds((const unsigned*)((const char*)(gbase) + (voff)[_i]), (LAS unsigned*)(lds + (bufoff) + ldsw + _i * 8192), 16, 0, 0); } while (0)
; #define PG8_LDA(dst, b, h) do { _Pragma("unroll") for (int m = 0; m < 4; ++m) _Pragma("unroll") for (int k = 0; k < 2; ++k) dst[m][k] = *(const LAS bf16x8*)(lds + PG8_SA(b, h) + aoff + m * 2048 + k * 1024); } while (0)
; #define PG8_MMA(ai, bj, At, Bt) do { __builtin_amdgcn_s_setprio(1); _Pragma("unroll") for (int m = 0; m < 4; ++m) _Pragma("unroll") for (int n = 0; n < 2; ++n) _Pragma("unroll") for (int k = 0; k < 2; ++k) \
;         acc[ai][bj][m][n] = __builtin_amdgcn_mfma_f32_16x16x32_bf16(Bt[n][k], At[m][k], acc[ai][bj][m][n], 0, 0, 0); __builtin_amdgcn_s_setprio(0); } while (0)
; #define PG8_WAIT_V(n) asm volatile("s_waitcnt vmcnt(" #n ")" ::: "memory")
; #define PG8_WAIT_L(n) asm volatile("s_waitcnt lgkmcnt(" #n ")" ::: "memory")
; #define PG8_BAR __builtin_amdgcn_s_barrier()
; #define PG8_SCHED __builtin_amdgcn_sched_barrier(0)
; template <class Epi, class Sched, bool ALIGN_EPI>
; DI void gemm_phase(LAS unsigned char* lds, const Gemm g, const Sched& S, const Epi& E) {
;     ...
;             PG8_LDA(At, 1, 1); PG8_STAGE(PG8_SB(1, 0), b3, voffB); PG8_STAGE(PG8_SB(1, 1), b3 + hstepB, voffB); PG8_STAGE(PG8_SA(1, 0), a3, voffA);
;             PG8_WAIT_V(8); PG8_WAIT_L(0); PG8_BAR; PG8_MMA(1, 0, At, B0); PG8_MMA(1, 1, At, B1); PG8_BAR; PG8_SCHED;
;         }
;         if constexpr (ALIGN_EPI) { if (wr == 0) PG8_BAR; }
	s_add_i32 s26, s45, s37
	v_lshl_add_u64 v[212:213], v[212:213], 0, s[8:9]
	s_mov_b32 m0, s26
	ds_read_b128 v[180:183], v152 offset:49152
	ds_read_b128 v[184:187], v152 offset:50176
	ds_read_b128 v[188:191], v152 offset:51200
	ds_read_b128 v[192:195], v152 offset:52224
	ds_read_b128 v[196:199], v152 offset:53248
	ds_read_b128 v[200:203], v152 offset:54272
	ds_read_b128 v[204:207], v152 offset:55296
	ds_read_b128 v[208:211], v152 offset:56320
	global_load_lds_dwordx4 v[212:213], off
	s_add_i32 m0, s26, 0x2000
	s_add_u32 s24, s24, 0x40080
	v_lshl_add_u64 v[212:213], v[214:215], 0, s[8:9]
	s_addc_u32 s25, s25, 0
	s_add_i32 s26, s46, s37
	global_load_lds_dwordx4 v[212:213], off
	v_lshl_add_u64 v[212:213], s[24:25], 0, v[128:129]
	s_mov_b32 m0, s26
	s_nop 0
	global_load_lds_dwordx4 v[212:213], off
	v_lshl_add_u64 v[212:213], s[24:25], 0, v[130:131]
	s_add_i32 m0, s26, 0x2000
	s_nop 0
	global_load_lds_dwordx4 v[212:213], off
	v_lshl_add_u64 v[212:213], v[216:217], 0, s[8:9]
	s_mov_b32 m0, s34
	s_nop 0
	global_load_lds_dwordx4 v[212:213], off
	v_lshl_add_u64 v[212:213], v[218:219], 0, s[8:9]
	s_mov_b32 m0, s35
	s_nop 0
	global_load_lds_dwordx4 v[212:213], off
	s_waitcnt vmcnt(8)
	s_waitcnt lgkmcnt(0)
	s_barrier
	s_setprio 1
	s_waitcnt lgkmcnt(0)
	v_mfma_f32_16x16x32_bf16 v[60:63], v[140:143], v[180:183], v[60:63]
	v_mfma_f32_16x16x32_bf16 v[56:59], v[156:159], v[180:183], v[56:59]
	v_mfma_f32_16x16x32_bf16 v[44:47], v[140:143], v[188:191], v[44:47]
	v_mfma_f32_16x16x32_bf16 v[40:43], v[156:159], v[188:191], v[40:43]
	v_mfma_f32_16x16x32_bf16 v[28:31], v[140:143], v[196:199], v[28:31]
	v_mfma_f32_16x16x32_bf16 v[24:27], v[156:159], v[196:199], v[24:27]
	v_mfma_f32_16x16x32_bf16 v[12:15], v[140:143], v[204:207], v[12:15]
	v_mfma_f32_16x16x32_bf16 v[8:11], v[156:159], v[204:207], v[8:11]
	v_mfma_f32_16x16x32_bf16 v[60:63], v[144:147], v[184:187], v[60:63]
	v_mfma_f32_16x16x32_bf16 v[56:59], v[160:163], v[184:187], v[56:59]
	v_mfma_f32_16x16x32_bf16 v[44:47], v[144:147], v[192:195], v[44:47]
	v_mfma_f32_16x16x32_bf16 v[40:43], v[160:163], v[192:195], v[40:43]
	v_mfma_f32_16x16x32_bf16 v[28:31], v[144:147], v[200:203], v[28:31]
	v_mfma_f32_16x16x32_bf16 v[24:27], v[160:163], v[200:203], v[24:27]
	v_mfma_f32_16x16x32_bf16 v[12:15], v[144:147], v[208:211], v[12:15]
	v_mfma_f32_16x16x32_bf16 v[8:11], v[160:163], v[208:211], v[8:11]
	v_mfma_f32_16x16x32_bf16 v[52:55], v[164:167], v[180:183], v[52:55]
	v_mfma_f32_16x16x32_bf16 v[48:51], v[172:175], v[180:183], v[48:51]
	v_mfma_f32_16x16x32_bf16 v[36:39], v[164:167], v[188:191], v[36:39]
	v_mfma_f32_16x16x32_bf16 v[32:35], v[172:175], v[188:191], v[32:35]
	v_mfma_f32_16x16x32_bf16 v[20:23], v[164:167], v[196:199], v[20:23]
	v_mfma_f32_16x16x32_bf16 v[16:19], v[172:175], v[196:199], v[16:19]
	v_mfma_f32_16x16x32_bf16 v[4:7], v[164:167], v[204:207], v[4:7]
	v_mfma_f32_16x16x32_bf16 v[0:3], v[172:175], v[204:207], v[0:3]
	v_mfma_f32_16x16x32_bf16 v[52:55], v[168:171], v[184:187], v[52:55]
	v_mfma_f32_16x16x32_bf16 v[48:51], v[176:179], v[184:187], v[48:51]
	v_mfma_f32_16x16x32_bf16 v[36:39], v[168:171], v[192:195], v[36:39]
	v_mfma_f32_16x16x32_bf16 v[32:35], v[176:179], v[192:195], v[32:35]
	v_mfma_f32_16x16x32_bf16 v[20:23], v[168:171], v[200:203], v[20:23]
	v_mfma_f32_16x16x32_bf16 v[16:19], v[176:179], v[200:203], v[16:19]
	v_mfma_f32_16x16x32_bf16 v[4:7], v[168:171], v[208:211], v[4:7]
	v_mfma_f32_16x16x32_bf16 v[0:3], v[176:179], v[208:211], v[0:3]
	s_setprio 0
	s_barrier
	s_add_i32 s52, s52, 2
	s_add_u32 s22, s22, 0x100
	s_addc_u32 s23, s23, 0
	s_add_u32 s50, s50, 0x100
	s_addc_u32 s51, s51, 0
	s_cmp_gt_u32 s52, 13
	s_cbranch_scc0 .LBB0_2661
	s_and_b64 vcc, exec, s[10:11]
	s_cbranch_vccz .LBB0_2664
	s_barrier
